# v38 plus one s_nop 0 between the post-barrier wait and the first MFMA of each burst
# baseline (speedup 1.0000x reference)
.LBB0_379:
	v_add_u32_e32 v14, s56, v140
	v_add_u32_e32 v30, s57, v140
	ds_read_b128 v[2:5], v14
	ds_read_b128 v[6:9], v14 offset:1024
	ds_read_b128 v[10:13], v14 offset:2048
	ds_read_b128 v[14:17], v14 offset:3072
	ds_read_b128 v[18:21], v30
	ds_read_b128 v[22:25], v30 offset:1024
	ds_read_b128 v[26:29], v30 offset:2048
	ds_read_b128 v[30:33], v30 offset:3072
	v_add_u32_e32 v141, 0, v1
	ds_read_b128 v[34:37], v141
	ds_read_b128 v[38:41], v141 offset:1024
	ds_read_b128 v[42:45], v141 offset:2048
	ds_read_b128 v[46:49], v141 offset:3072
	ds_read_b128 v[50:53], v141 offset:4096
	ds_read_b128 v[54:57], v141 offset:5120
	ds_read_b128 v[58:61], v141 offset:6144
	ds_read_b128 v[62:65], v141 offset:7168
	s_waitcnt vmcnt(8)
	s_waitcnt lgkmcnt(0)
	s_barrier
	s_setprio 1
	s_waitcnt lgkmcnt(0)
	s_nop 0
	v_mfma_f32_16x16x32_bf16 v[66:69], v[2:5], v[34:37], 0
	v_mfma_f32_16x16x32_bf16 v[66:69], v[6:9], v[38:41], v[66:69]
	v_mfma_f32_16x16x32_bf16 v[70:73], v[10:13], v[34:37], 0
	v_mfma_f32_16x16x32_bf16 v[70:73], v[14:17], v[38:41], v[70:73]
	v_mfma_f32_16x16x32_bf16 v[78:81], v[10:13], v[42:45], 0
	v_mfma_f32_16x16x32_bf16 v[78:81], v[14:17], v[46:49], v[78:81]
	v_mfma_f32_16x16x32_bf16 v[74:77], v[2:5], v[42:45], 0
	v_mfma_f32_16x16x32_bf16 v[74:77], v[6:9], v[46:49], v[74:77]
	v_mfma_f32_16x16x32_bf16 v[82:85], v[2:5], v[50:53], 0
	v_mfma_f32_16x16x32_bf16 v[82:85], v[6:9], v[54:57], v[82:85]
	v_mfma_f32_16x16x32_bf16 v[86:89], v[10:13], v[50:53], 0
	v_mfma_f32_16x16x32_bf16 v[86:89], v[14:17], v[54:57], v[86:89]
	v_mfma_f32_16x16x32_bf16 v[94:97], v[10:13], v[58:61], 0
	v_mfma_f32_16x16x32_bf16 v[94:97], v[14:17], v[62:65], v[94:97]
	v_mfma_f32_16x16x32_bf16 v[90:93], v[2:5], v[58:61], 0
	v_mfma_f32_16x16x32_bf16 v[90:93], v[6:9], v[62:65], v[90:93]
	s_setprio 0
	s_setprio 1
	v_mfma_f32_16x16x32_bf16 v[98:101], v[18:21], v[34:37], 0
	v_mfma_f32_16x16x32_bf16 v[34:37], v[26:29], v[34:37], 0
	v_mfma_f32_16x16x32_bf16 v[102:105], v[18:21], v[42:45], 0
	v_mfma_f32_16x16x32_bf16 v[42:45], v[26:29], v[42:45], 0
	v_mfma_f32_16x16x32_bf16 v[106:109], v[18:21], v[50:53], 0
	v_mfma_f32_16x16x32_bf16 v[50:53], v[26:29], v[50:53], 0
	v_mfma_f32_16x16x32_bf16 v[110:113], v[18:21], v[58:61], 0
	v_mfma_f32_16x16x32_bf16 v[58:61], v[26:29], v[58:61], 0
	v_mfma_f32_16x16x32_bf16 v[98:101], v[22:25], v[38:41], v[98:101]
	v_mfma_f32_16x16x32_bf16 v[38:41], v[30:33], v[38:41], v[34:37]
	v_mfma_f32_16x16x32_bf16 v[102:105], v[22:25], v[46:49], v[102:105]
	v_mfma_f32_16x16x32_bf16 v[46:49], v[30:33], v[46:49], v[42:45]
	v_mfma_f32_16x16x32_bf16 v[106:109], v[22:25], v[54:57], v[106:109]
	v_mfma_f32_16x16x32_bf16 v[54:57], v[30:33], v[54:57], v[50:53]
	s_setprio 2
	s_barrier
	v_mfma_f32_16x16x32_bf16 v[110:113], v[22:25], v[62:65], v[110:113]
	v_mfma_f32_16x16x32_bf16 v[62:65], v[30:33], v[62:65], v[58:61]
	s_setprio 0
	v_lshl_add_u64 v[136:137], s[38:39], 0, v[130:131]
	s_add_i32 s60, s56, s21
	v_mov_b32_e32 v135, v131
	v_lshl_add_u64 v[142:143], v[136:137], 0, s[10:11]
	s_mov_b32 m0, s60
	v_lshl_add_u64 v[244:245], s[38:39], 0, v[134:135]
	ds_read_b128 v[34:37], v141 offset:16384
	ds_read_b128 v[42:45], v141 offset:17408
	ds_read_b128 v[50:53], v141 offset:18432
	ds_read_b128 v[58:61], v141 offset:19456
	ds_read_b128 v[114:117], v141 offset:20480
	ds_read_b128 v[118:121], v141 offset:21504
	ds_read_b128 v[122:125], v141 offset:22528
	ds_read_b128 v[126:129], v141 offset:23552
	global_load_lds_dwordx4 v[142:143], off
	v_lshl_add_u64 v[142:143], v[244:245], 0, s[10:11]
	s_add_i32 m0, s60, 0x2000
	s_add_i32 s60, s57, s21
	global_load_lds_dwordx4 v[142:143], off
	s_mov_b32 m0, s60
	v_mov_b32_e32 v139, v131
	global_load_lds_dwordx4 v130, s[40:41]
	s_add_i32 m0, s60, 0x2000
	v_lshl_add_u64 v[246:247], s[36:37], 0, v[138:139]
	v_mov_b32_e32 v133, v131
	global_load_lds_dwordx4 v134, s[40:41]
	v_lshl_add_u64 v[142:143], v[246:247], 0, s[10:11]
	s_mov_b32 m0, s33
	v_lshl_add_u64 v[248:249], s[36:37], 0, v[132:133]
	global_load_lds_dwordx4 v[142:143], off
	v_lshl_add_u64 v[142:143], v[248:249], 0, s[10:11]
	s_mov_b32 m0, s46
	s_nop 0
	global_load_lds_dwordx4 v[142:143], off
	s_waitcnt vmcnt(8)
	s_waitcnt lgkmcnt(0)
	s_barrier
	s_setprio 1
	s_waitcnt lgkmcnt(0)
	s_nop 0
	v_mfma_f32_16x16x32_bf16 v[142:145], v[2:5], v[34:37], 0
	v_mfma_f32_16x16x32_bf16 v[148:151], v[10:13], v[34:37], 0
	v_mfma_f32_16x16x32_bf16 v[152:155], v[2:5], v[50:53], 0
	v_mfma_f32_16x16x32_bf16 v[156:159], v[10:13], v[50:53], 0
	v_mfma_f32_16x16x32_bf16 v[160:163], v[2:5], v[114:117], 0
	v_mfma_f32_16x16x32_bf16 v[164:167], v[10:13], v[114:117], 0
	v_mfma_f32_16x16x32_bf16 v[2:5], v[2:5], v[122:125], 0
	v_mfma_f32_16x16x32_bf16 v[10:13], v[10:13], v[122:125], 0
	v_mfma_f32_16x16x32_bf16 v[142:145], v[6:9], v[42:45], v[142:145]
	v_mfma_f32_16x16x32_bf16 v[148:151], v[14:17], v[42:45], v[148:151]
	v_mfma_f32_16x16x32_bf16 v[152:155], v[6:9], v[58:61], v[152:155]
	v_mfma_f32_16x16x32_bf16 v[156:159], v[14:17], v[58:61], v[156:159]
	v_mfma_f32_16x16x32_bf16 v[160:163], v[6:9], v[118:121], v[160:163]
	v_mfma_f32_16x16x32_bf16 v[164:167], v[14:17], v[118:121], v[164:167]
	v_mfma_f32_16x16x32_bf16 v[168:171], v[6:9], v[126:129], v[2:5]
	v_mfma_f32_16x16x32_bf16 v[172:175], v[14:17], v[126:129], v[10:13]
	s_setprio 0
	s_setprio 1
	v_mfma_f32_16x16x32_bf16 v[2:5], v[18:21], v[34:37], 0
	v_mfma_f32_16x16x32_bf16 v[6:9], v[26:29], v[34:37], 0
	v_mfma_f32_16x16x32_bf16 v[10:13], v[18:21], v[50:53], 0
	v_mfma_f32_16x16x32_bf16 v[14:17], v[26:29], v[50:53], 0
	v_mfma_f32_16x16x32_bf16 v[34:37], v[18:21], v[114:117], 0
	v_mfma_f32_16x16x32_bf16 v[50:53], v[26:29], v[114:117], 0
	v_mfma_f32_16x16x32_bf16 v[18:21], v[18:21], v[122:125], 0
	v_mfma_f32_16x16x32_bf16 v[26:29], v[26:29], v[122:125], 0
	v_mfma_f32_16x16x32_bf16 v[114:117], v[22:25], v[42:45], v[2:5]
	v_mfma_f32_16x16x32_bf16 v[188:191], v[22:25], v[118:121], v[34:37]
	v_mfma_f32_16x16x32_bf16 v[118:121], v[30:33], v[118:121], v[50:53]
	v_mfma_f32_16x16x32_bf16 v[176:179], v[30:33], v[42:45], v[6:9]
	v_mfma_f32_16x16x32_bf16 v[180:183], v[22:25], v[58:61], v[10:13]
	v_mfma_f32_16x16x32_bf16 v[184:187], v[30:33], v[58:61], v[14:17]
	s_setprio 2
	s_barrier
	v_mfma_f32_16x16x32_bf16 v[192:195], v[22:25], v[126:129], v[18:21]
	v_mfma_f32_16x16x32_bf16 v[196:199], v[30:33], v[126:129], v[26:29]
	s_setprio 0
	s_add_i32 s60, 0, 0x18000
	v_add_u32_e32 v2, s60, v140
	s_add_i32 s61, 0, 0x1c000
	ds_read_b128 v[200:203], v2
	ds_read_b128 v[204:207], v2 offset:1024
	ds_read_b128 v[208:211], v2 offset:2048
	ds_read_b128 v[212:215], v2 offset:3072
	v_add_u32_e32 v2, s61, v140
	ds_read_b128 v[216:219], v2
	ds_read_b128 v[220:223], v2 offset:1024
	ds_read_b128 v[224:227], v2 offset:2048
	ds_read_b128 v[228:231], v2 offset:3072
	s_mov_b32 m0, s47
	ds_read_b128 v[42:45], v141 offset:32768
	ds_read_b128 v[50:53], v141 offset:33792
	ds_read_b128 v[58:61], v141 offset:34816
	ds_read_b128 v[122:125], v141 offset:35840
	ds_read_b128 v[126:129], v141 offset:36864
	ds_read_b128 v[232:235], v141 offset:37888
	ds_read_b128 v[236:239], v141 offset:38912
	ds_read_b128 v[240:243], v141 offset:39936
	global_load_lds_dwordx4 v138, s[42:43]
	s_mov_b32 m0, s48
	s_nop 0
	global_load_lds_dwordx4 v132, s[42:43]
	s_waitcnt vmcnt(8)
	s_waitcnt lgkmcnt(0)
	s_barrier
	s_setprio 1
	s_waitcnt lgkmcnt(0)
	s_nop 0
	v_mfma_f32_16x16x32_bf16 v[2:5], v[200:203], v[42:45], v[66:69]
	v_mfma_f32_16x16x32_bf16 v[6:9], v[208:211], v[42:45], v[70:73]
	v_mfma_f32_16x16x32_bf16 v[10:13], v[200:203], v[58:61], v[74:77]
	v_mfma_f32_16x16x32_bf16 v[14:17], v[208:211], v[58:61], v[78:81]
	v_mfma_f32_16x16x32_bf16 v[18:21], v[200:203], v[126:129], v[82:85]
	v_mfma_f32_16x16x32_bf16 v[22:25], v[208:211], v[126:129], v[86:89]
	v_mfma_f32_16x16x32_bf16 v[26:29], v[200:203], v[236:239], v[90:93]
	v_mfma_f32_16x16x32_bf16 v[30:33], v[208:211], v[236:239], v[94:97]
	v_mfma_f32_16x16x32_bf16 v[2:5], v[204:207], v[50:53], v[2:5]
	v_mfma_f32_16x16x32_bf16 v[6:9], v[212:215], v[50:53], v[6:9]
	v_mfma_f32_16x16x32_bf16 v[10:13], v[204:207], v[122:125], v[10:13]
	v_mfma_f32_16x16x32_bf16 v[14:17], v[212:215], v[122:125], v[14:17]
	v_mfma_f32_16x16x32_bf16 v[18:21], v[204:207], v[232:235], v[18:21]
	v_mfma_f32_16x16x32_bf16 v[22:25], v[212:215], v[232:235], v[22:25]
	v_mfma_f32_16x16x32_bf16 v[26:29], v[204:207], v[240:243], v[26:29]
	v_mfma_f32_16x16x32_bf16 v[30:33], v[212:215], v[240:243], v[30:33]
	s_setprio 0
	s_setprio 1
	v_mfma_f32_16x16x32_bf16 v[34:37], v[216:219], v[42:45], v[98:101]
	v_mfma_f32_16x16x32_bf16 v[38:41], v[224:227], v[42:45], v[38:41]
	v_mfma_f32_16x16x32_bf16 v[34:37], v[220:223], v[50:53], v[34:37]
	v_mfma_f32_16x16x32_bf16 v[38:41], v[228:231], v[50:53], v[38:41]
	v_mfma_f32_16x16x32_bf16 v[42:45], v[216:219], v[58:61], v[102:105]
	v_mfma_f32_16x16x32_bf16 v[46:49], v[224:227], v[58:61], v[46:49]
	v_mfma_f32_16x16x32_bf16 v[50:53], v[216:219], v[126:129], v[106:109]
	v_mfma_f32_16x16x32_bf16 v[54:57], v[224:227], v[126:129], v[54:57]
	v_mfma_f32_16x16x32_bf16 v[58:61], v[216:219], v[236:239], v[110:113]
	v_mfma_f32_16x16x32_bf16 v[62:65], v[224:227], v[236:239], v[62:65]
	v_mfma_f32_16x16x32_bf16 v[42:45], v[220:223], v[122:125], v[42:45]
	v_mfma_f32_16x16x32_bf16 v[46:49], v[228:231], v[122:125], v[46:49]
	v_mfma_f32_16x16x32_bf16 v[50:53], v[220:223], v[232:235], v[50:53]
	v_mfma_f32_16x16x32_bf16 v[54:57], v[228:231], v[232:235], v[54:57]
	s_setprio 2
	s_barrier
	v_mfma_f32_16x16x32_bf16 v[58:61], v[220:223], v[240:243], v[58:61]
	v_mfma_f32_16x16x32_bf16 v[62:65], v[228:231], v[240:243], v[62:65]
	s_setprio 0
	s_add_i32 s60, s60, s21
	v_lshl_add_u64 v[66:67], v[136:137], 0, s[12:13]
	s_mov_b32 m0, s60
	ds_read_b128 v[94:97], v141 offset:49152
	ds_read_b128 v[98:101], v141 offset:50176
	ds_read_b128 v[102:105], v141 offset:51200
	ds_read_b128 v[106:109], v141 offset:52224
	ds_read_b128 v[110:113], v141 offset:53248
	ds_read_b128 v[232:235], v141 offset:54272
	ds_read_b128 v[236:239], v141 offset:55296
	ds_read_b128 v[240:243], v141 offset:56320
	global_load_lds_dwordx4 v[66:67], off
	v_lshl_add_u64 v[66:67], v[244:245], 0, s[12:13]
	s_add_i32 m0, s60, 0x2000
	s_add_i32 s60, s61, s21
	global_load_lds_dwordx4 v[66:67], off
	s_mov_b32 m0, s60
	v_lshl_add_u64 v[66:67], v[246:247], 0, s[12:13]
	global_load_lds_dwordx4 v130, s[44:45]
	s_add_i32 m0, s60, 0x2000
	s_nop 0
	global_load_lds_dwordx4 v134, s[44:45]
	s_mov_b32 m0, s52
	s_nop 0
	global_load_lds_dwordx4 v[66:67], off
	v_lshl_add_u64 v[66:67], v[248:249], 0, s[12:13]
	s_mov_b32 m0, s53
	s_nop 0
	global_load_lds_dwordx4 v[66:67], off
	s_waitcnt vmcnt(8)
	s_waitcnt lgkmcnt(0)
	s_barrier
	s_setprio 1
	s_waitcnt lgkmcnt(0)
	s_nop 0
	v_mfma_f32_16x16x32_bf16 v[66:69], v[200:203], v[94:97], v[142:145]
	v_mfma_f32_16x16x32_bf16 v[122:125], v[204:207], v[98:101], v[66:69]
	v_mfma_f32_16x16x32_bf16 v[66:69], v[208:211], v[94:97], v[148:151]
	v_mfma_f32_16x16x32_bf16 v[126:129], v[212:215], v[98:101], v[66:69]
	v_mfma_f32_16x16x32_bf16 v[66:69], v[200:203], v[102:105], v[152:155]
	v_mfma_f32_16x16x32_bf16 v[70:73], v[208:211], v[102:105], v[156:159]
	v_mfma_f32_16x16x32_bf16 v[74:77], v[200:203], v[110:113], v[160:163]
	v_mfma_f32_16x16x32_bf16 v[78:81], v[208:211], v[110:113], v[164:167]
	v_mfma_f32_16x16x32_bf16 v[82:85], v[200:203], v[236:239], v[168:171]
	v_mfma_f32_16x16x32_bf16 v[86:89], v[208:211], v[236:239], v[172:175]
	v_mfma_f32_16x16x32_bf16 v[66:69], v[204:207], v[106:109], v[66:69]
	v_mfma_f32_16x16x32_bf16 v[70:73], v[212:215], v[106:109], v[70:73]
	v_mfma_f32_16x16x32_bf16 v[74:77], v[204:207], v[232:235], v[74:77]
	v_mfma_f32_16x16x32_bf16 v[78:81], v[212:215], v[232:235], v[78:81]
	v_mfma_f32_16x16x32_bf16 v[82:85], v[204:207], v[240:243], v[82:85]
	v_mfma_f32_16x16x32_bf16 v[86:89], v[212:215], v[240:243], v[86:89]
	s_setprio 0
	s_setprio 1
	v_mfma_f32_16x16x32_bf16 v[90:93], v[216:219], v[94:97], v[114:117]
	v_mfma_f32_16x16x32_bf16 v[94:97], v[224:227], v[94:97], v[176:179]
	v_mfma_f32_16x16x32_bf16 v[90:93], v[220:223], v[98:101], v[90:93]
	v_mfma_f32_16x16x32_bf16 v[94:97], v[228:231], v[98:101], v[94:97]
	v_mfma_f32_16x16x32_bf16 v[98:101], v[216:219], v[102:105], v[180:183]
	v_mfma_f32_16x16x32_bf16 v[102:105], v[224:227], v[102:105], v[184:187]
	v_mfma_f32_16x16x32_bf16 v[98:101], v[220:223], v[106:109], v[98:101]
	v_mfma_f32_16x16x32_bf16 v[102:105], v[228:231], v[106:109], v[102:105]
	v_mfma_f32_16x16x32_bf16 v[106:109], v[216:219], v[110:113], v[188:191]
	v_mfma_f32_16x16x32_bf16 v[110:113], v[224:227], v[110:113], v[118:121]
	v_mfma_f32_16x16x32_bf16 v[114:117], v[216:219], v[236:239], v[192:195]
	v_mfma_f32_16x16x32_bf16 v[118:121], v[224:227], v[236:239], v[196:199]
	v_mfma_f32_16x16x32_bf16 v[106:109], v[220:223], v[232:235], v[106:109]
	v_mfma_f32_16x16x32_bf16 v[110:113], v[228:231], v[232:235], v[110:113]
	s_setprio 2
	s_barrier
	v_mfma_f32_16x16x32_bf16 v[114:117], v[220:223], v[240:243], v[114:117]
	v_mfma_f32_16x16x32_bf16 v[118:121], v[228:231], v[240:243], v[118:121]
	s_setprio 0
	s_add_i32 s59, s59, 2
	s_cmp_ge_i32 s59, s15
	s_cbranch_scc0 .LBB0_379
	v_mov_b32_e32 v136, v130
	s_branch .LBB0_382

.LBB0_383:
	v_add_u32_e32 v133, s56, v140
	ds_read_b128 v[142:145], v133
	ds_read_b128 v[148:151], v133 offset:1024
	ds_read_b128 v[152:155], v133 offset:2048
	ds_read_b128 v[156:159], v133 offset:3072
	v_add_u32_e32 v133, s57, v140
	ds_read_b128 v[160:163], v133
	ds_read_b128 v[164:167], v133 offset:1024
	ds_read_b128 v[168:171], v133 offset:2048
	ds_read_b128 v[172:175], v133 offset:3072
	s_add_u32 s38, s36, 0xfff80080
	s_addc_u32 s39, s37, -1
	s_cmp_eq_u32 s43, 28
	s_cselect_b32 s41, s31, s39
	s_cselect_b32 s40, s30, s38
	s_cselect_b32 s39, s35, s42
	s_cselect_b32 s38, s34, s15
	s_mov_b32 m0, s54
	v_add_u32_e32 v141, 0, v1
	ds_read_b128 v[176:179], v141
	ds_read_b128 v[180:183], v141 offset:1024
	ds_read_b128 v[184:187], v141 offset:2048
	ds_read_b128 v[188:191], v141 offset:3072
	ds_read_b128 v[192:195], v141 offset:4096
	ds_read_b128 v[196:199], v141 offset:5120
	ds_read_b128 v[200:203], v141 offset:6144
	ds_read_b128 v[204:207], v141 offset:7168
	global_load_lds_dwordx4 v130, s[36:37]
	s_mov_b32 m0, s55
	v_mov_b32_e32 v133, v131
	global_load_lds_dwordx4 v132, s[36:37]
	s_waitcnt vmcnt(8)
	s_waitcnt lgkmcnt(0)
	s_barrier
	s_setprio 1
	s_waitcnt lgkmcnt(0)
	s_nop 0
	v_mfma_f32_16x16x32_bf16 v[2:5], v[142:145], v[176:179], v[2:5]
	v_mfma_f32_16x16x32_bf16 v[2:5], v[148:151], v[180:183], v[2:5]
	v_mfma_f32_16x16x32_bf16 v[6:9], v[156:159], v[180:183], v[6:9]
	v_mfma_f32_16x16x32_bf16 v[6:9], v[152:155], v[176:179], v[6:9]
	v_mfma_f32_16x16x32_bf16 v[14:17], v[152:155], v[184:187], v[14:17]
	v_mfma_f32_16x16x32_bf16 v[14:17], v[156:159], v[188:191], v[14:17]
	v_mfma_f32_16x16x32_bf16 v[10:13], v[148:151], v[188:191], v[10:13]
	v_mfma_f32_16x16x32_bf16 v[10:13], v[142:145], v[184:187], v[10:13]
	v_mfma_f32_16x16x32_bf16 v[18:21], v[142:145], v[192:195], v[18:21]
	v_mfma_f32_16x16x32_bf16 v[18:21], v[148:151], v[196:199], v[18:21]
	v_mfma_f32_16x16x32_bf16 v[22:25], v[156:159], v[196:199], v[22:25]
	v_mfma_f32_16x16x32_bf16 v[22:25], v[152:155], v[192:195], v[22:25]
	v_mfma_f32_16x16x32_bf16 v[30:33], v[152:155], v[200:203], v[30:33]
	v_mfma_f32_16x16x32_bf16 v[30:33], v[156:159], v[204:207], v[30:33]
	v_mfma_f32_16x16x32_bf16 v[26:29], v[148:151], v[204:207], v[26:29]
	v_mfma_f32_16x16x32_bf16 v[26:29], v[142:145], v[200:203], v[26:29]
	s_setprio 0
	s_setprio 1
	v_mfma_f32_16x16x32_bf16 v[34:37], v[160:163], v[176:179], v[34:37]
	v_mfma_f32_16x16x32_bf16 v[34:37], v[164:167], v[180:183], v[34:37]
	v_mfma_f32_16x16x32_bf16 v[38:41], v[172:175], v[180:183], v[38:41]
	v_mfma_f32_16x16x32_bf16 v[38:41], v[168:171], v[176:179], v[38:41]
	v_mfma_f32_16x16x32_bf16 v[46:49], v[168:171], v[184:187], v[46:49]
	v_mfma_f32_16x16x32_bf16 v[46:49], v[172:175], v[188:191], v[46:49]
	v_mfma_f32_16x16x32_bf16 v[42:45], v[164:167], v[188:191], v[42:45]
	v_mfma_f32_16x16x32_bf16 v[42:45], v[160:163], v[184:187], v[42:45]
	v_mfma_f32_16x16x32_bf16 v[50:53], v[160:163], v[192:195], v[50:53]
	v_mfma_f32_16x16x32_bf16 v[50:53], v[164:167], v[196:199], v[50:53]
	v_mfma_f32_16x16x32_bf16 v[54:57], v[172:175], v[196:199], v[54:57]
	v_mfma_f32_16x16x32_bf16 v[54:57], v[168:171], v[192:195], v[54:57]
	v_mfma_f32_16x16x32_bf16 v[62:65], v[168:171], v[200:203], v[62:65]
	v_mfma_f32_16x16x32_bf16 v[62:65], v[172:175], v[204:207], v[62:65]
	s_setprio 2
	s_barrier
	v_mfma_f32_16x16x32_bf16 v[58:61], v[164:167], v[204:207], v[58:61]
	v_mfma_f32_16x16x32_bf16 v[58:61], v[160:163], v[200:203], v[58:61]
	s_setprio 0
	s_add_i32 s44, s56, s21
	s_mov_b32 m0, s44
	ds_read_b128 v[176:179], v141 offset:16384
	ds_read_b128 v[180:183], v141 offset:17408
	ds_read_b128 v[184:187], v141 offset:18432
	ds_read_b128 v[188:191], v141 offset:19456
	ds_read_b128 v[192:195], v141 offset:20480
	ds_read_b128 v[196:199], v141 offset:21504
	ds_read_b128 v[200:203], v141 offset:22528
	ds_read_b128 v[204:207], v141 offset:23552
	global_load_lds_dwordx4 v136, s[38:39]
	s_add_i32 m0, s44, 0x2000
	s_add_u32 s44, s38, 0x80000
	s_addc_u32 s45, s39, 0
	s_add_i32 s59, s57, s21
	global_load_lds_dwordx4 v134, s[38:39]
	s_mov_b32 m0, s59
	v_mov_b32_e32 v137, v131
	global_load_lds_dwordx4 v136, s[44:45]
	s_add_i32 m0, s59, 0x2000
	v_mov_b32_e32 v135, v131
	global_load_lds_dwordx4 v134, s[44:45]
	s_mov_b32 m0, s33
	v_lshl_add_u64 v[138:139], s[38:39], 0, v[136:137]
	global_load_lds_dwordx4 v130, s[40:41]
	s_mov_b32 m0, s46
	v_lshl_add_u64 v[208:209], s[38:39], 0, v[134:135]
	global_load_lds_dwordx4 v132, s[40:41]
	s_waitcnt vmcnt(8)
	s_waitcnt lgkmcnt(0)
	v_lshl_add_u64 v[210:211], s[40:41], 0, v[130:131]
	v_lshl_add_u64 v[212:213], s[40:41], 0, v[132:133]
	s_barrier
	s_setprio 1
	s_waitcnt lgkmcnt(0)
	s_nop 0
	v_mfma_f32_16x16x32_bf16 v[122:125], v[142:145], v[176:179], v[122:125]
	v_mfma_f32_16x16x32_bf16 v[122:125], v[148:151], v[180:183], v[122:125]
	v_mfma_f32_16x16x32_bf16 v[126:129], v[156:159], v[180:183], v[126:129]
	v_mfma_f32_16x16x32_bf16 v[126:129], v[152:155], v[176:179], v[126:129]
	v_mfma_f32_16x16x32_bf16 v[70:73], v[152:155], v[184:187], v[70:73]
	v_mfma_f32_16x16x32_bf16 v[70:73], v[156:159], v[188:191], v[70:73]
	v_mfma_f32_16x16x32_bf16 v[66:69], v[148:151], v[188:191], v[66:69]
	v_mfma_f32_16x16x32_bf16 v[66:69], v[142:145], v[184:187], v[66:69]
	v_mfma_f32_16x16x32_bf16 v[74:77], v[142:145], v[192:195], v[74:77]
	v_mfma_f32_16x16x32_bf16 v[74:77], v[148:151], v[196:199], v[74:77]
	v_mfma_f32_16x16x32_bf16 v[78:81], v[156:159], v[196:199], v[78:81]
	v_mfma_f32_16x16x32_bf16 v[78:81], v[152:155], v[192:195], v[78:81]
	v_mfma_f32_16x16x32_bf16 v[86:89], v[152:155], v[200:203], v[86:89]
	v_mfma_f32_16x16x32_bf16 v[86:89], v[156:159], v[204:207], v[86:89]
	v_mfma_f32_16x16x32_bf16 v[82:85], v[148:151], v[204:207], v[82:85]
	v_mfma_f32_16x16x32_bf16 v[82:85], v[142:145], v[200:203], v[82:85]
	s_setprio 0
	s_setprio 1
	v_mfma_f32_16x16x32_bf16 v[90:93], v[160:163], v[176:179], v[90:93]
	v_mfma_f32_16x16x32_bf16 v[90:93], v[164:167], v[180:183], v[90:93]
	v_mfma_f32_16x16x32_bf16 v[94:97], v[172:175], v[180:183], v[94:97]
	v_mfma_f32_16x16x32_bf16 v[94:97], v[168:171], v[176:179], v[94:97]
	v_mfma_f32_16x16x32_bf16 v[102:105], v[168:171], v[184:187], v[102:105]
	v_mfma_f32_16x16x32_bf16 v[102:105], v[172:175], v[188:191], v[102:105]
	v_mfma_f32_16x16x32_bf16 v[98:101], v[164:167], v[188:191], v[98:101]
	v_mfma_f32_16x16x32_bf16 v[98:101], v[160:163], v[184:187], v[98:101]
	v_mfma_f32_16x16x32_bf16 v[106:109], v[160:163], v[192:195], v[106:109]
	v_mfma_f32_16x16x32_bf16 v[106:109], v[164:167], v[196:199], v[106:109]
	v_mfma_f32_16x16x32_bf16 v[110:113], v[172:175], v[196:199], v[110:113]
	v_mfma_f32_16x16x32_bf16 v[110:113], v[168:171], v[192:195], v[110:113]
	v_mfma_f32_16x16x32_bf16 v[118:121], v[168:171], v[200:203], v[118:121]
	v_mfma_f32_16x16x32_bf16 v[118:121], v[172:175], v[204:207], v[118:121]
	s_setprio 2
	s_barrier
	v_mfma_f32_16x16x32_bf16 v[114:117], v[164:167], v[204:207], v[114:117]
	v_mfma_f32_16x16x32_bf16 v[114:117], v[160:163], v[200:203], v[114:117]
	s_setprio 0
	s_add_i32 s44, 0, 0x18000
	v_add_u32_e32 v135, s44, v140
	s_add_i32 s45, 0, 0x1c000
	ds_read_b128 v[142:145], v135
	ds_read_b128 v[148:151], v135 offset:1024
	ds_read_b128 v[152:155], v135 offset:2048
	ds_read_b128 v[156:159], v135 offset:3072
	v_add_u32_e32 v135, s45, v140
	ds_read_b128 v[160:163], v135
	ds_read_b128 v[164:167], v135 offset:1024
	ds_read_b128 v[168:171], v135 offset:2048
	ds_read_b128 v[172:175], v135 offset:3072
	s_add_u32 s40, s40, 0x80000
	s_addc_u32 s41, s41, 0
	s_mov_b32 m0, s47
	ds_read_b128 v[176:179], v141 offset:32768
	ds_read_b128 v[180:183], v141 offset:33792
	ds_read_b128 v[184:187], v141 offset:34816
	ds_read_b128 v[188:191], v141 offset:35840
	ds_read_b128 v[192:195], v141 offset:36864
	ds_read_b128 v[196:199], v141 offset:37888
	ds_read_b128 v[200:203], v141 offset:38912
	ds_read_b128 v[204:207], v141 offset:39936
	global_load_lds_dwordx4 v130, s[40:41]
	s_mov_b32 m0, s48
	s_nop 0
	global_load_lds_dwordx4 v132, s[40:41]
	s_waitcnt vmcnt(8)
	s_waitcnt lgkmcnt(0)
	s_barrier
	s_setprio 1
	s_waitcnt lgkmcnt(0)
	s_nop 0
	v_mfma_f32_16x16x32_bf16 v[2:5], v[142:145], v[176:179], v[2:5]
	v_mfma_f32_16x16x32_bf16 v[2:5], v[148:151], v[180:183], v[2:5]
	v_mfma_f32_16x16x32_bf16 v[6:9], v[156:159], v[180:183], v[6:9]
	v_mfma_f32_16x16x32_bf16 v[6:9], v[152:155], v[176:179], v[6:9]
	v_mfma_f32_16x16x32_bf16 v[14:17], v[152:155], v[184:187], v[14:17]
	v_mfma_f32_16x16x32_bf16 v[14:17], v[156:159], v[188:191], v[14:17]
	v_mfma_f32_16x16x32_bf16 v[10:13], v[148:151], v[188:191], v[10:13]
	v_mfma_f32_16x16x32_bf16 v[10:13], v[142:145], v[184:187], v[10:13]
	v_mfma_f32_16x16x32_bf16 v[18:21], v[142:145], v[192:195], v[18:21]
	v_mfma_f32_16x16x32_bf16 v[18:21], v[148:151], v[196:199], v[18:21]
	v_mfma_f32_16x16x32_bf16 v[22:25], v[156:159], v[196:199], v[22:25]
	v_mfma_f32_16x16x32_bf16 v[22:25], v[152:155], v[192:195], v[22:25]
	v_mfma_f32_16x16x32_bf16 v[30:33], v[152:155], v[200:203], v[30:33]
	v_mfma_f32_16x16x32_bf16 v[30:33], v[156:159], v[204:207], v[30:33]
	v_mfma_f32_16x16x32_bf16 v[26:29], v[148:151], v[204:207], v[26:29]
	v_mfma_f32_16x16x32_bf16 v[26:29], v[142:145], v[200:203], v[26:29]
	s_setprio 0
	s_setprio 1
	v_mfma_f32_16x16x32_bf16 v[34:37], v[160:163], v[176:179], v[34:37]
	v_mfma_f32_16x16x32_bf16 v[34:37], v[164:167], v[180:183], v[34:37]
	v_mfma_f32_16x16x32_bf16 v[38:41], v[172:175], v[180:183], v[38:41]
	v_mfma_f32_16x16x32_bf16 v[38:41], v[168:171], v[176:179], v[38:41]
	v_mfma_f32_16x16x32_bf16 v[46:49], v[168:171], v[184:187], v[46:49]
	v_mfma_f32_16x16x32_bf16 v[46:49], v[172:175], v[188:191], v[46:49]
	v_mfma_f32_16x16x32_bf16 v[42:45], v[164:167], v[188:191], v[42:45]
	v_mfma_f32_16x16x32_bf16 v[42:45], v[160:163], v[184:187], v[42:45]
	v_mfma_f32_16x16x32_bf16 v[50:53], v[160:163], v[192:195], v[50:53]
	v_mfma_f32_16x16x32_bf16 v[50:53], v[164:167], v[196:199], v[50:53]
	v_mfma_f32_16x16x32_bf16 v[54:57], v[172:175], v[196:199], v[54:57]
	v_mfma_f32_16x16x32_bf16 v[54:57], v[168:171], v[192:195], v[54:57]
	v_mfma_f32_16x16x32_bf16 v[62:65], v[168:171], v[200:203], v[62:65]
	v_mfma_f32_16x16x32_bf16 v[62:65], v[172:175], v[204:207], v[62:65]
	s_setprio 2
	s_barrier
	v_mfma_f32_16x16x32_bf16 v[58:61], v[164:167], v[204:207], v[58:61]
	v_mfma_f32_16x16x32_bf16 v[58:61], v[160:163], v[200:203], v[58:61]
	s_setprio 0
	s_add_i32 s40, s44, s21
	v_lshl_add_u64 v[138:139], v[138:139], 0, s[6:7]
	s_mov_b32 m0, s40
	ds_read_b128 v[176:179], v141 offset:49152
	ds_read_b128 v[180:183], v141 offset:50176
	ds_read_b128 v[184:187], v141 offset:51200
	ds_read_b128 v[188:191], v141 offset:52224
	ds_read_b128 v[192:195], v141 offset:53248
	ds_read_b128 v[196:199], v141 offset:54272
	ds_read_b128 v[200:203], v141 offset:55296
	ds_read_b128 v[204:207], v141 offset:56320
	global_load_lds_dwordx4 v[138:139], off
	s_add_i32 m0, s40, 0x2000
	s_add_u32 s38, s38, 0x80080
	v_lshl_add_u64 v[138:139], v[208:209], 0, s[6:7]
	s_addc_u32 s39, s39, 0
	s_add_i32 s40, s45, s21
	global_load_lds_dwordx4 v[138:139], off
	s_mov_b32 m0, s40
	v_lshl_add_u64 v[138:139], v[210:211], 0, s[6:7]
	global_load_lds_dwordx4 v136, s[38:39]
	s_add_i32 m0, s40, 0x2000
	s_nop 0
	global_load_lds_dwordx4 v134, s[38:39]
	s_mov_b32 m0, s52
	s_nop 0
	global_load_lds_dwordx4 v[138:139], off
	v_lshl_add_u64 v[138:139], v[212:213], 0, s[6:7]
	s_mov_b32 m0, s53
	s_nop 0
	global_load_lds_dwordx4 v[138:139], off
	s_waitcnt vmcnt(8)
	s_waitcnt lgkmcnt(0)
	s_barrier
	s_setprio 1
	s_waitcnt lgkmcnt(0)
	s_nop 0
	v_mfma_f32_16x16x32_bf16 v[122:125], v[142:145], v[176:179], v[122:125]
	v_mfma_f32_16x16x32_bf16 v[122:125], v[148:151], v[180:183], v[122:125]
	v_mfma_f32_16x16x32_bf16 v[126:129], v[156:159], v[180:183], v[126:129]
	v_mfma_f32_16x16x32_bf16 v[126:129], v[152:155], v[176:179], v[126:129]
	v_mfma_f32_16x16x32_bf16 v[70:73], v[152:155], v[184:187], v[70:73]
	v_mfma_f32_16x16x32_bf16 v[70:73], v[156:159], v[188:191], v[70:73]
	v_mfma_f32_16x16x32_bf16 v[66:69], v[148:151], v[188:191], v[66:69]
	v_mfma_f32_16x16x32_bf16 v[66:69], v[142:145], v[184:187], v[66:69]
	v_mfma_f32_16x16x32_bf16 v[74:77], v[142:145], v[192:195], v[74:77]
	v_mfma_f32_16x16x32_bf16 v[74:77], v[148:151], v[196:199], v[74:77]
	v_mfma_f32_16x16x32_bf16 v[78:81], v[156:159], v[196:199], v[78:81]
	v_mfma_f32_16x16x32_bf16 v[78:81], v[152:155], v[192:195], v[78:81]
	v_mfma_f32_16x16x32_bf16 v[86:89], v[152:155], v[200:203], v[86:89]
	v_mfma_f32_16x16x32_bf16 v[86:89], v[156:159], v[204:207], v[86:89]
	v_mfma_f32_16x16x32_bf16 v[82:85], v[148:151], v[204:207], v[82:85]
	v_mfma_f32_16x16x32_bf16 v[82:85], v[142:145], v[200:203], v[82:85]
	s_setprio 0
	s_setprio 1
	v_mfma_f32_16x16x32_bf16 v[90:93], v[160:163], v[176:179], v[90:93]
	v_mfma_f32_16x16x32_bf16 v[90:93], v[164:167], v[180:183], v[90:93]
	v_mfma_f32_16x16x32_bf16 v[94:97], v[172:175], v[180:183], v[94:97]
	v_mfma_f32_16x16x32_bf16 v[94:97], v[168:171], v[176:179], v[94:97]
	v_mfma_f32_16x16x32_bf16 v[102:105], v[168:171], v[184:187], v[102:105]
	v_mfma_f32_16x16x32_bf16 v[102:105], v[172:175], v[188:191], v[102:105]
	v_mfma_f32_16x16x32_bf16 v[98:101], v[164:167], v[188:191], v[98:101]
	v_mfma_f32_16x16x32_bf16 v[98:101], v[160:163], v[184:187], v[98:101]
	v_mfma_f32_16x16x32_bf16 v[106:109], v[160:163], v[192:195], v[106:109]
	v_mfma_f32_16x16x32_bf16 v[106:109], v[164:167], v[196:199], v[106:109]
	v_mfma_f32_16x16x32_bf16 v[110:113], v[172:175], v[196:199], v[110:113]
	v_mfma_f32_16x16x32_bf16 v[110:113], v[168:171], v[192:195], v[110:113]
	v_mfma_f32_16x16x32_bf16 v[118:121], v[168:171], v[200:203], v[118:121]
	v_mfma_f32_16x16x32_bf16 v[118:121], v[172:175], v[204:207], v[118:121]
	s_setprio 2
	s_barrier
	v_mfma_f32_16x16x32_bf16 v[114:117], v[164:167], v[204:207], v[114:117]
	v_mfma_f32_16x16x32_bf16 v[114:117], v[160:163], v[200:203], v[114:117]
	s_setprio 0
	s_add_i32 s43, s43, 2
	s_add_u32 s36, s36, 0x100
	s_addc_u32 s37, s37, 0
	s_add_u32 s15, s15, 0x100
	s_addc_u32 s42, s42, 0
	s_cmp_gt_u32 s43, 29
	s_cbranch_scc0 .LBB0_383
	s_and_b64 vcc, exec, s[8:9]
	s_cbranch_vccz .LBB0_386
	s_barrier

.LBB0_462:
	v_add_u32_e32 v14, s54, v140
	v_add_u32_e32 v30, s55, v140
	ds_read_b128 v[2:5], v14
	ds_read_b128 v[6:9], v14 offset:1024
	ds_read_b128 v[10:13], v14 offset:2048
	ds_read_b128 v[14:17], v14 offset:3072
	ds_read_b128 v[18:21], v30
	ds_read_b128 v[22:25], v30 offset:1024
	ds_read_b128 v[26:29], v30 offset:2048
	ds_read_b128 v[30:33], v30 offset:3072
	v_add_u32_e32 v141, 0, v1
	ds_read_b128 v[34:37], v141
	ds_read_b128 v[38:41], v141 offset:1024
	ds_read_b128 v[42:45], v141 offset:2048
	ds_read_b128 v[46:49], v141 offset:3072
	ds_read_b128 v[50:53], v141 offset:4096
	ds_read_b128 v[54:57], v141 offset:5120
	ds_read_b128 v[58:61], v141 offset:6144
	ds_read_b128 v[62:65], v141 offset:7168
	s_waitcnt vmcnt(8)
	s_waitcnt lgkmcnt(0)
	s_barrier
	s_setprio 1
	s_waitcnt lgkmcnt(0)
	s_nop 0
	v_mfma_f32_16x16x32_bf16 v[66:69], v[2:5], v[34:37], 0
	v_mfma_f32_16x16x32_bf16 v[66:69], v[6:9], v[38:41], v[66:69]
	v_mfma_f32_16x16x32_bf16 v[70:73], v[10:13], v[34:37], 0
	v_mfma_f32_16x16x32_bf16 v[70:73], v[14:17], v[38:41], v[70:73]
	v_mfma_f32_16x16x32_bf16 v[78:81], v[10:13], v[42:45], 0
	v_mfma_f32_16x16x32_bf16 v[78:81], v[14:17], v[46:49], v[78:81]
	v_mfma_f32_16x16x32_bf16 v[74:77], v[2:5], v[42:45], 0
	v_mfma_f32_16x16x32_bf16 v[74:77], v[6:9], v[46:49], v[74:77]
	v_mfma_f32_16x16x32_bf16 v[82:85], v[2:5], v[50:53], 0
	v_mfma_f32_16x16x32_bf16 v[82:85], v[6:9], v[54:57], v[82:85]
	v_mfma_f32_16x16x32_bf16 v[86:89], v[10:13], v[50:53], 0
	v_mfma_f32_16x16x32_bf16 v[86:89], v[14:17], v[54:57], v[86:89]
	v_mfma_f32_16x16x32_bf16 v[94:97], v[10:13], v[58:61], 0
	v_mfma_f32_16x16x32_bf16 v[94:97], v[14:17], v[62:65], v[94:97]
	v_mfma_f32_16x16x32_bf16 v[90:93], v[2:5], v[58:61], 0
	v_mfma_f32_16x16x32_bf16 v[90:93], v[6:9], v[62:65], v[90:93]
	s_setprio 0
	s_setprio 1
	v_mfma_f32_16x16x32_bf16 v[98:101], v[18:21], v[34:37], 0
	v_mfma_f32_16x16x32_bf16 v[34:37], v[26:29], v[34:37], 0
	v_mfma_f32_16x16x32_bf16 v[102:105], v[18:21], v[42:45], 0
	v_mfma_f32_16x16x32_bf16 v[42:45], v[26:29], v[42:45], 0
	v_mfma_f32_16x16x32_bf16 v[106:109], v[18:21], v[50:53], 0
	v_mfma_f32_16x16x32_bf16 v[50:53], v[26:29], v[50:53], 0
	v_mfma_f32_16x16x32_bf16 v[110:113], v[18:21], v[58:61], 0
	v_mfma_f32_16x16x32_bf16 v[58:61], v[26:29], v[58:61], 0
	v_mfma_f32_16x16x32_bf16 v[98:101], v[22:25], v[38:41], v[98:101]
	v_mfma_f32_16x16x32_bf16 v[38:41], v[30:33], v[38:41], v[34:37]
	v_mfma_f32_16x16x32_bf16 v[102:105], v[22:25], v[46:49], v[102:105]
	v_mfma_f32_16x16x32_bf16 v[46:49], v[30:33], v[46:49], v[42:45]
	v_mfma_f32_16x16x32_bf16 v[106:109], v[22:25], v[54:57], v[106:109]
	v_mfma_f32_16x16x32_bf16 v[54:57], v[30:33], v[54:57], v[50:53]
	s_setprio 2
	s_barrier
	v_mfma_f32_16x16x32_bf16 v[110:113], v[22:25], v[62:65], v[110:113]
	v_mfma_f32_16x16x32_bf16 v[62:65], v[30:33], v[62:65], v[58:61]
	s_setprio 0
	v_lshl_add_u64 v[136:137], s[36:37], 0, v[130:131]
	s_add_i32 s62, s54, s21
	v_mov_b32_e32 v135, v131
	v_lshl_add_u64 v[142:143], v[136:137], 0, s[12:13]
	s_mov_b32 m0, s62
	v_lshl_add_u64 v[244:245], s[36:37], 0, v[134:135]
	ds_read_b128 v[34:37], v141 offset:16384
	ds_read_b128 v[42:45], v141 offset:17408
	ds_read_b128 v[50:53], v141 offset:18432
	ds_read_b128 v[58:61], v141 offset:19456
	ds_read_b128 v[114:117], v141 offset:20480
	ds_read_b128 v[118:121], v141 offset:21504
	ds_read_b128 v[122:125], v141 offset:22528
	ds_read_b128 v[126:129], v141 offset:23552
	global_load_lds_dwordx4 v[142:143], off
	v_lshl_add_u64 v[142:143], v[244:245], 0, s[12:13]
	s_add_i32 m0, s62, 0x2000
	s_add_i32 s62, s55, s21
	global_load_lds_dwordx4 v[142:143], off
	s_mov_b32 m0, s62
	v_mov_b32_e32 v139, v131
	global_load_lds_dwordx4 v130, s[38:39]
	s_add_i32 m0, s62, 0x2000
	v_lshl_add_u64 v[246:247], s[34:35], 0, v[138:139]
	v_mov_b32_e32 v133, v131
	global_load_lds_dwordx4 v134, s[38:39]
	v_lshl_add_u64 v[142:143], v[246:247], 0, s[12:13]
	s_mov_b32 m0, s33
	v_lshl_add_u64 v[248:249], s[34:35], 0, v[132:133]
	global_load_lds_dwordx4 v[142:143], off
	v_lshl_add_u64 v[142:143], v[248:249], 0, s[12:13]
	s_mov_b32 m0, s44
	s_nop 0
	global_load_lds_dwordx4 v[142:143], off
	s_waitcnt vmcnt(8)
	s_waitcnt lgkmcnt(0)
	s_barrier
	s_setprio 1
	s_waitcnt lgkmcnt(0)
	s_nop 0
	v_mfma_f32_16x16x32_bf16 v[142:145], v[2:5], v[34:37], 0
	v_mfma_f32_16x16x32_bf16 v[148:151], v[10:13], v[34:37], 0
	v_mfma_f32_16x16x32_bf16 v[152:155], v[2:5], v[50:53], 0
	v_mfma_f32_16x16x32_bf16 v[156:159], v[10:13], v[50:53], 0
	v_mfma_f32_16x16x32_bf16 v[160:163], v[2:5], v[114:117], 0
	v_mfma_f32_16x16x32_bf16 v[164:167], v[10:13], v[114:117], 0
	v_mfma_f32_16x16x32_bf16 v[2:5], v[2:5], v[122:125], 0
	v_mfma_f32_16x16x32_bf16 v[10:13], v[10:13], v[122:125], 0
	v_mfma_f32_16x16x32_bf16 v[142:145], v[6:9], v[42:45], v[142:145]
	v_mfma_f32_16x16x32_bf16 v[148:151], v[14:17], v[42:45], v[148:151]
	v_mfma_f32_16x16x32_bf16 v[152:155], v[6:9], v[58:61], v[152:155]
	v_mfma_f32_16x16x32_bf16 v[156:159], v[14:17], v[58:61], v[156:159]
	v_mfma_f32_16x16x32_bf16 v[160:163], v[6:9], v[118:121], v[160:163]
	v_mfma_f32_16x16x32_bf16 v[164:167], v[14:17], v[118:121], v[164:167]
	v_mfma_f32_16x16x32_bf16 v[168:171], v[6:9], v[126:129], v[2:5]
	v_mfma_f32_16x16x32_bf16 v[172:175], v[14:17], v[126:129], v[10:13]
	s_setprio 0
	s_setprio 1
	v_mfma_f32_16x16x32_bf16 v[2:5], v[18:21], v[34:37], 0
	v_mfma_f32_16x16x32_bf16 v[6:9], v[26:29], v[34:37], 0
	v_mfma_f32_16x16x32_bf16 v[10:13], v[18:21], v[50:53], 0
	v_mfma_f32_16x16x32_bf16 v[14:17], v[26:29], v[50:53], 0
	v_mfma_f32_16x16x32_bf16 v[34:37], v[18:21], v[114:117], 0
	v_mfma_f32_16x16x32_bf16 v[50:53], v[26:29], v[114:117], 0
	v_mfma_f32_16x16x32_bf16 v[18:21], v[18:21], v[122:125], 0
	v_mfma_f32_16x16x32_bf16 v[26:29], v[26:29], v[122:125], 0
	v_mfma_f32_16x16x32_bf16 v[114:117], v[22:25], v[42:45], v[2:5]
	v_mfma_f32_16x16x32_bf16 v[122:125], v[30:33], v[42:45], v[6:9]
	v_mfma_f32_16x16x32_bf16 v[184:187], v[22:25], v[118:121], v[34:37]
	v_mfma_f32_16x16x32_bf16 v[118:121], v[30:33], v[118:121], v[50:53]
	v_mfma_f32_16x16x32_bf16 v[188:191], v[22:25], v[126:129], v[18:21]
	v_mfma_f32_16x16x32_bf16 v[126:129], v[30:33], v[126:129], v[26:29]
	s_setprio 2
	s_barrier
	v_mfma_f32_16x16x32_bf16 v[176:179], v[22:25], v[58:61], v[10:13]
	v_mfma_f32_16x16x32_bf16 v[180:183], v[30:33], v[58:61], v[14:17]
	s_setprio 0
	s_add_i32 s62, 0, 0x18000
	v_add_u32_e32 v2, s62, v140
	s_add_i32 s63, 0, 0x1c000
	ds_read_b128 v[192:195], v2
	ds_read_b128 v[196:199], v2 offset:1024
	ds_read_b128 v[200:203], v2 offset:2048
	ds_read_b128 v[204:207], v2 offset:3072
	v_add_u32_e32 v2, s63, v140
	ds_read_b128 v[208:211], v2
	ds_read_b128 v[212:215], v2 offset:1024
	ds_read_b128 v[216:219], v2 offset:2048
	ds_read_b128 v[220:223], v2 offset:3072
	s_mov_b32 m0, s45
	ds_read_b128 v[42:45], v141 offset:32768
	ds_read_b128 v[50:53], v141 offset:33792
	ds_read_b128 v[58:61], v141 offset:34816
	ds_read_b128 v[224:227], v141 offset:35840
	ds_read_b128 v[228:231], v141 offset:36864
	ds_read_b128 v[232:235], v141 offset:37888
	ds_read_b128 v[236:239], v141 offset:38912
	ds_read_b128 v[240:243], v141 offset:39936
	global_load_lds_dwordx4 v138, s[40:41]
	s_mov_b32 m0, s46
	s_nop 0
	global_load_lds_dwordx4 v132, s[40:41]
	s_waitcnt vmcnt(8)
	s_waitcnt lgkmcnt(0)
	s_barrier
	s_setprio 1
	s_waitcnt lgkmcnt(0)
	s_nop 0
	v_mfma_f32_16x16x32_bf16 v[2:5], v[192:195], v[42:45], v[66:69]
	v_mfma_f32_16x16x32_bf16 v[6:9], v[200:203], v[42:45], v[70:73]
	v_mfma_f32_16x16x32_bf16 v[10:13], v[192:195], v[58:61], v[74:77]
	v_mfma_f32_16x16x32_bf16 v[14:17], v[200:203], v[58:61], v[78:81]
	v_mfma_f32_16x16x32_bf16 v[18:21], v[192:195], v[228:231], v[82:85]
	v_mfma_f32_16x16x32_bf16 v[22:25], v[200:203], v[228:231], v[86:89]
	v_mfma_f32_16x16x32_bf16 v[26:29], v[192:195], v[236:239], v[90:93]
	v_mfma_f32_16x16x32_bf16 v[30:33], v[200:203], v[236:239], v[94:97]
	v_mfma_f32_16x16x32_bf16 v[2:5], v[196:199], v[50:53], v[2:5]
	v_mfma_f32_16x16x32_bf16 v[6:9], v[204:207], v[50:53], v[6:9]
	v_mfma_f32_16x16x32_bf16 v[10:13], v[196:199], v[224:227], v[10:13]
	v_mfma_f32_16x16x32_bf16 v[14:17], v[204:207], v[224:227], v[14:17]
	v_mfma_f32_16x16x32_bf16 v[18:21], v[196:199], v[232:235], v[18:21]
	v_mfma_f32_16x16x32_bf16 v[22:25], v[204:207], v[232:235], v[22:25]
	v_mfma_f32_16x16x32_bf16 v[26:29], v[196:199], v[240:243], v[26:29]
	v_mfma_f32_16x16x32_bf16 v[30:33], v[204:207], v[240:243], v[30:33]
	s_setprio 0
	s_setprio 1
	v_mfma_f32_16x16x32_bf16 v[34:37], v[208:211], v[42:45], v[98:101]
	v_mfma_f32_16x16x32_bf16 v[38:41], v[216:219], v[42:45], v[38:41]
	v_mfma_f32_16x16x32_bf16 v[34:37], v[212:215], v[50:53], v[34:37]
	v_mfma_f32_16x16x32_bf16 v[38:41], v[220:223], v[50:53], v[38:41]
	v_mfma_f32_16x16x32_bf16 v[42:45], v[208:211], v[58:61], v[102:105]
	v_mfma_f32_16x16x32_bf16 v[46:49], v[216:219], v[58:61], v[46:49]
	v_mfma_f32_16x16x32_bf16 v[50:53], v[208:211], v[228:231], v[106:109]
	v_mfma_f32_16x16x32_bf16 v[54:57], v[216:219], v[228:231], v[54:57]
	v_mfma_f32_16x16x32_bf16 v[58:61], v[208:211], v[236:239], v[110:113]
	v_mfma_f32_16x16x32_bf16 v[62:65], v[216:219], v[236:239], v[62:65]
	v_mfma_f32_16x16x32_bf16 v[42:45], v[212:215], v[224:227], v[42:45]
	v_mfma_f32_16x16x32_bf16 v[46:49], v[220:223], v[224:227], v[46:49]
	v_mfma_f32_16x16x32_bf16 v[50:53], v[212:215], v[232:235], v[50:53]
	v_mfma_f32_16x16x32_bf16 v[54:57], v[220:223], v[232:235], v[54:57]
	s_setprio 2
	s_barrier
	v_mfma_f32_16x16x32_bf16 v[58:61], v[212:215], v[240:243], v[58:61]
	v_mfma_f32_16x16x32_bf16 v[62:65], v[220:223], v[240:243], v[62:65]
	s_setprio 0
	s_add_i32 s62, s62, s21
	v_lshl_add_u64 v[66:67], v[136:137], 0, s[14:15]
	s_mov_b32 m0, s62
	ds_read_b128 v[102:105], v141 offset:49152
	ds_read_b128 v[106:109], v141 offset:50176
	ds_read_b128 v[110:113], v141 offset:51200
	ds_read_b128 v[224:227], v141 offset:52224
	ds_read_b128 v[228:231], v141 offset:53248
	ds_read_b128 v[232:235], v141 offset:54272
	ds_read_b128 v[236:239], v141 offset:55296
	ds_read_b128 v[240:243], v141 offset:56320
	global_load_lds_dwordx4 v[66:67], off
	v_lshl_add_u64 v[66:67], v[244:245], 0, s[14:15]
	s_add_i32 m0, s62, 0x2000
	s_add_i32 s62, s63, s21
	global_load_lds_dwordx4 v[66:67], off
	s_mov_b32 m0, s62
	v_lshl_add_u64 v[66:67], v[246:247], 0, s[14:15]
	global_load_lds_dwordx4 v130, s[42:43]
	s_add_i32 m0, s62, 0x2000
	s_nop 0
	global_load_lds_dwordx4 v134, s[42:43]
	s_mov_b32 m0, s50
	s_nop 0
	global_load_lds_dwordx4 v[66:67], off
	v_lshl_add_u64 v[66:67], v[248:249], 0, s[14:15]
	s_mov_b32 m0, s51
	s_nop 0
	global_load_lds_dwordx4 v[66:67], off
	s_waitcnt vmcnt(8)
	s_waitcnt lgkmcnt(0)
	s_barrier
	s_setprio 1
	s_waitcnt lgkmcnt(0)
	s_nop 0
	v_mfma_f32_16x16x32_bf16 v[66:69], v[192:195], v[102:105], v[142:145]
	v_mfma_f32_16x16x32_bf16 v[70:73], v[200:203], v[102:105], v[148:151]
	v_mfma_f32_16x16x32_bf16 v[74:77], v[192:195], v[110:113], v[152:155]
	v_mfma_f32_16x16x32_bf16 v[78:81], v[200:203], v[110:113], v[156:159]
	v_mfma_f32_16x16x32_bf16 v[82:85], v[192:195], v[228:231], v[160:163]
	v_mfma_f32_16x16x32_bf16 v[86:89], v[200:203], v[228:231], v[164:167]
	v_mfma_f32_16x16x32_bf16 v[90:93], v[192:195], v[236:239], v[168:171]
	v_mfma_f32_16x16x32_bf16 v[94:97], v[200:203], v[236:239], v[172:175]
	v_mfma_f32_16x16x32_bf16 v[66:69], v[196:199], v[106:109], v[66:69]
	v_mfma_f32_16x16x32_bf16 v[70:73], v[204:207], v[106:109], v[70:73]
	v_mfma_f32_16x16x32_bf16 v[74:77], v[196:199], v[224:227], v[74:77]
	v_mfma_f32_16x16x32_bf16 v[78:81], v[204:207], v[224:227], v[78:81]
	v_mfma_f32_16x16x32_bf16 v[82:85], v[196:199], v[232:235], v[82:85]
	v_mfma_f32_16x16x32_bf16 v[86:89], v[204:207], v[232:235], v[86:89]
	v_mfma_f32_16x16x32_bf16 v[90:93], v[196:199], v[240:243], v[90:93]
	v_mfma_f32_16x16x32_bf16 v[94:97], v[204:207], v[240:243], v[94:97]
	s_setprio 0
	s_setprio 1
	v_mfma_f32_16x16x32_bf16 v[98:101], v[208:211], v[102:105], v[114:117]
	v_mfma_f32_16x16x32_bf16 v[102:105], v[216:219], v[102:105], v[122:125]
	v_mfma_f32_16x16x32_bf16 v[98:101], v[212:215], v[106:109], v[98:101]
	v_mfma_f32_16x16x32_bf16 v[102:105], v[220:223], v[106:109], v[102:105]
	v_mfma_f32_16x16x32_bf16 v[106:109], v[208:211], v[110:113], v[176:179]
	v_mfma_f32_16x16x32_bf16 v[110:113], v[216:219], v[110:113], v[180:183]
	v_mfma_f32_16x16x32_bf16 v[114:117], v[208:211], v[228:231], v[184:187]
	v_mfma_f32_16x16x32_bf16 v[118:121], v[216:219], v[228:231], v[118:121]
	v_mfma_f32_16x16x32_bf16 v[122:125], v[208:211], v[236:239], v[188:191]
	v_mfma_f32_16x16x32_bf16 v[126:129], v[216:219], v[236:239], v[126:129]
	v_mfma_f32_16x16x32_bf16 v[106:109], v[212:215], v[224:227], v[106:109]
	v_mfma_f32_16x16x32_bf16 v[110:113], v[220:223], v[224:227], v[110:113]
	v_mfma_f32_16x16x32_bf16 v[114:117], v[212:215], v[232:235], v[114:117]
	v_mfma_f32_16x16x32_bf16 v[118:121], v[220:223], v[232:235], v[118:121]
	s_setprio 2
	s_barrier
	v_mfma_f32_16x16x32_bf16 v[122:125], v[212:215], v[240:243], v[122:125]
	v_mfma_f32_16x16x32_bf16 v[126:129], v[220:223], v[240:243], v[126:129]
	s_setprio 0
	s_add_i32 s61, s61, 2
	s_cmp_ge_i32 s61, s60
	s_cbranch_scc0 .LBB0_462
	v_mov_b32_e32 v136, v130
	s_branch .LBB0_465

.LBB0_466:
	v_add_u32_e32 v133, s54, v140
	ds_read_b128 v[142:145], v133
	ds_read_b128 v[148:151], v133 offset:1024
	ds_read_b128 v[152:155], v133 offset:2048
	ds_read_b128 v[156:159], v133 offset:3072
	v_add_u32_e32 v133, s55, v140
	ds_read_b128 v[160:163], v133
	ds_read_b128 v[164:167], v133 offset:1024
	ds_read_b128 v[168:171], v133 offset:2048
	ds_read_b128 v[172:175], v133 offset:3072
	s_add_u32 s36, s34, 0xffc00080
	s_addc_u32 s37, s35, -1
	s_cmp_eq_u32 s42, 4
	s_cselect_b32 s39, s29, s37
	s_cselect_b32 s38, s28, s36
	s_cselect_b32 s37, s31, s41
	s_cselect_b32 s36, s30, s40
	s_mov_b32 m0, s52
	v_add_u32_e32 v141, 0, v1
	ds_read_b128 v[176:179], v141
	ds_read_b128 v[180:183], v141 offset:1024
	ds_read_b128 v[184:187], v141 offset:2048
	ds_read_b128 v[188:191], v141 offset:3072
	ds_read_b128 v[192:195], v141 offset:4096
	ds_read_b128 v[196:199], v141 offset:5120
	ds_read_b128 v[200:203], v141 offset:6144
	ds_read_b128 v[204:207], v141 offset:7168
	global_load_lds_dwordx4 v130, s[34:35]
	s_mov_b32 m0, s53
	v_mov_b32_e32 v133, v131
	global_load_lds_dwordx4 v132, s[34:35]
	s_waitcnt vmcnt(8)
	s_waitcnt lgkmcnt(0)
	s_barrier
	s_setprio 1
	s_waitcnt lgkmcnt(0)
	s_nop 0
	v_mfma_f32_16x16x32_bf16 v[2:5], v[142:145], v[176:179], v[2:5]
	v_mfma_f32_16x16x32_bf16 v[2:5], v[148:151], v[180:183], v[2:5]
	v_mfma_f32_16x16x32_bf16 v[6:9], v[156:159], v[180:183], v[6:9]
	v_mfma_f32_16x16x32_bf16 v[6:9], v[152:155], v[176:179], v[6:9]
	v_mfma_f32_16x16x32_bf16 v[14:17], v[152:155], v[184:187], v[14:17]
	v_mfma_f32_16x16x32_bf16 v[14:17], v[156:159], v[188:191], v[14:17]
	v_mfma_f32_16x16x32_bf16 v[10:13], v[148:151], v[188:191], v[10:13]
	v_mfma_f32_16x16x32_bf16 v[10:13], v[142:145], v[184:187], v[10:13]
	v_mfma_f32_16x16x32_bf16 v[18:21], v[142:145], v[192:195], v[18:21]
	v_mfma_f32_16x16x32_bf16 v[18:21], v[148:151], v[196:199], v[18:21]
	v_mfma_f32_16x16x32_bf16 v[22:25], v[156:159], v[196:199], v[22:25]
	v_mfma_f32_16x16x32_bf16 v[22:25], v[152:155], v[192:195], v[22:25]
	v_mfma_f32_16x16x32_bf16 v[30:33], v[152:155], v[200:203], v[30:33]
	v_mfma_f32_16x16x32_bf16 v[30:33], v[156:159], v[204:207], v[30:33]
	v_mfma_f32_16x16x32_bf16 v[26:29], v[148:151], v[204:207], v[26:29]
	v_mfma_f32_16x16x32_bf16 v[26:29], v[142:145], v[200:203], v[26:29]
	s_setprio 0
	s_setprio 1
	v_mfma_f32_16x16x32_bf16 v[34:37], v[160:163], v[176:179], v[34:37]
	v_mfma_f32_16x16x32_bf16 v[34:37], v[164:167], v[180:183], v[34:37]
	v_mfma_f32_16x16x32_bf16 v[38:41], v[172:175], v[180:183], v[38:41]
	v_mfma_f32_16x16x32_bf16 v[38:41], v[168:171], v[176:179], v[38:41]
	v_mfma_f32_16x16x32_bf16 v[46:49], v[168:171], v[184:187], v[46:49]
	v_mfma_f32_16x16x32_bf16 v[46:49], v[172:175], v[188:191], v[46:49]
	v_mfma_f32_16x16x32_bf16 v[42:45], v[164:167], v[188:191], v[42:45]
	v_mfma_f32_16x16x32_bf16 v[42:45], v[160:163], v[184:187], v[42:45]
	v_mfma_f32_16x16x32_bf16 v[50:53], v[160:163], v[192:195], v[50:53]
	v_mfma_f32_16x16x32_bf16 v[50:53], v[164:167], v[196:199], v[50:53]
	v_mfma_f32_16x16x32_bf16 v[54:57], v[172:175], v[196:199], v[54:57]
	v_mfma_f32_16x16x32_bf16 v[54:57], v[168:171], v[192:195], v[54:57]
	v_mfma_f32_16x16x32_bf16 v[62:65], v[168:171], v[200:203], v[62:65]
	v_mfma_f32_16x16x32_bf16 v[62:65], v[172:175], v[204:207], v[62:65]
	s_setprio 2
	s_barrier
	v_mfma_f32_16x16x32_bf16 v[58:61], v[164:167], v[204:207], v[58:61]
	v_mfma_f32_16x16x32_bf16 v[58:61], v[160:163], v[200:203], v[58:61]
	s_setprio 0
	s_add_i32 s43, s54, s21
	s_mov_b32 m0, s43
	ds_read_b128 v[176:179], v141 offset:16384
	ds_read_b128 v[180:183], v141 offset:17408
	ds_read_b128 v[184:187], v141 offset:18432
	ds_read_b128 v[188:191], v141 offset:19456
	ds_read_b128 v[192:195], v141 offset:20480
	ds_read_b128 v[196:199], v141 offset:21504
	ds_read_b128 v[200:203], v141 offset:22528
	ds_read_b128 v[204:207], v141 offset:23552
	global_load_lds_dwordx4 v136, s[36:37]
	s_add_i32 m0, s43, 0x2000
	s_add_u32 s60, s36, 0x80000
	s_addc_u32 s61, s37, 0
	s_add_i32 s43, s55, s21
	global_load_lds_dwordx4 v134, s[36:37]
	s_mov_b32 m0, s43
	v_mov_b32_e32 v137, v131
	global_load_lds_dwordx4 v136, s[60:61]
	s_add_i32 m0, s43, 0x2000
	v_mov_b32_e32 v135, v131
	global_load_lds_dwordx4 v134, s[60:61]
	s_mov_b32 m0, s33
	v_lshl_add_u64 v[138:139], s[36:37], 0, v[136:137]
	global_load_lds_dwordx4 v130, s[38:39]
	s_mov_b32 m0, s44
	v_lshl_add_u64 v[208:209], s[36:37], 0, v[134:135]
	global_load_lds_dwordx4 v132, s[38:39]
	s_waitcnt vmcnt(8)
	s_waitcnt lgkmcnt(0)
	v_lshl_add_u64 v[210:211], s[38:39], 0, v[130:131]
	v_lshl_add_u64 v[212:213], s[38:39], 0, v[132:133]
	s_barrier
	s_setprio 1
	s_waitcnt lgkmcnt(0)
	s_nop 0
	v_mfma_f32_16x16x32_bf16 v[66:69], v[142:145], v[176:179], v[66:69]
	v_mfma_f32_16x16x32_bf16 v[66:69], v[148:151], v[180:183], v[66:69]
	v_mfma_f32_16x16x32_bf16 v[70:73], v[156:159], v[180:183], v[70:73]
	v_mfma_f32_16x16x32_bf16 v[70:73], v[152:155], v[176:179], v[70:73]
	v_mfma_f32_16x16x32_bf16 v[78:81], v[152:155], v[184:187], v[78:81]
	v_mfma_f32_16x16x32_bf16 v[78:81], v[156:159], v[188:191], v[78:81]
	v_mfma_f32_16x16x32_bf16 v[74:77], v[148:151], v[188:191], v[74:77]
	v_mfma_f32_16x16x32_bf16 v[74:77], v[142:145], v[184:187], v[74:77]
	v_mfma_f32_16x16x32_bf16 v[82:85], v[142:145], v[192:195], v[82:85]
	v_mfma_f32_16x16x32_bf16 v[82:85], v[148:151], v[196:199], v[82:85]
	v_mfma_f32_16x16x32_bf16 v[86:89], v[156:159], v[196:199], v[86:89]
	v_mfma_f32_16x16x32_bf16 v[86:89], v[152:155], v[192:195], v[86:89]
	v_mfma_f32_16x16x32_bf16 v[94:97], v[152:155], v[200:203], v[94:97]
	v_mfma_f32_16x16x32_bf16 v[94:97], v[156:159], v[204:207], v[94:97]
	v_mfma_f32_16x16x32_bf16 v[90:93], v[148:151], v[204:207], v[90:93]
	v_mfma_f32_16x16x32_bf16 v[90:93], v[142:145], v[200:203], v[90:93]
	s_setprio 0
	s_setprio 1
	v_mfma_f32_16x16x32_bf16 v[98:101], v[160:163], v[176:179], v[98:101]
	v_mfma_f32_16x16x32_bf16 v[98:101], v[164:167], v[180:183], v[98:101]
	v_mfma_f32_16x16x32_bf16 v[102:105], v[172:175], v[180:183], v[102:105]
	v_mfma_f32_16x16x32_bf16 v[102:105], v[168:171], v[176:179], v[102:105]
	v_mfma_f32_16x16x32_bf16 v[110:113], v[168:171], v[184:187], v[110:113]
	v_mfma_f32_16x16x32_bf16 v[110:113], v[172:175], v[188:191], v[110:113]
	v_mfma_f32_16x16x32_bf16 v[106:109], v[164:167], v[188:191], v[106:109]
	v_mfma_f32_16x16x32_bf16 v[106:109], v[160:163], v[184:187], v[106:109]
	v_mfma_f32_16x16x32_bf16 v[114:117], v[160:163], v[192:195], v[114:117]
	v_mfma_f32_16x16x32_bf16 v[114:117], v[164:167], v[196:199], v[114:117]
	v_mfma_f32_16x16x32_bf16 v[118:121], v[172:175], v[196:199], v[118:121]
	v_mfma_f32_16x16x32_bf16 v[118:121], v[168:171], v[192:195], v[118:121]
	v_mfma_f32_16x16x32_bf16 v[126:129], v[168:171], v[200:203], v[126:129]
	v_mfma_f32_16x16x32_bf16 v[126:129], v[172:175], v[204:207], v[126:129]
	s_setprio 2
	s_barrier
	v_mfma_f32_16x16x32_bf16 v[122:125], v[164:167], v[204:207], v[122:125]
	v_mfma_f32_16x16x32_bf16 v[122:125], v[160:163], v[200:203], v[122:125]
	s_setprio 0
	s_add_i32 s43, 0, 0x18000
	v_add_u32_e32 v135, s43, v140
	s_add_i32 s60, 0, 0x1c000
	ds_read_b128 v[142:145], v135
	ds_read_b128 v[148:151], v135 offset:1024
	ds_read_b128 v[152:155], v135 offset:2048
	ds_read_b128 v[156:159], v135 offset:3072
	v_add_u32_e32 v135, s60, v140
	ds_read_b128 v[160:163], v135
	ds_read_b128 v[164:167], v135 offset:1024
	ds_read_b128 v[168:171], v135 offset:2048
	ds_read_b128 v[172:175], v135 offset:3072
	s_add_u32 s38, s38, 0x400000
	s_addc_u32 s39, s39, 0
	s_mov_b32 m0, s45
	ds_read_b128 v[176:179], v141 offset:32768
	ds_read_b128 v[180:183], v141 offset:33792
	ds_read_b128 v[184:187], v141 offset:34816
	ds_read_b128 v[188:191], v141 offset:35840
	ds_read_b128 v[192:195], v141 offset:36864
	ds_read_b128 v[196:199], v141 offset:37888
	ds_read_b128 v[200:203], v141 offset:38912
	ds_read_b128 v[204:207], v141 offset:39936
	global_load_lds_dwordx4 v130, s[38:39]
	s_mov_b32 m0, s46
	s_nop 0
	global_load_lds_dwordx4 v132, s[38:39]
	s_waitcnt vmcnt(8)
	s_waitcnt lgkmcnt(0)
	s_barrier
	s_setprio 1
	s_waitcnt lgkmcnt(0)
	s_nop 0
	v_mfma_f32_16x16x32_bf16 v[2:5], v[142:145], v[176:179], v[2:5]
	v_mfma_f32_16x16x32_bf16 v[2:5], v[148:151], v[180:183], v[2:5]
	v_mfma_f32_16x16x32_bf16 v[6:9], v[156:159], v[180:183], v[6:9]
	v_mfma_f32_16x16x32_bf16 v[6:9], v[152:155], v[176:179], v[6:9]
	v_mfma_f32_16x16x32_bf16 v[14:17], v[152:155], v[184:187], v[14:17]
	v_mfma_f32_16x16x32_bf16 v[14:17], v[156:159], v[188:191], v[14:17]
	v_mfma_f32_16x16x32_bf16 v[10:13], v[148:151], v[188:191], v[10:13]
	v_mfma_f32_16x16x32_bf16 v[10:13], v[142:145], v[184:187], v[10:13]
	v_mfma_f32_16x16x32_bf16 v[18:21], v[142:145], v[192:195], v[18:21]
	v_mfma_f32_16x16x32_bf16 v[18:21], v[148:151], v[196:199], v[18:21]
	v_mfma_f32_16x16x32_bf16 v[22:25], v[156:159], v[196:199], v[22:25]
	v_mfma_f32_16x16x32_bf16 v[22:25], v[152:155], v[192:195], v[22:25]
	v_mfma_f32_16x16x32_bf16 v[30:33], v[152:155], v[200:203], v[30:33]
	v_mfma_f32_16x16x32_bf16 v[30:33], v[156:159], v[204:207], v[30:33]
	v_mfma_f32_16x16x32_bf16 v[26:29], v[148:151], v[204:207], v[26:29]
	v_mfma_f32_16x16x32_bf16 v[26:29], v[142:145], v[200:203], v[26:29]
	s_setprio 0
	s_setprio 1
	v_mfma_f32_16x16x32_bf16 v[34:37], v[160:163], v[176:179], v[34:37]
	v_mfma_f32_16x16x32_bf16 v[34:37], v[164:167], v[180:183], v[34:37]
	v_mfma_f32_16x16x32_bf16 v[38:41], v[172:175], v[180:183], v[38:41]
	v_mfma_f32_16x16x32_bf16 v[38:41], v[168:171], v[176:179], v[38:41]
	v_mfma_f32_16x16x32_bf16 v[46:49], v[168:171], v[184:187], v[46:49]
	v_mfma_f32_16x16x32_bf16 v[46:49], v[172:175], v[188:191], v[46:49]
	v_mfma_f32_16x16x32_bf16 v[42:45], v[164:167], v[188:191], v[42:45]
	v_mfma_f32_16x16x32_bf16 v[42:45], v[160:163], v[184:187], v[42:45]
	v_mfma_f32_16x16x32_bf16 v[50:53], v[160:163], v[192:195], v[50:53]
	v_mfma_f32_16x16x32_bf16 v[50:53], v[164:167], v[196:199], v[50:53]
	v_mfma_f32_16x16x32_bf16 v[54:57], v[172:175], v[196:199], v[54:57]
	v_mfma_f32_16x16x32_bf16 v[54:57], v[168:171], v[192:195], v[54:57]
	v_mfma_f32_16x16x32_bf16 v[62:65], v[168:171], v[200:203], v[62:65]
	v_mfma_f32_16x16x32_bf16 v[62:65], v[172:175], v[204:207], v[62:65]
	s_setprio 2
	s_barrier
	v_mfma_f32_16x16x32_bf16 v[58:61], v[164:167], v[204:207], v[58:61]
	v_mfma_f32_16x16x32_bf16 v[58:61], v[160:163], v[200:203], v[58:61]
	s_setprio 0
	s_add_i32 s38, s43, s21
	v_lshl_add_u64 v[138:139], v[138:139], 0, s[8:9]
	s_mov_b32 m0, s38
	ds_read_b128 v[176:179], v141 offset:49152
	ds_read_b128 v[180:183], v141 offset:50176
	ds_read_b128 v[184:187], v141 offset:51200
	ds_read_b128 v[188:191], v141 offset:52224
	ds_read_b128 v[192:195], v141 offset:53248
	ds_read_b128 v[196:199], v141 offset:54272
	ds_read_b128 v[200:203], v141 offset:55296
	ds_read_b128 v[204:207], v141 offset:56320
	global_load_lds_dwordx4 v[138:139], off
	s_add_i32 m0, s38, 0x2000
	s_add_u32 s36, s36, 0x80080
	v_lshl_add_u64 v[138:139], v[208:209], 0, s[8:9]
	s_addc_u32 s37, s37, 0
	s_add_i32 s38, s60, s21
	global_load_lds_dwordx4 v[138:139], off
	s_mov_b32 m0, s38
	v_lshl_add_u64 v[138:139], v[210:211], 0, s[8:9]
	global_load_lds_dwordx4 v136, s[36:37]
	s_add_i32 m0, s38, 0x2000
	s_nop 0
	global_load_lds_dwordx4 v134, s[36:37]
	s_mov_b32 m0, s50
	s_nop 0
	global_load_lds_dwordx4 v[138:139], off
	v_lshl_add_u64 v[138:139], v[212:213], 0, s[8:9]
	s_mov_b32 m0, s51
	s_nop 0
	global_load_lds_dwordx4 v[138:139], off
	s_waitcnt vmcnt(8)
	s_waitcnt lgkmcnt(0)
	s_barrier
	s_setprio 1
	s_waitcnt lgkmcnt(0)
	s_nop 0
	v_mfma_f32_16x16x32_bf16 v[66:69], v[142:145], v[176:179], v[66:69]
	v_mfma_f32_16x16x32_bf16 v[66:69], v[148:151], v[180:183], v[66:69]
	v_mfma_f32_16x16x32_bf16 v[70:73], v[156:159], v[180:183], v[70:73]
	v_mfma_f32_16x16x32_bf16 v[70:73], v[152:155], v[176:179], v[70:73]
	v_mfma_f32_16x16x32_bf16 v[78:81], v[152:155], v[184:187], v[78:81]
	v_mfma_f32_16x16x32_bf16 v[78:81], v[156:159], v[188:191], v[78:81]
	v_mfma_f32_16x16x32_bf16 v[74:77], v[148:151], v[188:191], v[74:77]
	v_mfma_f32_16x16x32_bf16 v[74:77], v[142:145], v[184:187], v[74:77]
	v_mfma_f32_16x16x32_bf16 v[82:85], v[142:145], v[192:195], v[82:85]
	v_mfma_f32_16x16x32_bf16 v[82:85], v[148:151], v[196:199], v[82:85]
	v_mfma_f32_16x16x32_bf16 v[86:89], v[156:159], v[196:199], v[86:89]
	v_mfma_f32_16x16x32_bf16 v[86:89], v[152:155], v[192:195], v[86:89]
	v_mfma_f32_16x16x32_bf16 v[94:97], v[152:155], v[200:203], v[94:97]
	v_mfma_f32_16x16x32_bf16 v[94:97], v[156:159], v[204:207], v[94:97]
	v_mfma_f32_16x16x32_bf16 v[90:93], v[148:151], v[204:207], v[90:93]
	v_mfma_f32_16x16x32_bf16 v[90:93], v[142:145], v[200:203], v[90:93]
	s_setprio 0
	s_setprio 1
	v_mfma_f32_16x16x32_bf16 v[98:101], v[160:163], v[176:179], v[98:101]
	v_mfma_f32_16x16x32_bf16 v[98:101], v[164:167], v[180:183], v[98:101]
	v_mfma_f32_16x16x32_bf16 v[102:105], v[172:175], v[180:183], v[102:105]
	v_mfma_f32_16x16x32_bf16 v[102:105], v[168:171], v[176:179], v[102:105]
	v_mfma_f32_16x16x32_bf16 v[110:113], v[168:171], v[184:187], v[110:113]
	v_mfma_f32_16x16x32_bf16 v[110:113], v[172:175], v[188:191], v[110:113]
	v_mfma_f32_16x16x32_bf16 v[106:109], v[164:167], v[188:191], v[106:109]
	v_mfma_f32_16x16x32_bf16 v[106:109], v[160:163], v[184:187], v[106:109]
	v_mfma_f32_16x16x32_bf16 v[114:117], v[160:163], v[192:195], v[114:117]
	v_mfma_f32_16x16x32_bf16 v[114:117], v[164:167], v[196:199], v[114:117]
	v_mfma_f32_16x16x32_bf16 v[118:121], v[172:175], v[196:199], v[118:121]
	v_mfma_f32_16x16x32_bf16 v[118:121], v[168:171], v[192:195], v[118:121]
	v_mfma_f32_16x16x32_bf16 v[126:129], v[168:171], v[200:203], v[126:129]
	v_mfma_f32_16x16x32_bf16 v[126:129], v[172:175], v[204:207], v[126:129]
	s_setprio 2
	s_barrier
	v_mfma_f32_16x16x32_bf16 v[122:125], v[164:167], v[204:207], v[122:125]
	v_mfma_f32_16x16x32_bf16 v[122:125], v[160:163], v[200:203], v[122:125]
	s_setprio 0
	s_add_i32 s42, s42, 2
	s_add_u32 s34, s34, 0x100
	s_addc_u32 s35, s35, 0
	s_add_u32 s40, s40, 0x100
	s_addc_u32 s41, s41, 0
	s_cmp_gt_u32 s42, 5
	s_cbranch_scc0 .LBB0_466
	s_and_b64 vcc, exec, s[10:11]
	s_cbranch_vccz .LBB0_469
	s_barrier

.LBB0_495:
	v_add_u32_e32 v14, s58, v140
	v_add_u32_e32 v30, s59, v140
	ds_read_b128 v[2:5], v14
	ds_read_b128 v[6:9], v14 offset:1024
	ds_read_b128 v[10:13], v14 offset:2048
	ds_read_b128 v[14:17], v14 offset:3072
	ds_read_b128 v[18:21], v30
	ds_read_b128 v[22:25], v30 offset:1024
	ds_read_b128 v[26:29], v30 offset:2048
	ds_read_b128 v[30:33], v30 offset:3072
	v_add_u32_e32 v141, 0, v1
	ds_read_b128 v[34:37], v141
	ds_read_b128 v[38:41], v141 offset:1024
	ds_read_b128 v[42:45], v141 offset:2048
	ds_read_b128 v[46:49], v141 offset:3072
	ds_read_b128 v[50:53], v141 offset:4096
	ds_read_b128 v[54:57], v141 offset:5120
	ds_read_b128 v[58:61], v141 offset:6144
	ds_read_b128 v[62:65], v141 offset:7168
	s_waitcnt vmcnt(8)
	s_waitcnt lgkmcnt(0)
	s_barrier
	s_setprio 1
	s_waitcnt lgkmcnt(0)
	s_nop 0
	v_mfma_f32_16x16x32_bf16 v[66:69], v[2:5], v[34:37], 0
	v_mfma_f32_16x16x32_bf16 v[66:69], v[6:9], v[38:41], v[66:69]
	v_mfma_f32_16x16x32_bf16 v[70:73], v[10:13], v[34:37], 0
	v_mfma_f32_16x16x32_bf16 v[70:73], v[14:17], v[38:41], v[70:73]
	v_mfma_f32_16x16x32_bf16 v[78:81], v[10:13], v[42:45], 0
	v_mfma_f32_16x16x32_bf16 v[78:81], v[14:17], v[46:49], v[78:81]
	v_mfma_f32_16x16x32_bf16 v[74:77], v[2:5], v[42:45], 0
	v_mfma_f32_16x16x32_bf16 v[74:77], v[6:9], v[46:49], v[74:77]
	v_mfma_f32_16x16x32_bf16 v[82:85], v[2:5], v[50:53], 0
	v_mfma_f32_16x16x32_bf16 v[82:85], v[6:9], v[54:57], v[82:85]
	v_mfma_f32_16x16x32_bf16 v[86:89], v[10:13], v[50:53], 0
	v_mfma_f32_16x16x32_bf16 v[86:89], v[14:17], v[54:57], v[86:89]
	v_mfma_f32_16x16x32_bf16 v[94:97], v[10:13], v[58:61], 0
	v_mfma_f32_16x16x32_bf16 v[94:97], v[14:17], v[62:65], v[94:97]
	v_mfma_f32_16x16x32_bf16 v[90:93], v[2:5], v[58:61], 0
	v_mfma_f32_16x16x32_bf16 v[90:93], v[6:9], v[62:65], v[90:93]
	s_setprio 0
	s_setprio 1
	v_mfma_f32_16x16x32_bf16 v[98:101], v[18:21], v[34:37], 0
	v_mfma_f32_16x16x32_bf16 v[34:37], v[26:29], v[34:37], 0
	v_mfma_f32_16x16x32_bf16 v[102:105], v[18:21], v[42:45], 0
	v_mfma_f32_16x16x32_bf16 v[42:45], v[26:29], v[42:45], 0
	v_mfma_f32_16x16x32_bf16 v[106:109], v[18:21], v[50:53], 0
	v_mfma_f32_16x16x32_bf16 v[50:53], v[26:29], v[50:53], 0
	v_mfma_f32_16x16x32_bf16 v[110:113], v[18:21], v[58:61], 0
	v_mfma_f32_16x16x32_bf16 v[58:61], v[26:29], v[58:61], 0
	v_mfma_f32_16x16x32_bf16 v[98:101], v[22:25], v[38:41], v[98:101]
	v_mfma_f32_16x16x32_bf16 v[38:41], v[30:33], v[38:41], v[34:37]
	v_mfma_f32_16x16x32_bf16 v[102:105], v[22:25], v[46:49], v[102:105]
	v_mfma_f32_16x16x32_bf16 v[46:49], v[30:33], v[46:49], v[42:45]
	v_mfma_f32_16x16x32_bf16 v[106:109], v[22:25], v[54:57], v[106:109]
	v_mfma_f32_16x16x32_bf16 v[54:57], v[30:33], v[54:57], v[50:53]
	s_setprio 2
	s_barrier
	v_mfma_f32_16x16x32_bf16 v[110:113], v[22:25], v[62:65], v[110:113]
	v_mfma_f32_16x16x32_bf16 v[62:65], v[30:33], v[62:65], v[58:61]
	s_setprio 0
	v_lshl_add_u64 v[136:137], s[38:39], 0, v[130:131]
	s_add_i32 s62, s58, s46
	v_mov_b32_e32 v135, v131
	v_lshl_add_u64 v[142:143], v[136:137], 0, s[10:11]
	s_mov_b32 m0, s62
	v_lshl_add_u64 v[244:245], s[38:39], 0, v[134:135]
	ds_read_b128 v[34:37], v141 offset:16384
	ds_read_b128 v[42:45], v141 offset:17408
	ds_read_b128 v[50:53], v141 offset:18432
	ds_read_b128 v[58:61], v141 offset:19456
	ds_read_b128 v[114:117], v141 offset:20480
	ds_read_b128 v[118:121], v141 offset:21504
	ds_read_b128 v[122:125], v141 offset:22528
	ds_read_b128 v[126:129], v141 offset:23552
	global_load_lds_dwordx4 v[142:143], off
	v_lshl_add_u64 v[142:143], v[244:245], 0, s[10:11]
	s_add_i32 m0, s62, 0x2000
	s_add_i32 s62, s59, s46
	global_load_lds_dwordx4 v[142:143], off
	s_mov_b32 m0, s62
	v_mov_b32_e32 v139, v131
	global_load_lds_dwordx4 v130, s[40:41]
	s_add_i32 m0, s62, 0x2000
	v_lshl_add_u64 v[246:247], s[36:37], 0, v[138:139]
	v_mov_b32_e32 v133, v131
	global_load_lds_dwordx4 v134, s[40:41]
	v_lshl_add_u64 v[142:143], v[246:247], 0, s[10:11]
	s_mov_b32 m0, s47
	v_lshl_add_u64 v[248:249], s[36:37], 0, v[132:133]
	global_load_lds_dwordx4 v[142:143], off
	v_lshl_add_u64 v[142:143], v[248:249], 0, s[10:11]
	s_mov_b32 m0, s48
	s_nop 0
	global_load_lds_dwordx4 v[142:143], off
	s_waitcnt vmcnt(8)
	s_waitcnt lgkmcnt(0)
	s_barrier
	s_setprio 1
	s_waitcnt lgkmcnt(0)
	s_nop 0
	v_mfma_f32_16x16x32_bf16 v[142:145], v[2:5], v[34:37], 0
	v_mfma_f32_16x16x32_bf16 v[148:151], v[10:13], v[34:37], 0
	v_mfma_f32_16x16x32_bf16 v[152:155], v[2:5], v[50:53], 0
	v_mfma_f32_16x16x32_bf16 v[156:159], v[10:13], v[50:53], 0
	v_mfma_f32_16x16x32_bf16 v[160:163], v[2:5], v[114:117], 0
	v_mfma_f32_16x16x32_bf16 v[164:167], v[10:13], v[114:117], 0
	v_mfma_f32_16x16x32_bf16 v[2:5], v[2:5], v[122:125], 0
	v_mfma_f32_16x16x32_bf16 v[10:13], v[10:13], v[122:125], 0
	v_mfma_f32_16x16x32_bf16 v[142:145], v[6:9], v[42:45], v[142:145]
	v_mfma_f32_16x16x32_bf16 v[148:151], v[14:17], v[42:45], v[148:151]
	v_mfma_f32_16x16x32_bf16 v[152:155], v[6:9], v[58:61], v[152:155]
	v_mfma_f32_16x16x32_bf16 v[156:159], v[14:17], v[58:61], v[156:159]
	v_mfma_f32_16x16x32_bf16 v[160:163], v[6:9], v[118:121], v[160:163]
	v_mfma_f32_16x16x32_bf16 v[164:167], v[14:17], v[118:121], v[164:167]
	v_mfma_f32_16x16x32_bf16 v[168:171], v[6:9], v[126:129], v[2:5]
	v_mfma_f32_16x16x32_bf16 v[172:175], v[14:17], v[126:129], v[10:13]
	s_setprio 0
	s_setprio 1
	v_mfma_f32_16x16x32_bf16 v[2:5], v[18:21], v[34:37], 0
	v_mfma_f32_16x16x32_bf16 v[6:9], v[26:29], v[34:37], 0
	v_mfma_f32_16x16x32_bf16 v[10:13], v[18:21], v[50:53], 0
	v_mfma_f32_16x16x32_bf16 v[14:17], v[26:29], v[50:53], 0
	v_mfma_f32_16x16x32_bf16 v[34:37], v[18:21], v[114:117], 0
	v_mfma_f32_16x16x32_bf16 v[50:53], v[26:29], v[114:117], 0
	v_mfma_f32_16x16x32_bf16 v[18:21], v[18:21], v[122:125], 0
	v_mfma_f32_16x16x32_bf16 v[26:29], v[26:29], v[122:125], 0
	v_mfma_f32_16x16x32_bf16 v[114:117], v[22:25], v[42:45], v[2:5]
	v_mfma_f32_16x16x32_bf16 v[122:125], v[30:33], v[42:45], v[6:9]
	v_mfma_f32_16x16x32_bf16 v[184:187], v[22:25], v[118:121], v[34:37]
	v_mfma_f32_16x16x32_bf16 v[118:121], v[30:33], v[118:121], v[50:53]
	v_mfma_f32_16x16x32_bf16 v[188:191], v[22:25], v[126:129], v[18:21]
	v_mfma_f32_16x16x32_bf16 v[126:129], v[30:33], v[126:129], v[26:29]
	s_setprio 2
	s_barrier
	v_mfma_f32_16x16x32_bf16 v[176:179], v[22:25], v[58:61], v[10:13]
	v_mfma_f32_16x16x32_bf16 v[180:183], v[30:33], v[58:61], v[14:17]
	s_setprio 0
	s_add_i32 s62, 0, 0x18000
	v_add_u32_e32 v2, s62, v140
	s_add_i32 s63, 0, 0x1c000
	ds_read_b128 v[192:195], v2
	ds_read_b128 v[196:199], v2 offset:1024
	ds_read_b128 v[200:203], v2 offset:2048
	ds_read_b128 v[204:207], v2 offset:3072
	v_add_u32_e32 v2, s63, v140
	ds_read_b128 v[208:211], v2
	ds_read_b128 v[212:215], v2 offset:1024
	ds_read_b128 v[216:219], v2 offset:2048
	ds_read_b128 v[220:223], v2 offset:3072
	s_mov_b32 m0, s49
	ds_read_b128 v[42:45], v141 offset:32768
	ds_read_b128 v[50:53], v141 offset:33792
	ds_read_b128 v[58:61], v141 offset:34816
	ds_read_b128 v[224:227], v141 offset:35840
	ds_read_b128 v[228:231], v141 offset:36864
	ds_read_b128 v[232:235], v141 offset:37888
	ds_read_b128 v[236:239], v141 offset:38912
	ds_read_b128 v[240:243], v141 offset:39936
	global_load_lds_dwordx4 v138, s[42:43]
	s_mov_b32 m0, s50
	s_nop 0
	global_load_lds_dwordx4 v132, s[42:43]
	s_waitcnt vmcnt(8)
	s_waitcnt lgkmcnt(0)
	s_barrier
	s_setprio 1
	s_waitcnt lgkmcnt(0)
	s_nop 0
	v_mfma_f32_16x16x32_bf16 v[2:5], v[192:195], v[42:45], v[66:69]
	v_mfma_f32_16x16x32_bf16 v[6:9], v[200:203], v[42:45], v[70:73]
	v_mfma_f32_16x16x32_bf16 v[10:13], v[192:195], v[58:61], v[74:77]
	v_mfma_f32_16x16x32_bf16 v[14:17], v[200:203], v[58:61], v[78:81]
	v_mfma_f32_16x16x32_bf16 v[18:21], v[192:195], v[228:231], v[82:85]
	v_mfma_f32_16x16x32_bf16 v[22:25], v[200:203], v[228:231], v[86:89]
	v_mfma_f32_16x16x32_bf16 v[26:29], v[192:195], v[236:239], v[90:93]
	v_mfma_f32_16x16x32_bf16 v[30:33], v[200:203], v[236:239], v[94:97]
	v_mfma_f32_16x16x32_bf16 v[2:5], v[196:199], v[50:53], v[2:5]
	v_mfma_f32_16x16x32_bf16 v[6:9], v[204:207], v[50:53], v[6:9]
	v_mfma_f32_16x16x32_bf16 v[10:13], v[196:199], v[224:227], v[10:13]
	v_mfma_f32_16x16x32_bf16 v[14:17], v[204:207], v[224:227], v[14:17]
	v_mfma_f32_16x16x32_bf16 v[18:21], v[196:199], v[232:235], v[18:21]
	v_mfma_f32_16x16x32_bf16 v[22:25], v[204:207], v[232:235], v[22:25]
	v_mfma_f32_16x16x32_bf16 v[26:29], v[196:199], v[240:243], v[26:29]
	v_mfma_f32_16x16x32_bf16 v[30:33], v[204:207], v[240:243], v[30:33]
	s_setprio 0
	s_setprio 1
	v_mfma_f32_16x16x32_bf16 v[34:37], v[208:211], v[42:45], v[98:101]
	v_mfma_f32_16x16x32_bf16 v[38:41], v[216:219], v[42:45], v[38:41]
	v_mfma_f32_16x16x32_bf16 v[34:37], v[212:215], v[50:53], v[34:37]
	v_mfma_f32_16x16x32_bf16 v[38:41], v[220:223], v[50:53], v[38:41]
	v_mfma_f32_16x16x32_bf16 v[42:45], v[208:211], v[58:61], v[102:105]
	v_mfma_f32_16x16x32_bf16 v[46:49], v[216:219], v[58:61], v[46:49]
	v_mfma_f32_16x16x32_bf16 v[50:53], v[208:211], v[228:231], v[106:109]
	v_mfma_f32_16x16x32_bf16 v[54:57], v[216:219], v[228:231], v[54:57]
	v_mfma_f32_16x16x32_bf16 v[58:61], v[208:211], v[236:239], v[110:113]
	v_mfma_f32_16x16x32_bf16 v[62:65], v[216:219], v[236:239], v[62:65]
	v_mfma_f32_16x16x32_bf16 v[42:45], v[212:215], v[224:227], v[42:45]
	v_mfma_f32_16x16x32_bf16 v[46:49], v[220:223], v[224:227], v[46:49]
	v_mfma_f32_16x16x32_bf16 v[50:53], v[212:215], v[232:235], v[50:53]
	v_mfma_f32_16x16x32_bf16 v[54:57], v[220:223], v[232:235], v[54:57]
	s_setprio 2
	s_barrier
	v_mfma_f32_16x16x32_bf16 v[58:61], v[212:215], v[240:243], v[58:61]
	v_mfma_f32_16x16x32_bf16 v[62:65], v[220:223], v[240:243], v[62:65]
	s_setprio 0
	s_add_i32 s62, s62, s46
	v_lshl_add_u64 v[66:67], v[136:137], 0, s[12:13]
	s_mov_b32 m0, s62
	ds_read_b128 v[102:105], v141 offset:49152
	ds_read_b128 v[106:109], v141 offset:50176
	ds_read_b128 v[110:113], v141 offset:51200
	ds_read_b128 v[224:227], v141 offset:52224
	ds_read_b128 v[228:231], v141 offset:53248
	ds_read_b128 v[232:235], v141 offset:54272
	ds_read_b128 v[236:239], v141 offset:55296
	ds_read_b128 v[240:243], v141 offset:56320
	global_load_lds_dwordx4 v[66:67], off
	v_lshl_add_u64 v[66:67], v[244:245], 0, s[12:13]
	s_add_i32 m0, s62, 0x2000
	s_add_i32 s62, s63, s46
	global_load_lds_dwordx4 v[66:67], off
	s_mov_b32 m0, s62
	v_lshl_add_u64 v[66:67], v[246:247], 0, s[12:13]
	global_load_lds_dwordx4 v130, s[44:45]
	s_add_i32 m0, s62, 0x2000
	s_nop 0
	global_load_lds_dwordx4 v134, s[44:45]
	s_mov_b32 m0, s54
	s_nop 0
	global_load_lds_dwordx4 v[66:67], off
	v_lshl_add_u64 v[66:67], v[248:249], 0, s[12:13]
	s_mov_b32 m0, s55
	s_nop 0
	global_load_lds_dwordx4 v[66:67], off
	s_waitcnt vmcnt(8)
	s_waitcnt lgkmcnt(0)
	s_barrier
	s_setprio 1
	s_waitcnt lgkmcnt(0)
	s_nop 0
	v_mfma_f32_16x16x32_bf16 v[66:69], v[192:195], v[102:105], v[142:145]
	v_mfma_f32_16x16x32_bf16 v[70:73], v[200:203], v[102:105], v[148:151]
	v_mfma_f32_16x16x32_bf16 v[74:77], v[192:195], v[110:113], v[152:155]
	v_mfma_f32_16x16x32_bf16 v[78:81], v[200:203], v[110:113], v[156:159]
	v_mfma_f32_16x16x32_bf16 v[82:85], v[192:195], v[228:231], v[160:163]
	v_mfma_f32_16x16x32_bf16 v[86:89], v[200:203], v[228:231], v[164:167]
	v_mfma_f32_16x16x32_bf16 v[90:93], v[192:195], v[236:239], v[168:171]
	v_mfma_f32_16x16x32_bf16 v[94:97], v[200:203], v[236:239], v[172:175]
	v_mfma_f32_16x16x32_bf16 v[66:69], v[196:199], v[106:109], v[66:69]
	v_mfma_f32_16x16x32_bf16 v[70:73], v[204:207], v[106:109], v[70:73]
	v_mfma_f32_16x16x32_bf16 v[74:77], v[196:199], v[224:227], v[74:77]
	v_mfma_f32_16x16x32_bf16 v[78:81], v[204:207], v[224:227], v[78:81]
	v_mfma_f32_16x16x32_bf16 v[82:85], v[196:199], v[232:235], v[82:85]
	v_mfma_f32_16x16x32_bf16 v[86:89], v[204:207], v[232:235], v[86:89]
	v_mfma_f32_16x16x32_bf16 v[90:93], v[196:199], v[240:243], v[90:93]
	v_mfma_f32_16x16x32_bf16 v[94:97], v[204:207], v[240:243], v[94:97]
	s_setprio 0
	s_setprio 1
	v_mfma_f32_16x16x32_bf16 v[98:101], v[208:211], v[102:105], v[114:117]
	v_mfma_f32_16x16x32_bf16 v[102:105], v[216:219], v[102:105], v[122:125]
	v_mfma_f32_16x16x32_bf16 v[98:101], v[212:215], v[106:109], v[98:101]
	v_mfma_f32_16x16x32_bf16 v[102:105], v[220:223], v[106:109], v[102:105]
	v_mfma_f32_16x16x32_bf16 v[106:109], v[208:211], v[110:113], v[176:179]
	v_mfma_f32_16x16x32_bf16 v[110:113], v[216:219], v[110:113], v[180:183]
	v_mfma_f32_16x16x32_bf16 v[114:117], v[208:211], v[228:231], v[184:187]
	v_mfma_f32_16x16x32_bf16 v[118:121], v[216:219], v[228:231], v[118:121]
	v_mfma_f32_16x16x32_bf16 v[122:125], v[208:211], v[236:239], v[188:191]
	v_mfma_f32_16x16x32_bf16 v[126:129], v[216:219], v[236:239], v[126:129]
	v_mfma_f32_16x16x32_bf16 v[106:109], v[212:215], v[224:227], v[106:109]
	v_mfma_f32_16x16x32_bf16 v[110:113], v[220:223], v[224:227], v[110:113]
	v_mfma_f32_16x16x32_bf16 v[114:117], v[212:215], v[232:235], v[114:117]
	v_mfma_f32_16x16x32_bf16 v[118:121], v[220:223], v[232:235], v[118:121]
	s_setprio 2
	s_barrier
	v_mfma_f32_16x16x32_bf16 v[122:125], v[212:215], v[240:243], v[122:125]
	v_mfma_f32_16x16x32_bf16 v[126:129], v[220:223], v[240:243], v[126:129]
	s_setprio 0
	s_add_i32 s27, s27, 2
	s_cmp_ge_i32 s27, s15
	s_cbranch_scc0 .LBB0_495
	v_mov_b32_e32 v136, v130
	s_branch .LBB0_498

.LBB0_499:
	v_add_u32_e32 v133, s58, v140
	ds_read_b128 v[142:145], v133
	ds_read_b128 v[148:151], v133 offset:1024
	ds_read_b128 v[152:155], v133 offset:2048
	ds_read_b128 v[156:159], v133 offset:3072
	v_add_u32_e32 v133, s59, v140
	ds_read_b128 v[160:163], v133
	ds_read_b128 v[164:167], v133 offset:1024
	ds_read_b128 v[168:171], v133 offset:2048
	ds_read_b128 v[172:175], v133 offset:3072
	s_add_u32 s38, s36, 0xfff80080
	s_addc_u32 s39, s37, -1
	s_cmp_eq_u32 s42, 4
	s_cselect_b32 s41, s31, s39
	s_cselect_b32 s40, s30, s38
	s_cselect_b32 s39, s35, s27
	s_cselect_b32 s38, s34, s15
	s_mov_b32 m0, s56
	v_add_u32_e32 v141, 0, v1
	ds_read_b128 v[176:179], v141
	ds_read_b128 v[180:183], v141 offset:1024
	ds_read_b128 v[184:187], v141 offset:2048
	ds_read_b128 v[188:191], v141 offset:3072
	ds_read_b128 v[192:195], v141 offset:4096
	ds_read_b128 v[196:199], v141 offset:5120
	ds_read_b128 v[200:203], v141 offset:6144
	ds_read_b128 v[204:207], v141 offset:7168
	global_load_lds_dwordx4 v130, s[36:37]
	s_mov_b32 m0, s57
	v_mov_b32_e32 v133, v131
	global_load_lds_dwordx4 v132, s[36:37]
	s_waitcnt vmcnt(8)
	s_waitcnt lgkmcnt(0)
	s_barrier
	s_setprio 1
	s_waitcnt lgkmcnt(0)
	s_nop 0
	v_mfma_f32_16x16x32_bf16 v[2:5], v[142:145], v[176:179], v[2:5]
	v_mfma_f32_16x16x32_bf16 v[2:5], v[148:151], v[180:183], v[2:5]
	v_mfma_f32_16x16x32_bf16 v[6:9], v[156:159], v[180:183], v[6:9]
	v_mfma_f32_16x16x32_bf16 v[6:9], v[152:155], v[176:179], v[6:9]
	v_mfma_f32_16x16x32_bf16 v[14:17], v[152:155], v[184:187], v[14:17]
	v_mfma_f32_16x16x32_bf16 v[14:17], v[156:159], v[188:191], v[14:17]
	v_mfma_f32_16x16x32_bf16 v[10:13], v[148:151], v[188:191], v[10:13]
	v_mfma_f32_16x16x32_bf16 v[10:13], v[142:145], v[184:187], v[10:13]
	v_mfma_f32_16x16x32_bf16 v[18:21], v[142:145], v[192:195], v[18:21]
	v_mfma_f32_16x16x32_bf16 v[18:21], v[148:151], v[196:199], v[18:21]
	v_mfma_f32_16x16x32_bf16 v[22:25], v[156:159], v[196:199], v[22:25]
	v_mfma_f32_16x16x32_bf16 v[22:25], v[152:155], v[192:195], v[22:25]
	v_mfma_f32_16x16x32_bf16 v[30:33], v[152:155], v[200:203], v[30:33]
	v_mfma_f32_16x16x32_bf16 v[30:33], v[156:159], v[204:207], v[30:33]
	v_mfma_f32_16x16x32_bf16 v[26:29], v[148:151], v[204:207], v[26:29]
	v_mfma_f32_16x16x32_bf16 v[26:29], v[142:145], v[200:203], v[26:29]
	s_setprio 0
	s_setprio 1
	v_mfma_f32_16x16x32_bf16 v[34:37], v[160:163], v[176:179], v[34:37]
	v_mfma_f32_16x16x32_bf16 v[34:37], v[164:167], v[180:183], v[34:37]
	v_mfma_f32_16x16x32_bf16 v[38:41], v[172:175], v[180:183], v[38:41]
	v_mfma_f32_16x16x32_bf16 v[38:41], v[168:171], v[176:179], v[38:41]
	v_mfma_f32_16x16x32_bf16 v[46:49], v[168:171], v[184:187], v[46:49]
	v_mfma_f32_16x16x32_bf16 v[46:49], v[172:175], v[188:191], v[46:49]
	v_mfma_f32_16x16x32_bf16 v[42:45], v[164:167], v[188:191], v[42:45]
	v_mfma_f32_16x16x32_bf16 v[42:45], v[160:163], v[184:187], v[42:45]
	v_mfma_f32_16x16x32_bf16 v[50:53], v[160:163], v[192:195], v[50:53]
	v_mfma_f32_16x16x32_bf16 v[50:53], v[164:167], v[196:199], v[50:53]
	v_mfma_f32_16x16x32_bf16 v[54:57], v[172:175], v[196:199], v[54:57]
	v_mfma_f32_16x16x32_bf16 v[54:57], v[168:171], v[192:195], v[54:57]
	v_mfma_f32_16x16x32_bf16 v[62:65], v[168:171], v[200:203], v[62:65]
	v_mfma_f32_16x16x32_bf16 v[62:65], v[172:175], v[204:207], v[62:65]
	s_setprio 2
	s_barrier
	v_mfma_f32_16x16x32_bf16 v[58:61], v[164:167], v[204:207], v[58:61]
	v_mfma_f32_16x16x32_bf16 v[58:61], v[160:163], v[200:203], v[58:61]
	s_setprio 0
	s_add_i32 s43, s58, s46
	s_mov_b32 m0, s43
	ds_read_b128 v[176:179], v141 offset:16384
	ds_read_b128 v[180:183], v141 offset:17408
	ds_read_b128 v[184:187], v141 offset:18432
	ds_read_b128 v[188:191], v141 offset:19456
	ds_read_b128 v[192:195], v141 offset:20480
	ds_read_b128 v[196:199], v141 offset:21504
	ds_read_b128 v[200:203], v141 offset:22528
	ds_read_b128 v[204:207], v141 offset:23552
	global_load_lds_dwordx4 v136, s[38:39]
	s_add_i32 m0, s43, 0x2000
	s_add_u32 s44, s38, 0x400000
	s_addc_u32 s45, s39, 0
	s_add_i32 s43, s59, s46
	global_load_lds_dwordx4 v134, s[38:39]
	s_mov_b32 m0, s43
	v_mov_b32_e32 v137, v131
	global_load_lds_dwordx4 v136, s[44:45]
	s_add_i32 m0, s43, 0x2000
	v_mov_b32_e32 v135, v131
	global_load_lds_dwordx4 v134, s[44:45]
	s_mov_b32 m0, s47
	v_lshl_add_u64 v[138:139], s[38:39], 0, v[136:137]
	global_load_lds_dwordx4 v130, s[40:41]
	s_mov_b32 m0, s48
	v_lshl_add_u64 v[208:209], s[38:39], 0, v[134:135]
	global_load_lds_dwordx4 v132, s[40:41]
	s_waitcnt vmcnt(8)
	s_waitcnt lgkmcnt(0)
	v_lshl_add_u64 v[210:211], s[40:41], 0, v[130:131]
	v_lshl_add_u64 v[212:213], s[40:41], 0, v[132:133]
	s_barrier
	s_setprio 1
	s_waitcnt lgkmcnt(0)
	s_nop 0
	v_mfma_f32_16x16x32_bf16 v[66:69], v[142:145], v[176:179], v[66:69]
	v_mfma_f32_16x16x32_bf16 v[66:69], v[148:151], v[180:183], v[66:69]
	v_mfma_f32_16x16x32_bf16 v[70:73], v[156:159], v[180:183], v[70:73]
	v_mfma_f32_16x16x32_bf16 v[70:73], v[152:155], v[176:179], v[70:73]
	v_mfma_f32_16x16x32_bf16 v[78:81], v[152:155], v[184:187], v[78:81]
	v_mfma_f32_16x16x32_bf16 v[78:81], v[156:159], v[188:191], v[78:81]
	v_mfma_f32_16x16x32_bf16 v[74:77], v[148:151], v[188:191], v[74:77]
	v_mfma_f32_16x16x32_bf16 v[74:77], v[142:145], v[184:187], v[74:77]
	v_mfma_f32_16x16x32_bf16 v[82:85], v[142:145], v[192:195], v[82:85]
	v_mfma_f32_16x16x32_bf16 v[82:85], v[148:151], v[196:199], v[82:85]
	v_mfma_f32_16x16x32_bf16 v[86:89], v[156:159], v[196:199], v[86:89]
	v_mfma_f32_16x16x32_bf16 v[86:89], v[152:155], v[192:195], v[86:89]
	v_mfma_f32_16x16x32_bf16 v[94:97], v[152:155], v[200:203], v[94:97]
	v_mfma_f32_16x16x32_bf16 v[94:97], v[156:159], v[204:207], v[94:97]
	v_mfma_f32_16x16x32_bf16 v[90:93], v[148:151], v[204:207], v[90:93]
	v_mfma_f32_16x16x32_bf16 v[90:93], v[142:145], v[200:203], v[90:93]
	s_setprio 0
	s_setprio 1
	v_mfma_f32_16x16x32_bf16 v[98:101], v[160:163], v[176:179], v[98:101]
	v_mfma_f32_16x16x32_bf16 v[98:101], v[164:167], v[180:183], v[98:101]
	v_mfma_f32_16x16x32_bf16 v[102:105], v[172:175], v[180:183], v[102:105]
	v_mfma_f32_16x16x32_bf16 v[102:105], v[168:171], v[176:179], v[102:105]
	v_mfma_f32_16x16x32_bf16 v[110:113], v[168:171], v[184:187], v[110:113]
	v_mfma_f32_16x16x32_bf16 v[110:113], v[172:175], v[188:191], v[110:113]
	v_mfma_f32_16x16x32_bf16 v[106:109], v[164:167], v[188:191], v[106:109]
	v_mfma_f32_16x16x32_bf16 v[106:109], v[160:163], v[184:187], v[106:109]
	v_mfma_f32_16x16x32_bf16 v[114:117], v[160:163], v[192:195], v[114:117]
	v_mfma_f32_16x16x32_bf16 v[114:117], v[164:167], v[196:199], v[114:117]
	v_mfma_f32_16x16x32_bf16 v[118:121], v[172:175], v[196:199], v[118:121]
	v_mfma_f32_16x16x32_bf16 v[118:121], v[168:171], v[192:195], v[118:121]
	v_mfma_f32_16x16x32_bf16 v[126:129], v[168:171], v[200:203], v[126:129]
	v_mfma_f32_16x16x32_bf16 v[126:129], v[172:175], v[204:207], v[126:129]
	s_setprio 2
	s_barrier
	v_mfma_f32_16x16x32_bf16 v[122:125], v[164:167], v[204:207], v[122:125]
	v_mfma_f32_16x16x32_bf16 v[122:125], v[160:163], v[200:203], v[122:125]
	s_setprio 0
	s_add_i32 s43, 0, 0x18000
	v_add_u32_e32 v135, s43, v140
	s_add_i32 s44, 0, 0x1c000
	ds_read_b128 v[142:145], v135
	ds_read_b128 v[148:151], v135 offset:1024
	ds_read_b128 v[152:155], v135 offset:2048
	ds_read_b128 v[156:159], v135 offset:3072
	v_add_u32_e32 v135, s44, v140
	ds_read_b128 v[160:163], v135
	ds_read_b128 v[164:167], v135 offset:1024
	ds_read_b128 v[168:171], v135 offset:2048
	ds_read_b128 v[172:175], v135 offset:3072
	s_add_u32 s40, s40, 0x80000
	s_addc_u32 s41, s41, 0
	s_mov_b32 m0, s49
	ds_read_b128 v[176:179], v141 offset:32768
	ds_read_b128 v[180:183], v141 offset:33792
	ds_read_b128 v[184:187], v141 offset:34816
	ds_read_b128 v[188:191], v141 offset:35840
	ds_read_b128 v[192:195], v141 offset:36864
	ds_read_b128 v[196:199], v141 offset:37888
	ds_read_b128 v[200:203], v141 offset:38912
	ds_read_b128 v[204:207], v141 offset:39936
	global_load_lds_dwordx4 v130, s[40:41]
	s_mov_b32 m0, s50
	s_nop 0
	global_load_lds_dwordx4 v132, s[40:41]
	s_waitcnt vmcnt(8)
	s_waitcnt lgkmcnt(0)
	s_barrier
	s_setprio 1
	s_waitcnt lgkmcnt(0)
	s_nop 0
	v_mfma_f32_16x16x32_bf16 v[2:5], v[142:145], v[176:179], v[2:5]
	v_mfma_f32_16x16x32_bf16 v[2:5], v[148:151], v[180:183], v[2:5]
	v_mfma_f32_16x16x32_bf16 v[6:9], v[156:159], v[180:183], v[6:9]
	v_mfma_f32_16x16x32_bf16 v[6:9], v[152:155], v[176:179], v[6:9]
	v_mfma_f32_16x16x32_bf16 v[14:17], v[152:155], v[184:187], v[14:17]
	v_mfma_f32_16x16x32_bf16 v[14:17], v[156:159], v[188:191], v[14:17]
	v_mfma_f32_16x16x32_bf16 v[10:13], v[148:151], v[188:191], v[10:13]
	v_mfma_f32_16x16x32_bf16 v[10:13], v[142:145], v[184:187], v[10:13]
	v_mfma_f32_16x16x32_bf16 v[18:21], v[142:145], v[192:195], v[18:21]
	v_mfma_f32_16x16x32_bf16 v[18:21], v[148:151], v[196:199], v[18:21]
	v_mfma_f32_16x16x32_bf16 v[22:25], v[156:159], v[196:199], v[22:25]
	v_mfma_f32_16x16x32_bf16 v[22:25], v[152:155], v[192:195], v[22:25]
	v_mfma_f32_16x16x32_bf16 v[30:33], v[152:155], v[200:203], v[30:33]
	v_mfma_f32_16x16x32_bf16 v[30:33], v[156:159], v[204:207], v[30:33]
	v_mfma_f32_16x16x32_bf16 v[26:29], v[148:151], v[204:207], v[26:29]
	v_mfma_f32_16x16x32_bf16 v[26:29], v[142:145], v[200:203], v[26:29]
	s_setprio 0
	s_setprio 1
	v_mfma_f32_16x16x32_bf16 v[34:37], v[160:163], v[176:179], v[34:37]
	v_mfma_f32_16x16x32_bf16 v[34:37], v[164:167], v[180:183], v[34:37]
	v_mfma_f32_16x16x32_bf16 v[38:41], v[172:175], v[180:183], v[38:41]
	v_mfma_f32_16x16x32_bf16 v[38:41], v[168:171], v[176:179], v[38:41]
	v_mfma_f32_16x16x32_bf16 v[46:49], v[168:171], v[184:187], v[46:49]
	v_mfma_f32_16x16x32_bf16 v[46:49], v[172:175], v[188:191], v[46:49]
	v_mfma_f32_16x16x32_bf16 v[42:45], v[164:167], v[188:191], v[42:45]
	v_mfma_f32_16x16x32_bf16 v[42:45], v[160:163], v[184:187], v[42:45]
	v_mfma_f32_16x16x32_bf16 v[50:53], v[160:163], v[192:195], v[50:53]
	v_mfma_f32_16x16x32_bf16 v[50:53], v[164:167], v[196:199], v[50:53]
	v_mfma_f32_16x16x32_bf16 v[54:57], v[172:175], v[196:199], v[54:57]
	v_mfma_f32_16x16x32_bf16 v[54:57], v[168:171], v[192:195], v[54:57]
	v_mfma_f32_16x16x32_bf16 v[62:65], v[168:171], v[200:203], v[62:65]
	v_mfma_f32_16x16x32_bf16 v[62:65], v[172:175], v[204:207], v[62:65]
	s_setprio 2
	s_barrier
	v_mfma_f32_16x16x32_bf16 v[58:61], v[164:167], v[204:207], v[58:61]
	v_mfma_f32_16x16x32_bf16 v[58:61], v[160:163], v[200:203], v[58:61]
	s_setprio 0
	s_add_i32 s40, s43, s46
	v_lshl_add_u64 v[138:139], v[138:139], 0, s[6:7]
	s_mov_b32 m0, s40
	ds_read_b128 v[176:179], v141 offset:49152
	ds_read_b128 v[180:183], v141 offset:50176
	ds_read_b128 v[184:187], v141 offset:51200
	ds_read_b128 v[188:191], v141 offset:52224
	ds_read_b128 v[192:195], v141 offset:53248
	ds_read_b128 v[196:199], v141 offset:54272
	ds_read_b128 v[200:203], v141 offset:55296
	ds_read_b128 v[204:207], v141 offset:56320
	global_load_lds_dwordx4 v[138:139], off
	s_add_i32 m0, s40, 0x2000
	s_add_u32 s38, s38, 0x400080
	v_lshl_add_u64 v[138:139], v[208:209], 0, s[6:7]
	s_addc_u32 s39, s39, 0
	s_add_i32 s40, s44, s46
	global_load_lds_dwordx4 v[138:139], off
	s_mov_b32 m0, s40
	v_lshl_add_u64 v[138:139], v[210:211], 0, s[6:7]
	global_load_lds_dwordx4 v136, s[38:39]
	s_add_i32 m0, s40, 0x2000
	s_nop 0
	global_load_lds_dwordx4 v134, s[38:39]
	s_mov_b32 m0, s54
	s_nop 0
	global_load_lds_dwordx4 v[138:139], off
	v_lshl_add_u64 v[138:139], v[212:213], 0, s[6:7]
	s_mov_b32 m0, s55
	s_nop 0
	global_load_lds_dwordx4 v[138:139], off
	s_waitcnt vmcnt(8)
	s_waitcnt lgkmcnt(0)
	s_barrier
	s_setprio 1
	s_waitcnt lgkmcnt(0)
	s_nop 0
	v_mfma_f32_16x16x32_bf16 v[66:69], v[142:145], v[176:179], v[66:69]
	v_mfma_f32_16x16x32_bf16 v[66:69], v[148:151], v[180:183], v[66:69]
	v_mfma_f32_16x16x32_bf16 v[70:73], v[156:159], v[180:183], v[70:73]
	v_mfma_f32_16x16x32_bf16 v[70:73], v[152:155], v[176:179], v[70:73]
	v_mfma_f32_16x16x32_bf16 v[78:81], v[152:155], v[184:187], v[78:81]
	v_mfma_f32_16x16x32_bf16 v[78:81], v[156:159], v[188:191], v[78:81]
	v_mfma_f32_16x16x32_bf16 v[74:77], v[148:151], v[188:191], v[74:77]
	v_mfma_f32_16x16x32_bf16 v[74:77], v[142:145], v[184:187], v[74:77]
	v_mfma_f32_16x16x32_bf16 v[82:85], v[142:145], v[192:195], v[82:85]
	v_mfma_f32_16x16x32_bf16 v[82:85], v[148:151], v[196:199], v[82:85]
	v_mfma_f32_16x16x32_bf16 v[86:89], v[156:159], v[196:199], v[86:89]
	v_mfma_f32_16x16x32_bf16 v[86:89], v[152:155], v[192:195], v[86:89]
	v_mfma_f32_16x16x32_bf16 v[94:97], v[152:155], v[200:203], v[94:97]
	v_mfma_f32_16x16x32_bf16 v[94:97], v[156:159], v[204:207], v[94:97]
	v_mfma_f32_16x16x32_bf16 v[90:93], v[148:151], v[204:207], v[90:93]
	v_mfma_f32_16x16x32_bf16 v[90:93], v[142:145], v[200:203], v[90:93]
	s_setprio 0
	s_setprio 1
	v_mfma_f32_16x16x32_bf16 v[98:101], v[160:163], v[176:179], v[98:101]
	v_mfma_f32_16x16x32_bf16 v[98:101], v[164:167], v[180:183], v[98:101]
	v_mfma_f32_16x16x32_bf16 v[102:105], v[172:175], v[180:183], v[102:105]
	v_mfma_f32_16x16x32_bf16 v[102:105], v[168:171], v[176:179], v[102:105]
	v_mfma_f32_16x16x32_bf16 v[110:113], v[168:171], v[184:187], v[110:113]
	v_mfma_f32_16x16x32_bf16 v[110:113], v[172:175], v[188:191], v[110:113]
	v_mfma_f32_16x16x32_bf16 v[106:109], v[164:167], v[188:191], v[106:109]
	v_mfma_f32_16x16x32_bf16 v[106:109], v[160:163], v[184:187], v[106:109]
	v_mfma_f32_16x16x32_bf16 v[114:117], v[160:163], v[192:195], v[114:117]
	v_mfma_f32_16x16x32_bf16 v[114:117], v[164:167], v[196:199], v[114:117]
	v_mfma_f32_16x16x32_bf16 v[118:121], v[172:175], v[196:199], v[118:121]
	v_mfma_f32_16x16x32_bf16 v[118:121], v[168:171], v[192:195], v[118:121]
	v_mfma_f32_16x16x32_bf16 v[126:129], v[168:171], v[200:203], v[126:129]
	v_mfma_f32_16x16x32_bf16 v[126:129], v[172:175], v[204:207], v[126:129]
	s_setprio 2
	s_barrier
	v_mfma_f32_16x16x32_bf16 v[122:125], v[164:167], v[204:207], v[122:125]
	v_mfma_f32_16x16x32_bf16 v[122:125], v[160:163], v[200:203], v[122:125]
	s_setprio 0
	s_add_i32 s42, s42, 2
	s_add_u32 s36, s36, 0x100
	s_addc_u32 s37, s37, 0
	s_add_u32 s15, s15, 0x100
	s_addc_u32 s27, s27, 0
	s_cmp_gt_u32 s42, 5
	s_cbranch_scc0 .LBB0_499
	s_and_b64 vcc, exec, s[8:9]
	s_cbranch_vccz .LBB0_502
	s_barrier

.LBB0_528:
	s_add_i32 s53, 0, 0x10000
	s_add_i32 s72, 0, 0x14000
	v_add_u32_e32 v16, s53, v147
	v_add_u32_e32 v32, s72, v147
	ds_read_b128 v[4:7], v16
	ds_read_b128 v[8:11], v16 offset:1024
	ds_read_b128 v[12:15], v16 offset:2048
	ds_read_b128 v[16:19], v16 offset:3072
	ds_read_b128 v[20:23], v32
	ds_read_b128 v[24:27], v32 offset:1024
	ds_read_b128 v[28:31], v32 offset:2048
	ds_read_b128 v[32:35], v32 offset:3072
	v_add_u32_e32 v231, 0, v146
	ds_read_b128 v[36:39], v231
	ds_read_b128 v[40:43], v231 offset:1024
	ds_read_b128 v[44:47], v231 offset:2048
	ds_read_b128 v[48:51], v231 offset:3072
	ds_read_b128 v[52:55], v231 offset:4096
	ds_read_b128 v[56:59], v231 offset:5120
	ds_read_b128 v[60:63], v231 offset:6144
	ds_read_b128 v[64:67], v231 offset:7168
	s_waitcnt vmcnt(8)
	s_waitcnt lgkmcnt(0)
	s_barrier
	s_setprio 1
	s_waitcnt lgkmcnt(0)
	s_nop 0
	v_mfma_f32_16x16x32_f16 v[68:71], v[4:7], v[36:39], 0
	v_mfma_f32_16x16x32_f16 v[68:71], v[8:11], v[40:43], v[68:71]
	v_mfma_f32_16x16x32_f16 v[72:75], v[12:15], v[36:39], 0
	v_mfma_f32_16x16x32_f16 v[72:75], v[16:19], v[40:43], v[72:75]
	v_mfma_f32_16x16x32_f16 v[80:83], v[12:15], v[44:47], 0
	v_mfma_f32_16x16x32_f16 v[80:83], v[16:19], v[48:51], v[80:83]
	v_mfma_f32_16x16x32_f16 v[76:79], v[4:7], v[44:47], 0
	v_mfma_f32_16x16x32_f16 v[76:79], v[8:11], v[48:51], v[76:79]
	v_mfma_f32_16x16x32_f16 v[84:87], v[4:7], v[52:55], 0
	v_mfma_f32_16x16x32_f16 v[84:87], v[8:11], v[56:59], v[84:87]
	v_mfma_f32_16x16x32_f16 v[88:91], v[12:15], v[52:55], 0
	v_mfma_f32_16x16x32_f16 v[88:91], v[16:19], v[56:59], v[88:91]
	v_mfma_f32_16x16x32_f16 v[96:99], v[12:15], v[60:63], 0
	v_mfma_f32_16x16x32_f16 v[96:99], v[16:19], v[64:67], v[96:99]
	v_mfma_f32_16x16x32_f16 v[92:95], v[4:7], v[60:63], 0
	v_mfma_f32_16x16x32_f16 v[92:95], v[8:11], v[64:67], v[92:95]
	s_setprio 0
	s_setprio 1
	v_mfma_f32_16x16x32_f16 v[100:103], v[20:23], v[36:39], 0
	v_mfma_f32_16x16x32_f16 v[36:39], v[28:31], v[36:39], 0
	v_mfma_f32_16x16x32_f16 v[104:107], v[20:23], v[44:47], 0
	v_mfma_f32_16x16x32_f16 v[44:47], v[28:31], v[44:47], 0
	v_mfma_f32_16x16x32_f16 v[108:111], v[20:23], v[52:55], 0
	v_mfma_f32_16x16x32_f16 v[52:55], v[28:31], v[52:55], 0
	v_mfma_f32_16x16x32_f16 v[112:115], v[20:23], v[60:63], 0
	v_mfma_f32_16x16x32_f16 v[60:63], v[28:31], v[60:63], 0
	v_mfma_f32_16x16x32_f16 v[100:103], v[24:27], v[40:43], v[100:103]
	v_mfma_f32_16x16x32_f16 v[40:43], v[32:35], v[40:43], v[36:39]
	v_mfma_f32_16x16x32_f16 v[104:107], v[24:27], v[48:51], v[104:107]
	v_mfma_f32_16x16x32_f16 v[48:51], v[32:35], v[48:51], v[44:47]
	v_mfma_f32_16x16x32_f16 v[108:111], v[24:27], v[56:59], v[108:111]
	v_mfma_f32_16x16x32_f16 v[56:59], v[32:35], v[56:59], v[52:55]
	s_setprio 2
	s_barrier
	v_mfma_f32_16x16x32_f16 v[112:115], v[24:27], v[64:67], v[112:115]
	v_mfma_f32_16x16x32_f16 v[64:67], v[32:35], v[64:67], v[60:63]
	s_setprio 0
	v_lshl_add_u64 v[136:137], s[6:7], 0, v[2:3]
	s_add_i32 s53, s53, s38
	v_mov_b32_e32 v135, v3
	v_lshl_add_u64 v[140:141], v[136:137], 0, s[74:75]
	s_mov_b32 m0, s53
	v_lshl_add_u64 v[144:145], s[6:7], 0, v[134:135]
	ds_read_b128 v[36:39], v231 offset:16384
	ds_read_b128 v[44:47], v231 offset:17408
	ds_read_b128 v[52:55], v231 offset:18432
	ds_read_b128 v[60:63], v231 offset:19456
	ds_read_b128 v[116:119], v231 offset:20480
	ds_read_b128 v[120:123], v231 offset:21504
	ds_read_b128 v[124:127], v231 offset:22528
	ds_read_b128 v[128:131], v231 offset:23552
	global_load_lds_dwordx4 v[140:141], off
	v_lshl_add_u64 v[140:141], v[144:145], 0, s[74:75]
	s_add_i32 m0, s53, 0x2000
	s_add_i32 s53, s72, s38
	global_load_lds_dwordx4 v[140:141], off
	s_mov_b32 m0, s53
	v_mov_b32_e32 v139, v3
	global_load_lds_dwordx4 v2, s[16:17]
	s_add_i32 m0, s53, 0x2000
	v_lshl_add_u64 v[248:249], s[8:9], 0, v[138:139]
	v_mov_b32_e32 v133, v3
	global_load_lds_dwordx4 v134, s[16:17]
	v_lshl_add_u64 v[140:141], v[248:249], 0, s[74:75]
	s_mov_b32 m0, s58
	v_lshl_add_u64 v[250:251], s[8:9], 0, v[132:133]
	global_load_lds_dwordx4 v[140:141], off
	v_lshl_add_u64 v[140:141], v[250:251], 0, s[74:75]
	s_mov_b32 m0, s59
	s_nop 0
	global_load_lds_dwordx4 v[140:141], off
	s_waitcnt vmcnt(8)
	s_waitcnt lgkmcnt(0)
	s_barrier
	s_setprio 1
	s_waitcnt lgkmcnt(0)
	s_nop 0
	v_mfma_f32_16x16x32_f16 v[140:143], v[4:7], v[36:39], 0
	v_mfma_f32_16x16x32_f16 v[148:151], v[12:15], v[36:39], 0
	v_mfma_f32_16x16x32_f16 v[152:155], v[4:7], v[52:55], 0
	v_mfma_f32_16x16x32_f16 v[156:159], v[12:15], v[52:55], 0
	v_mfma_f32_16x16x32_f16 v[160:163], v[4:7], v[116:119], 0
	v_mfma_f32_16x16x32_f16 v[164:167], v[12:15], v[116:119], 0
	v_mfma_f32_16x16x32_f16 v[4:7], v[4:7], v[124:127], 0
	v_mfma_f32_16x16x32_f16 v[12:15], v[12:15], v[124:127], 0
	v_mfma_f32_16x16x32_f16 v[140:143], v[8:11], v[44:47], v[140:143]
	v_mfma_f32_16x16x32_f16 v[148:151], v[16:19], v[44:47], v[148:151]
	v_mfma_f32_16x16x32_f16 v[152:155], v[8:11], v[60:63], v[152:155]
	v_mfma_f32_16x16x32_f16 v[156:159], v[16:19], v[60:63], v[156:159]
	v_mfma_f32_16x16x32_f16 v[160:163], v[8:11], v[120:123], v[160:163]
	v_mfma_f32_16x16x32_f16 v[164:167], v[16:19], v[120:123], v[164:167]
	v_mfma_f32_16x16x32_f16 v[168:171], v[8:11], v[128:131], v[4:7]
	v_mfma_f32_16x16x32_f16 v[172:175], v[16:19], v[128:131], v[12:15]
	s_setprio 0
	s_setprio 1
	v_mfma_f32_16x16x32_f16 v[4:7], v[20:23], v[36:39], 0
	v_mfma_f32_16x16x32_f16 v[8:11], v[28:31], v[36:39], 0
	v_mfma_f32_16x16x32_f16 v[12:15], v[20:23], v[52:55], 0
	v_mfma_f32_16x16x32_f16 v[16:19], v[28:31], v[52:55], 0
	v_mfma_f32_16x16x32_f16 v[36:39], v[20:23], v[116:119], 0
	v_mfma_f32_16x16x32_f16 v[52:55], v[28:31], v[116:119], 0
	v_mfma_f32_16x16x32_f16 v[20:23], v[20:23], v[124:127], 0
	v_mfma_f32_16x16x32_f16 v[28:31], v[28:31], v[124:127], 0
	v_mfma_f32_16x16x32_f16 v[116:119], v[24:27], v[44:47], v[4:7]
	v_mfma_f32_16x16x32_f16 v[124:127], v[32:35], v[44:47], v[8:11]
	v_mfma_f32_16x16x32_f16 v[184:187], v[24:27], v[120:123], v[36:39]
	v_mfma_f32_16x16x32_f16 v[120:123], v[32:35], v[120:123], v[52:55]
	v_mfma_f32_16x16x32_f16 v[188:191], v[24:27], v[128:131], v[20:23]
	v_mfma_f32_16x16x32_f16 v[128:131], v[32:35], v[128:131], v[28:31]
	s_setprio 2
	s_barrier
	v_mfma_f32_16x16x32_f16 v[176:179], v[24:27], v[60:63], v[12:15]
	v_mfma_f32_16x16x32_f16 v[180:183], v[32:35], v[60:63], v[16:19]
	s_setprio 0
	s_add_i32 s53, 0, 0x18000
	v_add_u32_e32 v4, s53, v147
	s_add_i32 s72, 0, 0x1c000
	ds_read_b128 v[192:195], v4
	ds_read_b128 v[196:199], v4 offset:1024
	ds_read_b128 v[200:203], v4 offset:2048
	ds_read_b128 v[204:207], v4 offset:3072
	v_add_u32_e32 v4, s72, v147
	ds_read_b128 v[208:211], v4
	ds_read_b128 v[212:215], v4 offset:1024
	ds_read_b128 v[216:219], v4 offset:2048
	ds_read_b128 v[220:223], v4 offset:3072
	s_mov_b32 m0, s60
	ds_read_b128 v[44:47], v231 offset:32768
	ds_read_b128 v[52:55], v231 offset:33792
	ds_read_b128 v[60:63], v231 offset:34816
	ds_read_b128 v[224:227], v231 offset:35840
	ds_read_b128 v[232:235], v231 offset:36864
	ds_read_b128 v[236:239], v231 offset:37888
	ds_read_b128 v[240:243], v231 offset:38912
	ds_read_b128 v[244:247], v231 offset:39936
	global_load_lds_dwordx4 v138, s[26:27]
	s_mov_b32 m0, s61
	s_nop 0
	global_load_lds_dwordx4 v132, s[26:27]
	s_waitcnt vmcnt(8)
	s_waitcnt lgkmcnt(0)
	s_barrier
	s_setprio 1
	s_waitcnt lgkmcnt(0)
	s_nop 0
	v_mfma_f32_16x16x32_f16 v[4:7], v[192:195], v[44:47], v[68:71]
	v_mfma_f32_16x16x32_f16 v[8:11], v[200:203], v[44:47], v[72:75]
	v_mfma_f32_16x16x32_f16 v[12:15], v[192:195], v[60:63], v[76:79]
	v_mfma_f32_16x16x32_f16 v[16:19], v[200:203], v[60:63], v[80:83]
	v_mfma_f32_16x16x32_f16 v[20:23], v[192:195], v[232:235], v[84:87]
	v_mfma_f32_16x16x32_f16 v[24:27], v[200:203], v[232:235], v[88:91]
	v_mfma_f32_16x16x32_f16 v[28:31], v[192:195], v[240:243], v[92:95]
	v_mfma_f32_16x16x32_f16 v[32:35], v[200:203], v[240:243], v[96:99]
	v_mfma_f32_16x16x32_f16 v[4:7], v[196:199], v[52:55], v[4:7]
	v_mfma_f32_16x16x32_f16 v[8:11], v[204:207], v[52:55], v[8:11]
	v_mfma_f32_16x16x32_f16 v[12:15], v[196:199], v[224:227], v[12:15]
	v_mfma_f32_16x16x32_f16 v[16:19], v[204:207], v[224:227], v[16:19]
	v_mfma_f32_16x16x32_f16 v[20:23], v[196:199], v[236:239], v[20:23]
	v_mfma_f32_16x16x32_f16 v[24:27], v[204:207], v[236:239], v[24:27]
	v_mfma_f32_16x16x32_f16 v[28:31], v[196:199], v[244:247], v[28:31]
	v_mfma_f32_16x16x32_f16 v[32:35], v[204:207], v[244:247], v[32:35]
	s_setprio 0
	s_setprio 1
	v_mfma_f32_16x16x32_f16 v[36:39], v[208:211], v[44:47], v[100:103]
	v_mfma_f32_16x16x32_f16 v[40:43], v[216:219], v[44:47], v[40:43]
	v_mfma_f32_16x16x32_f16 v[36:39], v[212:215], v[52:55], v[36:39]
	v_mfma_f32_16x16x32_f16 v[40:43], v[220:223], v[52:55], v[40:43]
	v_mfma_f32_16x16x32_f16 v[44:47], v[208:211], v[60:63], v[104:107]
	v_mfma_f32_16x16x32_f16 v[48:51], v[216:219], v[60:63], v[48:51]
	v_mfma_f32_16x16x32_f16 v[52:55], v[208:211], v[232:235], v[108:111]
	v_mfma_f32_16x16x32_f16 v[56:59], v[216:219], v[232:235], v[56:59]
	v_mfma_f32_16x16x32_f16 v[60:63], v[208:211], v[240:243], v[112:115]
	v_mfma_f32_16x16x32_f16 v[64:67], v[216:219], v[240:243], v[64:67]
	v_mfma_f32_16x16x32_f16 v[44:47], v[212:215], v[224:227], v[44:47]
	v_mfma_f32_16x16x32_f16 v[48:51], v[220:223], v[224:227], v[48:51]
	v_mfma_f32_16x16x32_f16 v[52:55], v[212:215], v[236:239], v[52:55]
	v_mfma_f32_16x16x32_f16 v[56:59], v[220:223], v[236:239], v[56:59]
	s_setprio 2
	s_barrier
	v_mfma_f32_16x16x32_f16 v[60:63], v[212:215], v[244:247], v[60:63]
	v_mfma_f32_16x16x32_f16 v[64:67], v[220:223], v[244:247], v[64:67]
	s_setprio 0
	s_add_i32 s53, s53, s38
	v_lshl_add_u64 v[68:69], v[136:137], 0, s[24:25]
	s_mov_b32 m0, s53
	ds_read_b128 v[104:107], v231 offset:49152
	ds_read_b128 v[108:111], v231 offset:50176
	ds_read_b128 v[112:115], v231 offset:51200
	ds_read_b128 v[224:227], v231 offset:52224
	ds_read_b128 v[232:235], v231 offset:53248
	ds_read_b128 v[236:239], v231 offset:54272
	ds_read_b128 v[240:243], v231 offset:55296
	ds_read_b128 v[244:247], v231 offset:56320
	global_load_lds_dwordx4 v[68:69], off
	v_lshl_add_u64 v[68:69], v[144:145], 0, s[24:25]
	s_add_i32 m0, s53, 0x2000
	s_add_i32 s53, s72, s38
	global_load_lds_dwordx4 v[68:69], off
	s_mov_b32 m0, s53
	v_lshl_add_u64 v[68:69], v[248:249], 0, s[24:25]
	global_load_lds_dwordx4 v2, s[28:29]
	s_add_i32 m0, s53, 0x2000
	s_nop 0
	global_load_lds_dwordx4 v134, s[28:29]
	s_mov_b32 m0, s64
	s_nop 0
	global_load_lds_dwordx4 v[68:69], off
	v_lshl_add_u64 v[68:69], v[250:251], 0, s[24:25]
	s_mov_b32 m0, s65
	s_nop 0
	global_load_lds_dwordx4 v[68:69], off
	s_waitcnt vmcnt(8)
	s_waitcnt lgkmcnt(0)
	s_barrier
	s_setprio 1
	s_waitcnt lgkmcnt(0)
	s_nop 0
	v_mfma_f32_16x16x32_f16 v[68:71], v[192:195], v[104:107], v[140:143]
	v_mfma_f32_16x16x32_f16 v[72:75], v[200:203], v[104:107], v[148:151]
	v_mfma_f32_16x16x32_f16 v[76:79], v[192:195], v[112:115], v[152:155]
	v_mfma_f32_16x16x32_f16 v[80:83], v[200:203], v[112:115], v[156:159]
	v_mfma_f32_16x16x32_f16 v[84:87], v[192:195], v[232:235], v[160:163]
	v_mfma_f32_16x16x32_f16 v[88:91], v[200:203], v[232:235], v[164:167]
	v_mfma_f32_16x16x32_f16 v[92:95], v[192:195], v[240:243], v[168:171]
	v_mfma_f32_16x16x32_f16 v[96:99], v[200:203], v[240:243], v[172:175]
	v_mfma_f32_16x16x32_f16 v[68:71], v[196:199], v[108:111], v[68:71]
	v_mfma_f32_16x16x32_f16 v[72:75], v[204:207], v[108:111], v[72:75]
	v_mfma_f32_16x16x32_f16 v[76:79], v[196:199], v[224:227], v[76:79]
	v_mfma_f32_16x16x32_f16 v[80:83], v[204:207], v[224:227], v[80:83]
	v_mfma_f32_16x16x32_f16 v[84:87], v[196:199], v[236:239], v[84:87]
	v_mfma_f32_16x16x32_f16 v[88:91], v[204:207], v[236:239], v[88:91]
	v_mfma_f32_16x16x32_f16 v[92:95], v[196:199], v[244:247], v[92:95]
	v_mfma_f32_16x16x32_f16 v[96:99], v[204:207], v[244:247], v[96:99]
	s_setprio 0
	s_setprio 1
	v_mfma_f32_16x16x32_f16 v[100:103], v[208:211], v[104:107], v[116:119]
	v_mfma_f32_16x16x32_f16 v[104:107], v[216:219], v[104:107], v[124:127]
	v_mfma_f32_16x16x32_f16 v[100:103], v[212:215], v[108:111], v[100:103]
	v_mfma_f32_16x16x32_f16 v[104:107], v[220:223], v[108:111], v[104:107]
	v_mfma_f32_16x16x32_f16 v[108:111], v[208:211], v[112:115], v[176:179]
	v_mfma_f32_16x16x32_f16 v[112:115], v[216:219], v[112:115], v[180:183]
	v_mfma_f32_16x16x32_f16 v[116:119], v[208:211], v[232:235], v[184:187]
	v_mfma_f32_16x16x32_f16 v[120:123], v[216:219], v[232:235], v[120:123]
	v_mfma_f32_16x16x32_f16 v[124:127], v[208:211], v[240:243], v[188:191]
	v_mfma_f32_16x16x32_f16 v[128:131], v[216:219], v[240:243], v[128:131]
	v_mfma_f32_16x16x32_f16 v[108:111], v[212:215], v[224:227], v[108:111]
	v_mfma_f32_16x16x32_f16 v[112:115], v[220:223], v[224:227], v[112:115]
	v_mfma_f32_16x16x32_f16 v[116:119], v[212:215], v[236:239], v[116:119]
	v_mfma_f32_16x16x32_f16 v[120:123], v[220:223], v[236:239], v[120:123]
	s_setprio 2
	s_barrier
	v_mfma_f32_16x16x32_f16 v[124:127], v[212:215], v[244:247], v[124:127]
	v_mfma_f32_16x16x32_f16 v[128:131], v[220:223], v[244:247], v[128:131]
	s_setprio 0
	s_add_i32 s41, s41, 2
	s_cmp_ge_i32 s41, s40
	s_cbranch_scc0 .LBB0_528
	v_mov_b32_e32 v136, v2
	s_branch .LBB0_531

.LBB0_532:
	s_add_u32 s6, s8, 0xfff80080
	s_addc_u32 s7, s9, -1
	s_add_i32 s29, 0, 0x10000
	s_cmp_eq_u32 s28, 28
	s_cselect_b32 s17, s13, s7
	s_cselect_b32 s16, s12, s6
	s_cselect_b32 s7, s15, s27
	s_cselect_b32 s6, s14, s26
	s_add_i32 s53, 0, 0x14000
	ds_read_b128 v[138:141], v240
	ds_read_b128 v[142:145], v240 offset:1024
	ds_read_b128 v[148:151], v240 offset:2048
	ds_read_b128 v[152:155], v240 offset:3072
	ds_read_b128 v[156:159], v240 offset:16384
	ds_read_b128 v[160:163], v240 offset:17408
	ds_read_b128 v[164:167], v240 offset:18432
	ds_read_b128 v[168:171], v240 offset:19456
	s_mov_b32 m0, s66
	ds_read_b128 v[172:175], v146
	ds_read_b128 v[176:179], v146 offset:1024
	ds_read_b128 v[180:183], v146 offset:2048
	ds_read_b128 v[184:187], v146 offset:3072
	ds_read_b128 v[188:191], v146 offset:4096
	ds_read_b128 v[192:195], v146 offset:5120
	ds_read_b128 v[196:199], v146 offset:6144
	ds_read_b128 v[200:203], v146 offset:7168
	global_load_lds_dwordx4 v2, s[8:9]
	s_mov_b32 m0, s67
	v_mov_b32_e32 v133, v3
	global_load_lds_dwordx4 v132, s[8:9]
	s_waitcnt vmcnt(8)
	s_waitcnt lgkmcnt(0)
	s_barrier
	s_setprio 1
	s_waitcnt lgkmcnt(0)
	s_nop 0
	v_mfma_f32_16x16x32_f16 v[4:7], v[138:141], v[172:175], v[4:7]
	v_mfma_f32_16x16x32_f16 v[4:7], v[142:145], v[176:179], v[4:7]
	v_mfma_f32_16x16x32_f16 v[8:11], v[152:155], v[176:179], v[8:11]
	v_mfma_f32_16x16x32_f16 v[8:11], v[148:151], v[172:175], v[8:11]
	v_mfma_f32_16x16x32_f16 v[16:19], v[148:151], v[180:183], v[16:19]
	v_mfma_f32_16x16x32_f16 v[16:19], v[152:155], v[184:187], v[16:19]
	v_mfma_f32_16x16x32_f16 v[12:15], v[142:145], v[184:187], v[12:15]
	v_mfma_f32_16x16x32_f16 v[12:15], v[138:141], v[180:183], v[12:15]
	v_mfma_f32_16x16x32_f16 v[20:23], v[138:141], v[188:191], v[20:23]
	v_mfma_f32_16x16x32_f16 v[20:23], v[142:145], v[192:195], v[20:23]
	v_mfma_f32_16x16x32_f16 v[24:27], v[152:155], v[192:195], v[24:27]
	v_mfma_f32_16x16x32_f16 v[24:27], v[148:151], v[188:191], v[24:27]
	v_mfma_f32_16x16x32_f16 v[32:35], v[148:151], v[196:199], v[32:35]
	v_mfma_f32_16x16x32_f16 v[32:35], v[152:155], v[200:203], v[32:35]
	v_mfma_f32_16x16x32_f16 v[28:31], v[142:145], v[200:203], v[28:31]
	v_mfma_f32_16x16x32_f16 v[28:31], v[138:141], v[196:199], v[28:31]
	s_setprio 0
	s_setprio 1
	v_mfma_f32_16x16x32_f16 v[36:39], v[156:159], v[172:175], v[36:39]
	v_mfma_f32_16x16x32_f16 v[36:39], v[160:163], v[176:179], v[36:39]
	v_mfma_f32_16x16x32_f16 v[40:43], v[168:171], v[176:179], v[40:43]
	v_mfma_f32_16x16x32_f16 v[40:43], v[164:167], v[172:175], v[40:43]
	v_mfma_f32_16x16x32_f16 v[48:51], v[164:167], v[180:183], v[48:51]
	v_mfma_f32_16x16x32_f16 v[48:51], v[168:171], v[184:187], v[48:51]
	v_mfma_f32_16x16x32_f16 v[44:47], v[160:163], v[184:187], v[44:47]
	v_mfma_f32_16x16x32_f16 v[44:47], v[156:159], v[180:183], v[44:47]
	v_mfma_f32_16x16x32_f16 v[52:55], v[156:159], v[188:191], v[52:55]
	v_mfma_f32_16x16x32_f16 v[52:55], v[160:163], v[192:195], v[52:55]
	v_mfma_f32_16x16x32_f16 v[56:59], v[168:171], v[192:195], v[56:59]
	v_mfma_f32_16x16x32_f16 v[56:59], v[164:167], v[188:191], v[56:59]
	v_mfma_f32_16x16x32_f16 v[64:67], v[164:167], v[196:199], v[64:67]
	v_mfma_f32_16x16x32_f16 v[64:67], v[168:171], v[200:203], v[64:67]
	s_setprio 2
	s_barrier
	v_mfma_f32_16x16x32_f16 v[60:63], v[160:163], v[200:203], v[60:63]
	v_mfma_f32_16x16x32_f16 v[60:63], v[156:159], v[196:199], v[60:63]
	s_setprio 0
	s_add_i32 s29, s29, s38
	s_mov_b32 m0, s29
	ds_read_b128 v[172:175], v146 offset:16384
	ds_read_b128 v[176:179], v146 offset:17408
	ds_read_b128 v[180:183], v146 offset:18432
	ds_read_b128 v[184:187], v146 offset:19456
	ds_read_b128 v[188:191], v146 offset:20480
	ds_read_b128 v[192:195], v146 offset:21504
	ds_read_b128 v[196:199], v146 offset:22528
	ds_read_b128 v[200:203], v146 offset:23552
	global_load_lds_dwordx4 v136, s[6:7]
	s_add_i32 m0, s29, 0x2000
	s_add_u32 s40, s6, 0x80000
	s_addc_u32 s41, s7, 0
	s_add_i32 s29, s53, s38
	global_load_lds_dwordx4 v134, s[6:7]
	s_mov_b32 m0, s29
	v_mov_b32_e32 v137, v3
	global_load_lds_dwordx4 v136, s[40:41]
	s_add_i32 m0, s29, 0x2000
	v_mov_b32_e32 v135, v3
	global_load_lds_dwordx4 v134, s[40:41]
	s_mov_b32 m0, s58
	v_lshl_add_u64 v[204:205], s[6:7], 0, v[136:137]
	global_load_lds_dwordx4 v2, s[16:17]
	s_mov_b32 m0, s59
	v_lshl_add_u64 v[206:207], s[6:7], 0, v[134:135]
	global_load_lds_dwordx4 v132, s[16:17]
	s_waitcnt vmcnt(8)
	s_waitcnt lgkmcnt(0)
	v_lshl_add_u64 v[208:209], s[16:17], 0, v[2:3]
	v_lshl_add_u64 v[210:211], s[16:17], 0, v[132:133]
	s_barrier
	s_setprio 1
	s_waitcnt lgkmcnt(0)
	s_nop 0
	v_mfma_f32_16x16x32_f16 v[68:71], v[138:141], v[172:175], v[68:71]
	v_mfma_f32_16x16x32_f16 v[68:71], v[142:145], v[176:179], v[68:71]
	v_mfma_f32_16x16x32_f16 v[72:75], v[152:155], v[176:179], v[72:75]
	v_mfma_f32_16x16x32_f16 v[72:75], v[148:151], v[172:175], v[72:75]
	v_mfma_f32_16x16x32_f16 v[80:83], v[148:151], v[180:183], v[80:83]
	v_mfma_f32_16x16x32_f16 v[80:83], v[152:155], v[184:187], v[80:83]
	v_mfma_f32_16x16x32_f16 v[76:79], v[142:145], v[184:187], v[76:79]
	v_mfma_f32_16x16x32_f16 v[76:79], v[138:141], v[180:183], v[76:79]
	v_mfma_f32_16x16x32_f16 v[84:87], v[138:141], v[188:191], v[84:87]
	v_mfma_f32_16x16x32_f16 v[84:87], v[142:145], v[192:195], v[84:87]
	v_mfma_f32_16x16x32_f16 v[88:91], v[152:155], v[192:195], v[88:91]
	v_mfma_f32_16x16x32_f16 v[88:91], v[148:151], v[188:191], v[88:91]
	v_mfma_f32_16x16x32_f16 v[96:99], v[148:151], v[196:199], v[96:99]
	v_mfma_f32_16x16x32_f16 v[96:99], v[152:155], v[200:203], v[96:99]
	v_mfma_f32_16x16x32_f16 v[92:95], v[142:145], v[200:203], v[92:95]
	v_mfma_f32_16x16x32_f16 v[92:95], v[138:141], v[196:199], v[92:95]
	s_setprio 0
	s_setprio 1
	v_mfma_f32_16x16x32_f16 v[100:103], v[156:159], v[172:175], v[100:103]
	v_mfma_f32_16x16x32_f16 v[100:103], v[160:163], v[176:179], v[100:103]
	v_mfma_f32_16x16x32_f16 v[104:107], v[168:171], v[176:179], v[104:107]
	v_mfma_f32_16x16x32_f16 v[104:107], v[164:167], v[172:175], v[104:107]
	v_mfma_f32_16x16x32_f16 v[112:115], v[164:167], v[180:183], v[112:115]
	v_mfma_f32_16x16x32_f16 v[112:115], v[168:171], v[184:187], v[112:115]
	v_mfma_f32_16x16x32_f16 v[108:111], v[160:163], v[184:187], v[108:111]
	v_mfma_f32_16x16x32_f16 v[108:111], v[156:159], v[180:183], v[108:111]
	v_mfma_f32_16x16x32_f16 v[116:119], v[156:159], v[188:191], v[116:119]
	v_mfma_f32_16x16x32_f16 v[116:119], v[160:163], v[192:195], v[116:119]
	v_mfma_f32_16x16x32_f16 v[120:123], v[168:171], v[192:195], v[120:123]
	v_mfma_f32_16x16x32_f16 v[120:123], v[164:167], v[188:191], v[120:123]
	v_mfma_f32_16x16x32_f16 v[128:131], v[164:167], v[196:199], v[128:131]
	v_mfma_f32_16x16x32_f16 v[128:131], v[168:171], v[200:203], v[128:131]
	s_setprio 2
	s_barrier
	v_mfma_f32_16x16x32_f16 v[124:127], v[160:163], v[200:203], v[124:127]
	v_mfma_f32_16x16x32_f16 v[124:127], v[156:159], v[196:199], v[124:127]
	s_setprio 0
	s_add_i32 s29, 0, 0x18000
	s_add_i32 s40, 0, 0x1c000
	ds_read_b128 v[138:141], v240 offset:32768
	ds_read_b128 v[142:145], v240 offset:33792
	ds_read_b128 v[148:151], v240 offset:34816
	ds_read_b128 v[152:155], v240 offset:35840
	ds_read_b128 v[156:159], v240 offset:49152
	ds_read_b128 v[160:163], v240 offset:50176
	ds_read_b128 v[164:167], v240 offset:51200
	ds_read_b128 v[168:171], v240 offset:52224
	s_add_u32 s16, s16, 0x80000
	s_addc_u32 s17, s17, 0
	s_mov_b32 m0, s60
	ds_read_b128 v[172:175], v146 offset:32768
	ds_read_b128 v[176:179], v146 offset:33792
	ds_read_b128 v[180:183], v146 offset:34816
	ds_read_b128 v[184:187], v146 offset:35840
	ds_read_b128 v[188:191], v146 offset:36864
	ds_read_b128 v[192:195], v146 offset:37888
	ds_read_b128 v[196:199], v146 offset:38912
	ds_read_b128 v[200:203], v146 offset:39936
	global_load_lds_dwordx4 v2, s[16:17]
	s_mov_b32 m0, s61
	s_nop 0
	global_load_lds_dwordx4 v132, s[16:17]
	s_waitcnt vmcnt(8)
	s_waitcnt lgkmcnt(0)
	s_barrier
	s_setprio 1
	s_waitcnt lgkmcnt(0)
	s_nop 0
	v_mfma_f32_16x16x32_f16 v[4:7], v[138:141], v[172:175], v[4:7]
	v_mfma_f32_16x16x32_f16 v[4:7], v[142:145], v[176:179], v[4:7]
	v_mfma_f32_16x16x32_f16 v[8:11], v[152:155], v[176:179], v[8:11]
	v_mfma_f32_16x16x32_f16 v[8:11], v[148:151], v[172:175], v[8:11]
	v_mfma_f32_16x16x32_f16 v[16:19], v[148:151], v[180:183], v[16:19]
	v_mfma_f32_16x16x32_f16 v[16:19], v[152:155], v[184:187], v[16:19]
	v_mfma_f32_16x16x32_f16 v[12:15], v[142:145], v[184:187], v[12:15]
	v_mfma_f32_16x16x32_f16 v[12:15], v[138:141], v[180:183], v[12:15]
	v_mfma_f32_16x16x32_f16 v[20:23], v[138:141], v[188:191], v[20:23]
	v_mfma_f32_16x16x32_f16 v[20:23], v[142:145], v[192:195], v[20:23]
	v_mfma_f32_16x16x32_f16 v[24:27], v[152:155], v[192:195], v[24:27]
	v_mfma_f32_16x16x32_f16 v[24:27], v[148:151], v[188:191], v[24:27]
	v_mfma_f32_16x16x32_f16 v[32:35], v[148:151], v[196:199], v[32:35]
	v_mfma_f32_16x16x32_f16 v[32:35], v[152:155], v[200:203], v[32:35]
	v_mfma_f32_16x16x32_f16 v[28:31], v[142:145], v[200:203], v[28:31]
	v_mfma_f32_16x16x32_f16 v[28:31], v[138:141], v[196:199], v[28:31]
	s_setprio 0
	s_setprio 1
	v_mfma_f32_16x16x32_f16 v[36:39], v[156:159], v[172:175], v[36:39]
	v_mfma_f32_16x16x32_f16 v[36:39], v[160:163], v[176:179], v[36:39]
	v_mfma_f32_16x16x32_f16 v[40:43], v[168:171], v[176:179], v[40:43]
	v_mfma_f32_16x16x32_f16 v[40:43], v[164:167], v[172:175], v[40:43]
	v_mfma_f32_16x16x32_f16 v[48:51], v[164:167], v[180:183], v[48:51]
	v_mfma_f32_16x16x32_f16 v[48:51], v[168:171], v[184:187], v[48:51]
	v_mfma_f32_16x16x32_f16 v[44:47], v[160:163], v[184:187], v[44:47]
	v_mfma_f32_16x16x32_f16 v[44:47], v[156:159], v[180:183], v[44:47]
	v_mfma_f32_16x16x32_f16 v[52:55], v[156:159], v[188:191], v[52:55]
	v_mfma_f32_16x16x32_f16 v[52:55], v[160:163], v[192:195], v[52:55]
	v_mfma_f32_16x16x32_f16 v[56:59], v[168:171], v[192:195], v[56:59]
	v_mfma_f32_16x16x32_f16 v[56:59], v[164:167], v[188:191], v[56:59]
	v_mfma_f32_16x16x32_f16 v[64:67], v[164:167], v[196:199], v[64:67]
	v_mfma_f32_16x16x32_f16 v[64:67], v[168:171], v[200:203], v[64:67]
	s_setprio 2
	s_barrier
	v_mfma_f32_16x16x32_f16 v[60:63], v[160:163], v[200:203], v[60:63]
	v_mfma_f32_16x16x32_f16 v[60:63], v[156:159], v[196:199], v[60:63]
	s_setprio 0
	s_add_i32 s16, s29, s38
	v_lshl_add_u64 v[204:205], v[204:205], 0, s[86:87]
	s_mov_b32 m0, s16
	ds_read_b128 v[172:175], v146 offset:49152
	ds_read_b128 v[176:179], v146 offset:50176
	ds_read_b128 v[180:183], v146 offset:51200
	ds_read_b128 v[184:187], v146 offset:52224
	ds_read_b128 v[188:191], v146 offset:53248
	ds_read_b128 v[192:195], v146 offset:54272
	ds_read_b128 v[196:199], v146 offset:55296
	ds_read_b128 v[200:203], v146 offset:56320
	global_load_lds_dwordx4 v[204:205], off
	s_add_i32 m0, s16, 0x2000
	s_add_u32 s6, s6, 0x80080
	v_lshl_add_u64 v[204:205], v[206:207], 0, s[86:87]
	s_addc_u32 s7, s7, 0
	s_add_i32 s16, s40, s38
	global_load_lds_dwordx4 v[204:205], off
	s_mov_b32 m0, s16
	v_lshl_add_u64 v[204:205], v[208:209], 0, s[86:87]
	global_load_lds_dwordx4 v136, s[6:7]
	s_add_i32 m0, s16, 0x2000
	s_nop 0
	global_load_lds_dwordx4 v134, s[6:7]
	s_mov_b32 m0, s64
	s_nop 0
	global_load_lds_dwordx4 v[204:205], off
	v_lshl_add_u64 v[204:205], v[210:211], 0, s[86:87]
	s_mov_b32 m0, s65
	s_nop 0
	global_load_lds_dwordx4 v[204:205], off
	s_waitcnt vmcnt(8)
	s_waitcnt lgkmcnt(0)
	s_barrier
	s_setprio 1
	s_waitcnt lgkmcnt(0)
	s_nop 0
	v_mfma_f32_16x16x32_f16 v[68:71], v[138:141], v[172:175], v[68:71]
	v_mfma_f32_16x16x32_f16 v[68:71], v[142:145], v[176:179], v[68:71]
	v_mfma_f32_16x16x32_f16 v[72:75], v[152:155], v[176:179], v[72:75]
	v_mfma_f32_16x16x32_f16 v[72:75], v[148:151], v[172:175], v[72:75]
	v_mfma_f32_16x16x32_f16 v[80:83], v[148:151], v[180:183], v[80:83]
	v_mfma_f32_16x16x32_f16 v[80:83], v[152:155], v[184:187], v[80:83]
	v_mfma_f32_16x16x32_f16 v[76:79], v[142:145], v[184:187], v[76:79]
	v_mfma_f32_16x16x32_f16 v[76:79], v[138:141], v[180:183], v[76:79]
	v_mfma_f32_16x16x32_f16 v[84:87], v[138:141], v[188:191], v[84:87]
	v_mfma_f32_16x16x32_f16 v[84:87], v[142:145], v[192:195], v[84:87]
	v_mfma_f32_16x16x32_f16 v[88:91], v[152:155], v[192:195], v[88:91]
	v_mfma_f32_16x16x32_f16 v[88:91], v[148:151], v[188:191], v[88:91]
	v_mfma_f32_16x16x32_f16 v[96:99], v[148:151], v[196:199], v[96:99]
	v_mfma_f32_16x16x32_f16 v[96:99], v[152:155], v[200:203], v[96:99]
	v_mfma_f32_16x16x32_f16 v[92:95], v[142:145], v[200:203], v[92:95]
	v_mfma_f32_16x16x32_f16 v[92:95], v[138:141], v[196:199], v[92:95]
	s_setprio 0
	s_setprio 1
	v_mfma_f32_16x16x32_f16 v[100:103], v[156:159], v[172:175], v[100:103]
	v_mfma_f32_16x16x32_f16 v[100:103], v[160:163], v[176:179], v[100:103]
	v_mfma_f32_16x16x32_f16 v[104:107], v[168:171], v[176:179], v[104:107]
	v_mfma_f32_16x16x32_f16 v[104:107], v[164:167], v[172:175], v[104:107]
	v_mfma_f32_16x16x32_f16 v[112:115], v[164:167], v[180:183], v[112:115]
	v_mfma_f32_16x16x32_f16 v[112:115], v[168:171], v[184:187], v[112:115]
	v_mfma_f32_16x16x32_f16 v[108:111], v[160:163], v[184:187], v[108:111]
	v_mfma_f32_16x16x32_f16 v[108:111], v[156:159], v[180:183], v[108:111]
	v_mfma_f32_16x16x32_f16 v[116:119], v[156:159], v[188:191], v[116:119]
	v_mfma_f32_16x16x32_f16 v[116:119], v[160:163], v[192:195], v[116:119]
	v_mfma_f32_16x16x32_f16 v[120:123], v[168:171], v[192:195], v[120:123]
	v_mfma_f32_16x16x32_f16 v[120:123], v[164:167], v[188:191], v[120:123]
	v_mfma_f32_16x16x32_f16 v[128:131], v[164:167], v[196:199], v[128:131]
	v_mfma_f32_16x16x32_f16 v[128:131], v[168:171], v[200:203], v[128:131]
	s_setprio 2
	s_barrier
	v_mfma_f32_16x16x32_f16 v[124:127], v[160:163], v[200:203], v[124:127]
	v_mfma_f32_16x16x32_f16 v[124:127], v[156:159], v[196:199], v[124:127]
	s_setprio 0
	s_add_i32 s28, s28, 2
	s_add_u32 s8, s8, 0x100
	s_addc_u32 s9, s9, 0
	s_add_u32 s26, s26, 0x100
	s_addc_u32 s27, s27, 0
	s_cmp_gt_u32 s28, 29
	s_cbranch_scc0 .LBB0_532
	s_and_b64 vcc, exec, s[50:51]
	s_cbranch_vccz .LBB0_535
	s_barrier

.LBB0_641:
	s_add_i32 s43, 0, 0x10000
	s_add_i32 s71, 0, 0x14000
	v_add_u32_e32 v16, s43, v232
	v_add_u32_e32 v32, s71, v232
	ds_read_b128 v[4:7], v16
	ds_read_b128 v[8:11], v16 offset:1024
	ds_read_b128 v[12:15], v16 offset:2048
	ds_read_b128 v[16:19], v16 offset:3072
	ds_read_b128 v[20:23], v32
	ds_read_b128 v[24:27], v32 offset:1024
	ds_read_b128 v[28:31], v32 offset:2048
	ds_read_b128 v[32:35], v32 offset:3072
	v_add_u32_e32 v233, 0, v231
	ds_read_b128 v[36:39], v233
	ds_read_b128 v[40:43], v233 offset:1024
	ds_read_b128 v[44:47], v233 offset:2048
	ds_read_b128 v[48:51], v233 offset:3072
	ds_read_b128 v[52:55], v233 offset:4096
	ds_read_b128 v[56:59], v233 offset:5120
	ds_read_b128 v[60:63], v233 offset:6144
	ds_read_b128 v[64:67], v233 offset:7168
	s_waitcnt vmcnt(8)
	s_waitcnt lgkmcnt(0)
	s_barrier
	s_setprio 1
	s_waitcnt lgkmcnt(0)
	s_nop 0
	v_mfma_f32_16x16x32_bf16 v[68:71], v[4:7], v[36:39], 0
	v_mfma_f32_16x16x32_bf16 v[68:71], v[8:11], v[40:43], v[68:71]
	v_mfma_f32_16x16x32_bf16 v[72:75], v[12:15], v[36:39], 0
	v_mfma_f32_16x16x32_bf16 v[72:75], v[16:19], v[40:43], v[72:75]
	v_mfma_f32_16x16x32_bf16 v[80:83], v[12:15], v[44:47], 0
	v_mfma_f32_16x16x32_bf16 v[80:83], v[16:19], v[48:51], v[80:83]
	v_mfma_f32_16x16x32_bf16 v[76:79], v[4:7], v[44:47], 0
	v_mfma_f32_16x16x32_bf16 v[76:79], v[8:11], v[48:51], v[76:79]
	v_mfma_f32_16x16x32_bf16 v[84:87], v[4:7], v[52:55], 0
	v_mfma_f32_16x16x32_bf16 v[84:87], v[8:11], v[56:59], v[84:87]
	v_mfma_f32_16x16x32_bf16 v[88:91], v[12:15], v[52:55], 0
	v_mfma_f32_16x16x32_bf16 v[88:91], v[16:19], v[56:59], v[88:91]
	v_mfma_f32_16x16x32_bf16 v[96:99], v[12:15], v[60:63], 0
	v_mfma_f32_16x16x32_bf16 v[96:99], v[16:19], v[64:67], v[96:99]
	v_mfma_f32_16x16x32_bf16 v[92:95], v[4:7], v[60:63], 0
	v_mfma_f32_16x16x32_bf16 v[92:95], v[8:11], v[64:67], v[92:95]
	s_setprio 0
	s_setprio 1
	v_mfma_f32_16x16x32_bf16 v[100:103], v[20:23], v[36:39], 0
	v_mfma_f32_16x16x32_bf16 v[36:39], v[28:31], v[36:39], 0
	v_mfma_f32_16x16x32_bf16 v[104:107], v[20:23], v[44:47], 0
	v_mfma_f32_16x16x32_bf16 v[44:47], v[28:31], v[44:47], 0
	v_mfma_f32_16x16x32_bf16 v[108:111], v[20:23], v[52:55], 0
	v_mfma_f32_16x16x32_bf16 v[52:55], v[28:31], v[52:55], 0
	v_mfma_f32_16x16x32_bf16 v[112:115], v[20:23], v[60:63], 0
	v_mfma_f32_16x16x32_bf16 v[60:63], v[28:31], v[60:63], 0
	v_mfma_f32_16x16x32_bf16 v[100:103], v[24:27], v[40:43], v[100:103]
	v_mfma_f32_16x16x32_bf16 v[40:43], v[32:35], v[40:43], v[36:39]
	v_mfma_f32_16x16x32_bf16 v[104:107], v[24:27], v[48:51], v[104:107]
	v_mfma_f32_16x16x32_bf16 v[48:51], v[32:35], v[48:51], v[44:47]
	v_mfma_f32_16x16x32_bf16 v[108:111], v[24:27], v[56:59], v[108:111]
	v_mfma_f32_16x16x32_bf16 v[56:59], v[32:35], v[56:59], v[52:55]
	s_setprio 2
	s_barrier
	v_mfma_f32_16x16x32_bf16 v[112:115], v[24:27], v[64:67], v[112:115]
	v_mfma_f32_16x16x32_bf16 v[64:67], v[32:35], v[64:67], v[60:63]
	s_setprio 0
	v_lshl_add_u64 v[186:187], s[8:9], 0, v[2:3]
	s_add_i32 s43, s43, s54
	v_mov_b32_e32 v191, v3
	v_lshl_add_u64 v[134:135], v[186:187], 0, s[80:81]
	s_mov_b32 m0, s43
	v_lshl_add_u64 v[246:247], s[8:9], 0, v[190:191]
	ds_read_b128 v[36:39], v233 offset:16384
	ds_read_b128 v[44:47], v233 offset:17408
	ds_read_b128 v[52:55], v233 offset:18432
	ds_read_b128 v[60:63], v233 offset:19456
	ds_read_b128 v[116:119], v233 offset:20480
	ds_read_b128 v[120:123], v233 offset:21504
	ds_read_b128 v[124:127], v233 offset:22528
	ds_read_b128 v[128:131], v233 offset:23552
	global_load_lds_dwordx4 v[134:135], off
	v_lshl_add_u64 v[134:135], v[246:247], 0, s[80:81]
	s_add_i32 m0, s43, 0x2000
	s_add_i32 s43, s71, s54
	global_load_lds_dwordx4 v[134:135], off
	s_mov_b32 m0, s43
	v_mov_b32_e32 v133, v3
	global_load_lds_dwordx4 v2, s[16:17]
	s_add_i32 m0, s43, 0x2000
	v_lshl_add_u64 v[248:249], s[6:7], 0, v[132:133]
	v_mov_b32_e32 v189, v3
	global_load_lds_dwordx4 v190, s[16:17]
	v_lshl_add_u64 v[134:135], v[248:249], 0, s[80:81]
	s_mov_b32 m0, s55
	v_lshl_add_u64 v[250:251], s[6:7], 0, v[188:189]
	global_load_lds_dwordx4 v[134:135], off
	v_lshl_add_u64 v[134:135], v[250:251], 0, s[80:81]
	s_mov_b32 m0, s56
	s_nop 0
	global_load_lds_dwordx4 v[134:135], off
	s_waitcnt vmcnt(8)
	s_waitcnt lgkmcnt(0)
	s_barrier
	s_setprio 1
	s_waitcnt lgkmcnt(0)
	s_nop 0
	v_mfma_f32_16x16x32_bf16 v[134:137], v[4:7], v[36:39], 0
	v_mfma_f32_16x16x32_bf16 v[138:141], v[12:15], v[36:39], 0
	v_mfma_f32_16x16x32_bf16 v[142:145], v[4:7], v[52:55], 0
	v_mfma_f32_16x16x32_bf16 v[146:149], v[12:15], v[52:55], 0
	v_mfma_f32_16x16x32_bf16 v[150:153], v[4:7], v[116:119], 0
	v_mfma_f32_16x16x32_bf16 v[154:157], v[12:15], v[116:119], 0
	v_mfma_f32_16x16x32_bf16 v[4:7], v[4:7], v[124:127], 0
	v_mfma_f32_16x16x32_bf16 v[12:15], v[12:15], v[124:127], 0
	v_mfma_f32_16x16x32_bf16 v[134:137], v[8:11], v[44:47], v[134:137]
	v_mfma_f32_16x16x32_bf16 v[138:141], v[16:19], v[44:47], v[138:141]
	v_mfma_f32_16x16x32_bf16 v[142:145], v[8:11], v[60:63], v[142:145]
	v_mfma_f32_16x16x32_bf16 v[146:149], v[16:19], v[60:63], v[146:149]
	v_mfma_f32_16x16x32_bf16 v[150:153], v[8:11], v[120:123], v[150:153]
	v_mfma_f32_16x16x32_bf16 v[154:157], v[16:19], v[120:123], v[154:157]
	v_mfma_f32_16x16x32_bf16 v[158:161], v[8:11], v[128:131], v[4:7]
	v_mfma_f32_16x16x32_bf16 v[162:165], v[16:19], v[128:131], v[12:15]
	s_setprio 0
	s_setprio 1
	v_mfma_f32_16x16x32_bf16 v[4:7], v[20:23], v[36:39], 0
	v_mfma_f32_16x16x32_bf16 v[8:11], v[28:31], v[36:39], 0
	v_mfma_f32_16x16x32_bf16 v[12:15], v[20:23], v[52:55], 0
	v_mfma_f32_16x16x32_bf16 v[16:19], v[28:31], v[52:55], 0
	v_mfma_f32_16x16x32_bf16 v[36:39], v[20:23], v[116:119], 0
	v_mfma_f32_16x16x32_bf16 v[52:55], v[28:31], v[116:119], 0
	v_mfma_f32_16x16x32_bf16 v[20:23], v[20:23], v[124:127], 0
	v_mfma_f32_16x16x32_bf16 v[28:31], v[28:31], v[124:127], 0
	v_mfma_f32_16x16x32_bf16 v[116:119], v[24:27], v[44:47], v[4:7]
	v_mfma_f32_16x16x32_bf16 v[124:127], v[32:35], v[44:47], v[8:11]
	v_mfma_f32_16x16x32_bf16 v[174:177], v[24:27], v[120:123], v[36:39]
	v_mfma_f32_16x16x32_bf16 v[120:123], v[32:35], v[120:123], v[52:55]
	v_mfma_f32_16x16x32_bf16 v[178:181], v[24:27], v[128:131], v[20:23]
	v_mfma_f32_16x16x32_bf16 v[128:131], v[32:35], v[128:131], v[28:31]
	s_setprio 2
	s_barrier
	v_mfma_f32_16x16x32_bf16 v[166:169], v[24:27], v[60:63], v[12:15]
	v_mfma_f32_16x16x32_bf16 v[170:173], v[32:35], v[60:63], v[16:19]
	s_setprio 0
	s_add_i32 s43, 0, 0x18000
	v_add_u32_e32 v4, s43, v232
	s_add_i32 s71, 0, 0x1c000
	ds_read_b128 v[182:185], v4
	ds_read_b128 v[192:195], v4 offset:1024
	ds_read_b128 v[196:199], v4 offset:2048
	ds_read_b128 v[200:203], v4 offset:3072
	v_add_u32_e32 v4, s71, v232
	ds_read_b128 v[204:207], v4
	ds_read_b128 v[208:211], v4 offset:1024
	ds_read_b128 v[212:215], v4 offset:2048
	ds_read_b128 v[216:219], v4 offset:3072
	s_mov_b32 m0, s57
	ds_read_b128 v[44:47], v233 offset:32768
	ds_read_b128 v[52:55], v233 offset:33792
	ds_read_b128 v[60:63], v233 offset:34816
	ds_read_b128 v[220:223], v233 offset:35840
	ds_read_b128 v[224:227], v233 offset:36864
	ds_read_b128 v[234:237], v233 offset:37888
	ds_read_b128 v[238:241], v233 offset:38912
	ds_read_b128 v[242:245], v233 offset:39936
	global_load_lds_dwordx4 v132, s[26:27]
	s_mov_b32 m0, s58
	s_nop 0
	global_load_lds_dwordx4 v188, s[26:27]
	s_waitcnt vmcnt(8)
	s_waitcnt lgkmcnt(0)
	s_barrier
	s_setprio 1
	s_waitcnt lgkmcnt(0)
	s_nop 0
	v_mfma_f32_16x16x32_bf16 v[4:7], v[182:185], v[44:47], v[68:71]
	v_mfma_f32_16x16x32_bf16 v[8:11], v[196:199], v[44:47], v[72:75]
	v_mfma_f32_16x16x32_bf16 v[12:15], v[182:185], v[60:63], v[76:79]
	v_mfma_f32_16x16x32_bf16 v[16:19], v[196:199], v[60:63], v[80:83]
	v_mfma_f32_16x16x32_bf16 v[20:23], v[182:185], v[224:227], v[84:87]
	v_mfma_f32_16x16x32_bf16 v[24:27], v[196:199], v[224:227], v[88:91]
	v_mfma_f32_16x16x32_bf16 v[28:31], v[182:185], v[238:241], v[92:95]
	v_mfma_f32_16x16x32_bf16 v[32:35], v[196:199], v[238:241], v[96:99]
	v_mfma_f32_16x16x32_bf16 v[4:7], v[192:195], v[52:55], v[4:7]
	v_mfma_f32_16x16x32_bf16 v[8:11], v[200:203], v[52:55], v[8:11]
	v_mfma_f32_16x16x32_bf16 v[12:15], v[192:195], v[220:223], v[12:15]
	v_mfma_f32_16x16x32_bf16 v[16:19], v[200:203], v[220:223], v[16:19]
	v_mfma_f32_16x16x32_bf16 v[20:23], v[192:195], v[234:237], v[20:23]
	v_mfma_f32_16x16x32_bf16 v[24:27], v[200:203], v[234:237], v[24:27]
	v_mfma_f32_16x16x32_bf16 v[28:31], v[192:195], v[242:245], v[28:31]
	v_mfma_f32_16x16x32_bf16 v[32:35], v[200:203], v[242:245], v[32:35]
	s_setprio 0
	s_setprio 1
	v_mfma_f32_16x16x32_bf16 v[36:39], v[204:207], v[44:47], v[100:103]
	v_mfma_f32_16x16x32_bf16 v[40:43], v[212:215], v[44:47], v[40:43]
	v_mfma_f32_16x16x32_bf16 v[36:39], v[208:211], v[52:55], v[36:39]
	v_mfma_f32_16x16x32_bf16 v[40:43], v[216:219], v[52:55], v[40:43]
	v_mfma_f32_16x16x32_bf16 v[44:47], v[204:207], v[60:63], v[104:107]
	v_mfma_f32_16x16x32_bf16 v[48:51], v[212:215], v[60:63], v[48:51]
	v_mfma_f32_16x16x32_bf16 v[52:55], v[204:207], v[224:227], v[108:111]
	v_mfma_f32_16x16x32_bf16 v[56:59], v[212:215], v[224:227], v[56:59]
	v_mfma_f32_16x16x32_bf16 v[60:63], v[204:207], v[238:241], v[112:115]
	v_mfma_f32_16x16x32_bf16 v[64:67], v[212:215], v[238:241], v[64:67]
	v_mfma_f32_16x16x32_bf16 v[44:47], v[208:211], v[220:223], v[44:47]
	v_mfma_f32_16x16x32_bf16 v[48:51], v[216:219], v[220:223], v[48:51]
	v_mfma_f32_16x16x32_bf16 v[52:55], v[208:211], v[234:237], v[52:55]
	v_mfma_f32_16x16x32_bf16 v[56:59], v[216:219], v[234:237], v[56:59]
	s_setprio 2
	s_barrier
	v_mfma_f32_16x16x32_bf16 v[60:63], v[208:211], v[242:245], v[60:63]
	v_mfma_f32_16x16x32_bf16 v[64:67], v[216:219], v[242:245], v[64:67]
	s_setprio 0
	s_add_i32 s43, s43, s54
	v_lshl_add_u64 v[68:69], v[186:187], 0, s[0:1]
	s_mov_b32 m0, s43
	ds_read_b128 v[104:107], v233 offset:49152
	ds_read_b128 v[108:111], v233 offset:50176
	ds_read_b128 v[112:115], v233 offset:51200
	ds_read_b128 v[220:223], v233 offset:52224
	ds_read_b128 v[224:227], v233 offset:53248
	ds_read_b128 v[234:237], v233 offset:54272
	ds_read_b128 v[238:241], v233 offset:55296
	ds_read_b128 v[242:245], v233 offset:56320
	global_load_lds_dwordx4 v[68:69], off
	v_lshl_add_u64 v[68:69], v[246:247], 0, s[0:1]
	s_add_i32 m0, s43, 0x2000
	s_add_i32 s43, s71, s54
	global_load_lds_dwordx4 v[68:69], off
	s_mov_b32 m0, s43
	v_lshl_add_u64 v[68:69], v[248:249], 0, s[0:1]
	global_load_lds_dwordx4 v2, s[28:29]
	s_add_i32 m0, s43, 0x2000
	s_nop 0
	global_load_lds_dwordx4 v190, s[28:29]
	s_mov_b32 m0, s62
	s_nop 0
	global_load_lds_dwordx4 v[68:69], off
	v_lshl_add_u64 v[68:69], v[250:251], 0, s[0:1]
	s_mov_b32 m0, s63
	s_nop 0
	global_load_lds_dwordx4 v[68:69], off
	s_waitcnt vmcnt(8)
	s_waitcnt lgkmcnt(0)
	s_barrier
	s_setprio 1
	s_waitcnt lgkmcnt(0)
	s_nop 0
	v_mfma_f32_16x16x32_bf16 v[68:71], v[182:185], v[104:107], v[134:137]
	v_mfma_f32_16x16x32_bf16 v[72:75], v[196:199], v[104:107], v[138:141]
	v_mfma_f32_16x16x32_bf16 v[76:79], v[182:185], v[112:115], v[142:145]
	v_mfma_f32_16x16x32_bf16 v[80:83], v[196:199], v[112:115], v[146:149]
	v_mfma_f32_16x16x32_bf16 v[84:87], v[182:185], v[224:227], v[150:153]
	v_mfma_f32_16x16x32_bf16 v[88:91], v[196:199], v[224:227], v[154:157]
	v_mfma_f32_16x16x32_bf16 v[92:95], v[182:185], v[238:241], v[158:161]
	v_mfma_f32_16x16x32_bf16 v[96:99], v[196:199], v[238:241], v[162:165]
	v_mfma_f32_16x16x32_bf16 v[68:71], v[192:195], v[108:111], v[68:71]
	v_mfma_f32_16x16x32_bf16 v[72:75], v[200:203], v[108:111], v[72:75]
	v_mfma_f32_16x16x32_bf16 v[76:79], v[192:195], v[220:223], v[76:79]
	v_mfma_f32_16x16x32_bf16 v[80:83], v[200:203], v[220:223], v[80:83]
	v_mfma_f32_16x16x32_bf16 v[84:87], v[192:195], v[234:237], v[84:87]
	v_mfma_f32_16x16x32_bf16 v[88:91], v[200:203], v[234:237], v[88:91]
	v_mfma_f32_16x16x32_bf16 v[92:95], v[192:195], v[242:245], v[92:95]
	v_mfma_f32_16x16x32_bf16 v[96:99], v[200:203], v[242:245], v[96:99]
	s_setprio 0
	s_setprio 1
	v_mfma_f32_16x16x32_bf16 v[100:103], v[204:207], v[104:107], v[116:119]
	v_mfma_f32_16x16x32_bf16 v[104:107], v[212:215], v[104:107], v[124:127]
	v_mfma_f32_16x16x32_bf16 v[100:103], v[208:211], v[108:111], v[100:103]
	v_mfma_f32_16x16x32_bf16 v[104:107], v[216:219], v[108:111], v[104:107]
	v_mfma_f32_16x16x32_bf16 v[108:111], v[204:207], v[112:115], v[166:169]
	v_mfma_f32_16x16x32_bf16 v[112:115], v[212:215], v[112:115], v[170:173]
	v_mfma_f32_16x16x32_bf16 v[116:119], v[204:207], v[224:227], v[174:177]
	v_mfma_f32_16x16x32_bf16 v[120:123], v[212:215], v[224:227], v[120:123]
	v_mfma_f32_16x16x32_bf16 v[124:127], v[204:207], v[238:241], v[178:181]
	v_mfma_f32_16x16x32_bf16 v[128:131], v[212:215], v[238:241], v[128:131]
	v_mfma_f32_16x16x32_bf16 v[108:111], v[208:211], v[220:223], v[108:111]
	v_mfma_f32_16x16x32_bf16 v[112:115], v[216:219], v[220:223], v[112:115]
	v_mfma_f32_16x16x32_bf16 v[116:119], v[208:211], v[234:237], v[116:119]
	v_mfma_f32_16x16x32_bf16 v[120:123], v[216:219], v[234:237], v[120:123]
	s_setprio 2
	s_barrier
	v_mfma_f32_16x16x32_bf16 v[124:127], v[208:211], v[242:245], v[124:127]
	v_mfma_f32_16x16x32_bf16 v[128:131], v[216:219], v[242:245], v[128:131]
	s_setprio 0
	s_add_i32 s42, s42, 2
	s_cmp_ge_i32 s42, s38
	s_cbranch_scc0 .LBB0_641
	v_mov_b32_e32 v192, v2
	s_branch .LBB0_644

.LBB0_649:
	s_or_b32 s38, s28, 1
	s_lshl_b64 s[42:43], s[38:39], 7
	s_sub_u32 s38, 0, s42
	s_subb_u32 s42, 0, s43
	s_add_u32 s38, s6, s38
	s_addc_u32 s43, s7, s42
	s_add_i32 s71, 0, 0x10000
	s_add_i32 s72, 0, 0x14000
	s_waitcnt lgkmcnt(0)
	ds_read_b128 v[132:135], v240
	ds_read_b128 v[136:139], v240 offset:1024
	ds_read_b128 v[140:143], v240 offset:2048
	ds_read_b128 v[144:147], v240 offset:3072
	ds_read_b128 v[148:151], v240 offset:16384
	ds_read_b128 v[152:155], v240 offset:17408
	ds_read_b128 v[156:159], v240 offset:18432
	ds_read_b128 v[160:163], v240 offset:19456
	s_add_u32 s42, s38, 0x160000
	s_mov_b32 m0, s64
	s_addc_u32 s43, s43, 0
	ds_read_b128 v[164:167], v231
	ds_read_b128 v[168:171], v231 offset:1024
	ds_read_b128 v[172:175], v231 offset:2048
	ds_read_b128 v[176:179], v231 offset:3072
	ds_read_b128 v[180:183], v231 offset:4096
	ds_read_b128 v[184:187], v231 offset:5120
	ds_read_b128 v[194:197], v231 offset:6144
	ds_read_b128 v[198:201], v231 offset:7168
	global_load_lds_dwordx4 v2, s[42:43]
	s_mov_b32 m0, s65
	v_mov_b32_e32 v189, v3
	global_load_lds_dwordx4 v188, s[42:43]
	s_waitcnt vmcnt(8)
	s_waitcnt lgkmcnt(0)
	s_barrier
	s_setprio 1
	s_waitcnt lgkmcnt(0)
	s_nop 0
	v_mfma_f32_16x16x32_bf16 v[4:7], v[132:135], v[164:167], v[4:7]
	v_mfma_f32_16x16x32_bf16 v[4:7], v[136:139], v[168:171], v[4:7]
	v_mfma_f32_16x16x32_bf16 v[8:11], v[144:147], v[168:171], v[8:11]
	v_mfma_f32_16x16x32_bf16 v[8:11], v[140:143], v[164:167], v[8:11]
	v_mfma_f32_16x16x32_bf16 v[16:19], v[140:143], v[172:175], v[16:19]
	v_mfma_f32_16x16x32_bf16 v[16:19], v[144:147], v[176:179], v[16:19]
	v_mfma_f32_16x16x32_bf16 v[12:15], v[136:139], v[176:179], v[12:15]
	v_mfma_f32_16x16x32_bf16 v[12:15], v[132:135], v[172:175], v[12:15]
	v_mfma_f32_16x16x32_bf16 v[20:23], v[132:135], v[180:183], v[20:23]
	v_mfma_f32_16x16x32_bf16 v[20:23], v[136:139], v[184:187], v[20:23]
	v_mfma_f32_16x16x32_bf16 v[24:27], v[144:147], v[184:187], v[24:27]
	v_mfma_f32_16x16x32_bf16 v[24:27], v[140:143], v[180:183], v[24:27]
	v_mfma_f32_16x16x32_bf16 v[32:35], v[140:143], v[194:197], v[32:35]
	v_mfma_f32_16x16x32_bf16 v[32:35], v[144:147], v[198:201], v[32:35]
	v_mfma_f32_16x16x32_bf16 v[28:31], v[136:139], v[198:201], v[28:31]
	v_mfma_f32_16x16x32_bf16 v[28:31], v[132:135], v[194:197], v[28:31]
	s_setprio 0
	s_setprio 1
	v_mfma_f32_16x16x32_bf16 v[36:39], v[148:151], v[164:167], v[36:39]
	v_mfma_f32_16x16x32_bf16 v[36:39], v[152:155], v[168:171], v[36:39]
	v_mfma_f32_16x16x32_bf16 v[40:43], v[160:163], v[168:171], v[40:43]
	v_mfma_f32_16x16x32_bf16 v[40:43], v[156:159], v[164:167], v[40:43]
	v_mfma_f32_16x16x32_bf16 v[48:51], v[156:159], v[172:175], v[48:51]
	v_mfma_f32_16x16x32_bf16 v[48:51], v[160:163], v[176:179], v[48:51]
	v_mfma_f32_16x16x32_bf16 v[44:47], v[152:155], v[176:179], v[44:47]
	v_mfma_f32_16x16x32_bf16 v[44:47], v[148:151], v[172:175], v[44:47]
	v_mfma_f32_16x16x32_bf16 v[52:55], v[148:151], v[180:183], v[52:55]
	v_mfma_f32_16x16x32_bf16 v[52:55], v[152:155], v[184:187], v[52:55]
	v_mfma_f32_16x16x32_bf16 v[56:59], v[160:163], v[184:187], v[56:59]
	v_mfma_f32_16x16x32_bf16 v[56:59], v[156:159], v[180:183], v[56:59]
	v_mfma_f32_16x16x32_bf16 v[64:67], v[156:159], v[194:197], v[64:67]
	v_mfma_f32_16x16x32_bf16 v[64:67], v[160:163], v[198:201], v[64:67]
	s_setprio 2
	s_barrier
	v_mfma_f32_16x16x32_bf16 v[60:63], v[152:155], v[198:201], v[60:63]
	v_mfma_f32_16x16x32_bf16 v[60:63], v[148:151], v[194:197], v[60:63]
	s_setprio 0
	s_add_i32 s38, s71, s54
	s_mov_b32 m0, s38
	ds_read_b128 v[164:167], v231 offset:16384
	ds_read_b128 v[168:171], v231 offset:17408
	ds_read_b128 v[172:175], v231 offset:18432
	ds_read_b128 v[176:179], v231 offset:19456
	ds_read_b128 v[180:183], v231 offset:20480
	ds_read_b128 v[184:187], v231 offset:21504
	ds_read_b128 v[194:197], v231 offset:22528
	ds_read_b128 v[198:201], v231 offset:23552
	global_load_lds_dwordx4 v192, s[16:17]
	s_add_i32 m0, s38, 0x2000
	s_add_u32 s42, s16, 0x160000
	s_addc_u32 s43, s17, 0
	s_add_i32 s38, s72, s54
	global_load_lds_dwordx4 v190, s[16:17]
	s_mov_b32 m0, s38
	v_mov_b32_e32 v193, v3
	global_load_lds_dwordx4 v192, s[42:43]
	s_add_i32 m0, s38, 0x2000
	v_mov_b32_e32 v191, v3
	global_load_lds_dwordx4 v190, s[42:43]
	s_mov_b32 m0, s55
	v_lshl_add_u64 v[202:203], s[16:17], 0, v[192:193]
	global_load_lds_dwordx4 v2, s[26:27]
	s_mov_b32 m0, s56
	v_lshl_add_u64 v[204:205], s[16:17], 0, v[190:191]
	global_load_lds_dwordx4 v188, s[26:27]
	s_waitcnt vmcnt(8)
	s_waitcnt lgkmcnt(0)
	v_lshl_add_u64 v[206:207], s[26:27], 0, v[2:3]
	v_lshl_add_u64 v[208:209], s[26:27], 0, v[188:189]
	s_barrier
	s_setprio 1
	s_waitcnt lgkmcnt(0)
	s_nop 0
	v_mfma_f32_16x16x32_bf16 v[68:71], v[132:135], v[164:167], v[68:71]
	v_mfma_f32_16x16x32_bf16 v[68:71], v[136:139], v[168:171], v[68:71]
	v_mfma_f32_16x16x32_bf16 v[72:75], v[144:147], v[168:171], v[72:75]
	v_mfma_f32_16x16x32_bf16 v[72:75], v[140:143], v[164:167], v[72:75]
	v_mfma_f32_16x16x32_bf16 v[80:83], v[140:143], v[172:175], v[80:83]
	v_mfma_f32_16x16x32_bf16 v[80:83], v[144:147], v[176:179], v[80:83]
	v_mfma_f32_16x16x32_bf16 v[76:79], v[136:139], v[176:179], v[76:79]
	v_mfma_f32_16x16x32_bf16 v[76:79], v[132:135], v[172:175], v[76:79]
	v_mfma_f32_16x16x32_bf16 v[84:87], v[132:135], v[180:183], v[84:87]
	v_mfma_f32_16x16x32_bf16 v[84:87], v[136:139], v[184:187], v[84:87]
	v_mfma_f32_16x16x32_bf16 v[88:91], v[144:147], v[184:187], v[88:91]
	v_mfma_f32_16x16x32_bf16 v[88:91], v[140:143], v[180:183], v[88:91]
	v_mfma_f32_16x16x32_bf16 v[96:99], v[140:143], v[194:197], v[96:99]
	v_mfma_f32_16x16x32_bf16 v[96:99], v[144:147], v[198:201], v[96:99]
	v_mfma_f32_16x16x32_bf16 v[92:95], v[136:139], v[198:201], v[92:95]
	v_mfma_f32_16x16x32_bf16 v[92:95], v[132:135], v[194:197], v[92:95]
	s_setprio 0
	s_setprio 1
	v_mfma_f32_16x16x32_bf16 v[100:103], v[148:151], v[164:167], v[100:103]
	v_mfma_f32_16x16x32_bf16 v[100:103], v[152:155], v[168:171], v[100:103]
	v_mfma_f32_16x16x32_bf16 v[104:107], v[160:163], v[168:171], v[104:107]
	v_mfma_f32_16x16x32_bf16 v[104:107], v[156:159], v[164:167], v[104:107]
	v_mfma_f32_16x16x32_bf16 v[112:115], v[156:159], v[172:175], v[112:115]
	v_mfma_f32_16x16x32_bf16 v[112:115], v[160:163], v[176:179], v[112:115]
	v_mfma_f32_16x16x32_bf16 v[108:111], v[152:155], v[176:179], v[108:111]
	v_mfma_f32_16x16x32_bf16 v[108:111], v[148:151], v[172:175], v[108:111]
	v_mfma_f32_16x16x32_bf16 v[116:119], v[148:151], v[180:183], v[116:119]
	v_mfma_f32_16x16x32_bf16 v[116:119], v[152:155], v[184:187], v[116:119]
	v_mfma_f32_16x16x32_bf16 v[120:123], v[160:163], v[184:187], v[120:123]
	v_mfma_f32_16x16x32_bf16 v[120:123], v[156:159], v[180:183], v[120:123]
	v_mfma_f32_16x16x32_bf16 v[128:131], v[156:159], v[194:197], v[128:131]
	v_mfma_f32_16x16x32_bf16 v[128:131], v[160:163], v[198:201], v[128:131]
	s_setprio 2
	s_barrier
	v_mfma_f32_16x16x32_bf16 v[124:127], v[152:155], v[198:201], v[124:127]
	v_mfma_f32_16x16x32_bf16 v[124:127], v[148:151], v[194:197], v[124:127]
	s_setprio 0
	s_add_i32 s38, 0, 0x18000
	s_add_i32 s42, 0, 0x1c000
	ds_read_b128 v[132:135], v240 offset:32768
	ds_read_b128 v[136:139], v240 offset:33792
	ds_read_b128 v[140:143], v240 offset:34816
	ds_read_b128 v[144:147], v240 offset:35840
	ds_read_b128 v[148:151], v240 offset:49152
	ds_read_b128 v[152:155], v240 offset:50176
	ds_read_b128 v[156:159], v240 offset:51200
	ds_read_b128 v[160:163], v240 offset:52224
	s_add_u32 s26, s26, 0x160000
	s_addc_u32 s27, s27, 0
	s_mov_b32 m0, s57
	ds_read_b128 v[164:167], v231 offset:32768
	ds_read_b128 v[168:171], v231 offset:33792
	ds_read_b128 v[172:175], v231 offset:34816
	ds_read_b128 v[176:179], v231 offset:35840
	ds_read_b128 v[180:183], v231 offset:36864
	ds_read_b128 v[184:187], v231 offset:37888
	ds_read_b128 v[194:197], v231 offset:38912
	ds_read_b128 v[198:201], v231 offset:39936
	global_load_lds_dwordx4 v2, s[26:27]
	s_mov_b32 m0, s58
	s_nop 0
	global_load_lds_dwordx4 v188, s[26:27]
	s_waitcnt vmcnt(8)
	s_waitcnt lgkmcnt(0)
	s_barrier
	s_setprio 1
	s_waitcnt lgkmcnt(0)
	s_nop 0
	v_mfma_f32_16x16x32_bf16 v[4:7], v[132:135], v[164:167], v[4:7]
	v_mfma_f32_16x16x32_bf16 v[4:7], v[136:139], v[168:171], v[4:7]
	v_mfma_f32_16x16x32_bf16 v[8:11], v[144:147], v[168:171], v[8:11]
	v_mfma_f32_16x16x32_bf16 v[8:11], v[140:143], v[164:167], v[8:11]
	v_mfma_f32_16x16x32_bf16 v[16:19], v[140:143], v[172:175], v[16:19]
	v_mfma_f32_16x16x32_bf16 v[16:19], v[144:147], v[176:179], v[16:19]
	v_mfma_f32_16x16x32_bf16 v[12:15], v[136:139], v[176:179], v[12:15]
	v_mfma_f32_16x16x32_bf16 v[12:15], v[132:135], v[172:175], v[12:15]
	v_mfma_f32_16x16x32_bf16 v[20:23], v[132:135], v[180:183], v[20:23]
	v_mfma_f32_16x16x32_bf16 v[20:23], v[136:139], v[184:187], v[20:23]
	v_mfma_f32_16x16x32_bf16 v[24:27], v[144:147], v[184:187], v[24:27]
	v_mfma_f32_16x16x32_bf16 v[24:27], v[140:143], v[180:183], v[24:27]
	v_mfma_f32_16x16x32_bf16 v[32:35], v[140:143], v[194:197], v[32:35]
	v_mfma_f32_16x16x32_bf16 v[32:35], v[144:147], v[198:201], v[32:35]
	v_mfma_f32_16x16x32_bf16 v[28:31], v[136:139], v[198:201], v[28:31]
	v_mfma_f32_16x16x32_bf16 v[28:31], v[132:135], v[194:197], v[28:31]
	s_setprio 0
	s_setprio 1
	v_mfma_f32_16x16x32_bf16 v[36:39], v[148:151], v[164:167], v[36:39]
	v_mfma_f32_16x16x32_bf16 v[36:39], v[152:155], v[168:171], v[36:39]
	v_mfma_f32_16x16x32_bf16 v[40:43], v[160:163], v[168:171], v[40:43]
	v_mfma_f32_16x16x32_bf16 v[40:43], v[156:159], v[164:167], v[40:43]
	v_mfma_f32_16x16x32_bf16 v[48:51], v[156:159], v[172:175], v[48:51]
	v_mfma_f32_16x16x32_bf16 v[48:51], v[160:163], v[176:179], v[48:51]
	v_mfma_f32_16x16x32_bf16 v[44:47], v[152:155], v[176:179], v[44:47]
	v_mfma_f32_16x16x32_bf16 v[44:47], v[148:151], v[172:175], v[44:47]
	v_mfma_f32_16x16x32_bf16 v[52:55], v[148:151], v[180:183], v[52:55]
	v_mfma_f32_16x16x32_bf16 v[52:55], v[152:155], v[184:187], v[52:55]
	v_mfma_f32_16x16x32_bf16 v[56:59], v[160:163], v[184:187], v[56:59]
	v_mfma_f32_16x16x32_bf16 v[56:59], v[156:159], v[180:183], v[56:59]
	v_mfma_f32_16x16x32_bf16 v[64:67], v[156:159], v[194:197], v[64:67]
	v_mfma_f32_16x16x32_bf16 v[64:67], v[160:163], v[198:201], v[64:67]
	s_setprio 2
	s_barrier
	v_mfma_f32_16x16x32_bf16 v[60:63], v[152:155], v[198:201], v[60:63]
	v_mfma_f32_16x16x32_bf16 v[60:63], v[148:151], v[194:197], v[60:63]
	s_setprio 0
	s_add_i32 s26, s38, s54
	v_lshl_add_u64 v[202:203], v[202:203], 0, s[4:5]
	s_mov_b32 m0, s26
	ds_read_b128 v[164:167], v231 offset:49152
	ds_read_b128 v[168:171], v231 offset:50176
	ds_read_b128 v[172:175], v231 offset:51200
	ds_read_b128 v[176:179], v231 offset:52224
	ds_read_b128 v[180:183], v231 offset:53248
	ds_read_b128 v[184:187], v231 offset:54272
	ds_read_b128 v[194:197], v231 offset:55296
	ds_read_b128 v[198:201], v231 offset:56320
	global_load_lds_dwordx4 v[202:203], off
	s_add_i32 m0, s26, 0x2000
	s_add_u32 s16, s16, 0x15ff80
	v_lshl_add_u64 v[202:203], v[204:205], 0, s[4:5]
	s_addc_u32 s17, s17, 0
	s_add_i32 s26, s42, s54
	global_load_lds_dwordx4 v[202:203], off
	s_mov_b32 m0, s26
	v_lshl_add_u64 v[202:203], v[206:207], 0, s[4:5]
	global_load_lds_dwordx4 v192, s[16:17]
	s_add_i32 m0, s26, 0x2000
	s_nop 0
	global_load_lds_dwordx4 v190, s[16:17]
	s_mov_b32 m0, s62
	s_nop 0
	global_load_lds_dwordx4 v[202:203], off
	v_lshl_add_u64 v[202:203], v[208:209], 0, s[4:5]
	s_mov_b32 m0, s63
	s_nop 0
	global_load_lds_dwordx4 v[202:203], off
	s_waitcnt vmcnt(8)
	s_waitcnt lgkmcnt(0)
	s_barrier
	s_setprio 1
	s_waitcnt lgkmcnt(0)
	s_nop 0
	v_mfma_f32_16x16x32_bf16 v[68:71], v[132:135], v[164:167], v[68:71]
	v_mfma_f32_16x16x32_bf16 v[68:71], v[136:139], v[168:171], v[68:71]
	v_mfma_f32_16x16x32_bf16 v[72:75], v[144:147], v[168:171], v[72:75]
	v_mfma_f32_16x16x32_bf16 v[72:75], v[140:143], v[164:167], v[72:75]
	v_mfma_f32_16x16x32_bf16 v[80:83], v[140:143], v[172:175], v[80:83]
	v_mfma_f32_16x16x32_bf16 v[80:83], v[144:147], v[176:179], v[80:83]
	v_mfma_f32_16x16x32_bf16 v[76:79], v[136:139], v[176:179], v[76:79]
	v_mfma_f32_16x16x32_bf16 v[76:79], v[132:135], v[172:175], v[76:79]
	v_mfma_f32_16x16x32_bf16 v[84:87], v[132:135], v[180:183], v[84:87]
	v_mfma_f32_16x16x32_bf16 v[84:87], v[136:139], v[184:187], v[84:87]
	v_mfma_f32_16x16x32_bf16 v[88:91], v[144:147], v[184:187], v[88:91]
	v_mfma_f32_16x16x32_bf16 v[88:91], v[140:143], v[180:183], v[88:91]
	v_mfma_f32_16x16x32_bf16 v[96:99], v[140:143], v[194:197], v[96:99]
	v_mfma_f32_16x16x32_bf16 v[96:99], v[144:147], v[198:201], v[96:99]
	v_mfma_f32_16x16x32_bf16 v[92:95], v[136:139], v[198:201], v[92:95]
	v_mfma_f32_16x16x32_bf16 v[92:95], v[132:135], v[194:197], v[92:95]
	s_setprio 0
	s_setprio 1
	v_mfma_f32_16x16x32_bf16 v[100:103], v[148:151], v[164:167], v[100:103]
	v_mfma_f32_16x16x32_bf16 v[100:103], v[152:155], v[168:171], v[100:103]
	v_mfma_f32_16x16x32_bf16 v[104:107], v[160:163], v[168:171], v[104:107]
	v_mfma_f32_16x16x32_bf16 v[104:107], v[156:159], v[164:167], v[104:107]
	v_mfma_f32_16x16x32_bf16 v[112:115], v[156:159], v[172:175], v[112:115]
	v_mfma_f32_16x16x32_bf16 v[112:115], v[160:163], v[176:179], v[112:115]
	v_mfma_f32_16x16x32_bf16 v[108:111], v[152:155], v[176:179], v[108:111]
	v_mfma_f32_16x16x32_bf16 v[108:111], v[148:151], v[172:175], v[108:111]
	v_mfma_f32_16x16x32_bf16 v[116:119], v[148:151], v[180:183], v[116:119]
	v_mfma_f32_16x16x32_bf16 v[116:119], v[152:155], v[184:187], v[116:119]
	v_mfma_f32_16x16x32_bf16 v[120:123], v[160:163], v[184:187], v[120:123]
	v_mfma_f32_16x16x32_bf16 v[120:123], v[156:159], v[180:183], v[120:123]
	v_mfma_f32_16x16x32_bf16 v[128:131], v[156:159], v[194:197], v[128:131]
	v_mfma_f32_16x16x32_bf16 v[128:131], v[160:163], v[198:201], v[128:131]
	s_setprio 2
	s_barrier
	v_mfma_f32_16x16x32_bf16 v[124:127], v[152:155], v[198:201], v[124:127]
	v_mfma_f32_16x16x32_bf16 v[124:127], v[148:151], v[194:197], v[124:127]
	s_setprio 0
	s_cmpk_gt_u32 s28, 0x55
	s_cbranch_scc1 .LBB0_651
	s_mov_b32 s28, s29
	s_branch .LBB0_645

.LBB0_749:
	s_add_i32 s47, 0, 0x10000
	s_add_i32 s49, 0, 0x14000
	v_add_u32_e32 v16, s47, v147
	v_add_u32_e32 v32, s49, v147
	ds_read_b128 v[4:7], v16
	ds_read_b128 v[8:11], v16 offset:1024
	ds_read_b128 v[12:15], v16 offset:2048
	ds_read_b128 v[16:19], v16 offset:3072
	ds_read_b128 v[20:23], v32
	ds_read_b128 v[24:27], v32 offset:1024
	ds_read_b128 v[28:31], v32 offset:2048
	ds_read_b128 v[32:35], v32 offset:3072
	v_add_u32_e32 v231, 0, v146
	ds_read_b128 v[36:39], v231
	ds_read_b128 v[40:43], v231 offset:1024
	ds_read_b128 v[44:47], v231 offset:2048
	ds_read_b128 v[48:51], v231 offset:3072
	ds_read_b128 v[52:55], v231 offset:4096
	ds_read_b128 v[56:59], v231 offset:5120
	ds_read_b128 v[60:63], v231 offset:6144
	ds_read_b128 v[64:67], v231 offset:7168
	s_waitcnt vmcnt(8)
	s_waitcnt lgkmcnt(0)
	s_barrier
	s_setprio 1
	s_waitcnt lgkmcnt(0)
	s_nop 0
	v_mfma_f32_16x16x32_f16 v[68:71], v[4:7], v[36:39], 0
	v_mfma_f32_16x16x32_f16 v[68:71], v[8:11], v[40:43], v[68:71]
	v_mfma_f32_16x16x32_f16 v[72:75], v[12:15], v[36:39], 0
	v_mfma_f32_16x16x32_f16 v[72:75], v[16:19], v[40:43], v[72:75]
	v_mfma_f32_16x16x32_f16 v[80:83], v[12:15], v[44:47], 0
	v_mfma_f32_16x16x32_f16 v[80:83], v[16:19], v[48:51], v[80:83]
	v_mfma_f32_16x16x32_f16 v[76:79], v[4:7], v[44:47], 0
	v_mfma_f32_16x16x32_f16 v[76:79], v[8:11], v[48:51], v[76:79]
	v_mfma_f32_16x16x32_f16 v[84:87], v[4:7], v[52:55], 0
	v_mfma_f32_16x16x32_f16 v[84:87], v[8:11], v[56:59], v[84:87]
	v_mfma_f32_16x16x32_f16 v[88:91], v[12:15], v[52:55], 0
	v_mfma_f32_16x16x32_f16 v[88:91], v[16:19], v[56:59], v[88:91]
	v_mfma_f32_16x16x32_f16 v[96:99], v[12:15], v[60:63], 0
	v_mfma_f32_16x16x32_f16 v[96:99], v[16:19], v[64:67], v[96:99]
	v_mfma_f32_16x16x32_f16 v[92:95], v[4:7], v[60:63], 0
	v_mfma_f32_16x16x32_f16 v[92:95], v[8:11], v[64:67], v[92:95]
	s_setprio 0
	s_setprio 1
	v_mfma_f32_16x16x32_f16 v[100:103], v[20:23], v[36:39], 0
	v_mfma_f32_16x16x32_f16 v[36:39], v[28:31], v[36:39], 0
	v_mfma_f32_16x16x32_f16 v[104:107], v[20:23], v[44:47], 0
	v_mfma_f32_16x16x32_f16 v[44:47], v[28:31], v[44:47], 0
	v_mfma_f32_16x16x32_f16 v[108:111], v[20:23], v[52:55], 0
	v_mfma_f32_16x16x32_f16 v[52:55], v[28:31], v[52:55], 0
	v_mfma_f32_16x16x32_f16 v[112:115], v[20:23], v[60:63], 0
	v_mfma_f32_16x16x32_f16 v[60:63], v[28:31], v[60:63], 0
	v_mfma_f32_16x16x32_f16 v[100:103], v[24:27], v[40:43], v[100:103]
	v_mfma_f32_16x16x32_f16 v[40:43], v[32:35], v[40:43], v[36:39]
	v_mfma_f32_16x16x32_f16 v[104:107], v[24:27], v[48:51], v[104:107]
	v_mfma_f32_16x16x32_f16 v[48:51], v[32:35], v[48:51], v[44:47]
	v_mfma_f32_16x16x32_f16 v[108:111], v[24:27], v[56:59], v[108:111]
	v_mfma_f32_16x16x32_f16 v[56:59], v[32:35], v[56:59], v[52:55]
	s_setprio 2
	s_barrier
	v_mfma_f32_16x16x32_f16 v[112:115], v[24:27], v[64:67], v[112:115]
	v_mfma_f32_16x16x32_f16 v[64:67], v[32:35], v[64:67], v[60:63]
	s_setprio 0
	v_lshl_add_u64 v[136:137], s[6:7], 0, v[2:3]
	s_add_i32 s47, s47, s62
	v_mov_b32_e32 v135, v3
	v_lshl_add_u64 v[140:141], v[136:137], 0, s[74:75]
	s_mov_b32 m0, s47
	v_lshl_add_u64 v[144:145], s[6:7], 0, v[134:135]
	ds_read_b128 v[36:39], v231 offset:16384
	ds_read_b128 v[44:47], v231 offset:17408
	ds_read_b128 v[52:55], v231 offset:18432
	ds_read_b128 v[60:63], v231 offset:19456
	ds_read_b128 v[116:119], v231 offset:20480
	ds_read_b128 v[120:123], v231 offset:21504
	ds_read_b128 v[124:127], v231 offset:22528
	ds_read_b128 v[128:131], v231 offset:23552
	global_load_lds_dwordx4 v[140:141], off
	v_lshl_add_u64 v[140:141], v[144:145], 0, s[74:75]
	s_add_i32 m0, s47, 0x2000
	s_add_i32 s47, s49, s62
	global_load_lds_dwordx4 v[140:141], off
	s_mov_b32 m0, s47
	v_mov_b32_e32 v139, v3
	global_load_lds_dwordx4 v2, s[16:17]
	s_add_i32 m0, s47, 0x2000
	v_lshl_add_u64 v[248:249], s[8:9], 0, v[138:139]
	v_mov_b32_e32 v133, v3
	global_load_lds_dwordx4 v134, s[16:17]
	v_lshl_add_u64 v[140:141], v[248:249], 0, s[74:75]
	s_mov_b32 m0, s63
	v_lshl_add_u64 v[250:251], s[8:9], 0, v[132:133]
	global_load_lds_dwordx4 v[140:141], off
	v_lshl_add_u64 v[140:141], v[250:251], 0, s[74:75]
	s_mov_b32 m0, s64
	s_nop 0
	global_load_lds_dwordx4 v[140:141], off
	s_waitcnt vmcnt(8)
	s_waitcnt lgkmcnt(0)
	s_barrier
	s_setprio 1
	s_waitcnt lgkmcnt(0)
	s_nop 0
	v_mfma_f32_16x16x32_f16 v[140:143], v[4:7], v[36:39], 0
	v_mfma_f32_16x16x32_f16 v[148:151], v[12:15], v[36:39], 0
	v_mfma_f32_16x16x32_f16 v[152:155], v[4:7], v[52:55], 0
	v_mfma_f32_16x16x32_f16 v[156:159], v[12:15], v[52:55], 0
	v_mfma_f32_16x16x32_f16 v[160:163], v[4:7], v[116:119], 0
	v_mfma_f32_16x16x32_f16 v[164:167], v[12:15], v[116:119], 0
	v_mfma_f32_16x16x32_f16 v[4:7], v[4:7], v[124:127], 0
	v_mfma_f32_16x16x32_f16 v[12:15], v[12:15], v[124:127], 0
	v_mfma_f32_16x16x32_f16 v[140:143], v[8:11], v[44:47], v[140:143]
	v_mfma_f32_16x16x32_f16 v[148:151], v[16:19], v[44:47], v[148:151]
	v_mfma_f32_16x16x32_f16 v[152:155], v[8:11], v[60:63], v[152:155]
	v_mfma_f32_16x16x32_f16 v[156:159], v[16:19], v[60:63], v[156:159]
	v_mfma_f32_16x16x32_f16 v[160:163], v[8:11], v[120:123], v[160:163]
	v_mfma_f32_16x16x32_f16 v[164:167], v[16:19], v[120:123], v[164:167]
	v_mfma_f32_16x16x32_f16 v[168:171], v[8:11], v[128:131], v[4:7]
	v_mfma_f32_16x16x32_f16 v[172:175], v[16:19], v[128:131], v[12:15]
	s_setprio 0
	s_setprio 1
	v_mfma_f32_16x16x32_f16 v[4:7], v[20:23], v[36:39], 0
	v_mfma_f32_16x16x32_f16 v[8:11], v[28:31], v[36:39], 0
	v_mfma_f32_16x16x32_f16 v[12:15], v[20:23], v[52:55], 0
	v_mfma_f32_16x16x32_f16 v[16:19], v[28:31], v[52:55], 0
	v_mfma_f32_16x16x32_f16 v[36:39], v[20:23], v[116:119], 0
	v_mfma_f32_16x16x32_f16 v[52:55], v[28:31], v[116:119], 0
	v_mfma_f32_16x16x32_f16 v[20:23], v[20:23], v[124:127], 0
	v_mfma_f32_16x16x32_f16 v[28:31], v[28:31], v[124:127], 0
	v_mfma_f32_16x16x32_f16 v[116:119], v[24:27], v[44:47], v[4:7]
	v_mfma_f32_16x16x32_f16 v[124:127], v[32:35], v[44:47], v[8:11]
	v_mfma_f32_16x16x32_f16 v[184:187], v[24:27], v[120:123], v[36:39]
	v_mfma_f32_16x16x32_f16 v[120:123], v[32:35], v[120:123], v[52:55]
	v_mfma_f32_16x16x32_f16 v[188:191], v[24:27], v[128:131], v[20:23]
	v_mfma_f32_16x16x32_f16 v[128:131], v[32:35], v[128:131], v[28:31]
	s_setprio 2
	s_barrier
	v_mfma_f32_16x16x32_f16 v[176:179], v[24:27], v[60:63], v[12:15]
	v_mfma_f32_16x16x32_f16 v[180:183], v[32:35], v[60:63], v[16:19]
	s_setprio 0
	s_add_i32 s47, 0, 0x18000
	v_add_u32_e32 v4, s47, v147
	s_add_i32 s49, 0, 0x1c000
	ds_read_b128 v[192:195], v4
	ds_read_b128 v[196:199], v4 offset:1024
	ds_read_b128 v[200:203], v4 offset:2048
	ds_read_b128 v[204:207], v4 offset:3072
	v_add_u32_e32 v4, s49, v147
	ds_read_b128 v[208:211], v4
	ds_read_b128 v[212:215], v4 offset:1024
	ds_read_b128 v[216:219], v4 offset:2048
	ds_read_b128 v[220:223], v4 offset:3072
	s_mov_b32 m0, s65
	ds_read_b128 v[44:47], v231 offset:32768
	ds_read_b128 v[52:55], v231 offset:33792
	ds_read_b128 v[60:63], v231 offset:34816
	ds_read_b128 v[224:227], v231 offset:35840
	ds_read_b128 v[232:235], v231 offset:36864
	ds_read_b128 v[236:239], v231 offset:37888
	ds_read_b128 v[240:243], v231 offset:38912
	ds_read_b128 v[244:247], v231 offset:39936
	global_load_lds_dwordx4 v138, s[26:27]
	s_mov_b32 m0, s66
	s_nop 0
	global_load_lds_dwordx4 v132, s[26:27]
	s_waitcnt vmcnt(8)
	s_waitcnt lgkmcnt(0)
	s_barrier
	s_setprio 1
	s_waitcnt lgkmcnt(0)
	s_nop 0
	v_mfma_f32_16x16x32_f16 v[4:7], v[192:195], v[44:47], v[68:71]
	v_mfma_f32_16x16x32_f16 v[8:11], v[200:203], v[44:47], v[72:75]
	v_mfma_f32_16x16x32_f16 v[12:15], v[192:195], v[60:63], v[76:79]
	v_mfma_f32_16x16x32_f16 v[16:19], v[200:203], v[60:63], v[80:83]
	v_mfma_f32_16x16x32_f16 v[20:23], v[192:195], v[232:235], v[84:87]
	v_mfma_f32_16x16x32_f16 v[24:27], v[200:203], v[232:235], v[88:91]
	v_mfma_f32_16x16x32_f16 v[28:31], v[192:195], v[240:243], v[92:95]
	v_mfma_f32_16x16x32_f16 v[32:35], v[200:203], v[240:243], v[96:99]
	v_mfma_f32_16x16x32_f16 v[4:7], v[196:199], v[52:55], v[4:7]
	v_mfma_f32_16x16x32_f16 v[8:11], v[204:207], v[52:55], v[8:11]
	v_mfma_f32_16x16x32_f16 v[12:15], v[196:199], v[224:227], v[12:15]
	v_mfma_f32_16x16x32_f16 v[16:19], v[204:207], v[224:227], v[16:19]
	v_mfma_f32_16x16x32_f16 v[20:23], v[196:199], v[236:239], v[20:23]
	v_mfma_f32_16x16x32_f16 v[24:27], v[204:207], v[236:239], v[24:27]
	v_mfma_f32_16x16x32_f16 v[28:31], v[196:199], v[244:247], v[28:31]
	v_mfma_f32_16x16x32_f16 v[32:35], v[204:207], v[244:247], v[32:35]
	s_setprio 0
	s_setprio 1
	v_mfma_f32_16x16x32_f16 v[36:39], v[208:211], v[44:47], v[100:103]
	v_mfma_f32_16x16x32_f16 v[40:43], v[216:219], v[44:47], v[40:43]
	v_mfma_f32_16x16x32_f16 v[36:39], v[212:215], v[52:55], v[36:39]
	v_mfma_f32_16x16x32_f16 v[40:43], v[220:223], v[52:55], v[40:43]
	v_mfma_f32_16x16x32_f16 v[44:47], v[208:211], v[60:63], v[104:107]
	v_mfma_f32_16x16x32_f16 v[48:51], v[216:219], v[60:63], v[48:51]
	v_mfma_f32_16x16x32_f16 v[52:55], v[208:211], v[232:235], v[108:111]
	v_mfma_f32_16x16x32_f16 v[56:59], v[216:219], v[232:235], v[56:59]
	v_mfma_f32_16x16x32_f16 v[60:63], v[208:211], v[240:243], v[112:115]
	v_mfma_f32_16x16x32_f16 v[64:67], v[216:219], v[240:243], v[64:67]
	v_mfma_f32_16x16x32_f16 v[44:47], v[212:215], v[224:227], v[44:47]
	v_mfma_f32_16x16x32_f16 v[48:51], v[220:223], v[224:227], v[48:51]
	v_mfma_f32_16x16x32_f16 v[52:55], v[212:215], v[236:239], v[52:55]
	v_mfma_f32_16x16x32_f16 v[56:59], v[220:223], v[236:239], v[56:59]
	s_setprio 2
	s_barrier
	v_mfma_f32_16x16x32_f16 v[60:63], v[212:215], v[244:247], v[60:63]
	v_mfma_f32_16x16x32_f16 v[64:67], v[220:223], v[244:247], v[64:67]
	s_setprio 0
	s_add_i32 s47, s47, s62
	v_lshl_add_u64 v[68:69], v[136:137], 0, s[24:25]
	s_mov_b32 m0, s47
	ds_read_b128 v[104:107], v231 offset:49152
	ds_read_b128 v[108:111], v231 offset:50176
	ds_read_b128 v[112:115], v231 offset:51200
	ds_read_b128 v[224:227], v231 offset:52224
	ds_read_b128 v[232:235], v231 offset:53248
	ds_read_b128 v[236:239], v231 offset:54272
	ds_read_b128 v[240:243], v231 offset:55296
	ds_read_b128 v[244:247], v231 offset:56320
	global_load_lds_dwordx4 v[68:69], off
	v_lshl_add_u64 v[68:69], v[144:145], 0, s[24:25]
	s_add_i32 m0, s47, 0x2000
	s_add_i32 s47, s49, s62
	global_load_lds_dwordx4 v[68:69], off
	s_mov_b32 m0, s47
	v_lshl_add_u64 v[68:69], v[248:249], 0, s[24:25]
	global_load_lds_dwordx4 v2, s[28:29]
	s_add_i32 m0, s47, 0x2000
	s_nop 0
	global_load_lds_dwordx4 v134, s[28:29]
	s_mov_b32 m0, s69
	s_nop 0
	global_load_lds_dwordx4 v[68:69], off
	v_lshl_add_u64 v[68:69], v[250:251], 0, s[24:25]
	s_mov_b32 m0, s70
	s_nop 0
	global_load_lds_dwordx4 v[68:69], off
	s_waitcnt vmcnt(8)
	s_waitcnt lgkmcnt(0)
	s_barrier
	s_setprio 1
	s_waitcnt lgkmcnt(0)
	s_nop 0
	v_mfma_f32_16x16x32_f16 v[68:71], v[192:195], v[104:107], v[140:143]
	v_mfma_f32_16x16x32_f16 v[72:75], v[200:203], v[104:107], v[148:151]
	v_mfma_f32_16x16x32_f16 v[76:79], v[192:195], v[112:115], v[152:155]
	v_mfma_f32_16x16x32_f16 v[80:83], v[200:203], v[112:115], v[156:159]
	v_mfma_f32_16x16x32_f16 v[84:87], v[192:195], v[232:235], v[160:163]
	v_mfma_f32_16x16x32_f16 v[88:91], v[200:203], v[232:235], v[164:167]
	v_mfma_f32_16x16x32_f16 v[92:95], v[192:195], v[240:243], v[168:171]
	v_mfma_f32_16x16x32_f16 v[96:99], v[200:203], v[240:243], v[172:175]
	v_mfma_f32_16x16x32_f16 v[68:71], v[196:199], v[108:111], v[68:71]
	v_mfma_f32_16x16x32_f16 v[72:75], v[204:207], v[108:111], v[72:75]
	v_mfma_f32_16x16x32_f16 v[76:79], v[196:199], v[224:227], v[76:79]
	v_mfma_f32_16x16x32_f16 v[80:83], v[204:207], v[224:227], v[80:83]
	v_mfma_f32_16x16x32_f16 v[84:87], v[196:199], v[236:239], v[84:87]
	v_mfma_f32_16x16x32_f16 v[88:91], v[204:207], v[236:239], v[88:91]
	v_mfma_f32_16x16x32_f16 v[92:95], v[196:199], v[244:247], v[92:95]
	v_mfma_f32_16x16x32_f16 v[96:99], v[204:207], v[244:247], v[96:99]
	s_setprio 0
	s_setprio 1
	v_mfma_f32_16x16x32_f16 v[100:103], v[208:211], v[104:107], v[116:119]
	v_mfma_f32_16x16x32_f16 v[104:107], v[216:219], v[104:107], v[124:127]
	v_mfma_f32_16x16x32_f16 v[100:103], v[212:215], v[108:111], v[100:103]
	v_mfma_f32_16x16x32_f16 v[104:107], v[220:223], v[108:111], v[104:107]
	v_mfma_f32_16x16x32_f16 v[108:111], v[208:211], v[112:115], v[176:179]
	v_mfma_f32_16x16x32_f16 v[112:115], v[216:219], v[112:115], v[180:183]
	v_mfma_f32_16x16x32_f16 v[116:119], v[208:211], v[232:235], v[184:187]
	v_mfma_f32_16x16x32_f16 v[120:123], v[216:219], v[232:235], v[120:123]
	v_mfma_f32_16x16x32_f16 v[124:127], v[208:211], v[240:243], v[188:191]
	v_mfma_f32_16x16x32_f16 v[128:131], v[216:219], v[240:243], v[128:131]
	v_mfma_f32_16x16x32_f16 v[108:111], v[212:215], v[224:227], v[108:111]
	v_mfma_f32_16x16x32_f16 v[112:115], v[220:223], v[224:227], v[112:115]
	v_mfma_f32_16x16x32_f16 v[116:119], v[212:215], v[236:239], v[116:119]
	v_mfma_f32_16x16x32_f16 v[120:123], v[220:223], v[236:239], v[120:123]
	s_setprio 2
	s_barrier
	v_mfma_f32_16x16x32_f16 v[124:127], v[212:215], v[244:247], v[124:127]
	v_mfma_f32_16x16x32_f16 v[128:131], v[220:223], v[244:247], v[128:131]
	s_setprio 0
	s_add_i32 s45, s45, 2
	s_cmp_ge_i32 s45, s44
	s_cbranch_scc0 .LBB0_749
	v_mov_b32_e32 v136, v2
	s_branch .LBB0_752

.LBB0_753:
	s_add_u32 s6, s8, 0xfff80080
	s_addc_u32 s7, s9, -1
	s_add_i32 s29, 0, 0x10000
	s_cmp_eq_u32 s28, 28
	s_cselect_b32 s17, s13, s7
	s_cselect_b32 s16, s12, s6
	v_add_u32_e32 v133, s29, v147
	s_cselect_b32 s7, s15, s27
	s_cselect_b32 s6, s14, s26
	s_add_i32 s47, 0, 0x14000
	ds_read_b128 v[138:141], v133
	ds_read_b128 v[142:145], v133 offset:1024
	ds_read_b128 v[148:151], v133 offset:2048
	ds_read_b128 v[152:155], v133 offset:3072
	v_add_u32_e32 v133, s47, v147
	ds_read_b128 v[156:159], v133
	ds_read_b128 v[160:163], v133 offset:1024
	ds_read_b128 v[164:167], v133 offset:2048
	ds_read_b128 v[168:171], v133 offset:3072
	s_mov_b32 m0, s71
	v_add_u32_e32 v212, 0, v146
	ds_read_b128 v[172:175], v212
	ds_read_b128 v[176:179], v212 offset:1024
	ds_read_b128 v[180:183], v212 offset:2048
	ds_read_b128 v[184:187], v212 offset:3072
	ds_read_b128 v[188:191], v212 offset:4096
	ds_read_b128 v[192:195], v212 offset:5120
	ds_read_b128 v[196:199], v212 offset:6144
	ds_read_b128 v[200:203], v212 offset:7168
	global_load_lds_dwordx4 v2, s[8:9]
	s_mov_b32 m0, s72
	v_mov_b32_e32 v133, v3
	global_load_lds_dwordx4 v132, s[8:9]
	s_waitcnt vmcnt(8)
	s_waitcnt lgkmcnt(0)
	s_barrier
	s_setprio 1
	s_waitcnt lgkmcnt(0)
	s_nop 0
	v_mfma_f32_16x16x32_f16 v[4:7], v[138:141], v[172:175], v[4:7]
	v_mfma_f32_16x16x32_f16 v[4:7], v[142:145], v[176:179], v[4:7]
	v_mfma_f32_16x16x32_f16 v[8:11], v[152:155], v[176:179], v[8:11]
	v_mfma_f32_16x16x32_f16 v[8:11], v[148:151], v[172:175], v[8:11]
	v_mfma_f32_16x16x32_f16 v[16:19], v[148:151], v[180:183], v[16:19]
	v_mfma_f32_16x16x32_f16 v[16:19], v[152:155], v[184:187], v[16:19]
	v_mfma_f32_16x16x32_f16 v[12:15], v[142:145], v[184:187], v[12:15]
	v_mfma_f32_16x16x32_f16 v[12:15], v[138:141], v[180:183], v[12:15]
	v_mfma_f32_16x16x32_f16 v[20:23], v[138:141], v[188:191], v[20:23]
	v_mfma_f32_16x16x32_f16 v[20:23], v[142:145], v[192:195], v[20:23]
	v_mfma_f32_16x16x32_f16 v[24:27], v[152:155], v[192:195], v[24:27]
	v_mfma_f32_16x16x32_f16 v[24:27], v[148:151], v[188:191], v[24:27]
	v_mfma_f32_16x16x32_f16 v[32:35], v[148:151], v[196:199], v[32:35]
	v_mfma_f32_16x16x32_f16 v[32:35], v[152:155], v[200:203], v[32:35]
	v_mfma_f32_16x16x32_f16 v[28:31], v[142:145], v[200:203], v[28:31]
	v_mfma_f32_16x16x32_f16 v[28:31], v[138:141], v[196:199], v[28:31]
	s_setprio 0
	s_setprio 1
	v_mfma_f32_16x16x32_f16 v[36:39], v[156:159], v[172:175], v[36:39]
	v_mfma_f32_16x16x32_f16 v[36:39], v[160:163], v[176:179], v[36:39]
	v_mfma_f32_16x16x32_f16 v[40:43], v[168:171], v[176:179], v[40:43]
	v_mfma_f32_16x16x32_f16 v[40:43], v[164:167], v[172:175], v[40:43]
	v_mfma_f32_16x16x32_f16 v[48:51], v[164:167], v[180:183], v[48:51]
	v_mfma_f32_16x16x32_f16 v[48:51], v[168:171], v[184:187], v[48:51]
	v_mfma_f32_16x16x32_f16 v[44:47], v[160:163], v[184:187], v[44:47]
	v_mfma_f32_16x16x32_f16 v[44:47], v[156:159], v[180:183], v[44:47]
	v_mfma_f32_16x16x32_f16 v[52:55], v[156:159], v[188:191], v[52:55]
	v_mfma_f32_16x16x32_f16 v[52:55], v[160:163], v[192:195], v[52:55]
	v_mfma_f32_16x16x32_f16 v[56:59], v[168:171], v[192:195], v[56:59]
	v_mfma_f32_16x16x32_f16 v[56:59], v[164:167], v[188:191], v[56:59]
	v_mfma_f32_16x16x32_f16 v[64:67], v[164:167], v[196:199], v[64:67]
	v_mfma_f32_16x16x32_f16 v[64:67], v[168:171], v[200:203], v[64:67]
	s_setprio 2
	s_barrier
	v_mfma_f32_16x16x32_f16 v[60:63], v[160:163], v[200:203], v[60:63]
	v_mfma_f32_16x16x32_f16 v[60:63], v[156:159], v[196:199], v[60:63]
	s_setprio 0
	s_add_i32 s29, s29, s62
	s_mov_b32 m0, s29
	ds_read_b128 v[172:175], v212 offset:16384
	ds_read_b128 v[176:179], v212 offset:17408
	ds_read_b128 v[180:183], v212 offset:18432
	ds_read_b128 v[184:187], v212 offset:19456
	ds_read_b128 v[188:191], v212 offset:20480
	ds_read_b128 v[192:195], v212 offset:21504
	ds_read_b128 v[196:199], v212 offset:22528
	ds_read_b128 v[200:203], v212 offset:23552
	global_load_lds_dwordx4 v136, s[6:7]
	s_add_i32 m0, s29, 0x2000
	s_add_u32 s44, s6, 0x80000
	s_addc_u32 s45, s7, 0
	s_add_i32 s29, s47, s62
	global_load_lds_dwordx4 v134, s[6:7]
	s_mov_b32 m0, s29
	v_mov_b32_e32 v137, v3
	global_load_lds_dwordx4 v136, s[44:45]
	s_add_i32 m0, s29, 0x2000
	v_mov_b32_e32 v135, v3
	global_load_lds_dwordx4 v134, s[44:45]
	s_mov_b32 m0, s63
	v_lshl_add_u64 v[204:205], s[6:7], 0, v[136:137]
	global_load_lds_dwordx4 v2, s[16:17]
	s_mov_b32 m0, s64
	v_lshl_add_u64 v[206:207], s[6:7], 0, v[134:135]
	global_load_lds_dwordx4 v132, s[16:17]
	s_waitcnt vmcnt(8)
	s_waitcnt lgkmcnt(0)
	v_lshl_add_u64 v[208:209], s[16:17], 0, v[2:3]
	v_lshl_add_u64 v[210:211], s[16:17], 0, v[132:133]
	s_barrier
	s_setprio 1
	s_waitcnt lgkmcnt(0)
	s_nop 0
	v_mfma_f32_16x16x32_f16 v[68:71], v[138:141], v[172:175], v[68:71]
	v_mfma_f32_16x16x32_f16 v[68:71], v[142:145], v[176:179], v[68:71]
	v_mfma_f32_16x16x32_f16 v[72:75], v[152:155], v[176:179], v[72:75]
	v_mfma_f32_16x16x32_f16 v[72:75], v[148:151], v[172:175], v[72:75]
	v_mfma_f32_16x16x32_f16 v[80:83], v[148:151], v[180:183], v[80:83]
	v_mfma_f32_16x16x32_f16 v[80:83], v[152:155], v[184:187], v[80:83]
	v_mfma_f32_16x16x32_f16 v[76:79], v[142:145], v[184:187], v[76:79]
	v_mfma_f32_16x16x32_f16 v[76:79], v[138:141], v[180:183], v[76:79]
	v_mfma_f32_16x16x32_f16 v[84:87], v[138:141], v[188:191], v[84:87]
	v_mfma_f32_16x16x32_f16 v[84:87], v[142:145], v[192:195], v[84:87]
	v_mfma_f32_16x16x32_f16 v[88:91], v[152:155], v[192:195], v[88:91]
	v_mfma_f32_16x16x32_f16 v[88:91], v[148:151], v[188:191], v[88:91]
	v_mfma_f32_16x16x32_f16 v[96:99], v[148:151], v[196:199], v[96:99]
	v_mfma_f32_16x16x32_f16 v[96:99], v[152:155], v[200:203], v[96:99]
	v_mfma_f32_16x16x32_f16 v[92:95], v[142:145], v[200:203], v[92:95]
	v_mfma_f32_16x16x32_f16 v[92:95], v[138:141], v[196:199], v[92:95]
	s_setprio 0
	s_setprio 1
	v_mfma_f32_16x16x32_f16 v[100:103], v[156:159], v[172:175], v[100:103]
	v_mfma_f32_16x16x32_f16 v[100:103], v[160:163], v[176:179], v[100:103]
	v_mfma_f32_16x16x32_f16 v[104:107], v[168:171], v[176:179], v[104:107]
	v_mfma_f32_16x16x32_f16 v[104:107], v[164:167], v[172:175], v[104:107]
	v_mfma_f32_16x16x32_f16 v[112:115], v[164:167], v[180:183], v[112:115]
	v_mfma_f32_16x16x32_f16 v[112:115], v[168:171], v[184:187], v[112:115]
	v_mfma_f32_16x16x32_f16 v[108:111], v[160:163], v[184:187], v[108:111]
	v_mfma_f32_16x16x32_f16 v[108:111], v[156:159], v[180:183], v[108:111]
	v_mfma_f32_16x16x32_f16 v[116:119], v[156:159], v[188:191], v[116:119]
	v_mfma_f32_16x16x32_f16 v[116:119], v[160:163], v[192:195], v[116:119]
	v_mfma_f32_16x16x32_f16 v[120:123], v[168:171], v[192:195], v[120:123]
	v_mfma_f32_16x16x32_f16 v[120:123], v[164:167], v[188:191], v[120:123]
	v_mfma_f32_16x16x32_f16 v[128:131], v[164:167], v[196:199], v[128:131]
	v_mfma_f32_16x16x32_f16 v[128:131], v[168:171], v[200:203], v[128:131]
	s_setprio 2
	s_barrier
	v_mfma_f32_16x16x32_f16 v[124:127], v[160:163], v[200:203], v[124:127]
	v_mfma_f32_16x16x32_f16 v[124:127], v[156:159], v[196:199], v[124:127]
	s_setprio 0
	s_add_i32 s29, 0, 0x18000
	v_add_u32_e32 v135, s29, v147
	s_add_i32 s44, 0, 0x1c000
	ds_read_b128 v[138:141], v135
	ds_read_b128 v[142:145], v135 offset:1024
	ds_read_b128 v[148:151], v135 offset:2048
	ds_read_b128 v[152:155], v135 offset:3072
	v_add_u32_e32 v135, s44, v147
	ds_read_b128 v[156:159], v135
	ds_read_b128 v[160:163], v135 offset:1024
	ds_read_b128 v[164:167], v135 offset:2048
	ds_read_b128 v[168:171], v135 offset:3072
	s_add_u32 s16, s16, 0x80000
	s_addc_u32 s17, s17, 0
	s_mov_b32 m0, s65
	ds_read_b128 v[172:175], v212 offset:32768
	ds_read_b128 v[176:179], v212 offset:33792
	ds_read_b128 v[180:183], v212 offset:34816
	ds_read_b128 v[184:187], v212 offset:35840
	ds_read_b128 v[188:191], v212 offset:36864
	ds_read_b128 v[192:195], v212 offset:37888
	ds_read_b128 v[196:199], v212 offset:38912
	ds_read_b128 v[200:203], v212 offset:39936
	global_load_lds_dwordx4 v2, s[16:17]
	s_mov_b32 m0, s66
	s_nop 0
	global_load_lds_dwordx4 v132, s[16:17]
	s_waitcnt vmcnt(8)
	s_waitcnt lgkmcnt(0)
	s_barrier
	s_setprio 1
	s_waitcnt lgkmcnt(0)
	s_nop 0
	v_mfma_f32_16x16x32_f16 v[4:7], v[138:141], v[172:175], v[4:7]
	v_mfma_f32_16x16x32_f16 v[4:7], v[142:145], v[176:179], v[4:7]
	v_mfma_f32_16x16x32_f16 v[8:11], v[152:155], v[176:179], v[8:11]
	v_mfma_f32_16x16x32_f16 v[8:11], v[148:151], v[172:175], v[8:11]
	v_mfma_f32_16x16x32_f16 v[16:19], v[148:151], v[180:183], v[16:19]
	v_mfma_f32_16x16x32_f16 v[16:19], v[152:155], v[184:187], v[16:19]
	v_mfma_f32_16x16x32_f16 v[12:15], v[142:145], v[184:187], v[12:15]
	v_mfma_f32_16x16x32_f16 v[12:15], v[138:141], v[180:183], v[12:15]
	v_mfma_f32_16x16x32_f16 v[20:23], v[138:141], v[188:191], v[20:23]
	v_mfma_f32_16x16x32_f16 v[20:23], v[142:145], v[192:195], v[20:23]
	v_mfma_f32_16x16x32_f16 v[24:27], v[152:155], v[192:195], v[24:27]
	v_mfma_f32_16x16x32_f16 v[24:27], v[148:151], v[188:191], v[24:27]
	v_mfma_f32_16x16x32_f16 v[32:35], v[148:151], v[196:199], v[32:35]
	v_mfma_f32_16x16x32_f16 v[32:35], v[152:155], v[200:203], v[32:35]
	v_mfma_f32_16x16x32_f16 v[28:31], v[142:145], v[200:203], v[28:31]
	v_mfma_f32_16x16x32_f16 v[28:31], v[138:141], v[196:199], v[28:31]
	s_setprio 0
	s_setprio 1
	v_mfma_f32_16x16x32_f16 v[36:39], v[156:159], v[172:175], v[36:39]
	v_mfma_f32_16x16x32_f16 v[36:39], v[160:163], v[176:179], v[36:39]
	v_mfma_f32_16x16x32_f16 v[40:43], v[168:171], v[176:179], v[40:43]
	v_mfma_f32_16x16x32_f16 v[40:43], v[164:167], v[172:175], v[40:43]
	v_mfma_f32_16x16x32_f16 v[48:51], v[164:167], v[180:183], v[48:51]
	v_mfma_f32_16x16x32_f16 v[48:51], v[168:171], v[184:187], v[48:51]
	v_mfma_f32_16x16x32_f16 v[44:47], v[160:163], v[184:187], v[44:47]
	v_mfma_f32_16x16x32_f16 v[44:47], v[156:159], v[180:183], v[44:47]
	v_mfma_f32_16x16x32_f16 v[52:55], v[156:159], v[188:191], v[52:55]
	v_mfma_f32_16x16x32_f16 v[52:55], v[160:163], v[192:195], v[52:55]
	v_mfma_f32_16x16x32_f16 v[56:59], v[168:171], v[192:195], v[56:59]
	v_mfma_f32_16x16x32_f16 v[56:59], v[164:167], v[188:191], v[56:59]
	v_mfma_f32_16x16x32_f16 v[64:67], v[164:167], v[196:199], v[64:67]
	v_mfma_f32_16x16x32_f16 v[64:67], v[168:171], v[200:203], v[64:67]
	s_setprio 2
	s_barrier
	v_mfma_f32_16x16x32_f16 v[60:63], v[160:163], v[200:203], v[60:63]
	v_mfma_f32_16x16x32_f16 v[60:63], v[156:159], v[196:199], v[60:63]
	s_setprio 0
	s_add_i32 s16, s29, s62
	v_lshl_add_u64 v[204:205], v[204:205], 0, s[86:87]
	s_mov_b32 m0, s16
	ds_read_b128 v[172:175], v212 offset:49152
	ds_read_b128 v[176:179], v212 offset:50176
	ds_read_b128 v[180:183], v212 offset:51200
	ds_read_b128 v[184:187], v212 offset:52224
	ds_read_b128 v[188:191], v212 offset:53248
	ds_read_b128 v[192:195], v212 offset:54272
	ds_read_b128 v[196:199], v212 offset:55296
	ds_read_b128 v[200:203], v212 offset:56320
	global_load_lds_dwordx4 v[204:205], off
	s_add_i32 m0, s16, 0x2000
	s_add_u32 s6, s6, 0x80080
	v_lshl_add_u64 v[204:205], v[206:207], 0, s[86:87]
	s_addc_u32 s7, s7, 0
	s_add_i32 s16, s44, s62
	global_load_lds_dwordx4 v[204:205], off
	s_mov_b32 m0, s16
	v_lshl_add_u64 v[204:205], v[208:209], 0, s[86:87]
	global_load_lds_dwordx4 v136, s[6:7]
	s_add_i32 m0, s16, 0x2000
	s_nop 0
	global_load_lds_dwordx4 v134, s[6:7]
	s_mov_b32 m0, s69
	s_nop 0
	global_load_lds_dwordx4 v[204:205], off
	v_lshl_add_u64 v[204:205], v[210:211], 0, s[86:87]
	s_mov_b32 m0, s70
	s_nop 0
	global_load_lds_dwordx4 v[204:205], off
	s_waitcnt vmcnt(8)
	s_waitcnt lgkmcnt(0)
	s_barrier
	s_setprio 1
	s_waitcnt lgkmcnt(0)
	s_nop 0
	v_mfma_f32_16x16x32_f16 v[68:71], v[138:141], v[172:175], v[68:71]
	v_mfma_f32_16x16x32_f16 v[68:71], v[142:145], v[176:179], v[68:71]
	v_mfma_f32_16x16x32_f16 v[72:75], v[152:155], v[176:179], v[72:75]
	v_mfma_f32_16x16x32_f16 v[72:75], v[148:151], v[172:175], v[72:75]
	v_mfma_f32_16x16x32_f16 v[80:83], v[148:151], v[180:183], v[80:83]
	v_mfma_f32_16x16x32_f16 v[80:83], v[152:155], v[184:187], v[80:83]
	v_mfma_f32_16x16x32_f16 v[76:79], v[142:145], v[184:187], v[76:79]
	v_mfma_f32_16x16x32_f16 v[76:79], v[138:141], v[180:183], v[76:79]
	v_mfma_f32_16x16x32_f16 v[84:87], v[138:141], v[188:191], v[84:87]
	v_mfma_f32_16x16x32_f16 v[84:87], v[142:145], v[192:195], v[84:87]
	v_mfma_f32_16x16x32_f16 v[88:91], v[152:155], v[192:195], v[88:91]
	v_mfma_f32_16x16x32_f16 v[88:91], v[148:151], v[188:191], v[88:91]
	v_mfma_f32_16x16x32_f16 v[96:99], v[148:151], v[196:199], v[96:99]
	v_mfma_f32_16x16x32_f16 v[96:99], v[152:155], v[200:203], v[96:99]
	v_mfma_f32_16x16x32_f16 v[92:95], v[142:145], v[200:203], v[92:95]
	v_mfma_f32_16x16x32_f16 v[92:95], v[138:141], v[196:199], v[92:95]
	s_setprio 0
	s_setprio 1
	v_mfma_f32_16x16x32_f16 v[100:103], v[156:159], v[172:175], v[100:103]
	v_mfma_f32_16x16x32_f16 v[100:103], v[160:163], v[176:179], v[100:103]
	v_mfma_f32_16x16x32_f16 v[104:107], v[168:171], v[176:179], v[104:107]
	v_mfma_f32_16x16x32_f16 v[104:107], v[164:167], v[172:175], v[104:107]
	v_mfma_f32_16x16x32_f16 v[112:115], v[164:167], v[180:183], v[112:115]
	v_mfma_f32_16x16x32_f16 v[112:115], v[168:171], v[184:187], v[112:115]
	v_mfma_f32_16x16x32_f16 v[108:111], v[160:163], v[184:187], v[108:111]
	v_mfma_f32_16x16x32_f16 v[108:111], v[156:159], v[180:183], v[108:111]
	v_mfma_f32_16x16x32_f16 v[116:119], v[156:159], v[188:191], v[116:119]
	v_mfma_f32_16x16x32_f16 v[116:119], v[160:163], v[192:195], v[116:119]
	v_mfma_f32_16x16x32_f16 v[120:123], v[168:171], v[192:195], v[120:123]
	v_mfma_f32_16x16x32_f16 v[120:123], v[164:167], v[188:191], v[120:123]
	v_mfma_f32_16x16x32_f16 v[128:131], v[164:167], v[196:199], v[128:131]
	v_mfma_f32_16x16x32_f16 v[128:131], v[168:171], v[200:203], v[128:131]
	s_setprio 2
	s_barrier
	v_mfma_f32_16x16x32_f16 v[124:127], v[160:163], v[200:203], v[124:127]
	v_mfma_f32_16x16x32_f16 v[124:127], v[156:159], v[196:199], v[124:127]
	s_setprio 0
	s_add_i32 s28, s28, 2
	s_add_u32 s8, s8, 0x100
	s_addc_u32 s9, s9, 0
	s_add_u32 s26, s26, 0x100
	s_addc_u32 s27, s27, 0
	s_cmp_gt_u32 s28, 29
	s_cbranch_scc0 .LBB0_753
	s_and_b64 vcc, exec, s[52:53]
	s_cbranch_vccz .LBB0_756
	s_barrier

.LBB0_1175:
	s_add_i32 s61, 0, 0x10000
	s_add_i32 s79, 0, 0x14000
	v_add_u32_e32 v16, s61, v209
	v_add_u32_e32 v32, s79, v209
	ds_read_b128 v[4:7], v16
	ds_read_b128 v[8:11], v16 offset:1024
	ds_read_b128 v[12:15], v16 offset:2048
	ds_read_b128 v[16:19], v16 offset:3072
	ds_read_b128 v[20:23], v32
	ds_read_b128 v[24:27], v32 offset:1024
	ds_read_b128 v[28:31], v32 offset:2048
	ds_read_b128 v[32:35], v32 offset:3072
	v_add_u32_e32 v231, 0, v208
	ds_read_b128 v[36:39], v231
	ds_read_b128 v[40:43], v231 offset:1024
	ds_read_b128 v[44:47], v231 offset:2048
	ds_read_b128 v[48:51], v231 offset:3072
	ds_read_b128 v[52:55], v231 offset:4096
	ds_read_b128 v[56:59], v231 offset:5120
	ds_read_b128 v[60:63], v231 offset:6144
	ds_read_b128 v[64:67], v231 offset:7168
	s_waitcnt vmcnt(8)
	s_waitcnt lgkmcnt(0)
	s_barrier
	s_setprio 1
	s_waitcnt lgkmcnt(0)
	s_nop 0
	v_mfma_f32_16x16x32_bf16 v[68:71], v[4:7], v[36:39], 0
	v_mfma_f32_16x16x32_bf16 v[68:71], v[8:11], v[40:43], v[68:71]
	v_mfma_f32_16x16x32_bf16 v[72:75], v[12:15], v[36:39], 0
	v_mfma_f32_16x16x32_bf16 v[72:75], v[16:19], v[40:43], v[72:75]
	v_mfma_f32_16x16x32_bf16 v[80:83], v[12:15], v[44:47], 0
	v_mfma_f32_16x16x32_bf16 v[80:83], v[16:19], v[48:51], v[80:83]
	v_mfma_f32_16x16x32_bf16 v[76:79], v[4:7], v[44:47], 0
	v_mfma_f32_16x16x32_bf16 v[76:79], v[8:11], v[48:51], v[76:79]
	v_mfma_f32_16x16x32_bf16 v[84:87], v[4:7], v[52:55], 0
	v_mfma_f32_16x16x32_bf16 v[84:87], v[8:11], v[56:59], v[84:87]
	v_mfma_f32_16x16x32_bf16 v[88:91], v[12:15], v[52:55], 0
	v_mfma_f32_16x16x32_bf16 v[88:91], v[16:19], v[56:59], v[88:91]
	v_mfma_f32_16x16x32_bf16 v[96:99], v[12:15], v[60:63], 0
	v_mfma_f32_16x16x32_bf16 v[96:99], v[16:19], v[64:67], v[96:99]
	v_mfma_f32_16x16x32_bf16 v[92:95], v[4:7], v[60:63], 0
	v_mfma_f32_16x16x32_bf16 v[92:95], v[8:11], v[64:67], v[92:95]
	s_setprio 0
	s_setprio 1
	v_mfma_f32_16x16x32_bf16 v[100:103], v[20:23], v[36:39], 0
	v_mfma_f32_16x16x32_bf16 v[36:39], v[28:31], v[36:39], 0
	v_mfma_f32_16x16x32_bf16 v[104:107], v[20:23], v[44:47], 0
	v_mfma_f32_16x16x32_bf16 v[44:47], v[28:31], v[44:47], 0
	v_mfma_f32_16x16x32_bf16 v[108:111], v[20:23], v[52:55], 0
	v_mfma_f32_16x16x32_bf16 v[52:55], v[28:31], v[52:55], 0
	v_mfma_f32_16x16x32_bf16 v[112:115], v[20:23], v[60:63], 0
	v_mfma_f32_16x16x32_bf16 v[60:63], v[28:31], v[60:63], 0
	v_mfma_f32_16x16x32_bf16 v[100:103], v[24:27], v[40:43], v[100:103]
	v_mfma_f32_16x16x32_bf16 v[40:43], v[32:35], v[40:43], v[36:39]
	v_mfma_f32_16x16x32_bf16 v[104:107], v[24:27], v[48:51], v[104:107]
	v_mfma_f32_16x16x32_bf16 v[48:51], v[32:35], v[48:51], v[44:47]
	v_mfma_f32_16x16x32_bf16 v[108:111], v[24:27], v[56:59], v[108:111]
	v_mfma_f32_16x16x32_bf16 v[56:59], v[32:35], v[56:59], v[52:55]
	s_setprio 2
	s_barrier
	v_mfma_f32_16x16x32_bf16 v[112:115], v[24:27], v[64:67], v[112:115]
	v_mfma_f32_16x16x32_bf16 v[64:67], v[32:35], v[64:67], v[60:63]
	s_setprio 0
	v_lshl_add_u64 v[186:187], s[12:13], 0, v[2:3]
	s_add_i32 s61, s61, s36
	v_mov_b32_e32 v191, v3
	v_lshl_add_u64 v[134:135], v[186:187], 0, s[74:75]
	s_mov_b32 m0, s61
	v_lshl_add_u64 v[226:227], s[12:13], 0, v[190:191]
	ds_read_b128 v[36:39], v231 offset:16384
	ds_read_b128 v[44:47], v231 offset:17408
	ds_read_b128 v[52:55], v231 offset:18432
	ds_read_b128 v[60:63], v231 offset:19456
	ds_read_b128 v[116:119], v231 offset:20480
	ds_read_b128 v[120:123], v231 offset:21504
	ds_read_b128 v[124:127], v231 offset:22528
	ds_read_b128 v[128:131], v231 offset:23552
	global_load_lds_dwordx4 v[134:135], off
	v_lshl_add_u64 v[134:135], v[226:227], 0, s[74:75]
	s_add_i32 m0, s61, 0x2000
	s_add_i32 s61, s79, s36
	global_load_lds_dwordx4 v[134:135], off
	s_mov_b32 m0, s61
	v_mov_b32_e32 v133, v3
	global_load_lds_dwordx4 v2, s[16:17]
	s_add_i32 m0, s61, 0x2000
	v_lshl_add_u64 v[248:249], s[6:7], 0, v[132:133]
	v_mov_b32_e32 v189, v3
	global_load_lds_dwordx4 v190, s[16:17]
	v_lshl_add_u64 v[134:135], v[248:249], 0, s[74:75]
	s_mov_b32 m0, s37
	v_lshl_add_u64 v[250:251], s[6:7], 0, v[188:189]
	global_load_lds_dwordx4 v[134:135], off
	v_lshl_add_u64 v[134:135], v[250:251], 0, s[74:75]
	s_mov_b32 m0, s66
	s_nop 0
	global_load_lds_dwordx4 v[134:135], off
	s_waitcnt vmcnt(8)
	s_waitcnt lgkmcnt(0)
	s_barrier
	s_setprio 1
	s_waitcnt lgkmcnt(0)
	s_nop 0
	v_mfma_f32_16x16x32_bf16 v[134:137], v[4:7], v[36:39], 0
	v_mfma_f32_16x16x32_bf16 v[138:141], v[12:15], v[36:39], 0
	v_mfma_f32_16x16x32_bf16 v[142:145], v[4:7], v[52:55], 0
	v_mfma_f32_16x16x32_bf16 v[146:149], v[12:15], v[52:55], 0
	v_mfma_f32_16x16x32_bf16 v[150:153], v[4:7], v[116:119], 0
	v_mfma_f32_16x16x32_bf16 v[154:157], v[12:15], v[116:119], 0
	v_mfma_f32_16x16x32_bf16 v[4:7], v[4:7], v[124:127], 0
	v_mfma_f32_16x16x32_bf16 v[12:15], v[12:15], v[124:127], 0
	v_mfma_f32_16x16x32_bf16 v[134:137], v[8:11], v[44:47], v[134:137]
	v_mfma_f32_16x16x32_bf16 v[138:141], v[16:19], v[44:47], v[138:141]
	v_mfma_f32_16x16x32_bf16 v[142:145], v[8:11], v[60:63], v[142:145]
	v_mfma_f32_16x16x32_bf16 v[146:149], v[16:19], v[60:63], v[146:149]
	v_mfma_f32_16x16x32_bf16 v[150:153], v[8:11], v[120:123], v[150:153]
	v_mfma_f32_16x16x32_bf16 v[154:157], v[16:19], v[120:123], v[154:157]
	v_mfma_f32_16x16x32_bf16 v[158:161], v[8:11], v[128:131], v[4:7]
	v_mfma_f32_16x16x32_bf16 v[162:165], v[16:19], v[128:131], v[12:15]
	s_setprio 0
	s_setprio 1
	v_mfma_f32_16x16x32_bf16 v[4:7], v[20:23], v[36:39], 0
	v_mfma_f32_16x16x32_bf16 v[8:11], v[28:31], v[36:39], 0
	v_mfma_f32_16x16x32_bf16 v[12:15], v[20:23], v[52:55], 0
	v_mfma_f32_16x16x32_bf16 v[16:19], v[28:31], v[52:55], 0
	v_mfma_f32_16x16x32_bf16 v[36:39], v[20:23], v[116:119], 0
	v_mfma_f32_16x16x32_bf16 v[52:55], v[28:31], v[116:119], 0
	v_mfma_f32_16x16x32_bf16 v[20:23], v[20:23], v[124:127], 0
	v_mfma_f32_16x16x32_bf16 v[28:31], v[28:31], v[124:127], 0
	v_mfma_f32_16x16x32_bf16 v[116:119], v[24:27], v[44:47], v[4:7]
	v_mfma_f32_16x16x32_bf16 v[124:127], v[32:35], v[44:47], v[8:11]
	v_mfma_f32_16x16x32_bf16 v[174:177], v[24:27], v[120:123], v[36:39]
	v_mfma_f32_16x16x32_bf16 v[120:123], v[32:35], v[120:123], v[52:55]
	v_mfma_f32_16x16x32_bf16 v[178:181], v[24:27], v[128:131], v[20:23]
	v_mfma_f32_16x16x32_bf16 v[128:131], v[32:35], v[128:131], v[28:31]
	s_setprio 2
	s_barrier
	v_mfma_f32_16x16x32_bf16 v[166:169], v[24:27], v[60:63], v[12:15]
	v_mfma_f32_16x16x32_bf16 v[170:173], v[32:35], v[60:63], v[16:19]
	s_setprio 0
	s_add_i32 s61, 0, 0x18000
	v_add_u32_e32 v4, s61, v209
	s_add_i32 s79, 0, 0x1c000
	ds_read_b128 v[182:185], v4
	ds_read_b128 v[192:195], v4 offset:1024
	ds_read_b128 v[196:199], v4 offset:2048
	ds_read_b128 v[200:203], v4 offset:3072
	v_add_u32_e32 v4, s79, v209
	ds_read_b128 v[204:207], v4
	ds_read_b128 v[210:213], v4 offset:1024
	ds_read_b128 v[214:217], v4 offset:2048
	ds_read_b128 v[218:221], v4 offset:3072
	s_mov_b32 m0, s67
	ds_read_b128 v[44:47], v231 offset:32768
	ds_read_b128 v[52:55], v231 offset:33792
	ds_read_b128 v[60:63], v231 offset:34816
	ds_read_b128 v[222:225], v231 offset:35840
	ds_read_b128 v[232:235], v231 offset:36864
	ds_read_b128 v[236:239], v231 offset:37888
	ds_read_b128 v[240:243], v231 offset:38912
	ds_read_b128 v[244:247], v231 offset:39936
	global_load_lds_dwordx4 v132, s[26:27]
	s_mov_b32 m0, s68
	s_nop 0
	global_load_lds_dwordx4 v188, s[26:27]
	s_waitcnt vmcnt(8)
	s_waitcnt lgkmcnt(0)
	s_barrier
	s_setprio 1
	s_waitcnt lgkmcnt(0)
	s_nop 0
	v_mfma_f32_16x16x32_bf16 v[4:7], v[182:185], v[44:47], v[68:71]
	v_mfma_f32_16x16x32_bf16 v[8:11], v[196:199], v[44:47], v[72:75]
	v_mfma_f32_16x16x32_bf16 v[12:15], v[182:185], v[60:63], v[76:79]
	v_mfma_f32_16x16x32_bf16 v[16:19], v[196:199], v[60:63], v[80:83]
	v_mfma_f32_16x16x32_bf16 v[20:23], v[182:185], v[232:235], v[84:87]
	v_mfma_f32_16x16x32_bf16 v[24:27], v[196:199], v[232:235], v[88:91]
	v_mfma_f32_16x16x32_bf16 v[28:31], v[182:185], v[240:243], v[92:95]
	v_mfma_f32_16x16x32_bf16 v[32:35], v[196:199], v[240:243], v[96:99]
	v_mfma_f32_16x16x32_bf16 v[4:7], v[192:195], v[52:55], v[4:7]
	v_mfma_f32_16x16x32_bf16 v[8:11], v[200:203], v[52:55], v[8:11]
	v_mfma_f32_16x16x32_bf16 v[12:15], v[192:195], v[222:225], v[12:15]
	v_mfma_f32_16x16x32_bf16 v[16:19], v[200:203], v[222:225], v[16:19]
	v_mfma_f32_16x16x32_bf16 v[20:23], v[192:195], v[236:239], v[20:23]
	v_mfma_f32_16x16x32_bf16 v[24:27], v[200:203], v[236:239], v[24:27]
	v_mfma_f32_16x16x32_bf16 v[28:31], v[192:195], v[244:247], v[28:31]
	v_mfma_f32_16x16x32_bf16 v[32:35], v[200:203], v[244:247], v[32:35]
	s_setprio 0
	s_setprio 1
	v_mfma_f32_16x16x32_bf16 v[36:39], v[204:207], v[44:47], v[100:103]
	v_mfma_f32_16x16x32_bf16 v[40:43], v[214:217], v[44:47], v[40:43]
	v_mfma_f32_16x16x32_bf16 v[36:39], v[210:213], v[52:55], v[36:39]
	v_mfma_f32_16x16x32_bf16 v[40:43], v[218:221], v[52:55], v[40:43]
	v_mfma_f32_16x16x32_bf16 v[44:47], v[204:207], v[60:63], v[104:107]
	v_mfma_f32_16x16x32_bf16 v[48:51], v[214:217], v[60:63], v[48:51]
	v_mfma_f32_16x16x32_bf16 v[52:55], v[204:207], v[232:235], v[108:111]
	v_mfma_f32_16x16x32_bf16 v[56:59], v[214:217], v[232:235], v[56:59]
	v_mfma_f32_16x16x32_bf16 v[60:63], v[204:207], v[240:243], v[112:115]
	v_mfma_f32_16x16x32_bf16 v[64:67], v[214:217], v[240:243], v[64:67]
	v_mfma_f32_16x16x32_bf16 v[44:47], v[210:213], v[222:225], v[44:47]
	v_mfma_f32_16x16x32_bf16 v[48:51], v[218:221], v[222:225], v[48:51]
	v_mfma_f32_16x16x32_bf16 v[52:55], v[210:213], v[236:239], v[52:55]
	v_mfma_f32_16x16x32_bf16 v[56:59], v[218:221], v[236:239], v[56:59]
	s_setprio 2
	s_barrier
	v_mfma_f32_16x16x32_bf16 v[60:63], v[210:213], v[244:247], v[60:63]
	v_mfma_f32_16x16x32_bf16 v[64:67], v[218:221], v[244:247], v[64:67]
	s_setprio 0
	s_add_i32 s61, s61, s36
	v_lshl_add_u64 v[68:69], v[186:187], 0, s[24:25]
	s_mov_b32 m0, s61
	ds_read_b128 v[104:107], v231 offset:49152
	ds_read_b128 v[108:111], v231 offset:50176
	ds_read_b128 v[112:115], v231 offset:51200
	ds_read_b128 v[222:225], v231 offset:52224
	ds_read_b128 v[232:235], v231 offset:53248
	ds_read_b128 v[236:239], v231 offset:54272
	ds_read_b128 v[240:243], v231 offset:55296
	ds_read_b128 v[244:247], v231 offset:56320
	global_load_lds_dwordx4 v[68:69], off
	v_lshl_add_u64 v[68:69], v[226:227], 0, s[24:25]
	s_add_i32 m0, s61, 0x2000
	s_add_i32 s61, s79, s36
	global_load_lds_dwordx4 v[68:69], off
	s_mov_b32 m0, s61
	v_lshl_add_u64 v[68:69], v[248:249], 0, s[24:25]
	global_load_lds_dwordx4 v2, s[28:29]
	s_add_i32 m0, s61, 0x2000
	s_nop 0
	global_load_lds_dwordx4 v190, s[28:29]
	s_mov_b32 m0, s71
	s_nop 0
	global_load_lds_dwordx4 v[68:69], off
	v_lshl_add_u64 v[68:69], v[250:251], 0, s[24:25]
	s_mov_b32 m0, s72
	s_nop 0
	global_load_lds_dwordx4 v[68:69], off
	s_waitcnt vmcnt(8)
	s_waitcnt lgkmcnt(0)
	s_barrier
	s_setprio 1
	s_waitcnt lgkmcnt(0)
	s_nop 0
	v_mfma_f32_16x16x32_bf16 v[68:71], v[182:185], v[104:107], v[134:137]
	v_mfma_f32_16x16x32_bf16 v[72:75], v[196:199], v[104:107], v[138:141]
	v_mfma_f32_16x16x32_bf16 v[76:79], v[182:185], v[112:115], v[142:145]
	v_mfma_f32_16x16x32_bf16 v[80:83], v[196:199], v[112:115], v[146:149]
	v_mfma_f32_16x16x32_bf16 v[84:87], v[182:185], v[232:235], v[150:153]
	v_mfma_f32_16x16x32_bf16 v[88:91], v[196:199], v[232:235], v[154:157]
	v_mfma_f32_16x16x32_bf16 v[92:95], v[182:185], v[240:243], v[158:161]
	v_mfma_f32_16x16x32_bf16 v[96:99], v[196:199], v[240:243], v[162:165]
	v_mfma_f32_16x16x32_bf16 v[68:71], v[192:195], v[108:111], v[68:71]
	v_mfma_f32_16x16x32_bf16 v[72:75], v[200:203], v[108:111], v[72:75]
	v_mfma_f32_16x16x32_bf16 v[76:79], v[192:195], v[222:225], v[76:79]
	v_mfma_f32_16x16x32_bf16 v[80:83], v[200:203], v[222:225], v[80:83]
	v_mfma_f32_16x16x32_bf16 v[84:87], v[192:195], v[236:239], v[84:87]
	v_mfma_f32_16x16x32_bf16 v[88:91], v[200:203], v[236:239], v[88:91]
	v_mfma_f32_16x16x32_bf16 v[92:95], v[192:195], v[244:247], v[92:95]
	v_mfma_f32_16x16x32_bf16 v[96:99], v[200:203], v[244:247], v[96:99]
	s_setprio 0
	s_setprio 1
	v_mfma_f32_16x16x32_bf16 v[100:103], v[204:207], v[104:107], v[116:119]
	v_mfma_f32_16x16x32_bf16 v[104:107], v[214:217], v[104:107], v[124:127]
	v_mfma_f32_16x16x32_bf16 v[100:103], v[210:213], v[108:111], v[100:103]
	v_mfma_f32_16x16x32_bf16 v[104:107], v[218:221], v[108:111], v[104:107]
	v_mfma_f32_16x16x32_bf16 v[108:111], v[204:207], v[112:115], v[166:169]
	v_mfma_f32_16x16x32_bf16 v[112:115], v[214:217], v[112:115], v[170:173]
	v_mfma_f32_16x16x32_bf16 v[116:119], v[204:207], v[232:235], v[174:177]
	v_mfma_f32_16x16x32_bf16 v[120:123], v[214:217], v[232:235], v[120:123]
	v_mfma_f32_16x16x32_bf16 v[124:127], v[204:207], v[240:243], v[178:181]
	v_mfma_f32_16x16x32_bf16 v[128:131], v[214:217], v[240:243], v[128:131]
	v_mfma_f32_16x16x32_bf16 v[108:111], v[210:213], v[222:225], v[108:111]
	v_mfma_f32_16x16x32_bf16 v[112:115], v[218:221], v[222:225], v[112:115]
	v_mfma_f32_16x16x32_bf16 v[116:119], v[210:213], v[236:239], v[116:119]
	v_mfma_f32_16x16x32_bf16 v[120:123], v[218:221], v[236:239], v[120:123]
	s_setprio 2
	s_barrier
	v_mfma_f32_16x16x32_bf16 v[124:127], v[210:213], v[244:247], v[124:127]
	v_mfma_f32_16x16x32_bf16 v[128:131], v[218:221], v[244:247], v[128:131]
	s_setprio 0
	s_add_i32 s43, s43, 2
	s_cmp_ge_i32 s43, s42
	s_cbranch_scc0 .LBB0_1175
.LBB0_1176:
	s_add_i32 s12, 0, 0x10000
	s_add_i32 s13, 0, 0x14000
	v_mov_b32_e32 v192, v2
	v_mov_b32_e32 v2, v132
	v_add_u32_e32 v144, s12, v209
	v_add_u32_e32 v160, s13, v209
	ds_read_b128 v[132:135], v144
	ds_read_b128 v[136:139], v144 offset:1024
	ds_read_b128 v[140:143], v144 offset:2048
	ds_read_b128 v[144:147], v144 offset:3072
	ds_read_b128 v[148:151], v160
	ds_read_b128 v[152:155], v160 offset:1024
	ds_read_b128 v[156:159], v160 offset:2048
	ds_read_b128 v[160:163], v160 offset:3072
	s_add_u32 s6, s6, 0x80180
	s_mov_b32 m0, s73
	v_add_u32_e32 v212, 0, v208
	s_addc_u32 s7, s7, 0
	ds_read_b128 v[164:167], v212
	ds_read_b128 v[168:171], v212 offset:1024
	ds_read_b128 v[172:175], v212 offset:2048
	ds_read_b128 v[176:179], v212 offset:3072
	ds_read_b128 v[180:183], v212 offset:4096
	ds_read_b128 v[184:187], v212 offset:5120
	ds_read_b128 v[194:197], v212 offset:6144
	ds_read_b128 v[198:201], v212 offset:7168
	global_load_lds_dwordx4 v2, s[6:7]
	s_mov_b32 m0, s76
	v_mov_b32_e32 v189, v3
	global_load_lds_dwordx4 v188, s[6:7]
	s_waitcnt vmcnt(8)
	s_waitcnt lgkmcnt(0)
	s_barrier
	s_setprio 1
	s_waitcnt lgkmcnt(0)
	s_nop 0
	v_mfma_f32_16x16x32_bf16 v[4:7], v[132:135], v[164:167], v[4:7]
	v_mfma_f32_16x16x32_bf16 v[4:7], v[136:139], v[168:171], v[4:7]
	v_mfma_f32_16x16x32_bf16 v[8:11], v[144:147], v[168:171], v[8:11]
	v_mfma_f32_16x16x32_bf16 v[8:11], v[140:143], v[164:167], v[8:11]
	v_mfma_f32_16x16x32_bf16 v[16:19], v[140:143], v[172:175], v[16:19]
	v_mfma_f32_16x16x32_bf16 v[16:19], v[144:147], v[176:179], v[16:19]
	v_mfma_f32_16x16x32_bf16 v[12:15], v[136:139], v[176:179], v[12:15]
	v_mfma_f32_16x16x32_bf16 v[12:15], v[132:135], v[172:175], v[12:15]
	v_mfma_f32_16x16x32_bf16 v[20:23], v[132:135], v[180:183], v[20:23]
	v_mfma_f32_16x16x32_bf16 v[20:23], v[136:139], v[184:187], v[20:23]
	v_mfma_f32_16x16x32_bf16 v[24:27], v[144:147], v[184:187], v[24:27]
	v_mfma_f32_16x16x32_bf16 v[24:27], v[140:143], v[180:183], v[24:27]
	v_mfma_f32_16x16x32_bf16 v[32:35], v[140:143], v[194:197], v[32:35]
	v_mfma_f32_16x16x32_bf16 v[32:35], v[144:147], v[198:201], v[32:35]
	v_mfma_f32_16x16x32_bf16 v[28:31], v[136:139], v[198:201], v[28:31]
	v_mfma_f32_16x16x32_bf16 v[28:31], v[132:135], v[194:197], v[28:31]
	s_setprio 0
	s_setprio 1
	v_mfma_f32_16x16x32_bf16 v[36:39], v[148:151], v[164:167], v[36:39]
	v_mfma_f32_16x16x32_bf16 v[36:39], v[152:155], v[168:171], v[36:39]
	v_mfma_f32_16x16x32_bf16 v[40:43], v[160:163], v[168:171], v[40:43]
	v_mfma_f32_16x16x32_bf16 v[40:43], v[156:159], v[164:167], v[40:43]
	v_mfma_f32_16x16x32_bf16 v[48:51], v[156:159], v[172:175], v[48:51]
	v_mfma_f32_16x16x32_bf16 v[48:51], v[160:163], v[176:179], v[48:51]
	v_mfma_f32_16x16x32_bf16 v[44:47], v[152:155], v[176:179], v[44:47]
	v_mfma_f32_16x16x32_bf16 v[44:47], v[148:151], v[172:175], v[44:47]
	v_mfma_f32_16x16x32_bf16 v[52:55], v[148:151], v[180:183], v[52:55]
	v_mfma_f32_16x16x32_bf16 v[52:55], v[152:155], v[184:187], v[52:55]
	v_mfma_f32_16x16x32_bf16 v[56:59], v[160:163], v[184:187], v[56:59]
	v_mfma_f32_16x16x32_bf16 v[56:59], v[156:159], v[180:183], v[56:59]
	v_mfma_f32_16x16x32_bf16 v[64:67], v[156:159], v[194:197], v[64:67]
	v_mfma_f32_16x16x32_bf16 v[64:67], v[160:163], v[198:201], v[64:67]
	s_setprio 2
	s_barrier
	v_mfma_f32_16x16x32_bf16 v[60:63], v[152:155], v[198:201], v[60:63]
	v_mfma_f32_16x16x32_bf16 v[60:63], v[148:151], v[194:197], v[60:63]
	s_setprio 0
	s_add_i32 s6, s12, s36
	s_mov_b32 m0, s6
	ds_read_b128 v[164:167], v212 offset:16384
	ds_read_b128 v[168:171], v212 offset:17408
	ds_read_b128 v[172:175], v212 offset:18432
	ds_read_b128 v[176:179], v212 offset:19456
	ds_read_b128 v[180:183], v212 offset:20480
	ds_read_b128 v[184:187], v212 offset:21504
	ds_read_b128 v[194:197], v212 offset:22528
	ds_read_b128 v[198:201], v212 offset:23552
	global_load_lds_dwordx4 v192, s[14:15]
	s_add_i32 m0, s6, 0x2000
	s_add_u32 s6, s14, 0x10000
	s_addc_u32 s7, s15, 0
	s_add_i32 s12, s13, s36
	global_load_lds_dwordx4 v190, s[14:15]
	s_mov_b32 m0, s12
	v_mov_b32_e32 v193, v3
	global_load_lds_dwordx4 v192, s[6:7]
	s_add_i32 m0, s12, 0x2000
	v_mov_b32_e32 v191, v3
	global_load_lds_dwordx4 v190, s[6:7]
	s_mov_b32 m0, s37
	v_lshl_add_u64 v[202:203], s[14:15], 0, v[192:193]
	global_load_lds_dwordx4 v2, s[10:11]
	s_mov_b32 m0, s66
	v_lshl_add_u64 v[204:205], s[14:15], 0, v[190:191]
	global_load_lds_dwordx4 v188, s[10:11]
	s_waitcnt vmcnt(8)
	s_waitcnt lgkmcnt(0)
	v_lshl_add_u64 v[206:207], s[10:11], 0, v[2:3]
	v_lshl_add_u64 v[210:211], s[10:11], 0, v[188:189]
	s_barrier
	s_setprio 1
	s_waitcnt lgkmcnt(0)
	s_nop 0
	v_mfma_f32_16x16x32_bf16 v[68:71], v[132:135], v[164:167], v[68:71]
	v_mfma_f32_16x16x32_bf16 v[68:71], v[136:139], v[168:171], v[68:71]
	v_mfma_f32_16x16x32_bf16 v[72:75], v[144:147], v[168:171], v[72:75]
	v_mfma_f32_16x16x32_bf16 v[72:75], v[140:143], v[164:167], v[72:75]
	v_mfma_f32_16x16x32_bf16 v[80:83], v[140:143], v[172:175], v[80:83]
	v_mfma_f32_16x16x32_bf16 v[80:83], v[144:147], v[176:179], v[80:83]
	v_mfma_f32_16x16x32_bf16 v[76:79], v[136:139], v[176:179], v[76:79]
	v_mfma_f32_16x16x32_bf16 v[76:79], v[132:135], v[172:175], v[76:79]
	v_mfma_f32_16x16x32_bf16 v[84:87], v[132:135], v[180:183], v[84:87]
	v_mfma_f32_16x16x32_bf16 v[84:87], v[136:139], v[184:187], v[84:87]
	v_mfma_f32_16x16x32_bf16 v[88:91], v[144:147], v[184:187], v[88:91]
	v_mfma_f32_16x16x32_bf16 v[88:91], v[140:143], v[180:183], v[88:91]
	v_mfma_f32_16x16x32_bf16 v[96:99], v[140:143], v[194:197], v[96:99]
	v_mfma_f32_16x16x32_bf16 v[96:99], v[144:147], v[198:201], v[96:99]
	v_mfma_f32_16x16x32_bf16 v[92:95], v[136:139], v[198:201], v[92:95]
	v_mfma_f32_16x16x32_bf16 v[92:95], v[132:135], v[194:197], v[92:95]
	s_setprio 0
	s_setprio 1
	v_mfma_f32_16x16x32_bf16 v[100:103], v[148:151], v[164:167], v[100:103]
	v_mfma_f32_16x16x32_bf16 v[100:103], v[152:155], v[168:171], v[100:103]
	v_mfma_f32_16x16x32_bf16 v[104:107], v[160:163], v[168:171], v[104:107]
	v_mfma_f32_16x16x32_bf16 v[104:107], v[156:159], v[164:167], v[104:107]
	v_mfma_f32_16x16x32_bf16 v[112:115], v[156:159], v[172:175], v[112:115]
	v_mfma_f32_16x16x32_bf16 v[112:115], v[160:163], v[176:179], v[112:115]
	v_mfma_f32_16x16x32_bf16 v[108:111], v[152:155], v[176:179], v[108:111]
	v_mfma_f32_16x16x32_bf16 v[108:111], v[148:151], v[172:175], v[108:111]
	v_mfma_f32_16x16x32_bf16 v[116:119], v[148:151], v[180:183], v[116:119]
	v_mfma_f32_16x16x32_bf16 v[116:119], v[152:155], v[184:187], v[116:119]
	v_mfma_f32_16x16x32_bf16 v[120:123], v[160:163], v[184:187], v[120:123]
	v_mfma_f32_16x16x32_bf16 v[120:123], v[156:159], v[180:183], v[120:123]
	v_mfma_f32_16x16x32_bf16 v[128:131], v[156:159], v[194:197], v[128:131]
	v_mfma_f32_16x16x32_bf16 v[128:131], v[160:163], v[198:201], v[128:131]
	s_setprio 2
	s_barrier
	v_mfma_f32_16x16x32_bf16 v[124:127], v[152:155], v[198:201], v[124:127]
	v_mfma_f32_16x16x32_bf16 v[124:127], v[148:151], v[194:197], v[124:127]
	s_setprio 0
	s_add_i32 s12, 0, 0x18000
	s_add_i32 s13, 0, 0x1c000
	v_add_u32_e32 v144, s12, v209
	v_add_u32_e32 v160, s13, v209
	ds_read_b128 v[132:135], v144
	ds_read_b128 v[136:139], v144 offset:1024
	ds_read_b128 v[140:143], v144 offset:2048
	ds_read_b128 v[144:147], v144 offset:3072
	ds_read_b128 v[148:151], v160
	ds_read_b128 v[152:155], v160 offset:1024
	ds_read_b128 v[156:159], v160 offset:2048
	ds_read_b128 v[160:163], v160 offset:3072
	s_add_u32 s6, s10, 0x80000
	s_addc_u32 s7, s11, 0
	s_mov_b32 m0, s67
	ds_read_b128 v[164:167], v212 offset:32768
	ds_read_b128 v[168:171], v212 offset:33792
	ds_read_b128 v[172:175], v212 offset:34816
	ds_read_b128 v[176:179], v212 offset:35840
	ds_read_b128 v[180:183], v212 offset:36864
	ds_read_b128 v[184:187], v212 offset:37888
	ds_read_b128 v[194:197], v212 offset:38912
	ds_read_b128 v[198:201], v212 offset:39936
	global_load_lds_dwordx4 v2, s[6:7]
	s_mov_b32 m0, s68
	s_nop 0
	global_load_lds_dwordx4 v188, s[6:7]
	s_waitcnt vmcnt(8)
	s_waitcnt lgkmcnt(0)
	s_barrier
	s_setprio 1
	s_waitcnt lgkmcnt(0)
	s_nop 0
	v_mfma_f32_16x16x32_bf16 v[4:7], v[132:135], v[164:167], v[4:7]
	v_mfma_f32_16x16x32_bf16 v[4:7], v[136:139], v[168:171], v[4:7]
	v_mfma_f32_16x16x32_bf16 v[8:11], v[144:147], v[168:171], v[8:11]
	v_mfma_f32_16x16x32_bf16 v[8:11], v[140:143], v[164:167], v[8:11]
	v_mfma_f32_16x16x32_bf16 v[16:19], v[140:143], v[172:175], v[16:19]
	v_mfma_f32_16x16x32_bf16 v[16:19], v[144:147], v[176:179], v[16:19]
	v_mfma_f32_16x16x32_bf16 v[12:15], v[136:139], v[176:179], v[12:15]
	v_mfma_f32_16x16x32_bf16 v[12:15], v[132:135], v[172:175], v[12:15]
	v_mfma_f32_16x16x32_bf16 v[20:23], v[132:135], v[180:183], v[20:23]
	v_mfma_f32_16x16x32_bf16 v[20:23], v[136:139], v[184:187], v[20:23]
	v_mfma_f32_16x16x32_bf16 v[24:27], v[144:147], v[184:187], v[24:27]
	v_mfma_f32_16x16x32_bf16 v[24:27], v[140:143], v[180:183], v[24:27]
	v_mfma_f32_16x16x32_bf16 v[32:35], v[140:143], v[194:197], v[32:35]
	v_mfma_f32_16x16x32_bf16 v[32:35], v[144:147], v[198:201], v[32:35]
	v_mfma_f32_16x16x32_bf16 v[28:31], v[136:139], v[198:201], v[28:31]
	v_mfma_f32_16x16x32_bf16 v[28:31], v[132:135], v[194:197], v[28:31]
	s_setprio 0
	s_setprio 1
	v_mfma_f32_16x16x32_bf16 v[36:39], v[148:151], v[164:167], v[36:39]
	v_mfma_f32_16x16x32_bf16 v[36:39], v[152:155], v[168:171], v[36:39]
	v_mfma_f32_16x16x32_bf16 v[40:43], v[160:163], v[168:171], v[40:43]
	v_mfma_f32_16x16x32_bf16 v[40:43], v[156:159], v[164:167], v[40:43]
	v_mfma_f32_16x16x32_bf16 v[48:51], v[156:159], v[172:175], v[48:51]
	v_mfma_f32_16x16x32_bf16 v[48:51], v[160:163], v[176:179], v[48:51]
	v_mfma_f32_16x16x32_bf16 v[44:47], v[152:155], v[176:179], v[44:47]
	v_mfma_f32_16x16x32_bf16 v[44:47], v[148:151], v[172:175], v[44:47]
	v_mfma_f32_16x16x32_bf16 v[52:55], v[148:151], v[180:183], v[52:55]
	v_mfma_f32_16x16x32_bf16 v[52:55], v[152:155], v[184:187], v[52:55]
	v_mfma_f32_16x16x32_bf16 v[56:59], v[160:163], v[184:187], v[56:59]
	v_mfma_f32_16x16x32_bf16 v[56:59], v[156:159], v[180:183], v[56:59]
	v_mfma_f32_16x16x32_bf16 v[64:67], v[156:159], v[194:197], v[64:67]
	v_mfma_f32_16x16x32_bf16 v[64:67], v[160:163], v[198:201], v[64:67]
	s_setprio 2
	s_barrier
	v_mfma_f32_16x16x32_bf16 v[60:63], v[152:155], v[198:201], v[60:63]
	v_mfma_f32_16x16x32_bf16 v[60:63], v[148:151], v[194:197], v[60:63]
	s_setprio 0
	s_add_i32 s6, s12, s36
	v_lshl_add_u64 v[202:203], v[202:203], 0, s[86:87]
	s_mov_b32 m0, s6
	ds_read_b128 v[164:167], v212 offset:49152
	ds_read_b128 v[168:171], v212 offset:50176
	ds_read_b128 v[172:175], v212 offset:51200
	ds_read_b128 v[176:179], v212 offset:52224
	ds_read_b128 v[180:183], v212 offset:53248
	ds_read_b128 v[184:187], v212 offset:54272
	ds_read_b128 v[194:197], v212 offset:55296
	ds_read_b128 v[198:201], v212 offset:56320
	global_load_lds_dwordx4 v[202:203], off
	s_add_i32 m0, s6, 0x2000
	s_add_u32 s6, s14, 0x10080
	v_lshl_add_u64 v[202:203], v[204:205], 0, s[86:87]
	s_addc_u32 s7, s15, 0
	s_add_i32 s12, s13, s36
	global_load_lds_dwordx4 v[202:203], off
	s_mov_b32 m0, s12
	v_lshl_add_u64 v[202:203], v[206:207], 0, s[86:87]
	global_load_lds_dwordx4 v192, s[6:7]
	s_add_i32 m0, s12, 0x2000
	s_nop 0
	global_load_lds_dwordx4 v190, s[6:7]
	s_mov_b32 m0, s71
	s_nop 0
	global_load_lds_dwordx4 v[202:203], off
	v_lshl_add_u64 v[202:203], v[210:211], 0, s[86:87]
	s_mov_b32 m0, s72
	s_nop 0
	global_load_lds_dwordx4 v[202:203], off
	s_waitcnt vmcnt(8)
	s_waitcnt lgkmcnt(0)
	s_barrier
	s_setprio 1
	s_waitcnt lgkmcnt(0)
	s_nop 0
	v_mfma_f32_16x16x32_bf16 v[68:71], v[132:135], v[164:167], v[68:71]
	v_mfma_f32_16x16x32_bf16 v[68:71], v[136:139], v[168:171], v[68:71]
	v_mfma_f32_16x16x32_bf16 v[72:75], v[144:147], v[168:171], v[72:75]
	v_mfma_f32_16x16x32_bf16 v[72:75], v[140:143], v[164:167], v[72:75]
	v_mfma_f32_16x16x32_bf16 v[80:83], v[140:143], v[172:175], v[80:83]
	v_mfma_f32_16x16x32_bf16 v[80:83], v[144:147], v[176:179], v[80:83]
	v_mfma_f32_16x16x32_bf16 v[76:79], v[136:139], v[176:179], v[76:79]
	v_mfma_f32_16x16x32_bf16 v[76:79], v[132:135], v[172:175], v[76:79]
	v_mfma_f32_16x16x32_bf16 v[84:87], v[132:135], v[180:183], v[84:87]
	v_mfma_f32_16x16x32_bf16 v[84:87], v[136:139], v[184:187], v[84:87]
	v_mfma_f32_16x16x32_bf16 v[88:91], v[144:147], v[184:187], v[88:91]
	v_mfma_f32_16x16x32_bf16 v[88:91], v[140:143], v[180:183], v[88:91]
	v_mfma_f32_16x16x32_bf16 v[96:99], v[140:143], v[194:197], v[96:99]
	v_mfma_f32_16x16x32_bf16 v[96:99], v[144:147], v[198:201], v[96:99]
	v_mfma_f32_16x16x32_bf16 v[92:95], v[136:139], v[198:201], v[92:95]
	v_mfma_f32_16x16x32_bf16 v[92:95], v[132:135], v[194:197], v[92:95]
	s_setprio 0
	s_setprio 1
	v_mfma_f32_16x16x32_bf16 v[100:103], v[148:151], v[164:167], v[100:103]
	v_mfma_f32_16x16x32_bf16 v[100:103], v[152:155], v[168:171], v[100:103]
	v_mfma_f32_16x16x32_bf16 v[104:107], v[160:163], v[168:171], v[104:107]
	v_mfma_f32_16x16x32_bf16 v[104:107], v[156:159], v[164:167], v[104:107]
	v_mfma_f32_16x16x32_bf16 v[112:115], v[156:159], v[172:175], v[112:115]
	v_mfma_f32_16x16x32_bf16 v[112:115], v[160:163], v[176:179], v[112:115]
	v_mfma_f32_16x16x32_bf16 v[108:111], v[152:155], v[176:179], v[108:111]
	v_mfma_f32_16x16x32_bf16 v[108:111], v[148:151], v[172:175], v[108:111]
	v_mfma_f32_16x16x32_bf16 v[116:119], v[148:151], v[180:183], v[116:119]
	v_mfma_f32_16x16x32_bf16 v[116:119], v[152:155], v[184:187], v[116:119]
	v_mfma_f32_16x16x32_bf16 v[120:123], v[160:163], v[184:187], v[120:123]
	v_mfma_f32_16x16x32_bf16 v[120:123], v[156:159], v[180:183], v[120:123]
	v_mfma_f32_16x16x32_bf16 v[128:131], v[156:159], v[194:197], v[128:131]
	v_mfma_f32_16x16x32_bf16 v[128:131], v[160:163], v[198:201], v[128:131]
	s_setprio 2
	s_barrier
	v_mfma_f32_16x16x32_bf16 v[124:127], v[152:155], v[198:201], v[124:127]
	v_mfma_f32_16x16x32_bf16 v[124:127], v[148:151], v[194:197], v[124:127]
	s_setprio 0
	s_and_b64 vcc, exec, s[58:59]
	s_cbranch_vccz .LBB0_1178
	s_barrier

.LBB0_1625:
	s_add_i32 s51, 0, 0x10000
	s_add_i32 s72, 0, 0x14000
	v_add_u32_e32 v16, s51, v232
	v_add_u32_e32 v32, s72, v232
	ds_read_b128 v[4:7], v16
	ds_read_b128 v[8:11], v16 offset:1024
	ds_read_b128 v[12:15], v16 offset:2048
	ds_read_b128 v[16:19], v16 offset:3072
	ds_read_b128 v[20:23], v32
	ds_read_b128 v[24:27], v32 offset:1024
	ds_read_b128 v[28:31], v32 offset:2048
	ds_read_b128 v[32:35], v32 offset:3072
	v_add_u32_e32 v233, 0, v231
	ds_read_b128 v[36:39], v233
	ds_read_b128 v[40:43], v233 offset:1024
	ds_read_b128 v[44:47], v233 offset:2048
	ds_read_b128 v[48:51], v233 offset:3072
	ds_read_b128 v[52:55], v233 offset:4096
	ds_read_b128 v[56:59], v233 offset:5120
	ds_read_b128 v[60:63], v233 offset:6144
	ds_read_b128 v[64:67], v233 offset:7168
	s_waitcnt vmcnt(8)
	s_waitcnt lgkmcnt(0)
	s_barrier
	s_setprio 1
	s_waitcnt lgkmcnt(0)
	s_nop 0
	v_mfma_f32_16x16x32_bf16 v[68:71], v[4:7], v[36:39], 0
	v_mfma_f32_16x16x32_bf16 v[68:71], v[8:11], v[40:43], v[68:71]
	v_mfma_f32_16x16x32_bf16 v[72:75], v[12:15], v[36:39], 0
	v_mfma_f32_16x16x32_bf16 v[72:75], v[16:19], v[40:43], v[72:75]
	v_mfma_f32_16x16x32_bf16 v[80:83], v[12:15], v[44:47], 0
	v_mfma_f32_16x16x32_bf16 v[80:83], v[16:19], v[48:51], v[80:83]
	v_mfma_f32_16x16x32_bf16 v[76:79], v[4:7], v[44:47], 0
	v_mfma_f32_16x16x32_bf16 v[76:79], v[8:11], v[48:51], v[76:79]
	v_mfma_f32_16x16x32_bf16 v[84:87], v[4:7], v[52:55], 0
	v_mfma_f32_16x16x32_bf16 v[84:87], v[8:11], v[56:59], v[84:87]
	v_mfma_f32_16x16x32_bf16 v[88:91], v[12:15], v[52:55], 0
	v_mfma_f32_16x16x32_bf16 v[88:91], v[16:19], v[56:59], v[88:91]
	v_mfma_f32_16x16x32_bf16 v[96:99], v[12:15], v[60:63], 0
	v_mfma_f32_16x16x32_bf16 v[96:99], v[16:19], v[64:67], v[96:99]
	v_mfma_f32_16x16x32_bf16 v[92:95], v[4:7], v[60:63], 0
	v_mfma_f32_16x16x32_bf16 v[92:95], v[8:11], v[64:67], v[92:95]
	s_setprio 0
	s_setprio 1
	v_mfma_f32_16x16x32_bf16 v[100:103], v[20:23], v[36:39], 0
	v_mfma_f32_16x16x32_bf16 v[36:39], v[28:31], v[36:39], 0
	v_mfma_f32_16x16x32_bf16 v[104:107], v[20:23], v[44:47], 0
	v_mfma_f32_16x16x32_bf16 v[44:47], v[28:31], v[44:47], 0
	v_mfma_f32_16x16x32_bf16 v[108:111], v[20:23], v[52:55], 0
	v_mfma_f32_16x16x32_bf16 v[52:55], v[28:31], v[52:55], 0
	v_mfma_f32_16x16x32_bf16 v[112:115], v[20:23], v[60:63], 0
	v_mfma_f32_16x16x32_bf16 v[60:63], v[28:31], v[60:63], 0
	v_mfma_f32_16x16x32_bf16 v[100:103], v[24:27], v[40:43], v[100:103]
	v_mfma_f32_16x16x32_bf16 v[40:43], v[32:35], v[40:43], v[36:39]
	v_mfma_f32_16x16x32_bf16 v[104:107], v[24:27], v[48:51], v[104:107]
	v_mfma_f32_16x16x32_bf16 v[48:51], v[32:35], v[48:51], v[44:47]
	v_mfma_f32_16x16x32_bf16 v[108:111], v[24:27], v[56:59], v[108:111]
	v_mfma_f32_16x16x32_bf16 v[56:59], v[32:35], v[56:59], v[52:55]
	s_setprio 2
	s_barrier
	v_mfma_f32_16x16x32_bf16 v[112:115], v[24:27], v[64:67], v[112:115]
	v_mfma_f32_16x16x32_bf16 v[64:67], v[32:35], v[64:67], v[60:63]
	s_setprio 0
	v_lshl_add_u64 v[186:187], s[12:13], 0, v[2:3]
	s_add_i32 s51, s51, s56
	v_mov_b32_e32 v191, v3
	v_lshl_add_u64 v[134:135], v[186:187], 0, s[74:75]
	s_mov_b32 m0, s51
	v_lshl_add_u64 v[246:247], s[12:13], 0, v[190:191]
	ds_read_b128 v[36:39], v233 offset:16384
	ds_read_b128 v[44:47], v233 offset:17408
	ds_read_b128 v[52:55], v233 offset:18432
	ds_read_b128 v[60:63], v233 offset:19456
	ds_read_b128 v[116:119], v233 offset:20480
	ds_read_b128 v[120:123], v233 offset:21504
	ds_read_b128 v[124:127], v233 offset:22528
	ds_read_b128 v[128:131], v233 offset:23552
	global_load_lds_dwordx4 v[134:135], off
	v_lshl_add_u64 v[134:135], v[246:247], 0, s[74:75]
	s_add_i32 m0, s51, 0x2000
	s_add_i32 s51, s72, s56
	global_load_lds_dwordx4 v[134:135], off
	s_mov_b32 m0, s51
	v_mov_b32_e32 v133, v3
	global_load_lds_dwordx4 v2, s[16:17]
	s_add_i32 m0, s51, 0x2000
	v_lshl_add_u64 v[248:249], s[14:15], 0, v[132:133]
	v_mov_b32_e32 v189, v3
	global_load_lds_dwordx4 v190, s[16:17]
	v_lshl_add_u64 v[134:135], v[248:249], 0, s[74:75]
	s_mov_b32 m0, s57
	v_lshl_add_u64 v[250:251], s[14:15], 0, v[188:189]
	global_load_lds_dwordx4 v[134:135], off
	v_lshl_add_u64 v[134:135], v[250:251], 0, s[74:75]
	s_mov_b32 m0, s58
	s_nop 0
	global_load_lds_dwordx4 v[134:135], off
	s_waitcnt vmcnt(8)
	s_waitcnt lgkmcnt(0)
	s_barrier
	s_setprio 1
	s_waitcnt lgkmcnt(0)
	s_nop 0
	v_mfma_f32_16x16x32_bf16 v[134:137], v[4:7], v[36:39], 0
	v_mfma_f32_16x16x32_bf16 v[138:141], v[12:15], v[36:39], 0
	v_mfma_f32_16x16x32_bf16 v[142:145], v[4:7], v[52:55], 0
	v_mfma_f32_16x16x32_bf16 v[146:149], v[12:15], v[52:55], 0
	v_mfma_f32_16x16x32_bf16 v[150:153], v[4:7], v[116:119], 0
	v_mfma_f32_16x16x32_bf16 v[154:157], v[12:15], v[116:119], 0
	v_mfma_f32_16x16x32_bf16 v[4:7], v[4:7], v[124:127], 0
	v_mfma_f32_16x16x32_bf16 v[12:15], v[12:15], v[124:127], 0
	v_mfma_f32_16x16x32_bf16 v[134:137], v[8:11], v[44:47], v[134:137]
	v_mfma_f32_16x16x32_bf16 v[138:141], v[16:19], v[44:47], v[138:141]
	v_mfma_f32_16x16x32_bf16 v[142:145], v[8:11], v[60:63], v[142:145]
	v_mfma_f32_16x16x32_bf16 v[146:149], v[16:19], v[60:63], v[146:149]
	v_mfma_f32_16x16x32_bf16 v[150:153], v[8:11], v[120:123], v[150:153]
	v_mfma_f32_16x16x32_bf16 v[154:157], v[16:19], v[120:123], v[154:157]
	v_mfma_f32_16x16x32_bf16 v[158:161], v[8:11], v[128:131], v[4:7]
	v_mfma_f32_16x16x32_bf16 v[162:165], v[16:19], v[128:131], v[12:15]
	s_setprio 0
	s_setprio 1
	v_mfma_f32_16x16x32_bf16 v[4:7], v[20:23], v[36:39], 0
	v_mfma_f32_16x16x32_bf16 v[8:11], v[28:31], v[36:39], 0
	v_mfma_f32_16x16x32_bf16 v[12:15], v[20:23], v[52:55], 0
	v_mfma_f32_16x16x32_bf16 v[16:19], v[28:31], v[52:55], 0
	v_mfma_f32_16x16x32_bf16 v[36:39], v[20:23], v[116:119], 0
	v_mfma_f32_16x16x32_bf16 v[52:55], v[28:31], v[116:119], 0
	v_mfma_f32_16x16x32_bf16 v[20:23], v[20:23], v[124:127], 0
	v_mfma_f32_16x16x32_bf16 v[28:31], v[28:31], v[124:127], 0
	v_mfma_f32_16x16x32_bf16 v[116:119], v[24:27], v[44:47], v[4:7]
	v_mfma_f32_16x16x32_bf16 v[124:127], v[32:35], v[44:47], v[8:11]
	v_mfma_f32_16x16x32_bf16 v[174:177], v[24:27], v[120:123], v[36:39]
	v_mfma_f32_16x16x32_bf16 v[120:123], v[32:35], v[120:123], v[52:55]
	v_mfma_f32_16x16x32_bf16 v[178:181], v[24:27], v[128:131], v[20:23]
	v_mfma_f32_16x16x32_bf16 v[128:131], v[32:35], v[128:131], v[28:31]
	s_setprio 2
	s_barrier
	v_mfma_f32_16x16x32_bf16 v[166:169], v[24:27], v[60:63], v[12:15]
	v_mfma_f32_16x16x32_bf16 v[170:173], v[32:35], v[60:63], v[16:19]
	s_setprio 0
	s_add_i32 s51, 0, 0x18000
	v_add_u32_e32 v4, s51, v232
	s_add_i32 s72, 0, 0x1c000
	ds_read_b128 v[182:185], v4
	ds_read_b128 v[192:195], v4 offset:1024
	ds_read_b128 v[196:199], v4 offset:2048
	ds_read_b128 v[200:203], v4 offset:3072
	v_add_u32_e32 v4, s72, v232
	ds_read_b128 v[204:207], v4
	ds_read_b128 v[208:211], v4 offset:1024
	ds_read_b128 v[212:215], v4 offset:2048
	ds_read_b128 v[216:219], v4 offset:3072
	s_mov_b32 m0, s59
	ds_read_b128 v[44:47], v233 offset:32768
	ds_read_b128 v[52:55], v233 offset:33792
	ds_read_b128 v[60:63], v233 offset:34816
	ds_read_b128 v[220:223], v233 offset:35840
	ds_read_b128 v[224:227], v233 offset:36864
	ds_read_b128 v[234:237], v233 offset:37888
	ds_read_b128 v[238:241], v233 offset:38912
	ds_read_b128 v[242:245], v233 offset:39936
	global_load_lds_dwordx4 v132, s[26:27]
	s_mov_b32 m0, s60
	s_nop 0
	global_load_lds_dwordx4 v188, s[26:27]
	s_waitcnt vmcnt(8)
	s_waitcnt lgkmcnt(0)
	s_barrier
	s_setprio 1
	s_waitcnt lgkmcnt(0)
	s_nop 0
	v_mfma_f32_16x16x32_bf16 v[4:7], v[182:185], v[44:47], v[68:71]
	v_mfma_f32_16x16x32_bf16 v[8:11], v[196:199], v[44:47], v[72:75]
	v_mfma_f32_16x16x32_bf16 v[12:15], v[182:185], v[60:63], v[76:79]
	v_mfma_f32_16x16x32_bf16 v[16:19], v[196:199], v[60:63], v[80:83]
	v_mfma_f32_16x16x32_bf16 v[20:23], v[182:185], v[224:227], v[84:87]
	v_mfma_f32_16x16x32_bf16 v[24:27], v[196:199], v[224:227], v[88:91]
	v_mfma_f32_16x16x32_bf16 v[28:31], v[182:185], v[238:241], v[92:95]
	v_mfma_f32_16x16x32_bf16 v[32:35], v[196:199], v[238:241], v[96:99]
	v_mfma_f32_16x16x32_bf16 v[4:7], v[192:195], v[52:55], v[4:7]
	v_mfma_f32_16x16x32_bf16 v[8:11], v[200:203], v[52:55], v[8:11]
	v_mfma_f32_16x16x32_bf16 v[12:15], v[192:195], v[220:223], v[12:15]
	v_mfma_f32_16x16x32_bf16 v[16:19], v[200:203], v[220:223], v[16:19]
	v_mfma_f32_16x16x32_bf16 v[20:23], v[192:195], v[234:237], v[20:23]
	v_mfma_f32_16x16x32_bf16 v[24:27], v[200:203], v[234:237], v[24:27]
	v_mfma_f32_16x16x32_bf16 v[28:31], v[192:195], v[242:245], v[28:31]
	v_mfma_f32_16x16x32_bf16 v[32:35], v[200:203], v[242:245], v[32:35]
	s_setprio 0
	s_setprio 1
	v_mfma_f32_16x16x32_bf16 v[36:39], v[204:207], v[44:47], v[100:103]
	v_mfma_f32_16x16x32_bf16 v[40:43], v[212:215], v[44:47], v[40:43]
	v_mfma_f32_16x16x32_bf16 v[36:39], v[208:211], v[52:55], v[36:39]
	v_mfma_f32_16x16x32_bf16 v[40:43], v[216:219], v[52:55], v[40:43]
	v_mfma_f32_16x16x32_bf16 v[44:47], v[204:207], v[60:63], v[104:107]
	v_mfma_f32_16x16x32_bf16 v[48:51], v[212:215], v[60:63], v[48:51]
	v_mfma_f32_16x16x32_bf16 v[52:55], v[204:207], v[224:227], v[108:111]
	v_mfma_f32_16x16x32_bf16 v[56:59], v[212:215], v[224:227], v[56:59]
	v_mfma_f32_16x16x32_bf16 v[60:63], v[204:207], v[238:241], v[112:115]
	v_mfma_f32_16x16x32_bf16 v[64:67], v[212:215], v[238:241], v[64:67]
	v_mfma_f32_16x16x32_bf16 v[44:47], v[208:211], v[220:223], v[44:47]
	v_mfma_f32_16x16x32_bf16 v[48:51], v[216:219], v[220:223], v[48:51]
	v_mfma_f32_16x16x32_bf16 v[52:55], v[208:211], v[234:237], v[52:55]
	v_mfma_f32_16x16x32_bf16 v[56:59], v[216:219], v[234:237], v[56:59]
	s_setprio 2
	s_barrier
	v_mfma_f32_16x16x32_bf16 v[60:63], v[208:211], v[242:245], v[60:63]
	v_mfma_f32_16x16x32_bf16 v[64:67], v[216:219], v[242:245], v[64:67]
	s_setprio 0
	s_add_i32 s51, s51, s56
	v_lshl_add_u64 v[68:69], v[186:187], 0, s[24:25]
	s_mov_b32 m0, s51
	ds_read_b128 v[104:107], v233 offset:49152
	ds_read_b128 v[108:111], v233 offset:50176
	ds_read_b128 v[112:115], v233 offset:51200
	ds_read_b128 v[220:223], v233 offset:52224
	ds_read_b128 v[224:227], v233 offset:53248
	ds_read_b128 v[234:237], v233 offset:54272
	ds_read_b128 v[238:241], v233 offset:55296
	ds_read_b128 v[242:245], v233 offset:56320
	global_load_lds_dwordx4 v[68:69], off
	v_lshl_add_u64 v[68:69], v[246:247], 0, s[24:25]
	s_add_i32 m0, s51, 0x2000
	s_add_i32 s51, s72, s56
	global_load_lds_dwordx4 v[68:69], off
	s_mov_b32 m0, s51
	v_lshl_add_u64 v[68:69], v[248:249], 0, s[24:25]
	global_load_lds_dwordx4 v2, s[28:29]
	s_add_i32 m0, s51, 0x2000
	s_nop 0
	global_load_lds_dwordx4 v190, s[28:29]
	s_mov_b32 m0, s64
	s_nop 0
	global_load_lds_dwordx4 v[68:69], off
	v_lshl_add_u64 v[68:69], v[250:251], 0, s[24:25]
	s_mov_b32 m0, s65
	s_nop 0
	global_load_lds_dwordx4 v[68:69], off
	s_waitcnt vmcnt(8)
	s_waitcnt lgkmcnt(0)
	s_barrier
	s_setprio 1
	s_waitcnt lgkmcnt(0)
	s_nop 0
	v_mfma_f32_16x16x32_bf16 v[68:71], v[182:185], v[104:107], v[134:137]
	v_mfma_f32_16x16x32_bf16 v[72:75], v[196:199], v[104:107], v[138:141]
	v_mfma_f32_16x16x32_bf16 v[76:79], v[182:185], v[112:115], v[142:145]
	v_mfma_f32_16x16x32_bf16 v[80:83], v[196:199], v[112:115], v[146:149]
	v_mfma_f32_16x16x32_bf16 v[84:87], v[182:185], v[224:227], v[150:153]
	v_mfma_f32_16x16x32_bf16 v[88:91], v[196:199], v[224:227], v[154:157]
	v_mfma_f32_16x16x32_bf16 v[92:95], v[182:185], v[238:241], v[158:161]
	v_mfma_f32_16x16x32_bf16 v[96:99], v[196:199], v[238:241], v[162:165]
	v_mfma_f32_16x16x32_bf16 v[68:71], v[192:195], v[108:111], v[68:71]
	v_mfma_f32_16x16x32_bf16 v[72:75], v[200:203], v[108:111], v[72:75]
	v_mfma_f32_16x16x32_bf16 v[76:79], v[192:195], v[220:223], v[76:79]
	v_mfma_f32_16x16x32_bf16 v[80:83], v[200:203], v[220:223], v[80:83]
	v_mfma_f32_16x16x32_bf16 v[84:87], v[192:195], v[234:237], v[84:87]
	v_mfma_f32_16x16x32_bf16 v[88:91], v[200:203], v[234:237], v[88:91]
	v_mfma_f32_16x16x32_bf16 v[92:95], v[192:195], v[242:245], v[92:95]
	v_mfma_f32_16x16x32_bf16 v[96:99], v[200:203], v[242:245], v[96:99]
	s_setprio 0
	s_setprio 1
	v_mfma_f32_16x16x32_bf16 v[100:103], v[204:207], v[104:107], v[116:119]
	v_mfma_f32_16x16x32_bf16 v[104:107], v[212:215], v[104:107], v[124:127]
	v_mfma_f32_16x16x32_bf16 v[100:103], v[208:211], v[108:111], v[100:103]
	v_mfma_f32_16x16x32_bf16 v[104:107], v[216:219], v[108:111], v[104:107]
	v_mfma_f32_16x16x32_bf16 v[108:111], v[204:207], v[112:115], v[166:169]
	v_mfma_f32_16x16x32_bf16 v[112:115], v[212:215], v[112:115], v[170:173]
	v_mfma_f32_16x16x32_bf16 v[116:119], v[204:207], v[224:227], v[174:177]
	v_mfma_f32_16x16x32_bf16 v[120:123], v[212:215], v[224:227], v[120:123]
	v_mfma_f32_16x16x32_bf16 v[124:127], v[204:207], v[238:241], v[178:181]
	v_mfma_f32_16x16x32_bf16 v[128:131], v[212:215], v[238:241], v[128:131]
	v_mfma_f32_16x16x32_bf16 v[108:111], v[208:211], v[220:223], v[108:111]
	v_mfma_f32_16x16x32_bf16 v[112:115], v[216:219], v[220:223], v[112:115]
	v_mfma_f32_16x16x32_bf16 v[116:119], v[208:211], v[234:237], v[116:119]
	v_mfma_f32_16x16x32_bf16 v[120:123], v[216:219], v[234:237], v[120:123]
	s_setprio 2
	s_barrier
	v_mfma_f32_16x16x32_bf16 v[124:127], v[208:211], v[242:245], v[124:127]
	v_mfma_f32_16x16x32_bf16 v[128:131], v[216:219], v[242:245], v[128:131]
	s_setprio 0
	s_add_i32 s43, s43, 2
	s_cmp_ge_i32 s43, s42
	s_cbranch_scc0 .LBB0_1625
	v_mov_b32_e32 v192, v2
	s_branch .LBB0_1628

.LBB0_1629:
	s_add_u32 s12, s14, 0xfff80080
	s_addc_u32 s13, s15, -1
	s_add_i32 s29, 0, 0x10000
	s_cmp_eq_u32 s28, 28
	s_cselect_b32 s17, s9, s13
	s_cselect_b32 s16, s8, s12
	s_cselect_b32 s13, s11, s27
	s_cselect_b32 s12, s10, s26
	s_add_i32 s51, 0, 0x14000
	v_add_u32_e32 v144, s29, v232
	v_add_u32_e32 v160, s51, v232
	s_waitcnt lgkmcnt(0)
	ds_read_b128 v[132:135], v144
	ds_read_b128 v[136:139], v144 offset:1024
	ds_read_b128 v[140:143], v144 offset:2048
	ds_read_b128 v[144:147], v144 offset:3072
	ds_read_b128 v[148:151], v160
	ds_read_b128 v[152:155], v160 offset:1024
	ds_read_b128 v[156:159], v160 offset:2048
	ds_read_b128 v[160:163], v160 offset:3072
	s_mov_b32 m0, s66
	v_add_u32_e32 v210, 0, v231
	ds_read_b128 v[164:167], v210
	ds_read_b128 v[168:171], v210 offset:1024
	ds_read_b128 v[172:175], v210 offset:2048
	ds_read_b128 v[176:179], v210 offset:3072
	ds_read_b128 v[180:183], v210 offset:4096
	ds_read_b128 v[184:187], v210 offset:5120
	ds_read_b128 v[194:197], v210 offset:6144
	ds_read_b128 v[198:201], v210 offset:7168
	global_load_lds_dwordx4 v2, s[14:15]
	s_mov_b32 m0, s67
	v_mov_b32_e32 v189, v3
	global_load_lds_dwordx4 v188, s[14:15]
	s_waitcnt vmcnt(8)
	s_waitcnt lgkmcnt(0)
	s_barrier
	s_setprio 1
	s_waitcnt lgkmcnt(0)
	s_nop 0
	v_mfma_f32_16x16x32_bf16 v[4:7], v[132:135], v[164:167], v[4:7]
	v_mfma_f32_16x16x32_bf16 v[4:7], v[136:139], v[168:171], v[4:7]
	v_mfma_f32_16x16x32_bf16 v[8:11], v[144:147], v[168:171], v[8:11]
	v_mfma_f32_16x16x32_bf16 v[8:11], v[140:143], v[164:167], v[8:11]
	v_mfma_f32_16x16x32_bf16 v[16:19], v[140:143], v[172:175], v[16:19]
	v_mfma_f32_16x16x32_bf16 v[16:19], v[144:147], v[176:179], v[16:19]
	v_mfma_f32_16x16x32_bf16 v[12:15], v[136:139], v[176:179], v[12:15]
	v_mfma_f32_16x16x32_bf16 v[12:15], v[132:135], v[172:175], v[12:15]
	v_mfma_f32_16x16x32_bf16 v[20:23], v[132:135], v[180:183], v[20:23]
	v_mfma_f32_16x16x32_bf16 v[20:23], v[136:139], v[184:187], v[20:23]
	v_mfma_f32_16x16x32_bf16 v[24:27], v[144:147], v[184:187], v[24:27]
	v_mfma_f32_16x16x32_bf16 v[24:27], v[140:143], v[180:183], v[24:27]
	v_mfma_f32_16x16x32_bf16 v[32:35], v[140:143], v[194:197], v[32:35]
	v_mfma_f32_16x16x32_bf16 v[32:35], v[144:147], v[198:201], v[32:35]
	v_mfma_f32_16x16x32_bf16 v[28:31], v[136:139], v[198:201], v[28:31]
	v_mfma_f32_16x16x32_bf16 v[28:31], v[132:135], v[194:197], v[28:31]
	s_setprio 0
	s_setprio 1
	v_mfma_f32_16x16x32_bf16 v[36:39], v[148:151], v[164:167], v[36:39]
	v_mfma_f32_16x16x32_bf16 v[36:39], v[152:155], v[168:171], v[36:39]
	v_mfma_f32_16x16x32_bf16 v[40:43], v[160:163], v[168:171], v[40:43]
	v_mfma_f32_16x16x32_bf16 v[40:43], v[156:159], v[164:167], v[40:43]
	v_mfma_f32_16x16x32_bf16 v[48:51], v[156:159], v[172:175], v[48:51]
	v_mfma_f32_16x16x32_bf16 v[48:51], v[160:163], v[176:179], v[48:51]
	v_mfma_f32_16x16x32_bf16 v[44:47], v[152:155], v[176:179], v[44:47]
	v_mfma_f32_16x16x32_bf16 v[44:47], v[148:151], v[172:175], v[44:47]
	v_mfma_f32_16x16x32_bf16 v[52:55], v[148:151], v[180:183], v[52:55]
	v_mfma_f32_16x16x32_bf16 v[52:55], v[152:155], v[184:187], v[52:55]
	v_mfma_f32_16x16x32_bf16 v[56:59], v[160:163], v[184:187], v[56:59]
	v_mfma_f32_16x16x32_bf16 v[56:59], v[156:159], v[180:183], v[56:59]
	v_mfma_f32_16x16x32_bf16 v[64:67], v[156:159], v[194:197], v[64:67]
	v_mfma_f32_16x16x32_bf16 v[64:67], v[160:163], v[198:201], v[64:67]
	s_setprio 2
	s_barrier
	v_mfma_f32_16x16x32_bf16 v[60:63], v[152:155], v[198:201], v[60:63]
	v_mfma_f32_16x16x32_bf16 v[60:63], v[148:151], v[194:197], v[60:63]
	s_setprio 0
	s_add_i32 s29, s29, s56
	s_mov_b32 m0, s29
	ds_read_b128 v[164:167], v210 offset:16384
	ds_read_b128 v[168:171], v210 offset:17408
	ds_read_b128 v[172:175], v210 offset:18432
	ds_read_b128 v[176:179], v210 offset:19456
	ds_read_b128 v[180:183], v210 offset:20480
	ds_read_b128 v[184:187], v210 offset:21504
	ds_read_b128 v[194:197], v210 offset:22528
	ds_read_b128 v[198:201], v210 offset:23552
	global_load_lds_dwordx4 v192, s[12:13]
	s_add_i32 m0, s29, 0x2000
	s_add_u32 s42, s12, 0x80000
	s_addc_u32 s43, s13, 0
	s_add_i32 s29, s51, s56
	global_load_lds_dwordx4 v190, s[12:13]
	s_mov_b32 m0, s29
	v_mov_b32_e32 v193, v3
	global_load_lds_dwordx4 v192, s[42:43]
	s_add_i32 m0, s29, 0x2000
	v_mov_b32_e32 v191, v3
	global_load_lds_dwordx4 v190, s[42:43]
	s_mov_b32 m0, s57
	v_lshl_add_u64 v[202:203], s[12:13], 0, v[192:193]
	global_load_lds_dwordx4 v2, s[16:17]
	s_mov_b32 m0, s58
	v_lshl_add_u64 v[204:205], s[12:13], 0, v[190:191]
	global_load_lds_dwordx4 v188, s[16:17]
	s_waitcnt vmcnt(8)
	s_waitcnt lgkmcnt(0)
	v_lshl_add_u64 v[206:207], s[16:17], 0, v[2:3]
	v_lshl_add_u64 v[208:209], s[16:17], 0, v[188:189]
	s_barrier
	s_setprio 1
	s_waitcnt lgkmcnt(0)
	s_nop 0
	v_mfma_f32_16x16x32_bf16 v[68:71], v[132:135], v[164:167], v[68:71]
	v_mfma_f32_16x16x32_bf16 v[68:71], v[136:139], v[168:171], v[68:71]
	v_mfma_f32_16x16x32_bf16 v[72:75], v[144:147], v[168:171], v[72:75]
	v_mfma_f32_16x16x32_bf16 v[72:75], v[140:143], v[164:167], v[72:75]
	v_mfma_f32_16x16x32_bf16 v[80:83], v[140:143], v[172:175], v[80:83]
	v_mfma_f32_16x16x32_bf16 v[80:83], v[144:147], v[176:179], v[80:83]
	v_mfma_f32_16x16x32_bf16 v[76:79], v[136:139], v[176:179], v[76:79]
	v_mfma_f32_16x16x32_bf16 v[76:79], v[132:135], v[172:175], v[76:79]
	v_mfma_f32_16x16x32_bf16 v[84:87], v[132:135], v[180:183], v[84:87]
	v_mfma_f32_16x16x32_bf16 v[84:87], v[136:139], v[184:187], v[84:87]
	v_mfma_f32_16x16x32_bf16 v[88:91], v[144:147], v[184:187], v[88:91]
	v_mfma_f32_16x16x32_bf16 v[88:91], v[140:143], v[180:183], v[88:91]
	v_mfma_f32_16x16x32_bf16 v[96:99], v[140:143], v[194:197], v[96:99]
	v_mfma_f32_16x16x32_bf16 v[96:99], v[144:147], v[198:201], v[96:99]
	v_mfma_f32_16x16x32_bf16 v[92:95], v[136:139], v[198:201], v[92:95]
	v_mfma_f32_16x16x32_bf16 v[92:95], v[132:135], v[194:197], v[92:95]
	s_setprio 0
	s_setprio 1
	v_mfma_f32_16x16x32_bf16 v[100:103], v[148:151], v[164:167], v[100:103]
	v_mfma_f32_16x16x32_bf16 v[100:103], v[152:155], v[168:171], v[100:103]
	v_mfma_f32_16x16x32_bf16 v[104:107], v[160:163], v[168:171], v[104:107]
	v_mfma_f32_16x16x32_bf16 v[104:107], v[156:159], v[164:167], v[104:107]
	v_mfma_f32_16x16x32_bf16 v[112:115], v[156:159], v[172:175], v[112:115]
	v_mfma_f32_16x16x32_bf16 v[112:115], v[160:163], v[176:179], v[112:115]
	v_mfma_f32_16x16x32_bf16 v[108:111], v[152:155], v[176:179], v[108:111]
	v_mfma_f32_16x16x32_bf16 v[108:111], v[148:151], v[172:175], v[108:111]
	v_mfma_f32_16x16x32_bf16 v[116:119], v[148:151], v[180:183], v[116:119]
	v_mfma_f32_16x16x32_bf16 v[116:119], v[152:155], v[184:187], v[116:119]
	v_mfma_f32_16x16x32_bf16 v[120:123], v[160:163], v[184:187], v[120:123]
	v_mfma_f32_16x16x32_bf16 v[120:123], v[156:159], v[180:183], v[120:123]
	v_mfma_f32_16x16x32_bf16 v[128:131], v[156:159], v[194:197], v[128:131]
	v_mfma_f32_16x16x32_bf16 v[128:131], v[160:163], v[198:201], v[128:131]
	s_setprio 2
	s_barrier
	v_mfma_f32_16x16x32_bf16 v[124:127], v[152:155], v[198:201], v[124:127]
	v_mfma_f32_16x16x32_bf16 v[124:127], v[148:151], v[194:197], v[124:127]
	s_setprio 0
	s_add_i32 s29, 0, 0x18000
	s_add_i32 s42, 0, 0x1c000
	v_add_u32_e32 v144, s29, v232
	v_add_u32_e32 v160, s42, v232
	ds_read_b128 v[132:135], v144
	ds_read_b128 v[136:139], v144 offset:1024
	ds_read_b128 v[140:143], v144 offset:2048
	ds_read_b128 v[144:147], v144 offset:3072
	ds_read_b128 v[148:151], v160
	ds_read_b128 v[152:155], v160 offset:1024
	ds_read_b128 v[156:159], v160 offset:2048
	ds_read_b128 v[160:163], v160 offset:3072
	s_add_u32 s16, s16, 0x80000
	s_addc_u32 s17, s17, 0
	s_mov_b32 m0, s59
	ds_read_b128 v[164:167], v210 offset:32768
	ds_read_b128 v[168:171], v210 offset:33792
	ds_read_b128 v[172:175], v210 offset:34816
	ds_read_b128 v[176:179], v210 offset:35840
	ds_read_b128 v[180:183], v210 offset:36864
	ds_read_b128 v[184:187], v210 offset:37888
	ds_read_b128 v[194:197], v210 offset:38912
	ds_read_b128 v[198:201], v210 offset:39936
	global_load_lds_dwordx4 v2, s[16:17]
	s_mov_b32 m0, s60
	s_nop 0
	global_load_lds_dwordx4 v188, s[16:17]
	s_waitcnt vmcnt(8)
	s_waitcnt lgkmcnt(0)
	s_barrier
	s_setprio 1
	s_waitcnt lgkmcnt(0)
	s_nop 0
	v_mfma_f32_16x16x32_bf16 v[4:7], v[132:135], v[164:167], v[4:7]
	v_mfma_f32_16x16x32_bf16 v[4:7], v[136:139], v[168:171], v[4:7]
	v_mfma_f32_16x16x32_bf16 v[8:11], v[144:147], v[168:171], v[8:11]
	v_mfma_f32_16x16x32_bf16 v[8:11], v[140:143], v[164:167], v[8:11]
	v_mfma_f32_16x16x32_bf16 v[16:19], v[140:143], v[172:175], v[16:19]
	v_mfma_f32_16x16x32_bf16 v[16:19], v[144:147], v[176:179], v[16:19]
	v_mfma_f32_16x16x32_bf16 v[12:15], v[136:139], v[176:179], v[12:15]
	v_mfma_f32_16x16x32_bf16 v[12:15], v[132:135], v[172:175], v[12:15]
	v_mfma_f32_16x16x32_bf16 v[20:23], v[132:135], v[180:183], v[20:23]
	v_mfma_f32_16x16x32_bf16 v[20:23], v[136:139], v[184:187], v[20:23]
	v_mfma_f32_16x16x32_bf16 v[24:27], v[144:147], v[184:187], v[24:27]
	v_mfma_f32_16x16x32_bf16 v[24:27], v[140:143], v[180:183], v[24:27]
	v_mfma_f32_16x16x32_bf16 v[32:35], v[140:143], v[194:197], v[32:35]
	v_mfma_f32_16x16x32_bf16 v[32:35], v[144:147], v[198:201], v[32:35]
	v_mfma_f32_16x16x32_bf16 v[28:31], v[136:139], v[198:201], v[28:31]
	v_mfma_f32_16x16x32_bf16 v[28:31], v[132:135], v[194:197], v[28:31]
	s_setprio 0
	s_setprio 1
	v_mfma_f32_16x16x32_bf16 v[36:39], v[148:151], v[164:167], v[36:39]
	v_mfma_f32_16x16x32_bf16 v[36:39], v[152:155], v[168:171], v[36:39]
	v_mfma_f32_16x16x32_bf16 v[40:43], v[160:163], v[168:171], v[40:43]
	v_mfma_f32_16x16x32_bf16 v[40:43], v[156:159], v[164:167], v[40:43]
	v_mfma_f32_16x16x32_bf16 v[48:51], v[156:159], v[172:175], v[48:51]
	v_mfma_f32_16x16x32_bf16 v[48:51], v[160:163], v[176:179], v[48:51]
	v_mfma_f32_16x16x32_bf16 v[44:47], v[152:155], v[176:179], v[44:47]
	v_mfma_f32_16x16x32_bf16 v[44:47], v[148:151], v[172:175], v[44:47]
	v_mfma_f32_16x16x32_bf16 v[52:55], v[148:151], v[180:183], v[52:55]
	v_mfma_f32_16x16x32_bf16 v[52:55], v[152:155], v[184:187], v[52:55]
	v_mfma_f32_16x16x32_bf16 v[56:59], v[160:163], v[184:187], v[56:59]
	v_mfma_f32_16x16x32_bf16 v[56:59], v[156:159], v[180:183], v[56:59]
	v_mfma_f32_16x16x32_bf16 v[64:67], v[156:159], v[194:197], v[64:67]
	v_mfma_f32_16x16x32_bf16 v[64:67], v[160:163], v[198:201], v[64:67]
	s_setprio 2
	s_barrier
	v_mfma_f32_16x16x32_bf16 v[60:63], v[152:155], v[198:201], v[60:63]
	v_mfma_f32_16x16x32_bf16 v[60:63], v[148:151], v[194:197], v[60:63]
	s_setprio 0
	s_add_i32 s16, s29, s56
	v_lshl_add_u64 v[202:203], v[202:203], 0, s[86:87]
	s_mov_b32 m0, s16
	ds_read_b128 v[164:167], v210 offset:49152
	ds_read_b128 v[168:171], v210 offset:50176
	ds_read_b128 v[172:175], v210 offset:51200
	ds_read_b128 v[176:179], v210 offset:52224
	ds_read_b128 v[180:183], v210 offset:53248
	ds_read_b128 v[184:187], v210 offset:54272
	ds_read_b128 v[194:197], v210 offset:55296
	ds_read_b128 v[198:201], v210 offset:56320
	global_load_lds_dwordx4 v[202:203], off
	s_add_i32 m0, s16, 0x2000
	s_add_u32 s12, s12, 0x80080
	v_lshl_add_u64 v[202:203], v[204:205], 0, s[86:87]
	s_addc_u32 s13, s13, 0
	s_add_i32 s16, s42, s56
	global_load_lds_dwordx4 v[202:203], off
	s_mov_b32 m0, s16
	v_lshl_add_u64 v[202:203], v[206:207], 0, s[86:87]
	global_load_lds_dwordx4 v192, s[12:13]
	s_add_i32 m0, s16, 0x2000
	s_nop 0
	global_load_lds_dwordx4 v190, s[12:13]
	s_mov_b32 m0, s64
	s_nop 0
	global_load_lds_dwordx4 v[202:203], off
	v_lshl_add_u64 v[202:203], v[208:209], 0, s[86:87]
	s_mov_b32 m0, s65
	s_nop 0
	global_load_lds_dwordx4 v[202:203], off
	s_waitcnt vmcnt(8)
	s_waitcnt lgkmcnt(0)
	s_barrier
	s_setprio 1
	s_waitcnt lgkmcnt(0)
	s_nop 0
	v_mfma_f32_16x16x32_bf16 v[68:71], v[132:135], v[164:167], v[68:71]
	v_mfma_f32_16x16x32_bf16 v[68:71], v[136:139], v[168:171], v[68:71]
	v_mfma_f32_16x16x32_bf16 v[72:75], v[144:147], v[168:171], v[72:75]
	v_mfma_f32_16x16x32_bf16 v[72:75], v[140:143], v[164:167], v[72:75]
	v_mfma_f32_16x16x32_bf16 v[80:83], v[140:143], v[172:175], v[80:83]
	v_mfma_f32_16x16x32_bf16 v[80:83], v[144:147], v[176:179], v[80:83]
	v_mfma_f32_16x16x32_bf16 v[76:79], v[136:139], v[176:179], v[76:79]
	v_mfma_f32_16x16x32_bf16 v[76:79], v[132:135], v[172:175], v[76:79]
	v_mfma_f32_16x16x32_bf16 v[84:87], v[132:135], v[180:183], v[84:87]
	v_mfma_f32_16x16x32_bf16 v[84:87], v[136:139], v[184:187], v[84:87]
	v_mfma_f32_16x16x32_bf16 v[88:91], v[144:147], v[184:187], v[88:91]
	v_mfma_f32_16x16x32_bf16 v[88:91], v[140:143], v[180:183], v[88:91]
	v_mfma_f32_16x16x32_bf16 v[96:99], v[140:143], v[194:197], v[96:99]
	v_mfma_f32_16x16x32_bf16 v[96:99], v[144:147], v[198:201], v[96:99]
	v_mfma_f32_16x16x32_bf16 v[92:95], v[136:139], v[198:201], v[92:95]
	v_mfma_f32_16x16x32_bf16 v[92:95], v[132:135], v[194:197], v[92:95]
	s_setprio 0
	s_setprio 1
	v_mfma_f32_16x16x32_bf16 v[100:103], v[148:151], v[164:167], v[100:103]
	v_mfma_f32_16x16x32_bf16 v[100:103], v[152:155], v[168:171], v[100:103]
	v_mfma_f32_16x16x32_bf16 v[104:107], v[160:163], v[168:171], v[104:107]
	v_mfma_f32_16x16x32_bf16 v[104:107], v[156:159], v[164:167], v[104:107]
	v_mfma_f32_16x16x32_bf16 v[112:115], v[156:159], v[172:175], v[112:115]
	v_mfma_f32_16x16x32_bf16 v[112:115], v[160:163], v[176:179], v[112:115]
	v_mfma_f32_16x16x32_bf16 v[108:111], v[152:155], v[176:179], v[108:111]
	v_mfma_f32_16x16x32_bf16 v[108:111], v[148:151], v[172:175], v[108:111]
	v_mfma_f32_16x16x32_bf16 v[116:119], v[148:151], v[180:183], v[116:119]
	v_mfma_f32_16x16x32_bf16 v[116:119], v[152:155], v[184:187], v[116:119]
	v_mfma_f32_16x16x32_bf16 v[120:123], v[160:163], v[184:187], v[120:123]
	v_mfma_f32_16x16x32_bf16 v[120:123], v[156:159], v[180:183], v[120:123]
	v_mfma_f32_16x16x32_bf16 v[128:131], v[156:159], v[194:197], v[128:131]
	v_mfma_f32_16x16x32_bf16 v[128:131], v[160:163], v[198:201], v[128:131]
	s_setprio 2
	s_barrier
	v_mfma_f32_16x16x32_bf16 v[124:127], v[152:155], v[198:201], v[124:127]
	v_mfma_f32_16x16x32_bf16 v[124:127], v[148:151], v[194:197], v[124:127]
	s_setprio 0
	s_add_i32 s28, s28, 2
	s_add_u32 s14, s14, 0x100
	s_addc_u32 s15, s15, 0
	s_add_u32 s26, s26, 0x100
	s_addc_u32 s27, s27, 0
	s_cmp_gt_u32 s28, 29
	s_cbranch_scc0 .LBB0_1629
	s_and_b64 vcc, exec, s[48:49]
	s_cbranch_vccz .LBB0_1632
	s_barrier

.LBB0_2065:
	s_add_i32 s51, 0, 0x10000
	s_add_i32 s71, 0, 0x14000
	v_add_u32_e32 v16, s51, v232
	v_add_u32_e32 v32, s71, v232
	ds_read_b128 v[4:7], v16
	ds_read_b128 v[8:11], v16 offset:1024
	ds_read_b128 v[12:15], v16 offset:2048
	ds_read_b128 v[16:19], v16 offset:3072
	ds_read_b128 v[20:23], v32
	ds_read_b128 v[24:27], v32 offset:1024
	ds_read_b128 v[28:31], v32 offset:2048
	ds_read_b128 v[32:35], v32 offset:3072
	v_add_u32_e32 v233, 0, v231
	ds_read_b128 v[36:39], v233
	ds_read_b128 v[40:43], v233 offset:1024
	ds_read_b128 v[44:47], v233 offset:2048
	ds_read_b128 v[48:51], v233 offset:3072
	ds_read_b128 v[52:55], v233 offset:4096
	ds_read_b128 v[56:59], v233 offset:5120
	ds_read_b128 v[60:63], v233 offset:6144
	ds_read_b128 v[64:67], v233 offset:7168
	s_waitcnt vmcnt(8)
	s_waitcnt lgkmcnt(0)
	s_barrier
	s_setprio 1
	s_waitcnt lgkmcnt(0)
	s_nop 0
	v_mfma_f32_16x16x32_bf16 v[68:71], v[4:7], v[36:39], 0
	v_mfma_f32_16x16x32_bf16 v[68:71], v[8:11], v[40:43], v[68:71]
	v_mfma_f32_16x16x32_bf16 v[72:75], v[12:15], v[36:39], 0
	v_mfma_f32_16x16x32_bf16 v[72:75], v[16:19], v[40:43], v[72:75]
	v_mfma_f32_16x16x32_bf16 v[80:83], v[12:15], v[44:47], 0
	v_mfma_f32_16x16x32_bf16 v[80:83], v[16:19], v[48:51], v[80:83]
	v_mfma_f32_16x16x32_bf16 v[76:79], v[4:7], v[44:47], 0
	v_mfma_f32_16x16x32_bf16 v[76:79], v[8:11], v[48:51], v[76:79]
	v_mfma_f32_16x16x32_bf16 v[84:87], v[4:7], v[52:55], 0
	v_mfma_f32_16x16x32_bf16 v[84:87], v[8:11], v[56:59], v[84:87]
	v_mfma_f32_16x16x32_bf16 v[88:91], v[12:15], v[52:55], 0
	v_mfma_f32_16x16x32_bf16 v[88:91], v[16:19], v[56:59], v[88:91]
	v_mfma_f32_16x16x32_bf16 v[96:99], v[12:15], v[60:63], 0
	v_mfma_f32_16x16x32_bf16 v[96:99], v[16:19], v[64:67], v[96:99]
	v_mfma_f32_16x16x32_bf16 v[92:95], v[4:7], v[60:63], 0
	v_mfma_f32_16x16x32_bf16 v[92:95], v[8:11], v[64:67], v[92:95]
	s_setprio 0
	s_setprio 1
	v_mfma_f32_16x16x32_bf16 v[100:103], v[20:23], v[36:39], 0
	v_mfma_f32_16x16x32_bf16 v[36:39], v[28:31], v[36:39], 0
	v_mfma_f32_16x16x32_bf16 v[104:107], v[20:23], v[44:47], 0
	v_mfma_f32_16x16x32_bf16 v[44:47], v[28:31], v[44:47], 0
	v_mfma_f32_16x16x32_bf16 v[108:111], v[20:23], v[52:55], 0
	v_mfma_f32_16x16x32_bf16 v[52:55], v[28:31], v[52:55], 0
	v_mfma_f32_16x16x32_bf16 v[112:115], v[20:23], v[60:63], 0
	v_mfma_f32_16x16x32_bf16 v[60:63], v[28:31], v[60:63], 0
	v_mfma_f32_16x16x32_bf16 v[100:103], v[24:27], v[40:43], v[100:103]
	v_mfma_f32_16x16x32_bf16 v[40:43], v[32:35], v[40:43], v[36:39]
	v_mfma_f32_16x16x32_bf16 v[104:107], v[24:27], v[48:51], v[104:107]
	v_mfma_f32_16x16x32_bf16 v[48:51], v[32:35], v[48:51], v[44:47]
	v_mfma_f32_16x16x32_bf16 v[108:111], v[24:27], v[56:59], v[108:111]
	v_mfma_f32_16x16x32_bf16 v[56:59], v[32:35], v[56:59], v[52:55]
	s_setprio 2
	s_barrier
	v_mfma_f32_16x16x32_bf16 v[112:115], v[24:27], v[64:67], v[112:115]
	v_mfma_f32_16x16x32_bf16 v[64:67], v[32:35], v[64:67], v[60:63]
	s_setprio 0
	v_lshl_add_u64 v[186:187], s[12:13], 0, v[2:3]
	s_add_i32 s51, s51, s38
	v_mov_b32_e32 v191, v3
	v_lshl_add_u64 v[134:135], v[186:187], 0, s[74:75]
	s_mov_b32 m0, s51
	v_lshl_add_u64 v[246:247], s[12:13], 0, v[190:191]
	ds_read_b128 v[36:39], v233 offset:16384
	ds_read_b128 v[44:47], v233 offset:17408
	ds_read_b128 v[52:55], v233 offset:18432
	ds_read_b128 v[60:63], v233 offset:19456
	ds_read_b128 v[116:119], v233 offset:20480
	ds_read_b128 v[120:123], v233 offset:21504
	ds_read_b128 v[124:127], v233 offset:22528
	ds_read_b128 v[128:131], v233 offset:23552
	global_load_lds_dwordx4 v[134:135], off
	v_lshl_add_u64 v[134:135], v[246:247], 0, s[74:75]
	s_add_i32 m0, s51, 0x2000
	s_add_i32 s51, s71, s38
	global_load_lds_dwordx4 v[134:135], off
	s_mov_b32 m0, s51
	v_mov_b32_e32 v133, v3
	global_load_lds_dwordx4 v2, s[16:17]
	s_add_i32 m0, s51, 0x2000
	v_lshl_add_u64 v[248:249], s[14:15], 0, v[132:133]
	v_mov_b32_e32 v189, v3
	global_load_lds_dwordx4 v190, s[16:17]
	v_lshl_add_u64 v[134:135], v[248:249], 0, s[74:75]
	s_mov_b32 m0, s56
	v_lshl_add_u64 v[250:251], s[14:15], 0, v[188:189]
	global_load_lds_dwordx4 v[134:135], off
	v_lshl_add_u64 v[134:135], v[250:251], 0, s[74:75]
	s_mov_b32 m0, s57
	s_nop 0
	global_load_lds_dwordx4 v[134:135], off
	s_waitcnt vmcnt(8)
	s_waitcnt lgkmcnt(0)
	s_barrier
	s_setprio 1
	s_waitcnt lgkmcnt(0)
	s_nop 0
	v_mfma_f32_16x16x32_bf16 v[134:137], v[4:7], v[36:39], 0
	v_mfma_f32_16x16x32_bf16 v[138:141], v[12:15], v[36:39], 0
	v_mfma_f32_16x16x32_bf16 v[142:145], v[4:7], v[52:55], 0
	v_mfma_f32_16x16x32_bf16 v[146:149], v[12:15], v[52:55], 0
	v_mfma_f32_16x16x32_bf16 v[150:153], v[4:7], v[116:119], 0
	v_mfma_f32_16x16x32_bf16 v[154:157], v[12:15], v[116:119], 0
	v_mfma_f32_16x16x32_bf16 v[4:7], v[4:7], v[124:127], 0
	v_mfma_f32_16x16x32_bf16 v[12:15], v[12:15], v[124:127], 0
	v_mfma_f32_16x16x32_bf16 v[134:137], v[8:11], v[44:47], v[134:137]
	v_mfma_f32_16x16x32_bf16 v[138:141], v[16:19], v[44:47], v[138:141]
	v_mfma_f32_16x16x32_bf16 v[142:145], v[8:11], v[60:63], v[142:145]
	v_mfma_f32_16x16x32_bf16 v[146:149], v[16:19], v[60:63], v[146:149]
	v_mfma_f32_16x16x32_bf16 v[150:153], v[8:11], v[120:123], v[150:153]
	v_mfma_f32_16x16x32_bf16 v[154:157], v[16:19], v[120:123], v[154:157]
	v_mfma_f32_16x16x32_bf16 v[158:161], v[8:11], v[128:131], v[4:7]
	v_mfma_f32_16x16x32_bf16 v[162:165], v[16:19], v[128:131], v[12:15]
	s_setprio 0
	s_setprio 1
	v_mfma_f32_16x16x32_bf16 v[4:7], v[20:23], v[36:39], 0
	v_mfma_f32_16x16x32_bf16 v[8:11], v[28:31], v[36:39], 0
	v_mfma_f32_16x16x32_bf16 v[12:15], v[20:23], v[52:55], 0
	v_mfma_f32_16x16x32_bf16 v[16:19], v[28:31], v[52:55], 0
	v_mfma_f32_16x16x32_bf16 v[36:39], v[20:23], v[116:119], 0
	v_mfma_f32_16x16x32_bf16 v[52:55], v[28:31], v[116:119], 0
	v_mfma_f32_16x16x32_bf16 v[20:23], v[20:23], v[124:127], 0
	v_mfma_f32_16x16x32_bf16 v[28:31], v[28:31], v[124:127], 0
	v_mfma_f32_16x16x32_bf16 v[116:119], v[24:27], v[44:47], v[4:7]
	v_mfma_f32_16x16x32_bf16 v[124:127], v[32:35], v[44:47], v[8:11]
	v_mfma_f32_16x16x32_bf16 v[174:177], v[24:27], v[120:123], v[36:39]
	v_mfma_f32_16x16x32_bf16 v[120:123], v[32:35], v[120:123], v[52:55]
	v_mfma_f32_16x16x32_bf16 v[178:181], v[24:27], v[128:131], v[20:23]
	v_mfma_f32_16x16x32_bf16 v[128:131], v[32:35], v[128:131], v[28:31]
	s_setprio 2
	s_barrier
	v_mfma_f32_16x16x32_bf16 v[166:169], v[24:27], v[60:63], v[12:15]
	v_mfma_f32_16x16x32_bf16 v[170:173], v[32:35], v[60:63], v[16:19]
	s_setprio 0
	s_add_i32 s51, 0, 0x18000
	v_add_u32_e32 v4, s51, v232
	s_add_i32 s71, 0, 0x1c000
	ds_read_b128 v[182:185], v4
	ds_read_b128 v[192:195], v4 offset:1024
	ds_read_b128 v[196:199], v4 offset:2048
	ds_read_b128 v[200:203], v4 offset:3072
	v_add_u32_e32 v4, s71, v232
	ds_read_b128 v[204:207], v4
	ds_read_b128 v[208:211], v4 offset:1024
	ds_read_b128 v[212:215], v4 offset:2048
	ds_read_b128 v[216:219], v4 offset:3072
	s_mov_b32 m0, s58
	ds_read_b128 v[44:47], v233 offset:32768
	ds_read_b128 v[52:55], v233 offset:33792
	ds_read_b128 v[60:63], v233 offset:34816
	ds_read_b128 v[220:223], v233 offset:35840
	ds_read_b128 v[224:227], v233 offset:36864
	ds_read_b128 v[234:237], v233 offset:37888
	ds_read_b128 v[238:241], v233 offset:38912
	ds_read_b128 v[242:245], v233 offset:39936
	global_load_lds_dwordx4 v132, s[26:27]
	s_mov_b32 m0, s59
	s_nop 0
	global_load_lds_dwordx4 v188, s[26:27]
	s_waitcnt vmcnt(8)
	s_waitcnt lgkmcnt(0)
	s_barrier
	s_setprio 1
	s_waitcnt lgkmcnt(0)
	s_nop 0
	v_mfma_f32_16x16x32_bf16 v[4:7], v[182:185], v[44:47], v[68:71]
	v_mfma_f32_16x16x32_bf16 v[8:11], v[196:199], v[44:47], v[72:75]
	v_mfma_f32_16x16x32_bf16 v[12:15], v[182:185], v[60:63], v[76:79]
	v_mfma_f32_16x16x32_bf16 v[16:19], v[196:199], v[60:63], v[80:83]
	v_mfma_f32_16x16x32_bf16 v[20:23], v[182:185], v[224:227], v[84:87]
	v_mfma_f32_16x16x32_bf16 v[24:27], v[196:199], v[224:227], v[88:91]
	v_mfma_f32_16x16x32_bf16 v[28:31], v[182:185], v[238:241], v[92:95]
	v_mfma_f32_16x16x32_bf16 v[32:35], v[196:199], v[238:241], v[96:99]
	v_mfma_f32_16x16x32_bf16 v[4:7], v[192:195], v[52:55], v[4:7]
	v_mfma_f32_16x16x32_bf16 v[8:11], v[200:203], v[52:55], v[8:11]
	v_mfma_f32_16x16x32_bf16 v[12:15], v[192:195], v[220:223], v[12:15]
	v_mfma_f32_16x16x32_bf16 v[16:19], v[200:203], v[220:223], v[16:19]
	v_mfma_f32_16x16x32_bf16 v[20:23], v[192:195], v[234:237], v[20:23]
	v_mfma_f32_16x16x32_bf16 v[24:27], v[200:203], v[234:237], v[24:27]
	v_mfma_f32_16x16x32_bf16 v[28:31], v[192:195], v[242:245], v[28:31]
	v_mfma_f32_16x16x32_bf16 v[32:35], v[200:203], v[242:245], v[32:35]
	s_setprio 0
	s_setprio 1
	v_mfma_f32_16x16x32_bf16 v[36:39], v[204:207], v[44:47], v[100:103]
	v_mfma_f32_16x16x32_bf16 v[40:43], v[212:215], v[44:47], v[40:43]
	v_mfma_f32_16x16x32_bf16 v[36:39], v[208:211], v[52:55], v[36:39]
	v_mfma_f32_16x16x32_bf16 v[40:43], v[216:219], v[52:55], v[40:43]
	v_mfma_f32_16x16x32_bf16 v[44:47], v[204:207], v[60:63], v[104:107]
	v_mfma_f32_16x16x32_bf16 v[48:51], v[212:215], v[60:63], v[48:51]
	v_mfma_f32_16x16x32_bf16 v[52:55], v[204:207], v[224:227], v[108:111]
	v_mfma_f32_16x16x32_bf16 v[56:59], v[212:215], v[224:227], v[56:59]
	v_mfma_f32_16x16x32_bf16 v[60:63], v[204:207], v[238:241], v[112:115]
	v_mfma_f32_16x16x32_bf16 v[64:67], v[212:215], v[238:241], v[64:67]
	v_mfma_f32_16x16x32_bf16 v[44:47], v[208:211], v[220:223], v[44:47]
	v_mfma_f32_16x16x32_bf16 v[48:51], v[216:219], v[220:223], v[48:51]
	v_mfma_f32_16x16x32_bf16 v[52:55], v[208:211], v[234:237], v[52:55]
	v_mfma_f32_16x16x32_bf16 v[56:59], v[216:219], v[234:237], v[56:59]
	s_setprio 2
	s_barrier
	v_mfma_f32_16x16x32_bf16 v[60:63], v[208:211], v[242:245], v[60:63]
	v_mfma_f32_16x16x32_bf16 v[64:67], v[216:219], v[242:245], v[64:67]
	s_setprio 0
	s_add_i32 s51, s51, s38
	v_lshl_add_u64 v[68:69], v[186:187], 0, s[24:25]
	s_mov_b32 m0, s51
	ds_read_b128 v[104:107], v233 offset:49152
	ds_read_b128 v[108:111], v233 offset:50176
	ds_read_b128 v[112:115], v233 offset:51200
	ds_read_b128 v[220:223], v233 offset:52224
	ds_read_b128 v[224:227], v233 offset:53248
	ds_read_b128 v[234:237], v233 offset:54272
	ds_read_b128 v[238:241], v233 offset:55296
	ds_read_b128 v[242:245], v233 offset:56320
	global_load_lds_dwordx4 v[68:69], off
	v_lshl_add_u64 v[68:69], v[246:247], 0, s[24:25]
	s_add_i32 m0, s51, 0x2000
	s_add_i32 s51, s71, s38
	global_load_lds_dwordx4 v[68:69], off
	s_mov_b32 m0, s51
	v_lshl_add_u64 v[68:69], v[248:249], 0, s[24:25]
	global_load_lds_dwordx4 v2, s[28:29]
	s_add_i32 m0, s51, 0x2000
	s_nop 0
	global_load_lds_dwordx4 v190, s[28:29]
	s_mov_b32 m0, s63
	s_nop 0
	global_load_lds_dwordx4 v[68:69], off
	v_lshl_add_u64 v[68:69], v[250:251], 0, s[24:25]
	s_mov_b32 m0, s64
	s_nop 0
	global_load_lds_dwordx4 v[68:69], off
	s_waitcnt vmcnt(8)
	s_waitcnt lgkmcnt(0)
	s_barrier
	s_setprio 1
	s_waitcnt lgkmcnt(0)
	s_nop 0
	v_mfma_f32_16x16x32_bf16 v[68:71], v[182:185], v[104:107], v[134:137]
	v_mfma_f32_16x16x32_bf16 v[72:75], v[196:199], v[104:107], v[138:141]
	v_mfma_f32_16x16x32_bf16 v[76:79], v[182:185], v[112:115], v[142:145]
	v_mfma_f32_16x16x32_bf16 v[80:83], v[196:199], v[112:115], v[146:149]
	v_mfma_f32_16x16x32_bf16 v[84:87], v[182:185], v[224:227], v[150:153]
	v_mfma_f32_16x16x32_bf16 v[88:91], v[196:199], v[224:227], v[154:157]
	v_mfma_f32_16x16x32_bf16 v[92:95], v[182:185], v[238:241], v[158:161]
	v_mfma_f32_16x16x32_bf16 v[96:99], v[196:199], v[238:241], v[162:165]
	v_mfma_f32_16x16x32_bf16 v[68:71], v[192:195], v[108:111], v[68:71]
	v_mfma_f32_16x16x32_bf16 v[72:75], v[200:203], v[108:111], v[72:75]
	v_mfma_f32_16x16x32_bf16 v[76:79], v[192:195], v[220:223], v[76:79]
	v_mfma_f32_16x16x32_bf16 v[80:83], v[200:203], v[220:223], v[80:83]
	v_mfma_f32_16x16x32_bf16 v[84:87], v[192:195], v[234:237], v[84:87]
	v_mfma_f32_16x16x32_bf16 v[88:91], v[200:203], v[234:237], v[88:91]
	v_mfma_f32_16x16x32_bf16 v[92:95], v[192:195], v[242:245], v[92:95]
	v_mfma_f32_16x16x32_bf16 v[96:99], v[200:203], v[242:245], v[96:99]
	s_setprio 0
	s_setprio 1
	v_mfma_f32_16x16x32_bf16 v[100:103], v[204:207], v[104:107], v[116:119]
	v_mfma_f32_16x16x32_bf16 v[104:107], v[212:215], v[104:107], v[124:127]
	v_mfma_f32_16x16x32_bf16 v[100:103], v[208:211], v[108:111], v[100:103]
	v_mfma_f32_16x16x32_bf16 v[104:107], v[216:219], v[108:111], v[104:107]
	v_mfma_f32_16x16x32_bf16 v[108:111], v[204:207], v[112:115], v[166:169]
	v_mfma_f32_16x16x32_bf16 v[112:115], v[212:215], v[112:115], v[170:173]
	v_mfma_f32_16x16x32_bf16 v[116:119], v[204:207], v[224:227], v[174:177]
	v_mfma_f32_16x16x32_bf16 v[120:123], v[212:215], v[224:227], v[120:123]
	v_mfma_f32_16x16x32_bf16 v[124:127], v[204:207], v[238:241], v[178:181]
	v_mfma_f32_16x16x32_bf16 v[128:131], v[212:215], v[238:241], v[128:131]
	v_mfma_f32_16x16x32_bf16 v[108:111], v[208:211], v[220:223], v[108:111]
	v_mfma_f32_16x16x32_bf16 v[112:115], v[216:219], v[220:223], v[112:115]
	v_mfma_f32_16x16x32_bf16 v[116:119], v[208:211], v[234:237], v[116:119]
	v_mfma_f32_16x16x32_bf16 v[120:123], v[216:219], v[234:237], v[120:123]
	s_setprio 2
	s_barrier
	v_mfma_f32_16x16x32_bf16 v[124:127], v[208:211], v[242:245], v[124:127]
	v_mfma_f32_16x16x32_bf16 v[128:131], v[216:219], v[242:245], v[128:131]
	s_setprio 0
	s_add_i32 s45, s45, 2
	s_cmp_ge_i32 s45, s44
	s_cbranch_scc0 .LBB0_2065
	v_mov_b32_e32 v192, v2
	s_branch .LBB0_2068

.LBB0_2069:
	s_add_u32 s12, s14, 0xfff80080
	s_addc_u32 s13, s15, -1
	s_add_i32 s29, 0, 0x10000
	s_cmp_eq_u32 s28, 4
	s_cselect_b32 s17, s9, s13
	s_cselect_b32 s16, s8, s12
	s_cselect_b32 s13, s11, s27
	s_cselect_b32 s12, s10, s26
	s_add_i32 s51, 0, 0x14000
	v_add_u32_e32 v144, s29, v232
	v_add_u32_e32 v160, s51, v232
	s_waitcnt lgkmcnt(0)
	ds_read_b128 v[132:135], v144
	ds_read_b128 v[136:139], v144 offset:1024
	ds_read_b128 v[140:143], v144 offset:2048
	ds_read_b128 v[144:147], v144 offset:3072
	ds_read_b128 v[148:151], v160
	ds_read_b128 v[152:155], v160 offset:1024
	ds_read_b128 v[156:159], v160 offset:2048
	ds_read_b128 v[160:163], v160 offset:3072
	s_mov_b32 m0, s65
	v_add_u32_e32 v210, 0, v231
	ds_read_b128 v[164:167], v210
	ds_read_b128 v[168:171], v210 offset:1024
	ds_read_b128 v[172:175], v210 offset:2048
	ds_read_b128 v[176:179], v210 offset:3072
	ds_read_b128 v[180:183], v210 offset:4096
	ds_read_b128 v[184:187], v210 offset:5120
	ds_read_b128 v[194:197], v210 offset:6144
	ds_read_b128 v[198:201], v210 offset:7168
	global_load_lds_dwordx4 v2, s[14:15]
	s_mov_b32 m0, s66
	v_mov_b32_e32 v189, v3
	global_load_lds_dwordx4 v188, s[14:15]
	s_waitcnt vmcnt(8)
	s_waitcnt lgkmcnt(0)
	s_barrier
	s_setprio 1
	s_waitcnt lgkmcnt(0)
	s_nop 0
	v_mfma_f32_16x16x32_bf16 v[4:7], v[132:135], v[164:167], v[4:7]
	v_mfma_f32_16x16x32_bf16 v[4:7], v[136:139], v[168:171], v[4:7]
	v_mfma_f32_16x16x32_bf16 v[8:11], v[144:147], v[168:171], v[8:11]
	v_mfma_f32_16x16x32_bf16 v[8:11], v[140:143], v[164:167], v[8:11]
	v_mfma_f32_16x16x32_bf16 v[16:19], v[140:143], v[172:175], v[16:19]
	v_mfma_f32_16x16x32_bf16 v[16:19], v[144:147], v[176:179], v[16:19]
	v_mfma_f32_16x16x32_bf16 v[12:15], v[136:139], v[176:179], v[12:15]
	v_mfma_f32_16x16x32_bf16 v[12:15], v[132:135], v[172:175], v[12:15]
	v_mfma_f32_16x16x32_bf16 v[20:23], v[132:135], v[180:183], v[20:23]
	v_mfma_f32_16x16x32_bf16 v[20:23], v[136:139], v[184:187], v[20:23]
	v_mfma_f32_16x16x32_bf16 v[24:27], v[144:147], v[184:187], v[24:27]
	v_mfma_f32_16x16x32_bf16 v[24:27], v[140:143], v[180:183], v[24:27]
	v_mfma_f32_16x16x32_bf16 v[32:35], v[140:143], v[194:197], v[32:35]
	v_mfma_f32_16x16x32_bf16 v[32:35], v[144:147], v[198:201], v[32:35]
	v_mfma_f32_16x16x32_bf16 v[28:31], v[136:139], v[198:201], v[28:31]
	v_mfma_f32_16x16x32_bf16 v[28:31], v[132:135], v[194:197], v[28:31]
	s_setprio 0
	s_setprio 1
	v_mfma_f32_16x16x32_bf16 v[36:39], v[148:151], v[164:167], v[36:39]
	v_mfma_f32_16x16x32_bf16 v[36:39], v[152:155], v[168:171], v[36:39]
	v_mfma_f32_16x16x32_bf16 v[40:43], v[160:163], v[168:171], v[40:43]
	v_mfma_f32_16x16x32_bf16 v[40:43], v[156:159], v[164:167], v[40:43]
	v_mfma_f32_16x16x32_bf16 v[48:51], v[156:159], v[172:175], v[48:51]
	v_mfma_f32_16x16x32_bf16 v[48:51], v[160:163], v[176:179], v[48:51]
	v_mfma_f32_16x16x32_bf16 v[44:47], v[152:155], v[176:179], v[44:47]
	v_mfma_f32_16x16x32_bf16 v[44:47], v[148:151], v[172:175], v[44:47]
	v_mfma_f32_16x16x32_bf16 v[52:55], v[148:151], v[180:183], v[52:55]
	v_mfma_f32_16x16x32_bf16 v[52:55], v[152:155], v[184:187], v[52:55]
	v_mfma_f32_16x16x32_bf16 v[56:59], v[160:163], v[184:187], v[56:59]
	v_mfma_f32_16x16x32_bf16 v[56:59], v[156:159], v[180:183], v[56:59]
	v_mfma_f32_16x16x32_bf16 v[64:67], v[156:159], v[194:197], v[64:67]
	v_mfma_f32_16x16x32_bf16 v[64:67], v[160:163], v[198:201], v[64:67]
	s_setprio 2
	s_barrier
	v_mfma_f32_16x16x32_bf16 v[60:63], v[152:155], v[198:201], v[60:63]
	v_mfma_f32_16x16x32_bf16 v[60:63], v[148:151], v[194:197], v[60:63]
	s_setprio 0
	s_add_i32 s29, s29, s38
	s_mov_b32 m0, s29
	ds_read_b128 v[164:167], v210 offset:16384
	ds_read_b128 v[168:171], v210 offset:17408
	ds_read_b128 v[172:175], v210 offset:18432
	ds_read_b128 v[176:179], v210 offset:19456
	ds_read_b128 v[180:183], v210 offset:20480
	ds_read_b128 v[184:187], v210 offset:21504
	ds_read_b128 v[194:197], v210 offset:22528
	ds_read_b128 v[198:201], v210 offset:23552
	global_load_lds_dwordx4 v192, s[12:13]
	s_add_i32 m0, s29, 0x2000
	s_add_u32 s44, s12, 0x20000
	s_addc_u32 s45, s13, 0
	s_add_i32 s29, s51, s38
	global_load_lds_dwordx4 v190, s[12:13]
	s_mov_b32 m0, s29
	v_mov_b32_e32 v193, v3
	global_load_lds_dwordx4 v192, s[44:45]
	s_add_i32 m0, s29, 0x2000
	v_mov_b32_e32 v191, v3
	global_load_lds_dwordx4 v190, s[44:45]
	s_mov_b32 m0, s56
	v_lshl_add_u64 v[202:203], s[12:13], 0, v[192:193]
	global_load_lds_dwordx4 v2, s[16:17]
	s_mov_b32 m0, s57
	v_lshl_add_u64 v[204:205], s[12:13], 0, v[190:191]
	global_load_lds_dwordx4 v188, s[16:17]
	s_waitcnt vmcnt(8)
	s_waitcnt lgkmcnt(0)
	v_lshl_add_u64 v[206:207], s[16:17], 0, v[2:3]
	v_lshl_add_u64 v[208:209], s[16:17], 0, v[188:189]
	s_barrier
	s_setprio 1
	s_waitcnt lgkmcnt(0)
	s_nop 0
	v_mfma_f32_16x16x32_bf16 v[68:71], v[132:135], v[164:167], v[68:71]
	v_mfma_f32_16x16x32_bf16 v[68:71], v[136:139], v[168:171], v[68:71]
	v_mfma_f32_16x16x32_bf16 v[72:75], v[144:147], v[168:171], v[72:75]
	v_mfma_f32_16x16x32_bf16 v[72:75], v[140:143], v[164:167], v[72:75]
	v_mfma_f32_16x16x32_bf16 v[80:83], v[140:143], v[172:175], v[80:83]
	v_mfma_f32_16x16x32_bf16 v[80:83], v[144:147], v[176:179], v[80:83]
	v_mfma_f32_16x16x32_bf16 v[76:79], v[136:139], v[176:179], v[76:79]
	v_mfma_f32_16x16x32_bf16 v[76:79], v[132:135], v[172:175], v[76:79]
	v_mfma_f32_16x16x32_bf16 v[84:87], v[132:135], v[180:183], v[84:87]
	v_mfma_f32_16x16x32_bf16 v[84:87], v[136:139], v[184:187], v[84:87]
	v_mfma_f32_16x16x32_bf16 v[88:91], v[144:147], v[184:187], v[88:91]
	v_mfma_f32_16x16x32_bf16 v[88:91], v[140:143], v[180:183], v[88:91]
	v_mfma_f32_16x16x32_bf16 v[96:99], v[140:143], v[194:197], v[96:99]
	v_mfma_f32_16x16x32_bf16 v[96:99], v[144:147], v[198:201], v[96:99]
	v_mfma_f32_16x16x32_bf16 v[92:95], v[136:139], v[198:201], v[92:95]
	v_mfma_f32_16x16x32_bf16 v[92:95], v[132:135], v[194:197], v[92:95]
	s_setprio 0
	s_setprio 1
	v_mfma_f32_16x16x32_bf16 v[100:103], v[148:151], v[164:167], v[100:103]
	v_mfma_f32_16x16x32_bf16 v[100:103], v[152:155], v[168:171], v[100:103]
	v_mfma_f32_16x16x32_bf16 v[104:107], v[160:163], v[168:171], v[104:107]
	v_mfma_f32_16x16x32_bf16 v[104:107], v[156:159], v[164:167], v[104:107]
	v_mfma_f32_16x16x32_bf16 v[112:115], v[156:159], v[172:175], v[112:115]
	v_mfma_f32_16x16x32_bf16 v[112:115], v[160:163], v[176:179], v[112:115]
	v_mfma_f32_16x16x32_bf16 v[108:111], v[152:155], v[176:179], v[108:111]
	v_mfma_f32_16x16x32_bf16 v[108:111], v[148:151], v[172:175], v[108:111]
	v_mfma_f32_16x16x32_bf16 v[116:119], v[148:151], v[180:183], v[116:119]
	v_mfma_f32_16x16x32_bf16 v[116:119], v[152:155], v[184:187], v[116:119]
	v_mfma_f32_16x16x32_bf16 v[120:123], v[160:163], v[184:187], v[120:123]
	v_mfma_f32_16x16x32_bf16 v[120:123], v[156:159], v[180:183], v[120:123]
	v_mfma_f32_16x16x32_bf16 v[128:131], v[156:159], v[194:197], v[128:131]
	v_mfma_f32_16x16x32_bf16 v[128:131], v[160:163], v[198:201], v[128:131]
	s_setprio 2
	s_barrier
	v_mfma_f32_16x16x32_bf16 v[124:127], v[152:155], v[198:201], v[124:127]
	v_mfma_f32_16x16x32_bf16 v[124:127], v[148:151], v[194:197], v[124:127]
	s_setprio 0
	s_add_i32 s29, 0, 0x18000
	s_add_i32 s44, 0, 0x1c000
	v_add_u32_e32 v144, s29, v232
	v_add_u32_e32 v160, s44, v232
	ds_read_b128 v[132:135], v144
	ds_read_b128 v[136:139], v144 offset:1024
	ds_read_b128 v[140:143], v144 offset:2048
	ds_read_b128 v[144:147], v144 offset:3072
	ds_read_b128 v[148:151], v160
	ds_read_b128 v[152:155], v160 offset:1024
	ds_read_b128 v[156:159], v160 offset:2048
	ds_read_b128 v[160:163], v160 offset:3072
	s_add_u32 s16, s16, 0x80000
	s_addc_u32 s17, s17, 0
	s_mov_b32 m0, s58
	ds_read_b128 v[164:167], v210 offset:32768
	ds_read_b128 v[168:171], v210 offset:33792
	ds_read_b128 v[172:175], v210 offset:34816
	ds_read_b128 v[176:179], v210 offset:35840
	ds_read_b128 v[180:183], v210 offset:36864
	ds_read_b128 v[184:187], v210 offset:37888
	ds_read_b128 v[194:197], v210 offset:38912
	ds_read_b128 v[198:201], v210 offset:39936
	global_load_lds_dwordx4 v2, s[16:17]
	s_mov_b32 m0, s59
	s_nop 0
	global_load_lds_dwordx4 v188, s[16:17]
	s_waitcnt vmcnt(8)
	s_waitcnt lgkmcnt(0)
	s_barrier
	s_setprio 1
	s_waitcnt lgkmcnt(0)
	s_nop 0
	v_mfma_f32_16x16x32_bf16 v[4:7], v[132:135], v[164:167], v[4:7]
	v_mfma_f32_16x16x32_bf16 v[4:7], v[136:139], v[168:171], v[4:7]
	v_mfma_f32_16x16x32_bf16 v[8:11], v[144:147], v[168:171], v[8:11]
	v_mfma_f32_16x16x32_bf16 v[8:11], v[140:143], v[164:167], v[8:11]
	v_mfma_f32_16x16x32_bf16 v[16:19], v[140:143], v[172:175], v[16:19]
	v_mfma_f32_16x16x32_bf16 v[16:19], v[144:147], v[176:179], v[16:19]
	v_mfma_f32_16x16x32_bf16 v[12:15], v[136:139], v[176:179], v[12:15]
	v_mfma_f32_16x16x32_bf16 v[12:15], v[132:135], v[172:175], v[12:15]
	v_mfma_f32_16x16x32_bf16 v[20:23], v[132:135], v[180:183], v[20:23]
	v_mfma_f32_16x16x32_bf16 v[20:23], v[136:139], v[184:187], v[20:23]
	v_mfma_f32_16x16x32_bf16 v[24:27], v[144:147], v[184:187], v[24:27]
	v_mfma_f32_16x16x32_bf16 v[24:27], v[140:143], v[180:183], v[24:27]
	v_mfma_f32_16x16x32_bf16 v[32:35], v[140:143], v[194:197], v[32:35]
	v_mfma_f32_16x16x32_bf16 v[32:35], v[144:147], v[198:201], v[32:35]
	v_mfma_f32_16x16x32_bf16 v[28:31], v[136:139], v[198:201], v[28:31]
	v_mfma_f32_16x16x32_bf16 v[28:31], v[132:135], v[194:197], v[28:31]
	s_setprio 0
	s_setprio 1
	v_mfma_f32_16x16x32_bf16 v[36:39], v[148:151], v[164:167], v[36:39]
	v_mfma_f32_16x16x32_bf16 v[36:39], v[152:155], v[168:171], v[36:39]
	v_mfma_f32_16x16x32_bf16 v[40:43], v[160:163], v[168:171], v[40:43]
	v_mfma_f32_16x16x32_bf16 v[40:43], v[156:159], v[164:167], v[40:43]
	v_mfma_f32_16x16x32_bf16 v[48:51], v[156:159], v[172:175], v[48:51]
	v_mfma_f32_16x16x32_bf16 v[48:51], v[160:163], v[176:179], v[48:51]
	v_mfma_f32_16x16x32_bf16 v[44:47], v[152:155], v[176:179], v[44:47]
	v_mfma_f32_16x16x32_bf16 v[44:47], v[148:151], v[172:175], v[44:47]
	v_mfma_f32_16x16x32_bf16 v[52:55], v[148:151], v[180:183], v[52:55]
	v_mfma_f32_16x16x32_bf16 v[52:55], v[152:155], v[184:187], v[52:55]
	v_mfma_f32_16x16x32_bf16 v[56:59], v[160:163], v[184:187], v[56:59]
	v_mfma_f32_16x16x32_bf16 v[56:59], v[156:159], v[180:183], v[56:59]
	v_mfma_f32_16x16x32_bf16 v[64:67], v[156:159], v[194:197], v[64:67]
	v_mfma_f32_16x16x32_bf16 v[64:67], v[160:163], v[198:201], v[64:67]
	s_setprio 2
	s_barrier
	v_mfma_f32_16x16x32_bf16 v[60:63], v[152:155], v[198:201], v[60:63]
	v_mfma_f32_16x16x32_bf16 v[60:63], v[148:151], v[194:197], v[60:63]
	s_setprio 0
	s_add_i32 s16, s29, s38
	v_lshl_add_u64 v[202:203], v[202:203], 0, s[86:87]
	s_mov_b32 m0, s16
	ds_read_b128 v[164:167], v210 offset:49152
	ds_read_b128 v[168:171], v210 offset:50176
	ds_read_b128 v[172:175], v210 offset:51200
	ds_read_b128 v[176:179], v210 offset:52224
	ds_read_b128 v[180:183], v210 offset:53248
	ds_read_b128 v[184:187], v210 offset:54272
	ds_read_b128 v[194:197], v210 offset:55296
	ds_read_b128 v[198:201], v210 offset:56320
	global_load_lds_dwordx4 v[202:203], off
	s_add_i32 m0, s16, 0x2000
	s_add_u32 s12, s12, 0x20080
	v_lshl_add_u64 v[202:203], v[204:205], 0, s[86:87]
	s_addc_u32 s13, s13, 0
	s_add_i32 s16, s44, s38
	global_load_lds_dwordx4 v[202:203], off
	s_mov_b32 m0, s16
	v_lshl_add_u64 v[202:203], v[206:207], 0, s[86:87]
	global_load_lds_dwordx4 v192, s[12:13]
	s_add_i32 m0, s16, 0x2000
	s_nop 0
	global_load_lds_dwordx4 v190, s[12:13]
	s_mov_b32 m0, s63
	s_nop 0
	global_load_lds_dwordx4 v[202:203], off
	v_lshl_add_u64 v[202:203], v[208:209], 0, s[86:87]
	s_mov_b32 m0, s64
	s_nop 0
	global_load_lds_dwordx4 v[202:203], off
	s_waitcnt vmcnt(8)
	s_waitcnt lgkmcnt(0)
	s_barrier
	s_setprio 1
	s_waitcnt lgkmcnt(0)
	s_nop 0
	v_mfma_f32_16x16x32_bf16 v[68:71], v[132:135], v[164:167], v[68:71]
	v_mfma_f32_16x16x32_bf16 v[68:71], v[136:139], v[168:171], v[68:71]
	v_mfma_f32_16x16x32_bf16 v[72:75], v[144:147], v[168:171], v[72:75]
	v_mfma_f32_16x16x32_bf16 v[72:75], v[140:143], v[164:167], v[72:75]
	v_mfma_f32_16x16x32_bf16 v[80:83], v[140:143], v[172:175], v[80:83]
	v_mfma_f32_16x16x32_bf16 v[80:83], v[144:147], v[176:179], v[80:83]
	v_mfma_f32_16x16x32_bf16 v[76:79], v[136:139], v[176:179], v[76:79]
	v_mfma_f32_16x16x32_bf16 v[76:79], v[132:135], v[172:175], v[76:79]
	v_mfma_f32_16x16x32_bf16 v[84:87], v[132:135], v[180:183], v[84:87]
	v_mfma_f32_16x16x32_bf16 v[84:87], v[136:139], v[184:187], v[84:87]
	v_mfma_f32_16x16x32_bf16 v[88:91], v[144:147], v[184:187], v[88:91]
	v_mfma_f32_16x16x32_bf16 v[88:91], v[140:143], v[180:183], v[88:91]
	v_mfma_f32_16x16x32_bf16 v[96:99], v[140:143], v[194:197], v[96:99]
	v_mfma_f32_16x16x32_bf16 v[96:99], v[144:147], v[198:201], v[96:99]
	v_mfma_f32_16x16x32_bf16 v[92:95], v[136:139], v[198:201], v[92:95]
	v_mfma_f32_16x16x32_bf16 v[92:95], v[132:135], v[194:197], v[92:95]
	s_setprio 0
	s_setprio 1
	v_mfma_f32_16x16x32_bf16 v[100:103], v[148:151], v[164:167], v[100:103]
	v_mfma_f32_16x16x32_bf16 v[100:103], v[152:155], v[168:171], v[100:103]
	v_mfma_f32_16x16x32_bf16 v[104:107], v[160:163], v[168:171], v[104:107]
	v_mfma_f32_16x16x32_bf16 v[104:107], v[156:159], v[164:167], v[104:107]
	v_mfma_f32_16x16x32_bf16 v[112:115], v[156:159], v[172:175], v[112:115]
	v_mfma_f32_16x16x32_bf16 v[112:115], v[160:163], v[176:179], v[112:115]
	v_mfma_f32_16x16x32_bf16 v[108:111], v[152:155], v[176:179], v[108:111]
	v_mfma_f32_16x16x32_bf16 v[108:111], v[148:151], v[172:175], v[108:111]
	v_mfma_f32_16x16x32_bf16 v[116:119], v[148:151], v[180:183], v[116:119]
	v_mfma_f32_16x16x32_bf16 v[116:119], v[152:155], v[184:187], v[116:119]
	v_mfma_f32_16x16x32_bf16 v[120:123], v[160:163], v[184:187], v[120:123]
	v_mfma_f32_16x16x32_bf16 v[120:123], v[156:159], v[180:183], v[120:123]
	v_mfma_f32_16x16x32_bf16 v[128:131], v[156:159], v[194:197], v[128:131]
	v_mfma_f32_16x16x32_bf16 v[128:131], v[160:163], v[198:201], v[128:131]
	s_setprio 2
	s_barrier
	v_mfma_f32_16x16x32_bf16 v[124:127], v[152:155], v[198:201], v[124:127]
	v_mfma_f32_16x16x32_bf16 v[124:127], v[148:151], v[194:197], v[124:127]
	s_setprio 0
	s_add_i32 s28, s28, 2
	s_add_u32 s14, s14, 0x100
	s_addc_u32 s15, s15, 0
	s_add_u32 s26, s26, 0x100
	s_addc_u32 s27, s27, 0
	s_cmp_gt_u32 s28, 5
	s_cbranch_scc0 .LBB0_2069
	s_and_b64 vcc, exec, s[48:49]
	s_cbranch_vccz .LBB0_2072
	s_barrier

.LBB0_2159:
	s_add_i32 s68, 0, 0x10000
	s_add_i32 s69, 0, 0x14000
	v_add_u32_e32 v16, s68, v143
	v_add_u32_e32 v32, s69, v143
	ds_read_b128 v[4:7], v16
	ds_read_b128 v[8:11], v16 offset:1024
	ds_read_b128 v[12:15], v16 offset:2048
	ds_read_b128 v[16:19], v16 offset:3072
	ds_read_b128 v[20:23], v32
	ds_read_b128 v[24:27], v32 offset:1024
	ds_read_b128 v[28:31], v32 offset:2048
	ds_read_b128 v[32:35], v32 offset:3072
	v_add_u32_e32 v231, 0, v142
	ds_read_b128 v[36:39], v231
	ds_read_b128 v[40:43], v231 offset:1024
	ds_read_b128 v[44:47], v231 offset:2048
	ds_read_b128 v[48:51], v231 offset:3072
	ds_read_b128 v[52:55], v231 offset:4096
	ds_read_b128 v[56:59], v231 offset:5120
	ds_read_b128 v[60:63], v231 offset:6144
	ds_read_b128 v[64:67], v231 offset:7168
	s_waitcnt vmcnt(8)
	s_waitcnt lgkmcnt(0)
	s_barrier
	s_setprio 1
	s_waitcnt lgkmcnt(0)
	s_nop 0
	v_mfma_f32_16x16x32_f16 v[68:71], v[4:7], v[36:39], 0
	v_mfma_f32_16x16x32_f16 v[72:75], v[12:15], v[36:39], 0
	v_mfma_f32_16x16x32_f16 v[76:79], v[4:7], v[44:47], 0
	v_mfma_f32_16x16x32_f16 v[80:83], v[12:15], v[44:47], 0
	v_mfma_f32_16x16x32_f16 v[84:87], v[4:7], v[52:55], 0
	v_mfma_f32_16x16x32_f16 v[88:91], v[12:15], v[52:55], 0
	v_mfma_f32_16x16x32_f16 v[92:95], v[4:7], v[60:63], 0
	v_mfma_f32_16x16x32_f16 v[96:99], v[12:15], v[60:63], 0
	v_mfma_f32_16x16x32_f16 v[68:71], v[8:11], v[40:43], v[68:71]
	v_mfma_f32_16x16x32_f16 v[72:75], v[16:19], v[40:43], v[72:75]
	v_mfma_f32_16x16x32_f16 v[76:79], v[8:11], v[48:51], v[76:79]
	v_mfma_f32_16x16x32_f16 v[80:83], v[16:19], v[48:51], v[80:83]
	v_mfma_f32_16x16x32_f16 v[84:87], v[8:11], v[56:59], v[84:87]
	v_mfma_f32_16x16x32_f16 v[88:91], v[16:19], v[56:59], v[88:91]
	v_mfma_f32_16x16x32_f16 v[92:95], v[8:11], v[64:67], v[92:95]
	v_mfma_f32_16x16x32_f16 v[100:103], v[16:19], v[64:67], v[96:99]
	s_setprio 0
	s_setprio 1
	v_mfma_f32_16x16x32_f16 v[96:99], v[20:23], v[36:39], 0
	v_mfma_f32_16x16x32_f16 v[36:39], v[28:31], v[36:39], 0
	v_mfma_f32_16x16x32_f16 v[104:107], v[20:23], v[44:47], 0
	v_mfma_f32_16x16x32_f16 v[44:47], v[28:31], v[44:47], 0
	v_mfma_f32_16x16x32_f16 v[108:111], v[20:23], v[52:55], 0
	v_mfma_f32_16x16x32_f16 v[52:55], v[28:31], v[52:55], 0
	v_mfma_f32_16x16x32_f16 v[112:115], v[20:23], v[60:63], 0
	v_mfma_f32_16x16x32_f16 v[60:63], v[28:31], v[60:63], 0
	v_mfma_f32_16x16x32_f16 v[116:119], v[24:27], v[40:43], v[96:99]
	v_mfma_f32_16x16x32_f16 v[36:39], v[32:35], v[40:43], v[36:39]
	v_mfma_f32_16x16x32_f16 v[40:43], v[24:27], v[48:51], v[104:107]
	v_mfma_f32_16x16x32_f16 v[44:47], v[32:35], v[48:51], v[44:47]
	v_mfma_f32_16x16x32_f16 v[48:51], v[24:27], v[56:59], v[108:111]
	v_mfma_f32_16x16x32_f16 v[52:55], v[32:35], v[56:59], v[52:55]
	s_setprio 2
	s_barrier
	v_mfma_f32_16x16x32_f16 v[56:59], v[24:27], v[64:67], v[112:115]
	v_mfma_f32_16x16x32_f16 v[60:63], v[32:35], v[64:67], v[60:63]
	s_setprio 0
	v_lshl_add_u64 v[138:139], s[8:9], 0, v[2:3]
	s_add_i32 s68, s68, s53
	v_mov_b32_e32 v135, v3
	v_lshl_add_u64 v[144:145], v[138:139], 0, s[74:75]
	s_mov_b32 m0, s68
	v_lshl_add_u64 v[192:193], s[8:9], 0, v[134:135]
	ds_read_b128 v[64:67], v231 offset:16384
	ds_read_b128 v[96:99], v231 offset:17408
	ds_read_b128 v[104:107], v231 offset:18432
	ds_read_b128 v[108:111], v231 offset:19456
	ds_read_b128 v[112:115], v231 offset:20480
	ds_read_b128 v[120:123], v231 offset:21504
	ds_read_b128 v[124:127], v231 offset:22528
	ds_read_b128 v[128:131], v231 offset:23552
	global_load_lds_dwordx4 v[144:145], off
	v_lshl_add_u64 v[144:145], v[192:193], 0, s[74:75]
	s_add_i32 m0, s68, 0x2000
	s_add_i32 s68, s69, s53
	global_load_lds_dwordx4 v[144:145], off
	s_mov_b32 m0, s68
	v_mov_b32_e32 v137, v3
	global_load_lds_dwordx4 v2, s[40:41]
	s_add_i32 m0, s68, 0x2000
	v_lshl_add_u64 v[248:249], s[6:7], 0, v[136:137]
	v_mov_b32_e32 v133, v3
	global_load_lds_dwordx4 v134, s[40:41]
	v_lshl_add_u64 v[144:145], v[248:249], 0, s[74:75]
	s_mov_b32 m0, s54
	v_lshl_add_u64 v[250:251], s[6:7], 0, v[132:133]
	global_load_lds_dwordx4 v[144:145], off
	v_lshl_add_u64 v[144:145], v[250:251], 0, s[74:75]
	s_mov_b32 m0, s55
	s_nop 0
	global_load_lds_dwordx4 v[144:145], off
	s_waitcnt vmcnt(8)
	s_waitcnt lgkmcnt(0)
	s_barrier
	s_setprio 1
	s_waitcnt lgkmcnt(0)
	s_nop 0
	v_mfma_f32_16x16x32_f16 v[144:147], v[4:7], v[64:67], 0
	v_mfma_f32_16x16x32_f16 v[148:151], v[12:15], v[64:67], 0
	v_mfma_f32_16x16x32_f16 v[152:155], v[4:7], v[104:107], 0
	v_mfma_f32_16x16x32_f16 v[156:159], v[12:15], v[104:107], 0
	v_mfma_f32_16x16x32_f16 v[160:163], v[4:7], v[112:115], 0
	v_mfma_f32_16x16x32_f16 v[164:167], v[12:15], v[112:115], 0
	v_mfma_f32_16x16x32_f16 v[4:7], v[4:7], v[124:127], 0
	v_mfma_f32_16x16x32_f16 v[12:15], v[12:15], v[124:127], 0
	v_mfma_f32_16x16x32_f16 v[144:147], v[8:11], v[96:99], v[144:147]
	v_mfma_f32_16x16x32_f16 v[152:155], v[8:11], v[108:111], v[152:155]
	v_mfma_f32_16x16x32_f16 v[160:163], v[8:11], v[120:123], v[160:163]
	v_mfma_f32_16x16x32_f16 v[4:7], v[8:11], v[128:131], v[4:7]
	v_mfma_f32_16x16x32_f16 v[8:11], v[16:19], v[128:131], v[12:15]
	v_mfma_f32_16x16x32_f16 v[148:151], v[16:19], v[96:99], v[148:151]
	v_mfma_f32_16x16x32_f16 v[156:159], v[16:19], v[108:111], v[156:159]
	v_mfma_f32_16x16x32_f16 v[164:167], v[16:19], v[120:123], v[164:167]
	s_setprio 0
	s_setprio 1
	v_mfma_f32_16x16x32_f16 v[12:15], v[20:23], v[64:67], 0
	v_mfma_f32_16x16x32_f16 v[16:19], v[28:31], v[64:67], 0
	v_mfma_f32_16x16x32_f16 v[64:67], v[20:23], v[104:107], 0
	v_mfma_f32_16x16x32_f16 v[104:107], v[28:31], v[104:107], 0
	v_mfma_f32_16x16x32_f16 v[168:171], v[20:23], v[112:115], 0
	v_mfma_f32_16x16x32_f16 v[112:115], v[28:31], v[112:115], 0
	v_mfma_f32_16x16x32_f16 v[20:23], v[20:23], v[124:127], 0
	v_mfma_f32_16x16x32_f16 v[28:31], v[28:31], v[124:127], 0
	v_mfma_f32_16x16x32_f16 v[12:15], v[24:27], v[96:99], v[12:15]
	v_mfma_f32_16x16x32_f16 v[172:175], v[32:35], v[96:99], v[16:19]
	v_mfma_f32_16x16x32_f16 v[176:179], v[24:27], v[108:111], v[64:67]
	v_mfma_f32_16x16x32_f16 v[180:183], v[32:35], v[108:111], v[104:107]
	v_mfma_f32_16x16x32_f16 v[168:171], v[24:27], v[120:123], v[168:171]
	v_mfma_f32_16x16x32_f16 v[184:187], v[32:35], v[120:123], v[112:115]
	s_setprio 2
	s_barrier
	v_mfma_f32_16x16x32_f16 v[188:191], v[24:27], v[128:131], v[20:23]
	v_mfma_f32_16x16x32_f16 v[196:199], v[32:35], v[128:131], v[28:31]
	s_setprio 0
	s_add_i32 s68, 0, 0x18000
	v_add_u32_e32 v24, s68, v143
	s_add_i32 s69, 0, 0x1c000
	ds_read_b128 v[16:19], v24
	ds_read_b128 v[20:23], v24 offset:1024
	ds_read_b128 v[28:31], v24 offset:2048
	ds_read_b128 v[200:203], v24 offset:3072
	v_add_u32_e32 v24, s69, v143
	ds_read_b128 v[204:207], v24
	ds_read_b128 v[208:211], v24 offset:1024
	ds_read_b128 v[212:215], v24 offset:2048
	ds_read_b128 v[216:219], v24 offset:3072
	s_mov_b32 m0, s56
	ds_read_b128 v[24:27], v231 offset:32768
	ds_read_b128 v[32:35], v231 offset:33792
	ds_read_b128 v[64:67], v231 offset:34816
	ds_read_b128 v[220:223], v231 offset:35840
	ds_read_b128 v[224:227], v231 offset:36864
	ds_read_b128 v[232:235], v231 offset:37888
	ds_read_b128 v[236:239], v231 offset:38912
	ds_read_b128 v[240:243], v231 offset:39936
	global_load_lds_dwordx4 v136, s[42:43]
	s_mov_b32 m0, s57
	s_nop 0
	global_load_lds_dwordx4 v132, s[42:43]
	s_waitcnt vmcnt(8)
	s_waitcnt lgkmcnt(0)
	s_barrier
	s_setprio 1
	s_waitcnt lgkmcnt(0)
	s_nop 0
	v_mfma_f32_16x16x32_f16 v[68:71], v[16:19], v[24:27], v[68:71]
	v_mfma_f32_16x16x32_f16 v[128:131], v[20:23], v[32:35], v[68:71]
	v_mfma_f32_16x16x32_f16 v[68:71], v[28:31], v[24:27], v[72:75]
	v_mfma_f32_16x16x32_f16 v[120:123], v[200:203], v[32:35], v[68:71]
	v_mfma_f32_16x16x32_f16 v[68:71], v[16:19], v[64:67], v[76:79]
	v_mfma_f32_16x16x32_f16 v[112:115], v[20:23], v[220:223], v[68:71]
	v_mfma_f32_16x16x32_f16 v[68:71], v[28:31], v[64:67], v[80:83]
	v_mfma_f32_16x16x32_f16 v[104:107], v[200:203], v[220:223], v[68:71]
	v_mfma_f32_16x16x32_f16 v[68:71], v[16:19], v[224:227], v[84:87]
	v_mfma_f32_16x16x32_f16 v[96:99], v[20:23], v[232:235], v[68:71]
	v_mfma_f32_16x16x32_f16 v[68:71], v[28:31], v[224:227], v[88:91]
	v_mfma_f32_16x16x32_f16 v[88:91], v[200:203], v[232:235], v[68:71]
	v_mfma_f32_16x16x32_f16 v[68:71], v[16:19], v[236:239], v[92:95]
	v_mfma_f32_16x16x32_f16 v[80:83], v[20:23], v[240:243], v[68:71]
	v_mfma_f32_16x16x32_f16 v[68:71], v[28:31], v[236:239], v[100:103]
	v_mfma_f32_16x16x32_f16 v[72:75], v[200:203], v[240:243], v[68:71]
	s_setprio 0
	s_setprio 1
	v_mfma_f32_16x16x32_f16 v[68:71], v[204:207], v[24:27], v[116:119]
	v_mfma_f32_16x16x32_f16 v[24:27], v[212:215], v[24:27], v[36:39]
	v_mfma_f32_16x16x32_f16 v[116:119], v[216:219], v[32:35], v[24:27]
	v_mfma_f32_16x16x32_f16 v[24:27], v[204:207], v[64:67], v[40:43]
	v_mfma_f32_16x16x32_f16 v[108:111], v[208:211], v[220:223], v[24:27]
	v_mfma_f32_16x16x32_f16 v[24:27], v[212:215], v[64:67], v[44:47]
	v_mfma_f32_16x16x32_f16 v[100:103], v[216:219], v[220:223], v[24:27]
	v_mfma_f32_16x16x32_f16 v[24:27], v[204:207], v[224:227], v[48:51]
	v_mfma_f32_16x16x32_f16 v[92:95], v[208:211], v[232:235], v[24:27]
	v_mfma_f32_16x16x32_f16 v[24:27], v[212:215], v[224:227], v[52:55]
	v_mfma_f32_16x16x32_f16 v[84:87], v[216:219], v[232:235], v[24:27]
	v_mfma_f32_16x16x32_f16 v[24:27], v[204:207], v[236:239], v[56:59]
	v_mfma_f32_16x16x32_f16 v[76:79], v[208:211], v[240:243], v[24:27]
	v_mfma_f32_16x16x32_f16 v[24:27], v[212:215], v[236:239], v[60:63]
	s_setprio 2
	s_barrier
	v_mfma_f32_16x16x32_f16 v[124:127], v[208:211], v[32:35], v[68:71]
	v_mfma_f32_16x16x32_f16 v[68:71], v[216:219], v[240:243], v[24:27]
	s_setprio 0
	s_add_i32 s68, s68, s53
	s_nop 2
	v_lshl_add_u64 v[24:25], v[138:139], 0, s[24:25]
	s_mov_b32 m0, s68
	ds_read_b128 v[36:39], v231 offset:49152
	ds_read_b128 v[44:47], v231 offset:50176
	ds_read_b128 v[220:223], v231 offset:51200
	ds_read_b128 v[224:227], v231 offset:52224
	ds_read_b128 v[232:235], v231 offset:53248
	ds_read_b128 v[236:239], v231 offset:54272
	ds_read_b128 v[240:243], v231 offset:55296
	ds_read_b128 v[244:247], v231 offset:56320
	global_load_lds_dwordx4 v[24:25], off
	v_lshl_add_u64 v[24:25], v[192:193], 0, s[24:25]
	s_add_i32 m0, s68, 0x2000
	s_add_i32 s68, s69, s53
	global_load_lds_dwordx4 v[24:25], off
	s_mov_b32 m0, s68
	v_lshl_add_u64 v[24:25], v[248:249], 0, s[24:25]
	global_load_lds_dwordx4 v2, s[44:45]
	s_add_i32 m0, s68, 0x2000
	s_nop 0
	global_load_lds_dwordx4 v134, s[44:45]
	s_mov_b32 m0, s59
	s_nop 0
	global_load_lds_dwordx4 v[24:25], off
	v_lshl_add_u64 v[24:25], v[250:251], 0, s[24:25]
	s_mov_b32 m0, s60
	s_nop 0
	global_load_lds_dwordx4 v[24:25], off
	s_waitcnt vmcnt(8)
	s_waitcnt lgkmcnt(0)
	s_barrier
	s_setprio 1
	s_waitcnt lgkmcnt(0)
	s_nop 0
	v_mfma_f32_16x16x32_f16 v[24:27], v[16:19], v[36:39], v[144:147]
	v_mfma_f32_16x16x32_f16 v[64:67], v[20:23], v[44:47], v[24:27]
	v_mfma_f32_16x16x32_f16 v[24:27], v[28:31], v[36:39], v[148:151]
	v_mfma_f32_16x16x32_f16 v[56:59], v[200:203], v[44:47], v[24:27]
	v_mfma_f32_16x16x32_f16 v[24:27], v[16:19], v[220:223], v[152:155]
	v_mfma_f32_16x16x32_f16 v[48:51], v[20:23], v[224:227], v[24:27]
	v_mfma_f32_16x16x32_f16 v[24:27], v[28:31], v[220:223], v[156:159]
	v_mfma_f32_16x16x32_f16 v[40:43], v[200:203], v[224:227], v[24:27]
	v_mfma_f32_16x16x32_f16 v[24:27], v[16:19], v[232:235], v[160:163]
	v_mfma_f32_16x16x32_f16 v[4:7], v[16:19], v[240:243], v[4:7]
	v_mfma_f32_16x16x32_f16 v[32:35], v[20:23], v[236:239], v[24:27]
	v_mfma_f32_16x16x32_f16 v[24:27], v[28:31], v[232:235], v[164:167]
	v_mfma_f32_16x16x32_f16 v[16:19], v[20:23], v[244:247], v[4:7]
	v_mfma_f32_16x16x32_f16 v[4:7], v[28:31], v[240:243], v[8:11]
	v_mfma_f32_16x16x32_f16 v[24:27], v[200:203], v[236:239], v[24:27]
	v_mfma_f32_16x16x32_f16 v[8:11], v[200:203], v[244:247], v[4:7]
	s_setprio 0
	s_setprio 1
	v_mfma_f32_16x16x32_f16 v[4:7], v[204:207], v[36:39], v[12:15]
	v_mfma_f32_16x16x32_f16 v[60:63], v[208:211], v[44:47], v[4:7]
	v_mfma_f32_16x16x32_f16 v[4:7], v[212:215], v[36:39], v[172:175]
	v_mfma_f32_16x16x32_f16 v[52:55], v[216:219], v[44:47], v[4:7]
	v_mfma_f32_16x16x32_f16 v[4:7], v[204:207], v[220:223], v[176:179]
	v_mfma_f32_16x16x32_f16 v[44:47], v[208:211], v[224:227], v[4:7]
	v_mfma_f32_16x16x32_f16 v[4:7], v[212:215], v[220:223], v[180:183]
	v_mfma_f32_16x16x32_f16 v[36:39], v[216:219], v[224:227], v[4:7]
	v_mfma_f32_16x16x32_f16 v[4:7], v[204:207], v[232:235], v[168:171]
	v_mfma_f32_16x16x32_f16 v[28:31], v[208:211], v[236:239], v[4:7]
	v_mfma_f32_16x16x32_f16 v[4:7], v[212:215], v[232:235], v[184:187]
	v_mfma_f32_16x16x32_f16 v[20:23], v[216:219], v[236:239], v[4:7]
	v_mfma_f32_16x16x32_f16 v[4:7], v[204:207], v[240:243], v[188:191]
	v_mfma_f32_16x16x32_f16 v[12:15], v[208:211], v[244:247], v[4:7]
	s_setprio 2
	s_barrier
	v_mfma_f32_16x16x32_f16 v[4:7], v[212:215], v[240:243], v[196:199]
	v_mfma_f32_16x16x32_f16 v[4:7], v[216:219], v[244:247], v[4:7]
	s_setprio 0
	s_add_i32 s67, s67, 2
	s_cmp_ge_i32 s67, s11
	s_cbranch_scc0 .LBB0_2159

.LBB0_2161:
	s_add_u32 s68, s6, s40
	s_addc_u32 s69, s7, s41
	s_add_u32 s42, s68, 0x200
	s_addc_u32 s43, s69, 0
	s_add_u32 s44, s8, s40
	s_addc_u32 s45, s9, s41
	s_add_u32 s67, s44, 0x200
	s_addc_u32 s70, s45, 0
	s_add_i32 s71, 0, 0x10000
	s_cmp_eq_u32 s11, 28
	s_cselect_b32 s45, s29, s43
	s_cselect_b32 s44, s28, s42
	v_add_u32_e32 v133, s71, v143
	s_cselect_b32 s43, s37, s70
	s_cselect_b32 s42, s36, s67
	s_add_i32 s67, 0, 0x14000
	ds_read_b128 v[144:147], v133
	ds_read_b128 v[148:151], v133 offset:1024
	ds_read_b128 v[152:155], v133 offset:2048
	ds_read_b128 v[156:159], v133 offset:3072
	v_add_u32_e32 v133, s67, v143
	ds_read_b128 v[160:163], v133
	ds_read_b128 v[164:167], v133 offset:1024
	ds_read_b128 v[168:171], v133 offset:2048
	ds_read_b128 v[172:175], v133 offset:3072
	v_lshl_add_u64 v[136:137], s[68:69], 0, v[2:3]
	s_mov_b32 m0, s61
	v_add_u32_e32 v216, 0, v142
	v_lshl_add_u64 v[136:137], v[136:137], 0, s[34:35]
	v_mov_b32_e32 v133, v3
	ds_read_b128 v[176:179], v216
	ds_read_b128 v[180:183], v216 offset:1024
	ds_read_b128 v[184:187], v216 offset:2048
	ds_read_b128 v[188:191], v216 offset:3072
	ds_read_b128 v[196:199], v216 offset:4096
	ds_read_b128 v[200:203], v216 offset:5120
	ds_read_b128 v[204:207], v216 offset:6144
	ds_read_b128 v[208:211], v216 offset:7168
	global_load_lds_dwordx4 v[136:137], off
	v_lshl_add_u64 v[136:137], s[68:69], 0, v[132:133]
	v_lshl_add_u64 v[136:137], v[136:137], 0, s[34:35]
	s_mov_b32 m0, s62
	s_nop 0
	global_load_lds_dwordx4 v[136:137], off
	s_waitcnt vmcnt(8)
	s_waitcnt lgkmcnt(0)
	s_barrier
	s_setprio 1
	s_waitcnt lgkmcnt(0)
	s_nop 0
	v_mfma_f32_16x16x32_f16 v[128:131], v[144:147], v[176:179], v[128:131]
	v_mfma_f32_16x16x32_f16 v[128:131], v[148:151], v[180:183], v[128:131]
	v_mfma_f32_16x16x32_f16 v[120:123], v[156:159], v[180:183], v[120:123]
	v_mfma_f32_16x16x32_f16 v[120:123], v[152:155], v[176:179], v[120:123]
	v_mfma_f32_16x16x32_f16 v[104:107], v[152:155], v[184:187], v[104:107]
	v_mfma_f32_16x16x32_f16 v[104:107], v[156:159], v[188:191], v[104:107]
	v_mfma_f32_16x16x32_f16 v[112:115], v[148:151], v[188:191], v[112:115]
	v_mfma_f32_16x16x32_f16 v[112:115], v[144:147], v[184:187], v[112:115]
	v_mfma_f32_16x16x32_f16 v[96:99], v[144:147], v[196:199], v[96:99]
	v_mfma_f32_16x16x32_f16 v[96:99], v[148:151], v[200:203], v[96:99]
	v_mfma_f32_16x16x32_f16 v[88:91], v[156:159], v[200:203], v[88:91]
	v_mfma_f32_16x16x32_f16 v[88:91], v[152:155], v[196:199], v[88:91]
	v_mfma_f32_16x16x32_f16 v[72:75], v[152:155], v[204:207], v[72:75]
	v_mfma_f32_16x16x32_f16 v[72:75], v[156:159], v[208:211], v[72:75]
	v_mfma_f32_16x16x32_f16 v[80:83], v[148:151], v[208:211], v[80:83]
	v_mfma_f32_16x16x32_f16 v[80:83], v[144:147], v[204:207], v[80:83]
	s_setprio 0
	s_setprio 1
	v_mfma_f32_16x16x32_f16 v[124:127], v[160:163], v[176:179], v[124:127]
	v_mfma_f32_16x16x32_f16 v[124:127], v[164:167], v[180:183], v[124:127]
	v_mfma_f32_16x16x32_f16 v[116:119], v[172:175], v[180:183], v[116:119]
	v_mfma_f32_16x16x32_f16 v[116:119], v[168:171], v[176:179], v[116:119]
	v_mfma_f32_16x16x32_f16 v[100:103], v[168:171], v[184:187], v[100:103]
	v_mfma_f32_16x16x32_f16 v[100:103], v[172:175], v[188:191], v[100:103]
	v_mfma_f32_16x16x32_f16 v[108:111], v[164:167], v[188:191], v[108:111]
	v_mfma_f32_16x16x32_f16 v[108:111], v[160:163], v[184:187], v[108:111]
	v_mfma_f32_16x16x32_f16 v[92:95], v[160:163], v[196:199], v[92:95]
	v_mfma_f32_16x16x32_f16 v[92:95], v[164:167], v[200:203], v[92:95]
	v_mfma_f32_16x16x32_f16 v[84:87], v[172:175], v[200:203], v[84:87]
	v_mfma_f32_16x16x32_f16 v[84:87], v[168:171], v[196:199], v[84:87]
	v_mfma_f32_16x16x32_f16 v[68:71], v[168:171], v[204:207], v[68:71]
	v_mfma_f32_16x16x32_f16 v[68:71], v[172:175], v[208:211], v[68:71]
	s_setprio 2
	s_barrier
	v_mfma_f32_16x16x32_f16 v[76:79], v[164:167], v[208:211], v[76:79]
	v_mfma_f32_16x16x32_f16 v[76:79], v[160:163], v[204:207], v[76:79]
	s_setprio 0
	s_add_i32 s68, s71, s53
	s_mov_b32 m0, s68
	ds_read_b128 v[176:179], v216 offset:16384
	ds_read_b128 v[180:183], v216 offset:17408
	ds_read_b128 v[184:187], v216 offset:18432
	ds_read_b128 v[188:191], v216 offset:19456
	ds_read_b128 v[196:199], v216 offset:20480
	ds_read_b128 v[200:203], v216 offset:21504
	ds_read_b128 v[204:207], v216 offset:22528
	ds_read_b128 v[208:211], v216 offset:23552
	global_load_lds_dwordx4 v138, s[42:43]
	s_add_i32 m0, s68, 0x2000
	s_add_u32 s68, s42, 0x80000
	s_addc_u32 s69, s43, 0
	s_add_i32 s67, s67, s53
	global_load_lds_dwordx4 v134, s[42:43]
	s_mov_b32 m0, s67
	v_mov_b32_e32 v139, v3
	global_load_lds_dwordx4 v138, s[68:69]
	s_add_i32 m0, s67, 0x2000
	v_mov_b32_e32 v135, v3
	global_load_lds_dwordx4 v134, s[68:69]
	s_mov_b32 m0, s54
	v_lshl_add_u64 v[136:137], s[42:43], 0, v[138:139]
	global_load_lds_dwordx4 v2, s[44:45]
	s_mov_b32 m0, s55
	v_lshl_add_u64 v[192:193], s[42:43], 0, v[134:135]
	global_load_lds_dwordx4 v132, s[44:45]
	s_waitcnt vmcnt(8)
	s_waitcnt lgkmcnt(0)
	v_lshl_add_u64 v[212:213], s[44:45], 0, v[2:3]
	v_lshl_add_u64 v[214:215], s[44:45], 0, v[132:133]
	s_barrier
	s_setprio 1
	s_waitcnt lgkmcnt(0)
	s_nop 0
	v_mfma_f32_16x16x32_f16 v[64:67], v[144:147], v[176:179], v[64:67]
	v_mfma_f32_16x16x32_f16 v[64:67], v[148:151], v[180:183], v[64:67]
	v_mfma_f32_16x16x32_f16 v[56:59], v[156:159], v[180:183], v[56:59]
	v_mfma_f32_16x16x32_f16 v[56:59], v[152:155], v[176:179], v[56:59]
	v_mfma_f32_16x16x32_f16 v[40:43], v[152:155], v[184:187], v[40:43]
	v_mfma_f32_16x16x32_f16 v[40:43], v[156:159], v[188:191], v[40:43]
	v_mfma_f32_16x16x32_f16 v[48:51], v[148:151], v[188:191], v[48:51]
	v_mfma_f32_16x16x32_f16 v[48:51], v[144:147], v[184:187], v[48:51]
	v_mfma_f32_16x16x32_f16 v[32:35], v[144:147], v[196:199], v[32:35]
	v_mfma_f32_16x16x32_f16 v[32:35], v[148:151], v[200:203], v[32:35]
	v_mfma_f32_16x16x32_f16 v[24:27], v[156:159], v[200:203], v[24:27]
	v_mfma_f32_16x16x32_f16 v[24:27], v[152:155], v[196:199], v[24:27]
	v_mfma_f32_16x16x32_f16 v[8:11], v[152:155], v[204:207], v[8:11]
	v_mfma_f32_16x16x32_f16 v[8:11], v[156:159], v[208:211], v[8:11]
	v_mfma_f32_16x16x32_f16 v[16:19], v[148:151], v[208:211], v[16:19]
	v_mfma_f32_16x16x32_f16 v[16:19], v[144:147], v[204:207], v[16:19]
	s_setprio 0
	s_setprio 1
	v_mfma_f32_16x16x32_f16 v[60:63], v[160:163], v[176:179], v[60:63]
	v_mfma_f32_16x16x32_f16 v[60:63], v[164:167], v[180:183], v[60:63]
	v_mfma_f32_16x16x32_f16 v[52:55], v[172:175], v[180:183], v[52:55]
	v_mfma_f32_16x16x32_f16 v[52:55], v[168:171], v[176:179], v[52:55]
	v_mfma_f32_16x16x32_f16 v[36:39], v[168:171], v[184:187], v[36:39]
	v_mfma_f32_16x16x32_f16 v[36:39], v[172:175], v[188:191], v[36:39]
	v_mfma_f32_16x16x32_f16 v[44:47], v[164:167], v[188:191], v[44:47]
	v_mfma_f32_16x16x32_f16 v[44:47], v[160:163], v[184:187], v[44:47]
	v_mfma_f32_16x16x32_f16 v[28:31], v[160:163], v[196:199], v[28:31]
	v_mfma_f32_16x16x32_f16 v[28:31], v[164:167], v[200:203], v[28:31]
	v_mfma_f32_16x16x32_f16 v[20:23], v[172:175], v[200:203], v[20:23]
	v_mfma_f32_16x16x32_f16 v[20:23], v[168:171], v[196:199], v[20:23]
	v_mfma_f32_16x16x32_f16 v[4:7], v[168:171], v[204:207], v[4:7]
	v_mfma_f32_16x16x32_f16 v[4:7], v[172:175], v[208:211], v[4:7]
	s_setprio 2
	s_barrier
	v_mfma_f32_16x16x32_f16 v[12:15], v[164:167], v[208:211], v[12:15]
	v_mfma_f32_16x16x32_f16 v[12:15], v[160:163], v[204:207], v[12:15]
	s_setprio 0
	s_add_i32 s67, 0, 0x18000
	v_add_u32_e32 v135, s67, v143
	s_add_i32 s68, 0, 0x1c000
	ds_read_b128 v[144:147], v135
	ds_read_b128 v[148:151], v135 offset:1024
	ds_read_b128 v[152:155], v135 offset:2048
	ds_read_b128 v[156:159], v135 offset:3072
	v_add_u32_e32 v135, s68, v143
	ds_read_b128 v[160:163], v135
	ds_read_b128 v[164:167], v135 offset:1024
	ds_read_b128 v[168:171], v135 offset:2048
	ds_read_b128 v[172:175], v135 offset:3072
	s_add_u32 s44, s44, 0x80000
	s_addc_u32 s45, s45, 0
	s_mov_b32 m0, s56
	ds_read_b128 v[176:179], v216 offset:32768
	ds_read_b128 v[180:183], v216 offset:33792
	ds_read_b128 v[184:187], v216 offset:34816
	ds_read_b128 v[188:191], v216 offset:35840
	ds_read_b128 v[196:199], v216 offset:36864
	ds_read_b128 v[200:203], v216 offset:37888
	ds_read_b128 v[204:207], v216 offset:38912
	ds_read_b128 v[208:211], v216 offset:39936
	global_load_lds_dwordx4 v2, s[44:45]
	s_mov_b32 m0, s57
	s_nop 0
	global_load_lds_dwordx4 v132, s[44:45]
	s_waitcnt vmcnt(8)
	s_waitcnt lgkmcnt(0)
	s_barrier
	s_setprio 1
	s_waitcnt lgkmcnt(0)
	s_nop 0
	v_mfma_f32_16x16x32_f16 v[128:131], v[144:147], v[176:179], v[128:131]
	v_mfma_f32_16x16x32_f16 v[128:131], v[148:151], v[180:183], v[128:131]
	v_mfma_f32_16x16x32_f16 v[120:123], v[156:159], v[180:183], v[120:123]
	v_mfma_f32_16x16x32_f16 v[120:123], v[152:155], v[176:179], v[120:123]
	v_mfma_f32_16x16x32_f16 v[104:107], v[152:155], v[184:187], v[104:107]
	v_mfma_f32_16x16x32_f16 v[104:107], v[156:159], v[188:191], v[104:107]
	v_mfma_f32_16x16x32_f16 v[112:115], v[148:151], v[188:191], v[112:115]
	v_mfma_f32_16x16x32_f16 v[112:115], v[144:147], v[184:187], v[112:115]
	v_mfma_f32_16x16x32_f16 v[96:99], v[144:147], v[196:199], v[96:99]
	v_mfma_f32_16x16x32_f16 v[96:99], v[148:151], v[200:203], v[96:99]
	v_mfma_f32_16x16x32_f16 v[88:91], v[156:159], v[200:203], v[88:91]
	v_mfma_f32_16x16x32_f16 v[88:91], v[152:155], v[196:199], v[88:91]
	v_mfma_f32_16x16x32_f16 v[72:75], v[152:155], v[204:207], v[72:75]
	v_mfma_f32_16x16x32_f16 v[72:75], v[156:159], v[208:211], v[72:75]
	v_mfma_f32_16x16x32_f16 v[80:83], v[148:151], v[208:211], v[80:83]
	v_mfma_f32_16x16x32_f16 v[80:83], v[144:147], v[204:207], v[80:83]
	s_setprio 0
	s_setprio 1
	v_mfma_f32_16x16x32_f16 v[124:127], v[160:163], v[176:179], v[124:127]
	v_mfma_f32_16x16x32_f16 v[124:127], v[164:167], v[180:183], v[124:127]
	v_mfma_f32_16x16x32_f16 v[116:119], v[172:175], v[180:183], v[116:119]
	v_mfma_f32_16x16x32_f16 v[116:119], v[168:171], v[176:179], v[116:119]
	v_mfma_f32_16x16x32_f16 v[100:103], v[168:171], v[184:187], v[100:103]
	v_mfma_f32_16x16x32_f16 v[100:103], v[172:175], v[188:191], v[100:103]
	v_mfma_f32_16x16x32_f16 v[108:111], v[164:167], v[188:191], v[108:111]
	v_mfma_f32_16x16x32_f16 v[108:111], v[160:163], v[184:187], v[108:111]
	v_mfma_f32_16x16x32_f16 v[92:95], v[160:163], v[196:199], v[92:95]
	v_mfma_f32_16x16x32_f16 v[92:95], v[164:167], v[200:203], v[92:95]
	v_mfma_f32_16x16x32_f16 v[84:87], v[172:175], v[200:203], v[84:87]
	v_mfma_f32_16x16x32_f16 v[84:87], v[168:171], v[196:199], v[84:87]
	v_mfma_f32_16x16x32_f16 v[68:71], v[168:171], v[204:207], v[68:71]
	v_mfma_f32_16x16x32_f16 v[68:71], v[172:175], v[208:211], v[68:71]
	s_setprio 2
	s_barrier
	v_mfma_f32_16x16x32_f16 v[76:79], v[164:167], v[208:211], v[76:79]
	v_mfma_f32_16x16x32_f16 v[76:79], v[160:163], v[204:207], v[76:79]
	s_setprio 0
	s_add_i32 s44, s67, s53
	v_lshl_add_u64 v[136:137], v[136:137], 0, s[86:87]
	s_mov_b32 m0, s44
	ds_read_b128 v[176:179], v216 offset:49152
	ds_read_b128 v[180:183], v216 offset:50176
	ds_read_b128 v[184:187], v216 offset:51200
	ds_read_b128 v[188:191], v216 offset:52224
	ds_read_b128 v[196:199], v216 offset:53248
	ds_read_b128 v[200:203], v216 offset:54272
	ds_read_b128 v[204:207], v216 offset:55296
	ds_read_b128 v[208:211], v216 offset:56320
	global_load_lds_dwordx4 v[136:137], off
	s_add_i32 m0, s44, 0x2000
	s_add_u32 s42, s42, 0x80080
	v_lshl_add_u64 v[136:137], v[192:193], 0, s[86:87]
	s_addc_u32 s43, s43, 0
	s_add_i32 s44, s68, s53
	global_load_lds_dwordx4 v[136:137], off
	s_mov_b32 m0, s44
	v_lshl_add_u64 v[136:137], v[212:213], 0, s[86:87]
	global_load_lds_dwordx4 v138, s[42:43]
	s_add_i32 m0, s44, 0x2000
	s_nop 0
	global_load_lds_dwordx4 v134, s[42:43]
	s_mov_b32 m0, s59
	s_nop 0
	global_load_lds_dwordx4 v[136:137], off
	v_lshl_add_u64 v[136:137], v[214:215], 0, s[86:87]
	s_mov_b32 m0, s60
	s_nop 0
	global_load_lds_dwordx4 v[136:137], off
	s_waitcnt vmcnt(8)
	s_waitcnt lgkmcnt(0)
	s_barrier
	s_setprio 1
	s_waitcnt lgkmcnt(0)
	s_nop 0
	v_mfma_f32_16x16x32_f16 v[64:67], v[144:147], v[176:179], v[64:67]
	v_mfma_f32_16x16x32_f16 v[64:67], v[148:151], v[180:183], v[64:67]
	v_mfma_f32_16x16x32_f16 v[56:59], v[156:159], v[180:183], v[56:59]
	v_mfma_f32_16x16x32_f16 v[56:59], v[152:155], v[176:179], v[56:59]
	v_mfma_f32_16x16x32_f16 v[40:43], v[152:155], v[184:187], v[40:43]
	v_mfma_f32_16x16x32_f16 v[40:43], v[156:159], v[188:191], v[40:43]
	v_mfma_f32_16x16x32_f16 v[48:51], v[148:151], v[188:191], v[48:51]
	v_mfma_f32_16x16x32_f16 v[48:51], v[144:147], v[184:187], v[48:51]
	v_mfma_f32_16x16x32_f16 v[32:35], v[144:147], v[196:199], v[32:35]
	v_mfma_f32_16x16x32_f16 v[32:35], v[148:151], v[200:203], v[32:35]
	v_mfma_f32_16x16x32_f16 v[24:27], v[156:159], v[200:203], v[24:27]
	v_mfma_f32_16x16x32_f16 v[24:27], v[152:155], v[196:199], v[24:27]
	v_mfma_f32_16x16x32_f16 v[8:11], v[152:155], v[204:207], v[8:11]
	v_mfma_f32_16x16x32_f16 v[8:11], v[156:159], v[208:211], v[8:11]
	v_mfma_f32_16x16x32_f16 v[16:19], v[148:151], v[208:211], v[16:19]
	v_mfma_f32_16x16x32_f16 v[16:19], v[144:147], v[204:207], v[16:19]
	s_setprio 0
	s_setprio 1
	v_mfma_f32_16x16x32_f16 v[60:63], v[160:163], v[176:179], v[60:63]
	v_mfma_f32_16x16x32_f16 v[60:63], v[164:167], v[180:183], v[60:63]
	v_mfma_f32_16x16x32_f16 v[52:55], v[172:175], v[180:183], v[52:55]
	v_mfma_f32_16x16x32_f16 v[52:55], v[168:171], v[176:179], v[52:55]
	v_mfma_f32_16x16x32_f16 v[36:39], v[168:171], v[184:187], v[36:39]
	v_mfma_f32_16x16x32_f16 v[36:39], v[172:175], v[188:191], v[36:39]
	v_mfma_f32_16x16x32_f16 v[44:47], v[164:167], v[188:191], v[44:47]
	v_mfma_f32_16x16x32_f16 v[44:47], v[160:163], v[184:187], v[44:47]
	v_mfma_f32_16x16x32_f16 v[28:31], v[160:163], v[196:199], v[28:31]
	v_mfma_f32_16x16x32_f16 v[28:31], v[164:167], v[200:203], v[28:31]
	v_mfma_f32_16x16x32_f16 v[20:23], v[172:175], v[200:203], v[20:23]
	v_mfma_f32_16x16x32_f16 v[20:23], v[168:171], v[196:199], v[20:23]
	v_mfma_f32_16x16x32_f16 v[4:7], v[168:171], v[204:207], v[4:7]
	v_mfma_f32_16x16x32_f16 v[4:7], v[172:175], v[208:211], v[4:7]
	s_setprio 2
	s_barrier
	v_mfma_f32_16x16x32_f16 v[12:15], v[164:167], v[208:211], v[12:15]
	v_mfma_f32_16x16x32_f16 v[12:15], v[160:163], v[204:207], v[12:15]
	s_setprio 0
	s_add_i32 s11, s11, 2
	s_add_u32 s40, s40, 0x100
	s_addc_u32 s41, s41, 0
	s_cmp_gt_u32 s11, 29
	s_cbranch_scc0 .LBB0_2161
	s_andn2_b64 vcc, exec, s[26:27]
	s_cbranch_vccnz .LBB0_2164
	s_add_u32 s6, s28, 0x80080
	s_addc_u32 s7, s29, 0
	s_mov_b32 m0, s61
	v_lshl_add_u64 v[144:145], s[6:7], 0, v[2:3]
	v_lshl_add_u64 v[136:137], s[6:7], 0, v[132:133]
	global_load_lds_dwordx4 v[144:145], off
	s_mov_b32 m0, s62
	s_mov_b32 s47, s65
	global_load_lds_dwordx4 v[136:137], off
	s_mov_b32 s64, s10
	s_mov_b64 s[8:9], s[14:15]
	s_mov_b64 s[6:7], s[12:13]
	s_mov_b32 s63, s66

.LBB0_2269:
	s_add_i32 s51, 0, 0x10000
	s_add_i32 s71, 0, 0x14000
	v_add_u32_e32 v16, s51, v232
	v_add_u32_e32 v32, s71, v232
	ds_read_b128 v[4:7], v16
	ds_read_b128 v[8:11], v16 offset:1024
	ds_read_b128 v[12:15], v16 offset:2048
	ds_read_b128 v[16:19], v16 offset:3072
	ds_read_b128 v[20:23], v32
	ds_read_b128 v[24:27], v32 offset:1024
	ds_read_b128 v[28:31], v32 offset:2048
	ds_read_b128 v[32:35], v32 offset:3072
	v_add_u32_e32 v233, 0, v231
	ds_read_b128 v[36:39], v233
	ds_read_b128 v[40:43], v233 offset:1024
	ds_read_b128 v[44:47], v233 offset:2048
	ds_read_b128 v[48:51], v233 offset:3072
	ds_read_b128 v[52:55], v233 offset:4096
	ds_read_b128 v[56:59], v233 offset:5120
	ds_read_b128 v[60:63], v233 offset:6144
	ds_read_b128 v[64:67], v233 offset:7168
	s_waitcnt vmcnt(8)
	s_waitcnt lgkmcnt(0)
	s_barrier
	s_setprio 1
	s_waitcnt lgkmcnt(0)
	s_nop 0
	v_mfma_f32_16x16x32_bf16 v[68:71], v[4:7], v[36:39], 0
	v_mfma_f32_16x16x32_bf16 v[68:71], v[8:11], v[40:43], v[68:71]
	v_mfma_f32_16x16x32_bf16 v[72:75], v[12:15], v[36:39], 0
	v_mfma_f32_16x16x32_bf16 v[72:75], v[16:19], v[40:43], v[72:75]
	v_mfma_f32_16x16x32_bf16 v[80:83], v[12:15], v[44:47], 0
	v_mfma_f32_16x16x32_bf16 v[80:83], v[16:19], v[48:51], v[80:83]
	v_mfma_f32_16x16x32_bf16 v[76:79], v[4:7], v[44:47], 0
	v_mfma_f32_16x16x32_bf16 v[76:79], v[8:11], v[48:51], v[76:79]
	v_mfma_f32_16x16x32_bf16 v[84:87], v[4:7], v[52:55], 0
	v_mfma_f32_16x16x32_bf16 v[84:87], v[8:11], v[56:59], v[84:87]
	v_mfma_f32_16x16x32_bf16 v[88:91], v[12:15], v[52:55], 0
	v_mfma_f32_16x16x32_bf16 v[88:91], v[16:19], v[56:59], v[88:91]
	v_mfma_f32_16x16x32_bf16 v[96:99], v[12:15], v[60:63], 0
	v_mfma_f32_16x16x32_bf16 v[96:99], v[16:19], v[64:67], v[96:99]
	v_mfma_f32_16x16x32_bf16 v[92:95], v[4:7], v[60:63], 0
	v_mfma_f32_16x16x32_bf16 v[92:95], v[8:11], v[64:67], v[92:95]
	s_setprio 0
	s_setprio 1
	v_mfma_f32_16x16x32_bf16 v[100:103], v[20:23], v[36:39], 0
	v_mfma_f32_16x16x32_bf16 v[36:39], v[28:31], v[36:39], 0
	v_mfma_f32_16x16x32_bf16 v[104:107], v[20:23], v[44:47], 0
	v_mfma_f32_16x16x32_bf16 v[44:47], v[28:31], v[44:47], 0
	v_mfma_f32_16x16x32_bf16 v[108:111], v[20:23], v[52:55], 0
	v_mfma_f32_16x16x32_bf16 v[52:55], v[28:31], v[52:55], 0
	v_mfma_f32_16x16x32_bf16 v[112:115], v[20:23], v[60:63], 0
	v_mfma_f32_16x16x32_bf16 v[60:63], v[28:31], v[60:63], 0
	v_mfma_f32_16x16x32_bf16 v[100:103], v[24:27], v[40:43], v[100:103]
	v_mfma_f32_16x16x32_bf16 v[40:43], v[32:35], v[40:43], v[36:39]
	v_mfma_f32_16x16x32_bf16 v[104:107], v[24:27], v[48:51], v[104:107]
	v_mfma_f32_16x16x32_bf16 v[48:51], v[32:35], v[48:51], v[44:47]
	v_mfma_f32_16x16x32_bf16 v[108:111], v[24:27], v[56:59], v[108:111]
	v_mfma_f32_16x16x32_bf16 v[56:59], v[32:35], v[56:59], v[52:55]
	s_setprio 2
	s_barrier
	v_mfma_f32_16x16x32_bf16 v[112:115], v[24:27], v[64:67], v[112:115]
	v_mfma_f32_16x16x32_bf16 v[64:67], v[32:35], v[64:67], v[60:63]
	s_setprio 0
	v_lshl_add_u64 v[186:187], s[12:13], 0, v[2:3]
	s_add_i32 s51, s51, s38
	v_mov_b32_e32 v191, v3
	v_lshl_add_u64 v[134:135], v[186:187], 0, s[74:75]
	s_mov_b32 m0, s51
	v_lshl_add_u64 v[246:247], s[12:13], 0, v[190:191]
	ds_read_b128 v[36:39], v233 offset:16384
	ds_read_b128 v[44:47], v233 offset:17408
	ds_read_b128 v[52:55], v233 offset:18432
	ds_read_b128 v[60:63], v233 offset:19456
	ds_read_b128 v[116:119], v233 offset:20480
	ds_read_b128 v[120:123], v233 offset:21504
	ds_read_b128 v[124:127], v233 offset:22528
	ds_read_b128 v[128:131], v233 offset:23552
	global_load_lds_dwordx4 v[134:135], off
	v_lshl_add_u64 v[134:135], v[246:247], 0, s[74:75]
	s_add_i32 m0, s51, 0x2000
	s_add_i32 s51, s71, s38
	global_load_lds_dwordx4 v[134:135], off
	s_mov_b32 m0, s51
	v_mov_b32_e32 v133, v3
	global_load_lds_dwordx4 v2, s[16:17]
	s_add_i32 m0, s51, 0x2000
	v_lshl_add_u64 v[248:249], s[14:15], 0, v[132:133]
	v_mov_b32_e32 v189, v3
	global_load_lds_dwordx4 v190, s[16:17]
	v_lshl_add_u64 v[134:135], v[248:249], 0, s[74:75]
	s_mov_b32 m0, s56
	v_lshl_add_u64 v[250:251], s[14:15], 0, v[188:189]
	global_load_lds_dwordx4 v[134:135], off
	v_lshl_add_u64 v[134:135], v[250:251], 0, s[74:75]
	s_mov_b32 m0, s57
	s_nop 0
	global_load_lds_dwordx4 v[134:135], off
	s_waitcnt vmcnt(8)
	s_waitcnt lgkmcnt(0)
	s_barrier
	s_setprio 1
	s_waitcnt lgkmcnt(0)
	s_nop 0
	v_mfma_f32_16x16x32_bf16 v[134:137], v[4:7], v[36:39], 0
	v_mfma_f32_16x16x32_bf16 v[138:141], v[12:15], v[36:39], 0
	v_mfma_f32_16x16x32_bf16 v[142:145], v[4:7], v[52:55], 0
	v_mfma_f32_16x16x32_bf16 v[146:149], v[12:15], v[52:55], 0
	v_mfma_f32_16x16x32_bf16 v[150:153], v[4:7], v[116:119], 0
	v_mfma_f32_16x16x32_bf16 v[154:157], v[12:15], v[116:119], 0
	v_mfma_f32_16x16x32_bf16 v[4:7], v[4:7], v[124:127], 0
	v_mfma_f32_16x16x32_bf16 v[12:15], v[12:15], v[124:127], 0
	v_mfma_f32_16x16x32_bf16 v[134:137], v[8:11], v[44:47], v[134:137]
	v_mfma_f32_16x16x32_bf16 v[138:141], v[16:19], v[44:47], v[138:141]
	v_mfma_f32_16x16x32_bf16 v[142:145], v[8:11], v[60:63], v[142:145]
	v_mfma_f32_16x16x32_bf16 v[146:149], v[16:19], v[60:63], v[146:149]
	v_mfma_f32_16x16x32_bf16 v[150:153], v[8:11], v[120:123], v[150:153]
	v_mfma_f32_16x16x32_bf16 v[154:157], v[16:19], v[120:123], v[154:157]
	v_mfma_f32_16x16x32_bf16 v[158:161], v[8:11], v[128:131], v[4:7]
	v_mfma_f32_16x16x32_bf16 v[162:165], v[16:19], v[128:131], v[12:15]
	s_setprio 0
	s_setprio 1
	v_mfma_f32_16x16x32_bf16 v[4:7], v[20:23], v[36:39], 0
	v_mfma_f32_16x16x32_bf16 v[8:11], v[28:31], v[36:39], 0
	v_mfma_f32_16x16x32_bf16 v[12:15], v[20:23], v[52:55], 0
	v_mfma_f32_16x16x32_bf16 v[16:19], v[28:31], v[52:55], 0
	v_mfma_f32_16x16x32_bf16 v[36:39], v[20:23], v[116:119], 0
	v_mfma_f32_16x16x32_bf16 v[52:55], v[28:31], v[116:119], 0
	v_mfma_f32_16x16x32_bf16 v[20:23], v[20:23], v[124:127], 0
	v_mfma_f32_16x16x32_bf16 v[28:31], v[28:31], v[124:127], 0
	v_mfma_f32_16x16x32_bf16 v[116:119], v[24:27], v[44:47], v[4:7]
	v_mfma_f32_16x16x32_bf16 v[124:127], v[32:35], v[44:47], v[8:11]
	v_mfma_f32_16x16x32_bf16 v[174:177], v[24:27], v[120:123], v[36:39]
	v_mfma_f32_16x16x32_bf16 v[120:123], v[32:35], v[120:123], v[52:55]
	v_mfma_f32_16x16x32_bf16 v[178:181], v[24:27], v[128:131], v[20:23]
	v_mfma_f32_16x16x32_bf16 v[128:131], v[32:35], v[128:131], v[28:31]
	s_setprio 2
	s_barrier
	v_mfma_f32_16x16x32_bf16 v[166:169], v[24:27], v[60:63], v[12:15]
	v_mfma_f32_16x16x32_bf16 v[170:173], v[32:35], v[60:63], v[16:19]
	s_setprio 0
	s_add_i32 s51, 0, 0x18000
	v_add_u32_e32 v4, s51, v232
	s_add_i32 s71, 0, 0x1c000
	ds_read_b128 v[182:185], v4
	ds_read_b128 v[192:195], v4 offset:1024
	ds_read_b128 v[196:199], v4 offset:2048
	ds_read_b128 v[200:203], v4 offset:3072
	v_add_u32_e32 v4, s71, v232
	ds_read_b128 v[204:207], v4
	ds_read_b128 v[208:211], v4 offset:1024
	ds_read_b128 v[212:215], v4 offset:2048
	ds_read_b128 v[216:219], v4 offset:3072
	s_mov_b32 m0, s58
	ds_read_b128 v[44:47], v233 offset:32768
	ds_read_b128 v[52:55], v233 offset:33792
	ds_read_b128 v[60:63], v233 offset:34816
	ds_read_b128 v[220:223], v233 offset:35840
	ds_read_b128 v[224:227], v233 offset:36864
	ds_read_b128 v[234:237], v233 offset:37888
	ds_read_b128 v[238:241], v233 offset:38912
	ds_read_b128 v[242:245], v233 offset:39936
	global_load_lds_dwordx4 v132, s[26:27]
	s_mov_b32 m0, s59
	s_nop 0
	global_load_lds_dwordx4 v188, s[26:27]
	s_waitcnt vmcnt(8)
	s_waitcnt lgkmcnt(0)
	s_barrier
	s_setprio 1
	s_waitcnt lgkmcnt(0)
	s_nop 0
	v_mfma_f32_16x16x32_bf16 v[4:7], v[182:185], v[44:47], v[68:71]
	v_mfma_f32_16x16x32_bf16 v[8:11], v[196:199], v[44:47], v[72:75]
	v_mfma_f32_16x16x32_bf16 v[12:15], v[182:185], v[60:63], v[76:79]
	v_mfma_f32_16x16x32_bf16 v[16:19], v[196:199], v[60:63], v[80:83]
	v_mfma_f32_16x16x32_bf16 v[20:23], v[182:185], v[224:227], v[84:87]
	v_mfma_f32_16x16x32_bf16 v[24:27], v[196:199], v[224:227], v[88:91]
	v_mfma_f32_16x16x32_bf16 v[28:31], v[182:185], v[238:241], v[92:95]
	v_mfma_f32_16x16x32_bf16 v[32:35], v[196:199], v[238:241], v[96:99]
	v_mfma_f32_16x16x32_bf16 v[4:7], v[192:195], v[52:55], v[4:7]
	v_mfma_f32_16x16x32_bf16 v[8:11], v[200:203], v[52:55], v[8:11]
	v_mfma_f32_16x16x32_bf16 v[12:15], v[192:195], v[220:223], v[12:15]
	v_mfma_f32_16x16x32_bf16 v[16:19], v[200:203], v[220:223], v[16:19]
	v_mfma_f32_16x16x32_bf16 v[20:23], v[192:195], v[234:237], v[20:23]
	v_mfma_f32_16x16x32_bf16 v[24:27], v[200:203], v[234:237], v[24:27]
	v_mfma_f32_16x16x32_bf16 v[28:31], v[192:195], v[242:245], v[28:31]
	v_mfma_f32_16x16x32_bf16 v[32:35], v[200:203], v[242:245], v[32:35]
	s_setprio 0
	s_setprio 1
	v_mfma_f32_16x16x32_bf16 v[36:39], v[204:207], v[44:47], v[100:103]
	v_mfma_f32_16x16x32_bf16 v[40:43], v[212:215], v[44:47], v[40:43]
	v_mfma_f32_16x16x32_bf16 v[36:39], v[208:211], v[52:55], v[36:39]
	v_mfma_f32_16x16x32_bf16 v[40:43], v[216:219], v[52:55], v[40:43]
	v_mfma_f32_16x16x32_bf16 v[44:47], v[204:207], v[60:63], v[104:107]
	v_mfma_f32_16x16x32_bf16 v[48:51], v[212:215], v[60:63], v[48:51]
	v_mfma_f32_16x16x32_bf16 v[52:55], v[204:207], v[224:227], v[108:111]
	v_mfma_f32_16x16x32_bf16 v[56:59], v[212:215], v[224:227], v[56:59]
	v_mfma_f32_16x16x32_bf16 v[60:63], v[204:207], v[238:241], v[112:115]
	v_mfma_f32_16x16x32_bf16 v[64:67], v[212:215], v[238:241], v[64:67]
	v_mfma_f32_16x16x32_bf16 v[44:47], v[208:211], v[220:223], v[44:47]
	v_mfma_f32_16x16x32_bf16 v[48:51], v[216:219], v[220:223], v[48:51]
	v_mfma_f32_16x16x32_bf16 v[52:55], v[208:211], v[234:237], v[52:55]
	v_mfma_f32_16x16x32_bf16 v[56:59], v[216:219], v[234:237], v[56:59]
	s_setprio 2
	s_barrier
	v_mfma_f32_16x16x32_bf16 v[60:63], v[208:211], v[242:245], v[60:63]
	v_mfma_f32_16x16x32_bf16 v[64:67], v[216:219], v[242:245], v[64:67]
	s_setprio 0
	s_add_i32 s51, s51, s38
	v_lshl_add_u64 v[68:69], v[186:187], 0, s[24:25]
	s_mov_b32 m0, s51
	ds_read_b128 v[104:107], v233 offset:49152
	ds_read_b128 v[108:111], v233 offset:50176
	ds_read_b128 v[112:115], v233 offset:51200
	ds_read_b128 v[220:223], v233 offset:52224
	ds_read_b128 v[224:227], v233 offset:53248
	ds_read_b128 v[234:237], v233 offset:54272
	ds_read_b128 v[238:241], v233 offset:55296
	ds_read_b128 v[242:245], v233 offset:56320
	global_load_lds_dwordx4 v[68:69], off
	v_lshl_add_u64 v[68:69], v[246:247], 0, s[24:25]
	s_add_i32 m0, s51, 0x2000
	s_add_i32 s51, s71, s38
	global_load_lds_dwordx4 v[68:69], off
	s_mov_b32 m0, s51
	v_lshl_add_u64 v[68:69], v[248:249], 0, s[24:25]
	global_load_lds_dwordx4 v2, s[28:29]
	s_add_i32 m0, s51, 0x2000
	s_nop 0
	global_load_lds_dwordx4 v190, s[28:29]
	s_mov_b32 m0, s63
	s_nop 0
	global_load_lds_dwordx4 v[68:69], off
	v_lshl_add_u64 v[68:69], v[250:251], 0, s[24:25]
	s_mov_b32 m0, s64
	s_nop 0
	global_load_lds_dwordx4 v[68:69], off
	s_waitcnt vmcnt(8)
	s_waitcnt lgkmcnt(0)
	s_barrier
	s_setprio 1
	s_waitcnt lgkmcnt(0)
	s_nop 0
	v_mfma_f32_16x16x32_bf16 v[68:71], v[182:185], v[104:107], v[134:137]
	v_mfma_f32_16x16x32_bf16 v[72:75], v[196:199], v[104:107], v[138:141]
	v_mfma_f32_16x16x32_bf16 v[76:79], v[182:185], v[112:115], v[142:145]
	v_mfma_f32_16x16x32_bf16 v[80:83], v[196:199], v[112:115], v[146:149]
	v_mfma_f32_16x16x32_bf16 v[84:87], v[182:185], v[224:227], v[150:153]
	v_mfma_f32_16x16x32_bf16 v[88:91], v[196:199], v[224:227], v[154:157]
	v_mfma_f32_16x16x32_bf16 v[92:95], v[182:185], v[238:241], v[158:161]
	v_mfma_f32_16x16x32_bf16 v[96:99], v[196:199], v[238:241], v[162:165]
	v_mfma_f32_16x16x32_bf16 v[68:71], v[192:195], v[108:111], v[68:71]
	v_mfma_f32_16x16x32_bf16 v[72:75], v[200:203], v[108:111], v[72:75]
	v_mfma_f32_16x16x32_bf16 v[76:79], v[192:195], v[220:223], v[76:79]
	v_mfma_f32_16x16x32_bf16 v[80:83], v[200:203], v[220:223], v[80:83]
	v_mfma_f32_16x16x32_bf16 v[84:87], v[192:195], v[234:237], v[84:87]
	v_mfma_f32_16x16x32_bf16 v[88:91], v[200:203], v[234:237], v[88:91]
	v_mfma_f32_16x16x32_bf16 v[92:95], v[192:195], v[242:245], v[92:95]
	v_mfma_f32_16x16x32_bf16 v[96:99], v[200:203], v[242:245], v[96:99]
	s_setprio 0
	s_setprio 1
	v_mfma_f32_16x16x32_bf16 v[100:103], v[204:207], v[104:107], v[116:119]
	v_mfma_f32_16x16x32_bf16 v[104:107], v[212:215], v[104:107], v[124:127]
	v_mfma_f32_16x16x32_bf16 v[100:103], v[208:211], v[108:111], v[100:103]
	v_mfma_f32_16x16x32_bf16 v[104:107], v[216:219], v[108:111], v[104:107]
	v_mfma_f32_16x16x32_bf16 v[108:111], v[204:207], v[112:115], v[166:169]
	v_mfma_f32_16x16x32_bf16 v[112:115], v[212:215], v[112:115], v[170:173]
	v_mfma_f32_16x16x32_bf16 v[116:119], v[204:207], v[224:227], v[174:177]
	v_mfma_f32_16x16x32_bf16 v[120:123], v[212:215], v[224:227], v[120:123]
	v_mfma_f32_16x16x32_bf16 v[124:127], v[204:207], v[238:241], v[178:181]
	v_mfma_f32_16x16x32_bf16 v[128:131], v[212:215], v[238:241], v[128:131]
	v_mfma_f32_16x16x32_bf16 v[108:111], v[208:211], v[220:223], v[108:111]
	v_mfma_f32_16x16x32_bf16 v[112:115], v[216:219], v[220:223], v[112:115]
	v_mfma_f32_16x16x32_bf16 v[116:119], v[208:211], v[234:237], v[116:119]
	v_mfma_f32_16x16x32_bf16 v[120:123], v[216:219], v[234:237], v[120:123]
	s_setprio 2
	s_barrier
	v_mfma_f32_16x16x32_bf16 v[124:127], v[208:211], v[242:245], v[124:127]
	v_mfma_f32_16x16x32_bf16 v[128:131], v[216:219], v[242:245], v[128:131]
	s_setprio 0
	s_add_i32 s41, s41, 2
	s_cmp_ge_i32 s41, s40
	s_cbranch_scc0 .LBB0_2269
	v_mov_b32_e32 v192, v2
	s_branch .LBB0_2272

.LBB0_2273:
	s_add_u32 s12, s14, 0xfffc0080
	s_addc_u32 s13, s15, -1
	s_add_i32 s29, 0, 0x10000
	s_cmp_eq_u32 s28, 12
	s_cselect_b32 s17, s9, s13
	s_cselect_b32 s16, s8, s12
	s_cselect_b32 s13, s11, s27
	s_cselect_b32 s12, s10, s26
	s_add_i32 s51, 0, 0x14000
	v_add_u32_e32 v144, s29, v232
	v_add_u32_e32 v160, s51, v232
	s_waitcnt lgkmcnt(0)
	ds_read_b128 v[132:135], v144
	ds_read_b128 v[136:139], v144 offset:1024
	ds_read_b128 v[140:143], v144 offset:2048
	ds_read_b128 v[144:147], v144 offset:3072
	ds_read_b128 v[148:151], v160
	ds_read_b128 v[152:155], v160 offset:1024
	ds_read_b128 v[156:159], v160 offset:2048
	ds_read_b128 v[160:163], v160 offset:3072
	s_mov_b32 m0, s65
	v_add_u32_e32 v210, 0, v231
	ds_read_b128 v[164:167], v210
	ds_read_b128 v[168:171], v210 offset:1024
	ds_read_b128 v[172:175], v210 offset:2048
	ds_read_b128 v[176:179], v210 offset:3072
	ds_read_b128 v[180:183], v210 offset:4096
	ds_read_b128 v[184:187], v210 offset:5120
	ds_read_b128 v[194:197], v210 offset:6144
	ds_read_b128 v[198:201], v210 offset:7168
	global_load_lds_dwordx4 v2, s[14:15]
	s_mov_b32 m0, s66
	v_mov_b32_e32 v189, v3
	global_load_lds_dwordx4 v188, s[14:15]
	s_waitcnt vmcnt(8)
	s_waitcnt lgkmcnt(0)
	s_barrier
	s_setprio 1
	s_waitcnt lgkmcnt(0)
	s_nop 0
	v_mfma_f32_16x16x32_bf16 v[4:7], v[132:135], v[164:167], v[4:7]
	v_mfma_f32_16x16x32_bf16 v[4:7], v[136:139], v[168:171], v[4:7]
	v_mfma_f32_16x16x32_bf16 v[8:11], v[144:147], v[168:171], v[8:11]
	v_mfma_f32_16x16x32_bf16 v[8:11], v[140:143], v[164:167], v[8:11]
	v_mfma_f32_16x16x32_bf16 v[16:19], v[140:143], v[172:175], v[16:19]
	v_mfma_f32_16x16x32_bf16 v[16:19], v[144:147], v[176:179], v[16:19]
	v_mfma_f32_16x16x32_bf16 v[12:15], v[136:139], v[176:179], v[12:15]
	v_mfma_f32_16x16x32_bf16 v[12:15], v[132:135], v[172:175], v[12:15]
	v_mfma_f32_16x16x32_bf16 v[20:23], v[132:135], v[180:183], v[20:23]
	v_mfma_f32_16x16x32_bf16 v[20:23], v[136:139], v[184:187], v[20:23]
	v_mfma_f32_16x16x32_bf16 v[24:27], v[144:147], v[184:187], v[24:27]
	v_mfma_f32_16x16x32_bf16 v[24:27], v[140:143], v[180:183], v[24:27]
	v_mfma_f32_16x16x32_bf16 v[32:35], v[140:143], v[194:197], v[32:35]
	v_mfma_f32_16x16x32_bf16 v[32:35], v[144:147], v[198:201], v[32:35]
	v_mfma_f32_16x16x32_bf16 v[28:31], v[136:139], v[198:201], v[28:31]
	v_mfma_f32_16x16x32_bf16 v[28:31], v[132:135], v[194:197], v[28:31]
	s_setprio 0
	s_setprio 1
	v_mfma_f32_16x16x32_bf16 v[36:39], v[148:151], v[164:167], v[36:39]
	v_mfma_f32_16x16x32_bf16 v[36:39], v[152:155], v[168:171], v[36:39]
	v_mfma_f32_16x16x32_bf16 v[40:43], v[160:163], v[168:171], v[40:43]
	v_mfma_f32_16x16x32_bf16 v[40:43], v[156:159], v[164:167], v[40:43]
	v_mfma_f32_16x16x32_bf16 v[48:51], v[156:159], v[172:175], v[48:51]
	v_mfma_f32_16x16x32_bf16 v[48:51], v[160:163], v[176:179], v[48:51]
	v_mfma_f32_16x16x32_bf16 v[44:47], v[152:155], v[176:179], v[44:47]
	v_mfma_f32_16x16x32_bf16 v[44:47], v[148:151], v[172:175], v[44:47]
	v_mfma_f32_16x16x32_bf16 v[52:55], v[148:151], v[180:183], v[52:55]
	v_mfma_f32_16x16x32_bf16 v[52:55], v[152:155], v[184:187], v[52:55]
	v_mfma_f32_16x16x32_bf16 v[56:59], v[160:163], v[184:187], v[56:59]
	v_mfma_f32_16x16x32_bf16 v[56:59], v[156:159], v[180:183], v[56:59]
	v_mfma_f32_16x16x32_bf16 v[64:67], v[156:159], v[194:197], v[64:67]
	v_mfma_f32_16x16x32_bf16 v[64:67], v[160:163], v[198:201], v[64:67]
	s_setprio 2
	s_barrier
	v_mfma_f32_16x16x32_bf16 v[60:63], v[152:155], v[198:201], v[60:63]
	v_mfma_f32_16x16x32_bf16 v[60:63], v[148:151], v[194:197], v[60:63]
	s_setprio 0
	s_add_i32 s29, s29, s38
	s_mov_b32 m0, s29
	ds_read_b128 v[164:167], v210 offset:16384
	ds_read_b128 v[168:171], v210 offset:17408
	ds_read_b128 v[172:175], v210 offset:18432
	ds_read_b128 v[176:179], v210 offset:19456
	ds_read_b128 v[180:183], v210 offset:20480
	ds_read_b128 v[184:187], v210 offset:21504
	ds_read_b128 v[194:197], v210 offset:22528
	ds_read_b128 v[198:201], v210 offset:23552
	global_load_lds_dwordx4 v192, s[12:13]
	s_add_i32 m0, s29, 0x2000
	s_add_u32 s40, s12, 0x100000
	s_addc_u32 s41, s13, 0
	s_add_i32 s29, s51, s38
	global_load_lds_dwordx4 v190, s[12:13]
	s_mov_b32 m0, s29
	v_mov_b32_e32 v193, v3
	global_load_lds_dwordx4 v192, s[40:41]
	s_add_i32 m0, s29, 0x2000
	v_mov_b32_e32 v191, v3
	global_load_lds_dwordx4 v190, s[40:41]
	s_mov_b32 m0, s56
	v_lshl_add_u64 v[202:203], s[12:13], 0, v[192:193]
	global_load_lds_dwordx4 v2, s[16:17]
	s_mov_b32 m0, s57
	v_lshl_add_u64 v[204:205], s[12:13], 0, v[190:191]
	global_load_lds_dwordx4 v188, s[16:17]
	s_waitcnt vmcnt(8)
	s_waitcnt lgkmcnt(0)
	v_lshl_add_u64 v[206:207], s[16:17], 0, v[2:3]
	v_lshl_add_u64 v[208:209], s[16:17], 0, v[188:189]
	s_barrier
	s_setprio 1
	s_waitcnt lgkmcnt(0)
	s_nop 0
	v_mfma_f32_16x16x32_bf16 v[68:71], v[132:135], v[164:167], v[68:71]
	v_mfma_f32_16x16x32_bf16 v[68:71], v[136:139], v[168:171], v[68:71]
	v_mfma_f32_16x16x32_bf16 v[72:75], v[144:147], v[168:171], v[72:75]
	v_mfma_f32_16x16x32_bf16 v[72:75], v[140:143], v[164:167], v[72:75]
	v_mfma_f32_16x16x32_bf16 v[80:83], v[140:143], v[172:175], v[80:83]
	v_mfma_f32_16x16x32_bf16 v[80:83], v[144:147], v[176:179], v[80:83]
	v_mfma_f32_16x16x32_bf16 v[76:79], v[136:139], v[176:179], v[76:79]
	v_mfma_f32_16x16x32_bf16 v[76:79], v[132:135], v[172:175], v[76:79]
	v_mfma_f32_16x16x32_bf16 v[84:87], v[132:135], v[180:183], v[84:87]
	v_mfma_f32_16x16x32_bf16 v[84:87], v[136:139], v[184:187], v[84:87]
	v_mfma_f32_16x16x32_bf16 v[88:91], v[144:147], v[184:187], v[88:91]
	v_mfma_f32_16x16x32_bf16 v[88:91], v[140:143], v[180:183], v[88:91]
	v_mfma_f32_16x16x32_bf16 v[96:99], v[140:143], v[194:197], v[96:99]
	v_mfma_f32_16x16x32_bf16 v[96:99], v[144:147], v[198:201], v[96:99]
	v_mfma_f32_16x16x32_bf16 v[92:95], v[136:139], v[198:201], v[92:95]
	v_mfma_f32_16x16x32_bf16 v[92:95], v[132:135], v[194:197], v[92:95]
	s_setprio 0
	s_setprio 1
	v_mfma_f32_16x16x32_bf16 v[100:103], v[148:151], v[164:167], v[100:103]
	v_mfma_f32_16x16x32_bf16 v[100:103], v[152:155], v[168:171], v[100:103]
	v_mfma_f32_16x16x32_bf16 v[104:107], v[160:163], v[168:171], v[104:107]
	v_mfma_f32_16x16x32_bf16 v[104:107], v[156:159], v[164:167], v[104:107]
	v_mfma_f32_16x16x32_bf16 v[112:115], v[156:159], v[172:175], v[112:115]
	v_mfma_f32_16x16x32_bf16 v[112:115], v[160:163], v[176:179], v[112:115]
	v_mfma_f32_16x16x32_bf16 v[108:111], v[152:155], v[176:179], v[108:111]
	v_mfma_f32_16x16x32_bf16 v[108:111], v[148:151], v[172:175], v[108:111]
	v_mfma_f32_16x16x32_bf16 v[116:119], v[148:151], v[180:183], v[116:119]
	v_mfma_f32_16x16x32_bf16 v[116:119], v[152:155], v[184:187], v[116:119]
	v_mfma_f32_16x16x32_bf16 v[120:123], v[160:163], v[184:187], v[120:123]
	v_mfma_f32_16x16x32_bf16 v[120:123], v[156:159], v[180:183], v[120:123]
	v_mfma_f32_16x16x32_bf16 v[128:131], v[156:159], v[194:197], v[128:131]
	v_mfma_f32_16x16x32_bf16 v[128:131], v[160:163], v[198:201], v[128:131]
	s_setprio 2
	s_barrier
	v_mfma_f32_16x16x32_bf16 v[124:127], v[152:155], v[198:201], v[124:127]
	v_mfma_f32_16x16x32_bf16 v[124:127], v[148:151], v[194:197], v[124:127]
	s_setprio 0
	s_add_i32 s29, 0, 0x18000
	s_add_i32 s40, 0, 0x1c000
	v_add_u32_e32 v144, s29, v232
	v_add_u32_e32 v160, s40, v232
	ds_read_b128 v[132:135], v144
	ds_read_b128 v[136:139], v144 offset:1024
	ds_read_b128 v[140:143], v144 offset:2048
	ds_read_b128 v[144:147], v144 offset:3072
	ds_read_b128 v[148:151], v160
	ds_read_b128 v[152:155], v160 offset:1024
	ds_read_b128 v[156:159], v160 offset:2048
	ds_read_b128 v[160:163], v160 offset:3072
	s_add_u32 s16, s16, 0x40000
	s_addc_u32 s17, s17, 0
	s_mov_b32 m0, s58
	ds_read_b128 v[164:167], v210 offset:32768
	ds_read_b128 v[168:171], v210 offset:33792
	ds_read_b128 v[172:175], v210 offset:34816
	ds_read_b128 v[176:179], v210 offset:35840
	ds_read_b128 v[180:183], v210 offset:36864
	ds_read_b128 v[184:187], v210 offset:37888
	ds_read_b128 v[194:197], v210 offset:38912
	ds_read_b128 v[198:201], v210 offset:39936
	global_load_lds_dwordx4 v2, s[16:17]
	s_mov_b32 m0, s59
	s_nop 0
	global_load_lds_dwordx4 v188, s[16:17]
	s_waitcnt vmcnt(8)
	s_waitcnt lgkmcnt(0)
	s_barrier
	s_setprio 1
	s_waitcnt lgkmcnt(0)
	s_nop 0
	v_mfma_f32_16x16x32_bf16 v[4:7], v[132:135], v[164:167], v[4:7]
	v_mfma_f32_16x16x32_bf16 v[4:7], v[136:139], v[168:171], v[4:7]
	v_mfma_f32_16x16x32_bf16 v[8:11], v[144:147], v[168:171], v[8:11]
	v_mfma_f32_16x16x32_bf16 v[8:11], v[140:143], v[164:167], v[8:11]
	v_mfma_f32_16x16x32_bf16 v[16:19], v[140:143], v[172:175], v[16:19]
	v_mfma_f32_16x16x32_bf16 v[16:19], v[144:147], v[176:179], v[16:19]
	v_mfma_f32_16x16x32_bf16 v[12:15], v[136:139], v[176:179], v[12:15]
	v_mfma_f32_16x16x32_bf16 v[12:15], v[132:135], v[172:175], v[12:15]
	v_mfma_f32_16x16x32_bf16 v[20:23], v[132:135], v[180:183], v[20:23]
	v_mfma_f32_16x16x32_bf16 v[20:23], v[136:139], v[184:187], v[20:23]
	v_mfma_f32_16x16x32_bf16 v[24:27], v[144:147], v[184:187], v[24:27]
	v_mfma_f32_16x16x32_bf16 v[24:27], v[140:143], v[180:183], v[24:27]
	v_mfma_f32_16x16x32_bf16 v[32:35], v[140:143], v[194:197], v[32:35]
	v_mfma_f32_16x16x32_bf16 v[32:35], v[144:147], v[198:201], v[32:35]
	v_mfma_f32_16x16x32_bf16 v[28:31], v[136:139], v[198:201], v[28:31]
	v_mfma_f32_16x16x32_bf16 v[28:31], v[132:135], v[194:197], v[28:31]
	s_setprio 0
	s_setprio 1
	v_mfma_f32_16x16x32_bf16 v[36:39], v[148:151], v[164:167], v[36:39]
	v_mfma_f32_16x16x32_bf16 v[36:39], v[152:155], v[168:171], v[36:39]
	v_mfma_f32_16x16x32_bf16 v[40:43], v[160:163], v[168:171], v[40:43]
	v_mfma_f32_16x16x32_bf16 v[40:43], v[156:159], v[164:167], v[40:43]
	v_mfma_f32_16x16x32_bf16 v[48:51], v[156:159], v[172:175], v[48:51]
	v_mfma_f32_16x16x32_bf16 v[48:51], v[160:163], v[176:179], v[48:51]
	v_mfma_f32_16x16x32_bf16 v[44:47], v[152:155], v[176:179], v[44:47]
	v_mfma_f32_16x16x32_bf16 v[44:47], v[148:151], v[172:175], v[44:47]
	v_mfma_f32_16x16x32_bf16 v[52:55], v[148:151], v[180:183], v[52:55]
	v_mfma_f32_16x16x32_bf16 v[52:55], v[152:155], v[184:187], v[52:55]
	v_mfma_f32_16x16x32_bf16 v[56:59], v[160:163], v[184:187], v[56:59]
	v_mfma_f32_16x16x32_bf16 v[56:59], v[156:159], v[180:183], v[56:59]
	v_mfma_f32_16x16x32_bf16 v[64:67], v[156:159], v[194:197], v[64:67]
	v_mfma_f32_16x16x32_bf16 v[64:67], v[160:163], v[198:201], v[64:67]
	s_setprio 2
	s_barrier
	v_mfma_f32_16x16x32_bf16 v[60:63], v[152:155], v[198:201], v[60:63]
	v_mfma_f32_16x16x32_bf16 v[60:63], v[148:151], v[194:197], v[60:63]
	s_setprio 0
	s_add_i32 s16, s29, s38
	v_lshl_add_u64 v[202:203], v[202:203], 0, s[86:87]
	s_mov_b32 m0, s16
	ds_read_b128 v[164:167], v210 offset:49152
	ds_read_b128 v[168:171], v210 offset:50176
	ds_read_b128 v[172:175], v210 offset:51200
	ds_read_b128 v[176:179], v210 offset:52224
	ds_read_b128 v[180:183], v210 offset:53248
	ds_read_b128 v[184:187], v210 offset:54272
	ds_read_b128 v[194:197], v210 offset:55296
	ds_read_b128 v[198:201], v210 offset:56320
	global_load_lds_dwordx4 v[202:203], off
	s_add_i32 m0, s16, 0x2000
	s_add_u32 s12, s12, 0x100080
	v_lshl_add_u64 v[202:203], v[204:205], 0, s[86:87]
	s_addc_u32 s13, s13, 0
	s_add_i32 s16, s40, s38
	global_load_lds_dwordx4 v[202:203], off
	s_mov_b32 m0, s16
	v_lshl_add_u64 v[202:203], v[206:207], 0, s[86:87]
	global_load_lds_dwordx4 v192, s[12:13]
	s_add_i32 m0, s16, 0x2000
	s_nop 0
	global_load_lds_dwordx4 v190, s[12:13]
	s_mov_b32 m0, s63
	s_nop 0
	global_load_lds_dwordx4 v[202:203], off
	v_lshl_add_u64 v[202:203], v[208:209], 0, s[86:87]
	s_mov_b32 m0, s64
	s_nop 0
	global_load_lds_dwordx4 v[202:203], off
	s_waitcnt vmcnt(8)
	s_waitcnt lgkmcnt(0)
	s_barrier
	s_setprio 1
	s_waitcnt lgkmcnt(0)
	s_nop 0
	v_mfma_f32_16x16x32_bf16 v[68:71], v[132:135], v[164:167], v[68:71]
	v_mfma_f32_16x16x32_bf16 v[68:71], v[136:139], v[168:171], v[68:71]
	v_mfma_f32_16x16x32_bf16 v[72:75], v[144:147], v[168:171], v[72:75]
	v_mfma_f32_16x16x32_bf16 v[72:75], v[140:143], v[164:167], v[72:75]
	v_mfma_f32_16x16x32_bf16 v[80:83], v[140:143], v[172:175], v[80:83]
	v_mfma_f32_16x16x32_bf16 v[80:83], v[144:147], v[176:179], v[80:83]
	v_mfma_f32_16x16x32_bf16 v[76:79], v[136:139], v[176:179], v[76:79]
	v_mfma_f32_16x16x32_bf16 v[76:79], v[132:135], v[172:175], v[76:79]
	v_mfma_f32_16x16x32_bf16 v[84:87], v[132:135], v[180:183], v[84:87]
	v_mfma_f32_16x16x32_bf16 v[84:87], v[136:139], v[184:187], v[84:87]
	v_mfma_f32_16x16x32_bf16 v[88:91], v[144:147], v[184:187], v[88:91]
	v_mfma_f32_16x16x32_bf16 v[88:91], v[140:143], v[180:183], v[88:91]
	v_mfma_f32_16x16x32_bf16 v[96:99], v[140:143], v[194:197], v[96:99]
	v_mfma_f32_16x16x32_bf16 v[96:99], v[144:147], v[198:201], v[96:99]
	v_mfma_f32_16x16x32_bf16 v[92:95], v[136:139], v[198:201], v[92:95]
	v_mfma_f32_16x16x32_bf16 v[92:95], v[132:135], v[194:197], v[92:95]
	s_setprio 0
	s_setprio 1
	v_mfma_f32_16x16x32_bf16 v[100:103], v[148:151], v[164:167], v[100:103]
	v_mfma_f32_16x16x32_bf16 v[100:103], v[152:155], v[168:171], v[100:103]
	v_mfma_f32_16x16x32_bf16 v[104:107], v[160:163], v[168:171], v[104:107]
	v_mfma_f32_16x16x32_bf16 v[104:107], v[156:159], v[164:167], v[104:107]
	v_mfma_f32_16x16x32_bf16 v[112:115], v[156:159], v[172:175], v[112:115]
	v_mfma_f32_16x16x32_bf16 v[112:115], v[160:163], v[176:179], v[112:115]
	v_mfma_f32_16x16x32_bf16 v[108:111], v[152:155], v[176:179], v[108:111]
	v_mfma_f32_16x16x32_bf16 v[108:111], v[148:151], v[172:175], v[108:111]
	v_mfma_f32_16x16x32_bf16 v[116:119], v[148:151], v[180:183], v[116:119]
	v_mfma_f32_16x16x32_bf16 v[116:119], v[152:155], v[184:187], v[116:119]
	v_mfma_f32_16x16x32_bf16 v[120:123], v[160:163], v[184:187], v[120:123]
	v_mfma_f32_16x16x32_bf16 v[120:123], v[156:159], v[180:183], v[120:123]
	v_mfma_f32_16x16x32_bf16 v[128:131], v[156:159], v[194:197], v[128:131]
	v_mfma_f32_16x16x32_bf16 v[128:131], v[160:163], v[198:201], v[128:131]
	s_setprio 2
	s_barrier
	v_mfma_f32_16x16x32_bf16 v[124:127], v[152:155], v[198:201], v[124:127]
	v_mfma_f32_16x16x32_bf16 v[124:127], v[148:151], v[194:197], v[124:127]
	s_setprio 0
	s_add_i32 s28, s28, 2
	s_add_u32 s14, s14, 0x100
	s_addc_u32 s15, s15, 0
	s_add_u32 s26, s26, 0x100
	s_addc_u32 s27, s27, 0
	s_cmp_gt_u32 s28, 13
	s_cbranch_scc0 .LBB0_2273
	s_and_b64 vcc, exec, s[48:49]
	s_cbranch_vccz .LBB0_2276
	s_barrier
